# v41 + EpiResid epilogue SSQ cross-row hops (lane^16, lane^32) via v_permlane16/32_swap instead of ds_bpermute (40 sites), no scratch reg, store-data WAR pad
# speedup vs baseline: 1.0009x; 1.0009x over previous
;     __device__ __forceinline__ void operator()(AccT acc, const pg8::Unit& u, int wr, int wc, int fr, int fq) const {
;         const int row0 = u.pm * 256 + wr * 64 + fr, col0 = u.pn * 256 + wc * 32 + 8 * fq, lane = fq * 16 + fr;
;         const int bidx = u.pm < 64 ? (u.pm >> 4) : 4;
;         const float* gp = gate + (size_t)bidx * MODW + col0;
;         f32x4 gv[2][2], gz[2][2];
; #pragma unroll
;         for (int bj = 0; bj < 2; ++bj)
; #pragma unroll
;             for (int n = 0; n < 2; ++n) { gv[bj][n] = *(const f32x4*)(gp + bj * 128 + n * 4) * coef;
;                 if (WZ) gz[bj][n] = *(const f32x4*)(gnext + col0 + bj * 128 + n * 4) * (*(const f32x4*)(scnext + (size_t)bidx * MODW + col0 + bj * 128 + n * 4) + 1.f); }
;         const int st4 = ((lane & 3) * 16 + (lane >> 2)) * 4, ld4 = ((lane & 15) * 4 + (lane >> 4)) * 4;
;         const size_t eo = (size_t)(u.pm * 256 + wr * 64 + (lane >> 2)) * LDP + u.pn * 256 + wc * 32 + (lane & 3) * 8;
;         hf_t* hout = H + eo; bf16_t* zout = Z + eo; float ss[8];
;         if constexpr (B32) {
;             const float* base = (const float*)(u.pm < 64 ? baseL : baseC) + (size_t)row0 * D + col0;
;             f32x4 hb[4][2][2];
; #pragma unroll
;             for (int ai = 0; ai < 2; ++ai) {
; #pragma unroll
;                 for (int m = 0; m < 4; ++m)
; #pragma unroll
;                     for (int bj = 0; bj < 2; ++bj)
; #pragma unroll
;                         for (int n = 0; n < 2; ++n) hb[m][bj][n] = *(const f32x4*)(base + (size_t)(ai * 128 + m * 16) * D + bj * 128 + n * 4);
;                 asm volatile("" ::: "memory");
; #pragma unroll
;                 for (int m = 0; m < 4; ++m) { const size_t ro = (size_t)(ai * 128 + m * 16) * LDP; float t = 0.f;
; #pragma unroll
;                     for (int bj = 0; bj < 2; ++bj) { const f32x4 h0 = hb[m][bj][0] + gv[bj][0] * acc[ai][bj][m][0], h1 = hb[m][bj][1] + gv[bj][1] * acc[ai][bj][m][1];
;                         const h16x4 q0 = __builtin_convertvector(h0, h16x4), q1 = __builtin_convertvector(h1, h16x4);
;                         { const h16x8 hv8 = (h16x8){q0[0], q0[1], q0[2], q0[3], q1[0], q1[1], q1[2], q1[3]}; *(u32x4*)(hout + ro + bj * 128) = gather4(__builtin_bit_cast(u32x4, hv8), st4); }
.LBB0_350:
	s_lshr_b32 s2, s33, 4
	s_lshl_b32 s21, s33, 8
	s_mul_i32 s40, s2, 0x4800
	s_add_i32 s21, s21, s84
	s_lshl_b32 s23, s96, 8
	s_lshl_b64 s[8:9], s[40:41], 2
	s_add_u32 s28, s54, s8
	v_or_b32_e32 v192, s23, v213
	s_addc_u32 s29, s55, s9
	v_lshlrev_b64 v[128:129], 2, v[192:193]
	s_add_u32 s8, s57, s8
	v_lshl_add_u64 v[148:149], s[28:29], 0, v[128:129]
	s_addc_u32 s9, s72, s9
	v_lshl_add_u64 v[150:151], s[14:15], 0, v[128:129]
	v_lshl_add_u64 v[152:153], s[8:9], 0, v[128:129]
	global_load_dwordx4 v[128:131], v[148:149], off offset:16
	global_load_dwordx4 v[132:135], v[148:149], off
	v_or_b32_e32 v192, s23, v217
	s_movk_i32 s2, 0x840
	v_or_b32_e32 v160, s21, v212
	s_lshl_b32 s40, s96, 2
	s_waitcnt vmcnt(0)
	v_pk_mul_f32 v[186:187], v[130:131], 0.5 op_sel_hi:[1,0]
	v_pk_mul_f32 v[190:191], v[134:135], 0.5 op_sel_hi:[1,0]
	v_pk_mul_f32 v[196:197], v[132:133], 0.5 op_sel_hi:[1,0]
	global_load_dwordx4 v[132:135], v[150:151], off offset:16
	global_load_dwordx4 v[136:139], v[150:151], off
	global_load_dwordx4 v[140:143], v[152:153], off offset:16
	global_load_dwordx4 v[144:147], v[152:153], off
	v_pk_mul_f32 v[188:189], v[128:129], 0.5 op_sel_hi:[1,0]
	s_waitcnt vmcnt(1)
	v_pk_add_f32 v[128:129], v[142:143], 1.0 op_sel_hi:[1,0]
	v_pk_add_f32 v[130:131], v[140:141], 1.0 op_sel_hi:[1,0]
	v_pk_mul_f32 v[178:179], v[134:135], v[128:129]
	v_pk_mul_f32 v[180:181], v[132:133], v[130:131]
	global_load_dwordx4 v[128:131], v[148:149], off offset:528
	global_load_dwordx4 v[132:135], v[148:149], off offset:512
	s_waitcnt vmcnt(2)
	v_pk_add_f32 v[146:147], v[146:147], 1.0 op_sel_hi:[1,0]
	v_pk_add_f32 v[144:145], v[144:145], 1.0 op_sel_hi:[1,0]
	v_pk_mul_f32 v[174:175], v[138:139], v[146:147]
	v_pk_mul_f32 v[176:177], v[136:137], v[144:145]
	s_waitcnt vmcnt(1)
	v_pk_mul_f32 v[172:173], v[128:129], 0.5 op_sel_hi:[1,0]
	s_waitcnt vmcnt(0)
	v_pk_mul_f32 v[182:183], v[134:135], 0.5 op_sel_hi:[1,0]
	v_pk_mul_f32 v[184:185], v[132:133], 0.5 op_sel_hi:[1,0]
	global_load_dwordx4 v[132:135], v[150:151], off offset:528
	global_load_dwordx4 v[136:139], v[150:151], off offset:512
	global_load_dwordx4 v[140:143], v[152:153], off offset:528
	global_load_dwordx4 v[144:147], v[152:153], off offset:512
	v_pk_mul_f32 v[170:171], v[130:131], 0.5 op_sel_hi:[1,0]
	s_waitcnt vmcnt(1)
	v_pk_add_f32 v[128:129], v[142:143], 1.0 op_sel_hi:[1,0]
	s_nop 0
	v_pk_mul_f32 v[166:167], v[134:135], v[128:129]
	v_or_b32_e32 v128, s21, v215
	v_mad_i64_i32 v[128:129], s[8:9], v128, s2, v[192:193]
	v_lshlrev_b64 v[128:129], 1, v[128:129]
	v_lshl_add_u64 v[200:201], s[10:11], 0, v[128:129]
	global_load_dwordx4 v[222:225], v[200:201], off
	global_load_dwordx4 v[152:155], v[200:201], off offset:256
	s_mov_b32 s2, 0x10000
	v_add_co_u32_e32 v206, vcc, s2, v200
	s_waitcnt vmcnt(2)
	v_pk_add_f32 v[146:147], v[146:147], 1.0 op_sel_hi:[1,0]
	v_pk_add_f32 v[144:145], v[144:145], 1.0 op_sel_hi:[1,0]
	v_addc_co_u32_e32 v207, vcc, 0, v201, vcc
	v_pk_mul_f32 v[162:163], v[138:139], v[146:147]
	v_pk_mul_f32 v[164:165], v[136:137], v[144:145]
	global_load_dwordx4 v[148:151], v[206:207], off offset:2048
	global_load_dwordx4 v[144:147], v[206:207], off offset:2304
	s_mov_b32 s8, 0x21000
	v_add_co_u32_e32 v204, vcc, s8, v200
	s_mov_b32 s9, 0x31000
	s_nop 0
	v_addc_co_u32_e32 v205, vcc, 0, v201, vcc
	v_add_co_u32_e32 v202, vcc, s9, v200
	v_pk_add_f32 v[130:131], v[140:141], 1.0 op_sel_hi:[1,0]
	s_nop 0
	v_addc_co_u32_e32 v203, vcc, 0, v201, vcc
	v_pk_mul_f32 v[168:169], v[132:133], v[130:131]
	v_lshl_add_u64 v[198:199], s[12:13], 0, v[128:129]
	global_load_dwordx4 v[140:143], v[204:205], off
	global_load_dwordx4 v[136:139], v[204:205], off offset:256
	global_load_dwordx4 v[132:135], v[202:203], off offset:2048
	global_load_dwordx4 v[128:131], v[202:203], off offset:2304
	s_mov_b32 s21, 0xb5000
	s_waitcnt vmcnt(7)
	ds_bpermute_b32 v159, v216, v222
	ds_bpermute_b32 v161, v216, v223
	ds_bpermute_b32 v192, v216, v224
	ds_bpermute_b32 v224, v216, v225
	s_waitcnt lgkmcnt(3)
	v_cvt_f32_f16_e32 v194, v159
	v_cvt_f32_f16_sdwa v195, v159 dst_sel:DWORD dst_unused:UNUSED_PAD src0_sel:WORD_1
	s_waitcnt lgkmcnt(2)
	v_cvt_f32_f16_e32 v222, v161
	v_cvt_f32_f16_sdwa v223, v161 dst_sel:DWORD dst_unused:UNUSED_PAD src0_sel:WORD_1
	v_ashrrev_i32_e32 v161, 31, v160
	v_pk_fma_f32 v[124:125], v[124:125], v[196:197], v[194:195]
	s_waitcnt lgkmcnt(1)
	v_cvt_f32_f16_e32 v194, v192
	v_pk_fma_f32 v[126:127], v[126:127], v[190:191], v[222:223]
	v_cvt_f32_f16_sdwa v195, v192 dst_sel:DWORD dst_unused:UNUSED_PAD src0_sel:WORD_1
	s_waitcnt lgkmcnt(0)
	v_cvt_f32_f16_e32 v222, v224
	v_cvt_f32_f16_sdwa v223, v224 dst_sel:DWORD dst_unused:UNUSED_PAD src0_sel:WORD_1
	v_pk_fma_f32 v[194:195], v[120:121], v[188:189], v[194:195]
	v_cvt_pk_f16_f32 v121, v126, v127
	v_pk_fma_f32 v[222:223], v[122:123], v[186:187], v[222:223]
	v_cvt_pk_f16_f32 v122, v194, v195
	v_cvt_pk_f16_f32 v123, v222, v223
	v_cvt_pk_f16_f32 v120, v124, v125
	ds_bpermute_b32 v120, v214, v120
	ds_bpermute_b32 v121, v214, v121
	ds_bpermute_b32 v122, v214, v122
	ds_bpermute_b32 v123, v214, v123
	s_waitcnt lgkmcnt(0)
	global_store_dwordx4 v[200:201], v[120:123], off
	s_nop 1
	v_mul_f32_e32 v120, v125, v125
	v_mul_f32_e32 v121, v127, v127
	v_fmac_f32_e32 v120, v124, v124
	v_fmac_f32_e32 v121, v126, v126
	v_add_f32_e32 v120, v120, v121
	v_mul_f32_e32 v121, v195, v195
	v_mul_f32_e32 v122, v223, v223
	v_fmac_f32_e32 v121, v194, v194
	v_fmac_f32_e32 v122, v222, v222
	v_add_f32_e32 v121, v121, v122
	v_add_f32_e32 v159, v120, v121
	v_pk_mul_f32 v[120:121], v[174:175], v[126:127]
	v_pk_mul_f32 v[122:123], v[176:177], v[124:125]
	v_pk_mul_f32 v[124:125], v[178:179], v[222:223]
	v_pk_mul_f32 v[126:127], v[180:181], v[194:195]
	v_cvt_pk_bf16_f32 v122, v122, v123
	v_cvt_pk_bf16_f32 v121, v120, v121
	ds_bpermute_b32 v120, v214, v122
	v_cvt_pk_bf16_f32 v123, v126, v127
	v_cvt_pk_bf16_f32 v124, v124, v125
	ds_bpermute_b32 v121, v214, v121
	ds_bpermute_b32 v122, v214, v123
	ds_bpermute_b32 v123, v214, v124
	s_waitcnt vmcnt(7)
; __device__ __forceinline__ unsigned cvt_pk_bf16(float lo, float hi) { unsigned r; asm volatile("v_cvt_pk_bf16_f32 %0, %1, %2" : "=v"(r) : "v"(lo), "v"(hi)); return r; }
;     __device__ __forceinline__ void operator()(AccT acc, const pg8::Unit& u, int wr, int wc, int fr, int fq) const {
;     ...
;                 for (int m = 0; m < 4; ++m) { const size_t ro = (size_t)(ai * 128 + m * 16) * LDP; float t = 0.f;
; #pragma unroll
;                     for (int bj = 0; bj < 2; ++bj) { const h16x8 b8 = __builtin_bit_cast(h16x8, gather4(__builtin_bit_cast(u32x4, hb[m][bj]), ld4));
;                         const f32x4 h0 = (f32x4){(float)b8[0], (float)b8[1], (float)b8[2], (float)b8[3]} + gv[bj][0] * acc[ai][bj][m][0], h1 = (f32x4){(float)b8[4], (float)b8[5], (float)b8[6], (float)b8[7]} + gv[bj][1] * acc[ai][bj][m][1];
;                         const h16x4 q0 = __builtin_convertvector(h0, h16x4), q1 = __builtin_convertvector(h1, h16x4);
;                         { const h16x8 hv8 = (h16x8){q0[0], q0[1], q0[2], q0[3], q1[0], q1[1], q1[2], q1[3]}; *(u32x4*)(hout + ro + bj * 128) = gather4(__builtin_bit_cast(u32x4, hv8), st4); }
;                         t += ((h0[0] * h0[0] + h0[1] * h0[1]) + (h0[2] * h0[2] + h0[3] * h0[3])) + ((h1[0] * h1[0] + h1[1] * h1[1]) + (h1[2] * h1[2] + h1[3] * h1[3]));
;                         if (WZ) { const f32x4 z0 = h0 * gz[bj][0], z1 = h1 * gz[bj][1]; u32x4 w; w.x = cvt_pk_bf16(z0[0], z0[1]); w.y = cvt_pk_bf16(z0[2], z0[3]); w.z = cvt_pk_bf16(z1[0], z1[1]); w.w = cvt_pk_bf16(z1[2], z1[3]);
;                             *(u32x4*)(zout + ro + bj * 128) = gather4(w, st4); } }
	ds_bpermute_b32 v124, v216, v154
	ds_bpermute_b32 v125, v216, v155
	s_waitcnt lgkmcnt(2)
	global_store_dwordx4 v[198:199], v[120:123], off
	ds_bpermute_b32 v121, v216, v152
	ds_bpermute_b32 v123, v216, v153
	s_waitcnt lgkmcnt(1)
	v_cvt_f32_f16_e32 v120, v121
	v_cvt_f32_f16_sdwa v121, v121 dst_sel:DWORD dst_unused:UNUSED_PAD src0_sel:WORD_1
	s_waitcnt lgkmcnt(0)
	v_cvt_f32_f16_e32 v122, v123
	v_cvt_f32_f16_sdwa v123, v123 dst_sel:DWORD dst_unused:UNUSED_PAD src0_sel:WORD_1
	v_pk_fma_f32 v[116:117], v[116:117], v[184:185], v[120:121]
	v_cvt_f32_f16_e32 v120, v124
	v_pk_fma_f32 v[118:119], v[118:119], v[182:183], v[122:123]
	v_cvt_f32_f16_sdwa v121, v124 dst_sel:DWORD dst_unused:UNUSED_PAD src0_sel:WORD_1
	v_cvt_f32_f16_e32 v122, v125
	v_cvt_f32_f16_sdwa v123, v125 dst_sel:DWORD dst_unused:UNUSED_PAD src0_sel:WORD_1
	v_pk_fma_f32 v[120:121], v[112:113], v[172:173], v[120:121]
	v_cvt_pk_f16_f32 v113, v118, v119
	v_pk_fma_f32 v[122:123], v[114:115], v[170:171], v[122:123]
	v_cvt_pk_f16_f32 v114, v120, v121
	v_cvt_pk_f16_f32 v115, v122, v123
	v_cvt_pk_f16_f32 v112, v116, v117
	ds_bpermute_b32 v112, v214, v112
	ds_bpermute_b32 v113, v214, v113
	ds_bpermute_b32 v114, v214, v114
	ds_bpermute_b32 v115, v214, v115
	s_waitcnt lgkmcnt(0)
	global_store_dwordx4 v[200:201], v[112:115], off offset:256
	s_nop 1
	v_mul_f32_e32 v112, v117, v117
	v_mul_f32_e32 v113, v119, v119
	v_fmac_f32_e32 v112, v116, v116
	v_fmac_f32_e32 v113, v118, v118
	v_add_f32_e32 v112, v112, v113
	v_mul_f32_e32 v113, v121, v121
	v_mul_f32_e32 v114, v123, v123
	v_fmac_f32_e32 v113, v120, v120
	v_fmac_f32_e32 v114, v122, v122
	v_add_f32_e32 v113, v113, v114
	v_add_f32_e32 v112, v112, v113
	v_add_f32_e32 v152, v159, v112
	v_pk_mul_f32 v[112:113], v[162:163], v[118:119]
	v_pk_mul_f32 v[114:115], v[164:165], v[116:117]
	v_pk_mul_f32 v[116:117], v[166:167], v[122:123]
	v_pk_mul_f32 v[118:119], v[168:169], v[120:121]
	v_cvt_pk_bf16_f32 v114, v114, v115
	v_cvt_pk_bf16_f32 v113, v112, v113
	ds_bpermute_b32 v112, v214, v114
	v_cvt_pk_bf16_f32 v115, v118, v119
	v_cvt_pk_bf16_f32 v116, v116, v117
	ds_bpermute_b32 v113, v214, v113
	ds_bpermute_b32 v114, v214, v115
	ds_bpermute_b32 v115, v214, v116
	s_waitcnt vmcnt(8)
	ds_bpermute_b32 v116, v216, v150
	ds_bpermute_b32 v117, v216, v151
	s_waitcnt lgkmcnt(2)
	global_store_dwordx4 v[198:199], v[112:115], off offset:256
	ds_bpermute_b32 v113, v216, v148
	ds_bpermute_b32 v115, v216, v149
	s_waitcnt lgkmcnt(1)
	v_cvt_f32_f16_e32 v112, v113
	v_cvt_f32_f16_sdwa v113, v113 dst_sel:DWORD dst_unused:UNUSED_PAD src0_sel:WORD_1
	s_waitcnt lgkmcnt(0)
	v_cvt_f32_f16_e32 v114, v115
	v_cvt_f32_f16_sdwa v115, v115 dst_sel:DWORD dst_unused:UNUSED_PAD src0_sel:WORD_1
	v_pk_fma_f32 v[108:109], v[108:109], v[196:197], v[112:113]
	v_cvt_f32_f16_e32 v112, v116
	v_pk_fma_f32 v[110:111], v[110:111], v[190:191], v[114:115]
	v_cvt_f32_f16_sdwa v113, v116 dst_sel:DWORD dst_unused:UNUSED_PAD src0_sel:WORD_1
	v_cvt_f32_f16_e32 v114, v117
	v_cvt_f32_f16_sdwa v115, v117 dst_sel:DWORD dst_unused:UNUSED_PAD src0_sel:WORD_1
	v_pk_fma_f32 v[104:105], v[104:105], v[188:189], v[112:113]
	v_cvt_pk_f16_f32 v113, v110, v111
	v_pk_fma_f32 v[106:107], v[106:107], v[186:187], v[114:115]
	v_cvt_pk_f16_f32 v114, v104, v105
	v_cvt_pk_f16_f32 v115, v106, v107
	v_cvt_pk_f16_f32 v112, v108, v109
	ds_bpermute_b32 v112, v214, v112
	ds_bpermute_b32 v113, v214, v113
	ds_bpermute_b32 v114, v214, v114
	ds_bpermute_b32 v115, v214, v115
	v_pk_mul_f32 v[116:117], v[178:179], v[106:107]
	v_pk_mul_f32 v[118:119], v[180:181], v[104:105]
	s_waitcnt lgkmcnt(0)
	global_store_dwordx4 v[206:207], v[112:115], off offset:2048
	s_nop 1
	v_pk_mul_f32 v[112:113], v[174:175], v[110:111]
	v_pk_mul_f32 v[114:115], v[176:177], v[108:109]
	s_nop 0
	v_cvt_pk_bf16_f32 v114, v114, v115
	v_cvt_pk_bf16_f32 v113, v112, v113
	v_cvt_pk_bf16_f32 v115, v118, v119
	v_cvt_pk_bf16_f32 v116, v116, v117
	ds_bpermute_b32 v112, v214, v114
	ds_bpermute_b32 v113, v214, v113
	ds_bpermute_b32 v114, v214, v115
	ds_bpermute_b32 v115, v214, v116
	v_add_co_u32_e32 v116, vcc, s2, v198
	s_waitcnt vmcnt(9)
	ds_bpermute_b32 v118, v216, v146
	v_addc_co_u32_e32 v117, vcc, 0, v199, vcc
	s_waitcnt lgkmcnt(1)
	global_store_dwordx4 v[116:117], v[112:115], off offset:2048
	ds_bpermute_b32 v113, v216, v144
	ds_bpermute_b32 v115, v216, v145
	ds_bpermute_b32 v119, v216, v147
	s_mov_b32 s2, 0x84000
	s_waitcnt lgkmcnt(2)
	v_cvt_f32_f16_e32 v112, v113
	v_cvt_f32_f16_sdwa v113, v113 dst_sel:DWORD dst_unused:UNUSED_PAD src0_sel:WORD_1
	s_waitcnt lgkmcnt(1)
	v_cvt_f32_f16_e32 v114, v115
	v_cvt_f32_f16_sdwa v115, v115 dst_sel:DWORD dst_unused:UNUSED_PAD src0_sel:WORD_1
	v_pk_fma_f32 v[100:101], v[100:101], v[184:185], v[112:113]
	v_cvt_f32_f16_e32 v112, v118
	v_pk_fma_f32 v[102:103], v[102:103], v[182:183], v[114:115]
	v_cvt_f32_f16_sdwa v113, v118 dst_sel:DWORD dst_unused:UNUSED_PAD src0_sel:WORD_1
	s_waitcnt lgkmcnt(0)
	v_cvt_f32_f16_e32 v114, v119
	v_cvt_f32_f16_sdwa v115, v119 dst_sel:DWORD dst_unused:UNUSED_PAD src0_sel:WORD_1
	v_pk_fma_f32 v[96:97], v[96:97], v[172:173], v[112:113]
	v_cvt_pk_f16_f32 v113, v102, v103
	v_pk_fma_f32 v[98:99], v[98:99], v[170:171], v[114:115]
	v_cvt_pk_f16_f32 v114, v96, v97
	v_cvt_pk_f16_f32 v115, v98, v99
	v_cvt_pk_f16_f32 v112, v100, v101
	ds_bpermute_b32 v112, v214, v112
	ds_bpermute_b32 v113, v214, v113
	ds_bpermute_b32 v114, v214, v114
	ds_bpermute_b32 v115, v214, v115
	v_pk_mul_f32 v[118:119], v[166:167], v[98:99]
	v_pk_mul_f32 v[120:121], v[168:169], v[96:97]
	s_waitcnt lgkmcnt(0)
; __device__ __forceinline__ unsigned cvt_pk_bf16(float lo, float hi) { unsigned r; asm volatile("v_cvt_pk_bf16_f32 %0, %1, %2" : "=v"(r) : "v"(lo), "v"(hi)); return r; }
;     __device__ __forceinline__ void operator()(AccT acc, const pg8::Unit& u, int wr, int wc, int fr, int fq) const {
;     ...
;                 for (int m = 0; m < 4; ++m) { const size_t ro = (size_t)(ai * 128 + m * 16) * LDP; float t = 0.f;
; #pragma unroll
;                     for (int bj = 0; bj < 2; ++bj) { const h16x8 b8 = __builtin_bit_cast(h16x8, gather4(__builtin_bit_cast(u32x4, hb[m][bj]), ld4));
;                         const f32x4 h0 = (f32x4){(float)b8[0], (float)b8[1], (float)b8[2], (float)b8[3]} + gv[bj][0] * acc[ai][bj][m][0], h1 = (f32x4){(float)b8[4], (float)b8[5], (float)b8[6], (float)b8[7]} + gv[bj][1] * acc[ai][bj][m][1];
;                         const h16x4 q0 = __builtin_convertvector(h0, h16x4), q1 = __builtin_convertvector(h1, h16x4);
;                         { const h16x8 hv8 = (h16x8){q0[0], q0[1], q0[2], q0[3], q1[0], q1[1], q1[2], q1[3]}; *(u32x4*)(hout + ro + bj * 128) = gather4(__builtin_bit_cast(u32x4, hv8), st4); }
;                         t += ((h0[0] * h0[0] + h0[1] * h0[1]) + (h0[2] * h0[2] + h0[3] * h0[3])) + ((h1[0] * h1[0] + h1[1] * h1[1]) + (h1[2] * h1[2] + h1[3] * h1[3]));
;                         if (WZ) { const f32x4 z0 = h0 * gz[bj][0], z1 = h1 * gz[bj][1]; u32x4 w; w.x = cvt_pk_bf16(z0[0], z0[1]); w.y = cvt_pk_bf16(z0[2], z0[3]); w.z = cvt_pk_bf16(z1[0], z1[1]); w.w = cvt_pk_bf16(z1[2], z1[3]);
;                             *(u32x4*)(zout + ro + bj * 128) = gather4(w, st4); } }
	global_store_dwordx4 v[206:207], v[112:115], off offset:2304
	s_nop 1
	v_pk_mul_f32 v[112:113], v[162:163], v[102:103]
	v_pk_mul_f32 v[114:115], v[164:165], v[100:101]
	s_nop 0
	v_cvt_pk_bf16_f32 v114, v114, v115
	v_cvt_pk_bf16_f32 v113, v112, v113
	v_cvt_pk_bf16_f32 v115, v120, v121
	v_cvt_pk_bf16_f32 v118, v118, v119
	ds_bpermute_b32 v112, v214, v114
	ds_bpermute_b32 v113, v214, v113
	ds_bpermute_b32 v114, v214, v115
	ds_bpermute_b32 v115, v214, v118
	v_add_co_u32_e32 v120, vcc, s8, v198
	s_mov_b32 s8, 0x94000
	s_nop 0
	v_addc_co_u32_e32 v121, vcc, 0, v199, vcc
	s_waitcnt lgkmcnt(0)
	global_store_dwordx4 v[116:117], v[112:115], off offset:2304
	s_waitcnt vmcnt(11)
	ds_bpermute_b32 v113, v216, v140
	ds_bpermute_b32 v115, v216, v141
	ds_bpermute_b32 v116, v216, v142
	ds_bpermute_b32 v117, v216, v143
	s_waitcnt lgkmcnt(3)
	v_cvt_f32_f16_e32 v112, v113
	v_cvt_f32_f16_sdwa v113, v113 dst_sel:DWORD dst_unused:UNUSED_PAD src0_sel:WORD_1
	s_waitcnt lgkmcnt(2)
	v_cvt_f32_f16_e32 v114, v115
	v_cvt_f32_f16_sdwa v115, v115 dst_sel:DWORD dst_unused:UNUSED_PAD src0_sel:WORD_1
	v_pk_fma_f32 v[92:93], v[92:93], v[196:197], v[112:113]
	s_waitcnt lgkmcnt(1)
	v_cvt_f32_f16_e32 v112, v116
	v_pk_fma_f32 v[94:95], v[94:95], v[190:191], v[114:115]
	v_cvt_f32_f16_sdwa v113, v116 dst_sel:DWORD dst_unused:UNUSED_PAD src0_sel:WORD_1
	s_waitcnt lgkmcnt(0)
	v_cvt_f32_f16_e32 v114, v117
	v_cvt_f32_f16_sdwa v115, v117 dst_sel:DWORD dst_unused:UNUSED_PAD src0_sel:WORD_1
	v_pk_fma_f32 v[88:89], v[88:89], v[188:189], v[112:113]
	v_cvt_pk_f16_f32 v113, v94, v95
	v_pk_fma_f32 v[90:91], v[90:91], v[186:187], v[114:115]
	v_cvt_pk_f16_f32 v114, v88, v89
	v_cvt_pk_f16_f32 v115, v90, v91
	v_cvt_pk_f16_f32 v112, v92, v93
	ds_bpermute_b32 v112, v214, v112
	ds_bpermute_b32 v113, v214, v113
	ds_bpermute_b32 v114, v214, v114
	ds_bpermute_b32 v115, v214, v115
	v_pk_mul_f32 v[116:117], v[178:179], v[90:91]
	v_pk_mul_f32 v[118:119], v[180:181], v[88:89]
	s_waitcnt lgkmcnt(0)
	global_store_dwordx4 v[204:205], v[112:115], off
	s_nop 1
	v_pk_mul_f32 v[112:113], v[174:175], v[94:95]
	v_pk_mul_f32 v[114:115], v[176:177], v[92:93]
	s_nop 0
	v_cvt_pk_bf16_f32 v114, v114, v115
	v_cvt_pk_bf16_f32 v113, v112, v113
	v_cvt_pk_bf16_f32 v115, v118, v119
	v_cvt_pk_bf16_f32 v116, v116, v117
	ds_bpermute_b32 v112, v214, v114
	ds_bpermute_b32 v113, v214, v113
	ds_bpermute_b32 v114, v214, v115
	ds_bpermute_b32 v115, v214, v116
	s_waitcnt vmcnt(11)
	ds_bpermute_b32 v116, v216, v138
	ds_bpermute_b32 v117, v216, v139
	s_waitcnt lgkmcnt(2)
	global_store_dwordx4 v[120:121], v[112:115], off
	ds_bpermute_b32 v112, v216, v136
	ds_bpermute_b32 v113, v216, v137
	s_waitcnt lgkmcnt(1)
	v_cvt_f32_f16_e32 v114, v112
	v_cvt_f32_f16_sdwa v115, v112 dst_sel:DWORD dst_unused:UNUSED_PAD src0_sel:WORD_1
	s_waitcnt lgkmcnt(0)
	v_cvt_f32_f16_e32 v112, v113
	v_cvt_f32_f16_sdwa v113, v113 dst_sel:DWORD dst_unused:UNUSED_PAD src0_sel:WORD_1
	v_pk_fma_f32 v[114:115], v[84:85], v[184:185], v[114:115]
	v_cvt_f32_f16_e32 v84, v116
	v_pk_fma_f32 v[112:113], v[86:87], v[182:183], v[112:113]
	v_cvt_f32_f16_sdwa v85, v116 dst_sel:DWORD dst_unused:UNUSED_PAD src0_sel:WORD_1
	v_cvt_f32_f16_e32 v86, v117
	v_cvt_f32_f16_sdwa v87, v117 dst_sel:DWORD dst_unused:UNUSED_PAD src0_sel:WORD_1
	v_pk_fma_f32 v[118:119], v[80:81], v[172:173], v[84:85]
	v_cvt_pk_f16_f32 v81, v112, v113
	v_pk_fma_f32 v[116:117], v[82:83], v[170:171], v[86:87]
	v_cvt_pk_f16_f32 v82, v118, v119
	v_cvt_pk_f16_f32 v83, v116, v117
	v_cvt_pk_f16_f32 v80, v114, v115
	ds_bpermute_b32 v80, v214, v80
	ds_bpermute_b32 v81, v214, v81
	ds_bpermute_b32 v82, v214, v82
	ds_bpermute_b32 v83, v214, v83
	v_pk_mul_f32 v[84:85], v[166:167], v[116:117]
	v_pk_mul_f32 v[86:87], v[168:169], v[118:119]
	s_waitcnt lgkmcnt(0)
	global_store_dwordx4 v[204:205], v[80:83], off offset:256
	s_nop 1
	v_pk_mul_f32 v[80:81], v[162:163], v[112:113]
	v_pk_mul_f32 v[82:83], v[164:165], v[114:115]
	s_nop 0
	v_cvt_pk_bf16_f32 v82, v82, v83
	v_cvt_pk_bf16_f32 v81, v80, v81
	v_cvt_pk_bf16_f32 v83, v86, v87
	v_cvt_pk_bf16_f32 v84, v84, v85
	ds_bpermute_b32 v80, v214, v82
	ds_bpermute_b32 v81, v214, v81
	ds_bpermute_b32 v82, v214, v83
	ds_bpermute_b32 v83, v214, v84
	s_waitcnt vmcnt(12)
	ds_bpermute_b32 v84, v216, v134
	ds_bpermute_b32 v85, v216, v135
	s_waitcnt lgkmcnt(2)
	global_store_dwordx4 v[120:121], v[80:83], off offset:256
	ds_bpermute_b32 v81, v216, v132
	ds_bpermute_b32 v83, v216, v133
	s_waitcnt lgkmcnt(1)
	v_cvt_f32_f16_e32 v80, v81
	v_cvt_f32_f16_sdwa v81, v81 dst_sel:DWORD dst_unused:UNUSED_PAD src0_sel:WORD_1
	s_waitcnt lgkmcnt(0)
	v_cvt_f32_f16_e32 v82, v83
	v_cvt_f32_f16_sdwa v83, v83 dst_sel:DWORD dst_unused:UNUSED_PAD src0_sel:WORD_1
	v_pk_fma_f32 v[122:123], v[76:77], v[196:197], v[80:81]
	v_cvt_f32_f16_e32 v76, v84
	v_pk_fma_f32 v[120:121], v[78:79], v[190:191], v[82:83]
	v_cvt_f32_f16_sdwa v77, v84 dst_sel:DWORD dst_unused:UNUSED_PAD src0_sel:WORD_1
	v_cvt_f32_f16_e32 v78, v85
	v_cvt_f32_f16_sdwa v79, v85 dst_sel:DWORD dst_unused:UNUSED_PAD src0_sel:WORD_1
	v_pk_fma_f32 v[126:127], v[72:73], v[188:189], v[76:77]
	v_cvt_pk_f16_f32 v73, v120, v121
	v_pk_fma_f32 v[124:125], v[74:75], v[186:187], v[78:79]
	v_cvt_pk_f16_f32 v74, v126, v127
	v_cvt_pk_f16_f32 v75, v124, v125
	v_cvt_pk_f16_f32 v72, v122, v123
	ds_bpermute_b32 v72, v214, v72
	ds_bpermute_b32 v73, v214, v73
	ds_bpermute_b32 v74, v214, v74
	ds_bpermute_b32 v75, v214, v75
	v_pk_mul_f32 v[76:77], v[178:179], v[124:125]
	v_pk_mul_f32 v[78:79], v[180:181], v[126:127]
	s_waitcnt lgkmcnt(0)
; __device__ __forceinline__ unsigned cvt_pk_bf16(float lo, float hi) { unsigned r; asm volatile("v_cvt_pk_bf16_f32 %0, %1, %2" : "=v"(r) : "v"(lo), "v"(hi)); return r; }
;     __device__ __forceinline__ void operator()(AccT acc, const pg8::Unit& u, int wr, int wc, int fr, int fq) const {
;     ...
;             for (int ai = 0; ai < 2; ++ai) {
; #pragma unroll
;                 for (int m = 0; m < 4; ++m)
; #pragma unroll
;                     for (int bj = 0; bj < 2; ++bj) hb[m][bj] = *(const h16x8*)(base + (size_t)(ai * 128 + m * 16) * LDP + bj * 128);
;                 asm volatile("" ::: "memory");
; #pragma unroll
;                 for (int m = 0; m < 4; ++m) { const size_t ro = (size_t)(ai * 128 + m * 16) * LDP; float t = 0.f;
; #pragma unroll
;                     for (int bj = 0; bj < 2; ++bj) { const h16x8 b8 = __builtin_bit_cast(h16x8, gather4(__builtin_bit_cast(u32x4, hb[m][bj]), ld4));
;                         const f32x4 h0 = (f32x4){(float)b8[0], (float)b8[1], (float)b8[2], (float)b8[3]} + gv[bj][0] * acc[ai][bj][m][0], h1 = (f32x4){(float)b8[4], (float)b8[5], (float)b8[6], (float)b8[7]} + gv[bj][1] * acc[ai][bj][m][1];
;                         const h16x4 q0 = __builtin_convertvector(h0, h16x4), q1 = __builtin_convertvector(h1, h16x4);
;                         { const h16x8 hv8 = (h16x8){q0[0], q0[1], q0[2], q0[3], q1[0], q1[1], q1[2], q1[3]}; *(u32x4*)(hout + ro + bj * 128) = gather4(__builtin_bit_cast(u32x4, hv8), st4); }
;                         t += ((h0[0] * h0[0] + h0[1] * h0[1]) + (h0[2] * h0[2] + h0[3] * h0[3])) + ((h1[0] * h1[0] + h1[1] * h1[1]) + (h1[2] * h1[2] + h1[3] * h1[3]));
;                         if (WZ) { const f32x4 z0 = h0 * gz[bj][0], z1 = h1 * gz[bj][1]; u32x4 w; w.x = cvt_pk_bf16(z0[0], z0[1]); w.y = cvt_pk_bf16(z0[2], z0[3]); w.z = cvt_pk_bf16(z1[0], z1[1]); w.w = cvt_pk_bf16(z1[2], z1[3]);
;                             *(u32x4*)(zout + ro + bj * 128) = gather4(w, st4); } }
;                     ss[ai * 4 + m] = t; }
	global_store_dwordx4 v[202:203], v[72:75], off offset:2048
	s_nop 1
	v_pk_mul_f32 v[72:73], v[174:175], v[120:121]
	v_pk_mul_f32 v[74:75], v[176:177], v[122:123]
	s_nop 0
	v_cvt_pk_bf16_f32 v74, v74, v75
	v_cvt_pk_bf16_f32 v73, v72, v73
	v_cvt_pk_bf16_f32 v75, v78, v79
	v_cvt_pk_bf16_f32 v76, v76, v77
	ds_bpermute_b32 v72, v214, v74
	ds_bpermute_b32 v73, v214, v73
	ds_bpermute_b32 v74, v214, v75
	ds_bpermute_b32 v75, v214, v76
	v_add_co_u32_e32 v76, vcc, s9, v198
	s_waitcnt vmcnt(13)
	ds_bpermute_b32 v78, v216, v130
	v_addc_co_u32_e32 v77, vcc, 0, v199, vcc
	s_waitcnt lgkmcnt(1)
	global_store_dwordx4 v[76:77], v[72:75], off offset:2048
	ds_bpermute_b32 v73, v216, v128
	ds_bpermute_b32 v75, v216, v129
	ds_bpermute_b32 v79, v216, v131
	v_add_co_u32_e32 v142, vcc, s2, v200
	s_waitcnt lgkmcnt(2)
	v_cvt_f32_f16_e32 v72, v73
	v_cvt_f32_f16_sdwa v73, v73 dst_sel:DWORD dst_unused:UNUSED_PAD src0_sel:WORD_1
	s_waitcnt lgkmcnt(1)
	v_cvt_f32_f16_e32 v74, v75
	v_cvt_f32_f16_sdwa v75, v75 dst_sel:DWORD dst_unused:UNUSED_PAD src0_sel:WORD_1
	v_addc_co_u32_e32 v143, vcc, 0, v201, vcc
	v_pk_fma_f32 v[130:131], v[68:69], v[184:185], v[72:73]
	v_pk_fma_f32 v[128:129], v[70:71], v[182:183], v[74:75]
	v_cvt_f32_f16_e32 v68, v78
	v_cvt_f32_f16_sdwa v69, v78 dst_sel:DWORD dst_unused:UNUSED_PAD src0_sel:WORD_1
	s_waitcnt lgkmcnt(0)
	v_cvt_f32_f16_e32 v70, v79
	v_cvt_f32_f16_sdwa v71, v79 dst_sel:DWORD dst_unused:UNUSED_PAD src0_sel:WORD_1
	v_add_co_u32_e32 v140, vcc, s8, v200
	v_pk_fma_f32 v[134:135], v[64:65], v[172:173], v[68:69]
	v_pk_fma_f32 v[132:133], v[66:67], v[170:171], v[70:71]
	v_cvt_pk_f16_f32 v66, v134, v135
	v_cvt_pk_f16_f32 v67, v132, v133
	v_cvt_pk_f16_f32 v65, v128, v129
	v_cvt_pk_f16_f32 v64, v130, v131
	ds_bpermute_b32 v64, v214, v64
	ds_bpermute_b32 v65, v214, v65
	ds_bpermute_b32 v66, v214, v66
	ds_bpermute_b32 v67, v214, v67
	v_pk_mul_f32 v[68:69], v[166:167], v[132:133]
	v_pk_mul_f32 v[70:71], v[168:169], v[134:135]
	v_addc_co_u32_e32 v141, vcc, 0, v201, vcc
	s_waitcnt lgkmcnt(0)
	global_store_dwordx4 v[202:203], v[64:67], off offset:2304
	s_mov_b32 s9, 0xa5000
	v_add_co_u32_e32 v138, vcc, s9, v200
	v_pk_mul_f32 v[64:65], v[162:163], v[128:129]
	v_pk_mul_f32 v[66:67], v[164:165], v[130:131]
	v_addc_co_u32_e32 v139, vcc, 0, v201, vcc
	v_cvt_pk_bf16_f32 v66, v66, v67
	v_cvt_pk_bf16_f32 v65, v64, v65
	v_cvt_pk_bf16_f32 v67, v70, v71
	v_cvt_pk_bf16_f32 v68, v68, v69
	ds_bpermute_b32 v64, v214, v66
	ds_bpermute_b32 v65, v214, v65
	ds_bpermute_b32 v66, v214, v67
	ds_bpermute_b32 v67, v214, v68
	v_add_co_u32_e32 v136, vcc, s21, v200
	s_waitcnt lgkmcnt(0)
	global_store_dwordx4 v[76:77], v[64:67], off offset:2304
	global_load_dwordx4 v[144:147], v[142:143], off
	global_load_dwordx4 v[148:151], v[142:143], off offset:256
	global_load_dwordx4 v[84:87], v[140:141], off offset:2048
	global_load_dwordx4 v[80:83], v[140:141], off offset:2304
	v_addc_co_u32_e32 v137, vcc, 0, v201, vcc
	global_load_dwordx4 v[76:79], v[138:139], off
	global_load_dwordx4 v[72:75], v[138:139], off offset:256
	global_load_dwordx4 v[68:71], v[136:137], off offset:2048
	global_load_dwordx4 v[64:67], v[136:137], off offset:2304
	s_waitcnt vmcnt(7)
	ds_bpermute_b32 v153, v216, v144
	ds_bpermute_b32 v154, v216, v145
	ds_bpermute_b32 v155, v216, v146
	ds_bpermute_b32 v159, v216, v147
	s_waitcnt lgkmcnt(3)
	v_cvt_f32_f16_e32 v144, v153
	v_cvt_f32_f16_sdwa v145, v153 dst_sel:DWORD dst_unused:UNUSED_PAD src0_sel:WORD_1
	s_waitcnt lgkmcnt(2)
	v_cvt_f32_f16_e32 v146, v154
	v_cvt_f32_f16_sdwa v147, v154 dst_sel:DWORD dst_unused:UNUSED_PAD src0_sel:WORD_1
	v_pk_fma_f32 v[60:61], v[60:61], v[196:197], v[144:145]
	s_waitcnt lgkmcnt(1)
	v_cvt_f32_f16_e32 v144, v155
	v_pk_fma_f32 v[62:63], v[62:63], v[190:191], v[146:147]
	v_cvt_f32_f16_sdwa v145, v155 dst_sel:DWORD dst_unused:UNUSED_PAD src0_sel:WORD_1
	s_waitcnt lgkmcnt(0)
	v_cvt_f32_f16_e32 v146, v159
	v_cvt_f32_f16_sdwa v147, v159 dst_sel:DWORD dst_unused:UNUSED_PAD src0_sel:WORD_1
	v_pk_fma_f32 v[56:57], v[56:57], v[188:189], v[144:145]
	v_cvt_pk_f16_f32 v145, v62, v63
	v_pk_fma_f32 v[58:59], v[58:59], v[186:187], v[146:147]
	v_cvt_pk_f16_f32 v146, v56, v57
	v_cvt_pk_f16_f32 v147, v58, v59
	v_cvt_pk_f16_f32 v144, v60, v61
	ds_bpermute_b32 v144, v214, v144
	ds_bpermute_b32 v145, v214, v145
	ds_bpermute_b32 v146, v214, v146
	ds_bpermute_b32 v147, v214, v147
	v_pk_mul_f32 v[194:195], v[180:181], v[56:57]
	v_pk_mul_f32 v[154:155], v[178:179], v[58:59]
	s_waitcnt lgkmcnt(0)
	global_store_dwordx4 v[142:143], v[144:147], off
	s_nop 1
	v_pk_mul_f32 v[144:145], v[174:175], v[62:63]
	v_pk_mul_f32 v[146:147], v[176:177], v[60:61]
	s_nop 0
	v_cvt_pk_bf16_f32 v146, v146, v147
	v_cvt_pk_bf16_f32 v145, v144, v145
	v_cvt_pk_bf16_f32 v147, v194, v195
	v_cvt_pk_bf16_f32 v153, v154, v155
	ds_bpermute_b32 v144, v214, v146
	ds_bpermute_b32 v145, v214, v145
	ds_bpermute_b32 v146, v214, v147
	ds_bpermute_b32 v147, v214, v153
	v_add_co_u32_e32 v154, vcc, s2, v198
	s_nop 1
	v_addc_co_u32_e32 v155, vcc, 0, v199, vcc
	s_waitcnt lgkmcnt(0)
	global_store_dwordx4 v[154:155], v[144:147], off
	s_waitcnt vmcnt(8)
	ds_bpermute_b32 v145, v216, v148
	ds_bpermute_b32 v147, v216, v149
	ds_bpermute_b32 v148, v216, v150
	ds_bpermute_b32 v149, v216, v151
	s_waitcnt lgkmcnt(3)
	v_cvt_f32_f16_e32 v144, v145
	v_cvt_f32_f16_sdwa v145, v145 dst_sel:DWORD dst_unused:UNUSED_PAD src0_sel:WORD_1
	s_waitcnt lgkmcnt(2)
	v_cvt_f32_f16_e32 v146, v147
	v_cvt_f32_f16_sdwa v147, v147 dst_sel:DWORD dst_unused:UNUSED_PAD src0_sel:WORD_1
	v_pk_fma_f32 v[52:53], v[52:53], v[184:185], v[144:145]
	s_waitcnt lgkmcnt(1)
; __device__ __forceinline__ unsigned cvt_pk_bf16(float lo, float hi) { unsigned r; asm volatile("v_cvt_pk_bf16_f32 %0, %1, %2" : "=v"(r) : "v"(lo), "v"(hi)); return r; }
;     __device__ __forceinline__ void operator()(AccT acc, const pg8::Unit& u, int wr, int wc, int fr, int fq) const {
;     ...
;                 for (int m = 0; m < 4; ++m) { const size_t ro = (size_t)(ai * 128 + m * 16) * LDP; float t = 0.f;
; #pragma unroll
;                     for (int bj = 0; bj < 2; ++bj) { const h16x8 b8 = __builtin_bit_cast(h16x8, gather4(__builtin_bit_cast(u32x4, hb[m][bj]), ld4));
;                         const f32x4 h0 = (f32x4){(float)b8[0], (float)b8[1], (float)b8[2], (float)b8[3]} + gv[bj][0] * acc[ai][bj][m][0], h1 = (f32x4){(float)b8[4], (float)b8[5], (float)b8[6], (float)b8[7]} + gv[bj][1] * acc[ai][bj][m][1];
;                         const h16x4 q0 = __builtin_convertvector(h0, h16x4), q1 = __builtin_convertvector(h1, h16x4);
;                         { const h16x8 hv8 = (h16x8){q0[0], q0[1], q0[2], q0[3], q1[0], q1[1], q1[2], q1[3]}; *(u32x4*)(hout + ro + bj * 128) = gather4(__builtin_bit_cast(u32x4, hv8), st4); }
;                         t += ((h0[0] * h0[0] + h0[1] * h0[1]) + (h0[2] * h0[2] + h0[3] * h0[3])) + ((h1[0] * h1[0] + h1[1] * h1[1]) + (h1[2] * h1[2] + h1[3] * h1[3]));
;                         if (WZ) { const f32x4 z0 = h0 * gz[bj][0], z1 = h1 * gz[bj][1]; u32x4 w; w.x = cvt_pk_bf16(z0[0], z0[1]); w.y = cvt_pk_bf16(z0[2], z0[3]); w.z = cvt_pk_bf16(z1[0], z1[1]); w.w = cvt_pk_bf16(z1[2], z1[3]);
;                             *(u32x4*)(zout + ro + bj * 128) = gather4(w, st4); } }
;                     ss[ai * 4 + m] = t; }
	v_cvt_f32_f16_e32 v144, v148
	v_pk_fma_f32 v[54:55], v[54:55], v[182:183], v[146:147]
	v_cvt_f32_f16_sdwa v145, v148 dst_sel:DWORD dst_unused:UNUSED_PAD src0_sel:WORD_1
	s_waitcnt lgkmcnt(0)
	v_cvt_f32_f16_e32 v146, v149
	v_cvt_f32_f16_sdwa v147, v149 dst_sel:DWORD dst_unused:UNUSED_PAD src0_sel:WORD_1
	v_pk_fma_f32 v[48:49], v[48:49], v[172:173], v[144:145]
	v_cvt_pk_f16_f32 v145, v54, v55
	v_pk_fma_f32 v[50:51], v[50:51], v[170:171], v[146:147]
	v_cvt_pk_f16_f32 v146, v48, v49
	v_cvt_pk_f16_f32 v147, v50, v51
	v_cvt_pk_f16_f32 v144, v52, v53
	ds_bpermute_b32 v144, v214, v144
	ds_bpermute_b32 v145, v214, v145
	ds_bpermute_b32 v146, v214, v146
	ds_bpermute_b32 v147, v214, v147
	v_pk_mul_f32 v[148:149], v[168:169], v[48:49]
	s_waitcnt lgkmcnt(0)
	global_store_dwordx4 v[142:143], v[144:147], off offset:256
	v_pk_mul_f32 v[142:143], v[162:163], v[54:55]
	s_nop 0
	v_pk_mul_f32 v[144:145], v[164:165], v[52:53]
	v_pk_mul_f32 v[146:147], v[166:167], v[50:51]
	v_cvt_pk_bf16_f32 v144, v144, v145
	v_cvt_pk_bf16_f32 v143, v142, v143
	v_cvt_pk_bf16_f32 v145, v148, v149
	ds_bpermute_b32 v142, v214, v144
	v_cvt_pk_bf16_f32 v146, v146, v147
	ds_bpermute_b32 v143, v214, v143
	ds_bpermute_b32 v144, v214, v145
	ds_bpermute_b32 v145, v214, v146
	s_waitcnt lgkmcnt(0)
	global_store_dwordx4 v[154:155], v[142:145], off offset:256
	s_waitcnt vmcnt(9)
	ds_bpermute_b32 v142, v216, v84
	ds_bpermute_b32 v143, v216, v85
	ds_bpermute_b32 v144, v216, v86
	ds_bpermute_b32 v145, v216, v87
	s_waitcnt lgkmcnt(3)
	v_cvt_f32_f16_e32 v84, v142
	v_cvt_f32_f16_sdwa v85, v142 dst_sel:DWORD dst_unused:UNUSED_PAD src0_sel:WORD_1
	s_waitcnt lgkmcnt(2)
	v_cvt_f32_f16_e32 v86, v143
	v_cvt_f32_f16_sdwa v87, v143 dst_sel:DWORD dst_unused:UNUSED_PAD src0_sel:WORD_1
	v_pk_fma_f32 v[44:45], v[44:45], v[196:197], v[84:85]
	s_waitcnt lgkmcnt(1)
	v_cvt_f32_f16_e32 v84, v144
	v_pk_fma_f32 v[46:47], v[46:47], v[190:191], v[86:87]
	v_cvt_f32_f16_sdwa v85, v144 dst_sel:DWORD dst_unused:UNUSED_PAD src0_sel:WORD_1
	s_waitcnt lgkmcnt(0)
	v_cvt_f32_f16_e32 v86, v145
	v_cvt_f32_f16_sdwa v87, v145 dst_sel:DWORD dst_unused:UNUSED_PAD src0_sel:WORD_1
	v_pk_fma_f32 v[40:41], v[40:41], v[188:189], v[84:85]
	v_cvt_pk_f16_f32 v85, v46, v47
	v_pk_fma_f32 v[42:43], v[42:43], v[186:187], v[86:87]
	v_cvt_pk_f16_f32 v86, v40, v41
	v_cvt_pk_f16_f32 v87, v42, v43
	v_cvt_pk_f16_f32 v84, v44, v45
	ds_bpermute_b32 v84, v214, v84
	ds_bpermute_b32 v85, v214, v85
	ds_bpermute_b32 v86, v214, v86
	ds_bpermute_b32 v87, v214, v87
	v_pk_mul_f32 v[142:143], v[178:179], v[42:43]
	v_pk_mul_f32 v[144:145], v[180:181], v[40:41]
	s_waitcnt lgkmcnt(0)
	global_store_dwordx4 v[140:141], v[84:87], off offset:2048
	s_nop 1
	v_pk_mul_f32 v[84:85], v[174:175], v[46:47]
	v_pk_mul_f32 v[86:87], v[176:177], v[44:45]
	s_nop 0
	v_cvt_pk_bf16_f32 v86, v86, v87
	v_cvt_pk_bf16_f32 v85, v84, v85
	v_cvt_pk_bf16_f32 v87, v144, v145
	v_cvt_pk_bf16_f32 v142, v142, v143
	ds_bpermute_b32 v84, v214, v86
	ds_bpermute_b32 v85, v214, v85
	ds_bpermute_b32 v86, v214, v87
	ds_bpermute_b32 v87, v214, v142
	v_add_co_u32_e32 v142, vcc, s8, v198
	s_nop 1
	v_addc_co_u32_e32 v143, vcc, 0, v199, vcc
	s_waitcnt lgkmcnt(0)
	global_store_dwordx4 v[142:143], v[84:87], off offset:2048
	s_waitcnt vmcnt(10)
	ds_bpermute_b32 v84, v216, v80
	ds_bpermute_b32 v85, v216, v81
	ds_bpermute_b32 v86, v216, v82
	ds_bpermute_b32 v87, v216, v83
	s_waitcnt lgkmcnt(3)
	v_cvt_f32_f16_e32 v80, v84
	v_cvt_f32_f16_sdwa v81, v84 dst_sel:DWORD dst_unused:UNUSED_PAD src0_sel:WORD_1
	s_waitcnt lgkmcnt(2)
	v_cvt_f32_f16_e32 v82, v85
	v_cvt_f32_f16_sdwa v83, v85 dst_sel:DWORD dst_unused:UNUSED_PAD src0_sel:WORD_1
	v_pk_fma_f32 v[36:37], v[36:37], v[184:185], v[80:81]
	s_waitcnt lgkmcnt(1)
	v_cvt_f32_f16_e32 v80, v86
	v_pk_fma_f32 v[38:39], v[38:39], v[182:183], v[82:83]
	v_cvt_f32_f16_sdwa v81, v86 dst_sel:DWORD dst_unused:UNUSED_PAD src0_sel:WORD_1
	s_waitcnt lgkmcnt(0)
	v_cvt_f32_f16_e32 v82, v87
	v_cvt_f32_f16_sdwa v83, v87 dst_sel:DWORD dst_unused:UNUSED_PAD src0_sel:WORD_1
	v_pk_fma_f32 v[32:33], v[32:33], v[172:173], v[80:81]
	v_cvt_pk_f16_f32 v81, v38, v39
	v_pk_fma_f32 v[34:35], v[34:35], v[170:171], v[82:83]
	v_cvt_pk_f16_f32 v82, v32, v33
	v_cvt_pk_f16_f32 v83, v34, v35
	v_cvt_pk_f16_f32 v80, v36, v37
	ds_bpermute_b32 v80, v214, v80
	ds_bpermute_b32 v81, v214, v81
	ds_bpermute_b32 v82, v214, v82
	ds_bpermute_b32 v83, v214, v83
	v_pk_mul_f32 v[84:85], v[166:167], v[34:35]
	v_pk_mul_f32 v[86:87], v[168:169], v[32:33]
	s_waitcnt lgkmcnt(0)
	global_store_dwordx4 v[140:141], v[80:83], off offset:2304
	s_nop 1
	v_pk_mul_f32 v[80:81], v[162:163], v[38:39]
	v_pk_mul_f32 v[82:83], v[164:165], v[36:37]
	s_nop 0
	v_cvt_pk_bf16_f32 v82, v82, v83
	v_cvt_pk_bf16_f32 v81, v80, v81
	v_cvt_pk_bf16_f32 v83, v86, v87
	v_cvt_pk_bf16_f32 v84, v84, v85
	ds_bpermute_b32 v80, v214, v82
	ds_bpermute_b32 v81, v214, v81
	ds_bpermute_b32 v82, v214, v83
	ds_bpermute_b32 v83, v214, v84
	s_waitcnt lgkmcnt(0)
	global_store_dwordx4 v[142:143], v[80:83], off offset:2304
	s_waitcnt vmcnt(11)
	ds_bpermute_b32 v80, v216, v76
	ds_bpermute_b32 v81, v216, v77
	ds_bpermute_b32 v82, v216, v78
	ds_bpermute_b32 v83, v216, v79
	s_waitcnt lgkmcnt(3)
	v_cvt_f32_f16_e32 v76, v80
	v_cvt_f32_f16_sdwa v77, v80 dst_sel:DWORD dst_unused:UNUSED_PAD src0_sel:WORD_1
	s_waitcnt lgkmcnt(2)
	v_cvt_f32_f16_e32 v78, v81
	v_cvt_f32_f16_sdwa v79, v81 dst_sel:DWORD dst_unused:UNUSED_PAD src0_sel:WORD_1
	v_pk_fma_f32 v[28:29], v[28:29], v[196:197], v[76:77]
	s_waitcnt lgkmcnt(1)
	v_cvt_f32_f16_e32 v76, v82
	v_pk_fma_f32 v[30:31], v[30:31], v[190:191], v[78:79]
	v_cvt_f32_f16_sdwa v77, v82 dst_sel:DWORD dst_unused:UNUSED_PAD src0_sel:WORD_1
	s_waitcnt lgkmcnt(0)
; __device__ __forceinline__ unsigned cvt_pk_bf16(float lo, float hi) { unsigned r; asm volatile("v_cvt_pk_bf16_f32 %0, %1, %2" : "=v"(r) : "v"(lo), "v"(hi)); return r; }
; __device__ __forceinline__ float xlane(float v, int src_lane) { return __uint_as_float(__builtin_amdgcn_ds_bpermute(src_lane << 2, __float_as_uint(v))); }
;     __device__ __forceinline__ void operator()(AccT acc, const pg8::Unit& u, int wr, int wc, int fr, int fq) const {
;     ...
;                 for (int m = 0; m < 4; ++m) { const size_t ro = (size_t)(ai * 128 + m * 16) * LDP; float t = 0.f;
; #pragma unroll
;                     for (int bj = 0; bj < 2; ++bj) { const h16x8 b8 = __builtin_bit_cast(h16x8, gather4(__builtin_bit_cast(u32x4, hb[m][bj]), ld4));
;                         const f32x4 h0 = (f32x4){(float)b8[0], (float)b8[1], (float)b8[2], (float)b8[3]} + gv[bj][0] * acc[ai][bj][m][0], h1 = (f32x4){(float)b8[4], (float)b8[5], (float)b8[6], (float)b8[7]} + gv[bj][1] * acc[ai][bj][m][1];
;                         const h16x4 q0 = __builtin_convertvector(h0, h16x4), q1 = __builtin_convertvector(h1, h16x4);
;                         { const h16x8 hv8 = (h16x8){q0[0], q0[1], q0[2], q0[3], q1[0], q1[1], q1[2], q1[3]}; *(u32x4*)(hout + ro + bj * 128) = gather4(__builtin_bit_cast(u32x4, hv8), st4); }
;                         t += ((h0[0] * h0[0] + h0[1] * h0[1]) + (h0[2] * h0[2] + h0[3] * h0[3])) + ((h1[0] * h1[0] + h1[1] * h1[1]) + (h1[2] * h1[2] + h1[3] * h1[3]));
;                         if (WZ) { const f32x4 z0 = h0 * gz[bj][0], z1 = h1 * gz[bj][1]; u32x4 w; w.x = cvt_pk_bf16(z0[0], z0[1]); w.y = cvt_pk_bf16(z0[2], z0[3]); w.z = cvt_pk_bf16(z1[0], z1[1]); w.w = cvt_pk_bf16(z1[2], z1[3]);
;                             *(u32x4*)(zout + ro + bj * 128) = gather4(w, st4); } }
;                     ss[ai * 4 + m] = t; }
;     ...
;         for (int g = 0; g < 8; ++g) { float t = ss[g]; t += xlane(t, lane ^ 16); t += xlane(t, lane ^ 32);
;             if (fq == 0) SSQ[(size_t)(row0 + (g >> 2) * 128 + (g & 3) * 16) * 32 + u.pn * 4 + wc] = t; }
	v_cvt_f32_f16_e32 v78, v83
	v_cvt_f32_f16_sdwa v79, v83 dst_sel:DWORD dst_unused:UNUSED_PAD src0_sel:WORD_1
	v_pk_fma_f32 v[24:25], v[24:25], v[188:189], v[76:77]
	v_cvt_pk_f16_f32 v77, v30, v31
	v_pk_fma_f32 v[26:27], v[26:27], v[186:187], v[78:79]
	v_cvt_pk_f16_f32 v78, v24, v25
	v_cvt_pk_f16_f32 v79, v26, v27
	v_cvt_pk_f16_f32 v76, v28, v29
	ds_bpermute_b32 v76, v214, v76
	ds_bpermute_b32 v77, v214, v77
	ds_bpermute_b32 v78, v214, v78
	ds_bpermute_b32 v79, v214, v79
	v_pk_mul_f32 v[80:81], v[178:179], v[26:27]
	v_pk_mul_f32 v[82:83], v[180:181], v[24:25]
	s_waitcnt lgkmcnt(0)
	global_store_dwordx4 v[138:139], v[76:79], off
	s_nop 1
	v_pk_mul_f32 v[76:77], v[174:175], v[30:31]
	v_pk_mul_f32 v[78:79], v[176:177], v[28:29]
	s_nop 0
	v_cvt_pk_bf16_f32 v78, v78, v79
	v_cvt_pk_bf16_f32 v77, v76, v77
	v_cvt_pk_bf16_f32 v79, v82, v83
	v_cvt_pk_bf16_f32 v80, v80, v81
	ds_bpermute_b32 v76, v214, v78
	ds_bpermute_b32 v77, v214, v77
	ds_bpermute_b32 v78, v214, v79
	ds_bpermute_b32 v79, v214, v80
	v_add_co_u32_e32 v80, vcc, s9, v198
	s_lshl_b64 s[8:9], s[40:41], 2
	s_nop 0
	v_addc_co_u32_e32 v81, vcc, 0, v199, vcc
	s_waitcnt lgkmcnt(0)
	global_store_dwordx4 v[80:81], v[76:79], off
	s_waitcnt vmcnt(12)
	ds_bpermute_b32 v76, v216, v72
	ds_bpermute_b32 v77, v216, v73
	ds_bpermute_b32 v78, v216, v74
	ds_bpermute_b32 v79, v216, v75
	s_add_u32 s28, s88, s8
	s_waitcnt lgkmcnt(3)
	v_cvt_f32_f16_e32 v72, v76
	v_cvt_f32_f16_sdwa v73, v76 dst_sel:DWORD dst_unused:UNUSED_PAD src0_sel:WORD_1
	s_waitcnt lgkmcnt(2)
	v_cvt_f32_f16_e32 v74, v77
	v_cvt_f32_f16_sdwa v75, v77 dst_sel:DWORD dst_unused:UNUSED_PAD src0_sel:WORD_1
	s_addc_u32 s29, s97, s9
	v_pk_fma_f32 v[20:21], v[20:21], v[184:185], v[72:73]
	s_waitcnt lgkmcnt(1)
	v_cvt_f32_f16_e32 v72, v78
	v_pk_fma_f32 v[22:23], v[22:23], v[182:183], v[74:75]
	v_cvt_f32_f16_sdwa v73, v78 dst_sel:DWORD dst_unused:UNUSED_PAD src0_sel:WORD_1
	s_waitcnt lgkmcnt(0)
	v_cvt_f32_f16_e32 v74, v79
	v_cvt_f32_f16_sdwa v75, v79 dst_sel:DWORD dst_unused:UNUSED_PAD src0_sel:WORD_1
	v_pk_fma_f32 v[16:17], v[16:17], v[172:173], v[72:73]
	v_cvt_pk_f16_f32 v73, v22, v23
	v_pk_fma_f32 v[18:19], v[18:19], v[170:171], v[74:75]
	v_cvt_pk_f16_f32 v74, v16, v17
	v_cvt_pk_f16_f32 v75, v18, v19
	v_cvt_pk_f16_f32 v72, v20, v21
	ds_bpermute_b32 v72, v214, v72
	ds_bpermute_b32 v73, v214, v73
	ds_bpermute_b32 v74, v214, v74
	ds_bpermute_b32 v75, v214, v75
	v_pk_mul_f32 v[76:77], v[166:167], v[18:19]
	v_pk_mul_f32 v[78:79], v[168:169], v[16:17]
	s_waitcnt lgkmcnt(0)
	global_store_dwordx4 v[138:139], v[72:75], off offset:256
	s_nop 1
	v_pk_mul_f32 v[72:73], v[162:163], v[22:23]
	v_pk_mul_f32 v[74:75], v[164:165], v[20:21]
	s_nop 0
	v_cvt_pk_bf16_f32 v74, v74, v75
	v_cvt_pk_bf16_f32 v73, v72, v73
	v_cvt_pk_bf16_f32 v75, v78, v79
	v_cvt_pk_bf16_f32 v76, v76, v77
	ds_bpermute_b32 v72, v214, v74
	ds_bpermute_b32 v73, v214, v73
	ds_bpermute_b32 v74, v214, v75
	ds_bpermute_b32 v75, v214, v76
	s_waitcnt lgkmcnt(0)
	global_store_dwordx4 v[80:81], v[72:75], off offset:256
	s_waitcnt vmcnt(13)
	ds_bpermute_b32 v72, v216, v68
	ds_bpermute_b32 v73, v216, v69
	ds_bpermute_b32 v74, v216, v70
	ds_bpermute_b32 v75, v216, v71
	s_waitcnt lgkmcnt(3)
	v_cvt_f32_f16_e32 v68, v72
	v_cvt_f32_f16_sdwa v69, v72 dst_sel:DWORD dst_unused:UNUSED_PAD src0_sel:WORD_1
	s_waitcnt lgkmcnt(2)
	v_cvt_f32_f16_e32 v70, v73
	v_cvt_f32_f16_sdwa v71, v73 dst_sel:DWORD dst_unused:UNUSED_PAD src0_sel:WORD_1
	v_pk_fma_f32 v[12:13], v[12:13], v[196:197], v[68:69]
	s_waitcnt lgkmcnt(1)
	v_cvt_f32_f16_e32 v68, v74
	v_pk_fma_f32 v[14:15], v[14:15], v[190:191], v[70:71]
	v_cvt_f32_f16_sdwa v69, v74 dst_sel:DWORD dst_unused:UNUSED_PAD src0_sel:WORD_1
	s_waitcnt lgkmcnt(0)
	v_cvt_f32_f16_e32 v70, v75
	v_cvt_f32_f16_sdwa v71, v75 dst_sel:DWORD dst_unused:UNUSED_PAD src0_sel:WORD_1
	v_pk_fma_f32 v[8:9], v[8:9], v[188:189], v[68:69]
	v_cvt_pk_f16_f32 v69, v14, v15
	v_pk_fma_f32 v[10:11], v[10:11], v[186:187], v[70:71]
	v_cvt_pk_f16_f32 v70, v8, v9
	v_cvt_pk_f16_f32 v71, v10, v11
	v_cvt_pk_f16_f32 v68, v12, v13
	ds_bpermute_b32 v68, v214, v68
	ds_bpermute_b32 v69, v214, v69
	ds_bpermute_b32 v70, v214, v70
	ds_bpermute_b32 v71, v214, v71
	v_pk_mul_f32 v[72:73], v[178:179], v[10:11]
	v_pk_mul_f32 v[74:75], v[180:181], v[8:9]
	s_waitcnt lgkmcnt(0)
	global_store_dwordx4 v[136:137], v[68:71], off offset:2048
	s_nop 1
	v_pk_mul_f32 v[68:69], v[174:175], v[14:15]
	v_pk_mul_f32 v[70:71], v[176:177], v[12:13]
	s_nop 0
	v_cvt_pk_bf16_f32 v70, v70, v71
	v_cvt_pk_bf16_f32 v69, v68, v69
	v_cvt_pk_bf16_f32 v71, v74, v75
	v_cvt_pk_bf16_f32 v72, v72, v73
	ds_bpermute_b32 v68, v214, v70
	ds_bpermute_b32 v69, v214, v69
	ds_bpermute_b32 v70, v214, v71
	ds_bpermute_b32 v71, v214, v72
	v_add_co_u32_e32 v72, vcc, s21, v198
	s_nop 1
	v_addc_co_u32_e32 v73, vcc, 0, v199, vcc
	s_waitcnt lgkmcnt(0)
	global_store_dwordx4 v[72:73], v[68:71], off offset:2048
	s_waitcnt vmcnt(14)
	ds_bpermute_b32 v68, v216, v64
	ds_bpermute_b32 v69, v216, v65
	ds_bpermute_b32 v70, v216, v66
	ds_bpermute_b32 v71, v216, v67
	s_waitcnt lgkmcnt(3)
	v_cvt_f32_f16_e32 v64, v68
	v_cvt_f32_f16_sdwa v65, v68 dst_sel:DWORD dst_unused:UNUSED_PAD src0_sel:WORD_1
	s_waitcnt lgkmcnt(2)
	v_cvt_f32_f16_e32 v66, v69
	v_cvt_f32_f16_sdwa v67, v69 dst_sel:DWORD dst_unused:UNUSED_PAD src0_sel:WORD_1
	v_pk_fma_f32 v[4:5], v[4:5], v[184:185], v[64:65]
	s_waitcnt lgkmcnt(1)
	v_cvt_f32_f16_e32 v64, v70
	v_pk_fma_f32 v[6:7], v[6:7], v[182:183], v[66:67]
	v_cvt_f32_f16_sdwa v65, v70 dst_sel:DWORD dst_unused:UNUSED_PAD src0_sel:WORD_1
	s_waitcnt lgkmcnt(0)
	v_cvt_f32_f16_e32 v66, v71
	v_cvt_f32_f16_sdwa v67, v71 dst_sel:DWORD dst_unused:UNUSED_PAD src0_sel:WORD_1
	v_pk_fma_f32 v[0:1], v[0:1], v[172:173], v[64:65]
	v_cvt_pk_f16_f32 v65, v6, v7
	v_pk_fma_f32 v[2:3], v[2:3], v[170:171], v[66:67]
	v_cvt_pk_f16_f32 v66, v0, v1
	v_cvt_pk_f16_f32 v67, v2, v3
	v_cvt_pk_f16_f32 v64, v4, v5
	ds_bpermute_b32 v64, v214, v64
	ds_bpermute_b32 v65, v214, v65
	ds_bpermute_b32 v66, v214, v66
	ds_bpermute_b32 v67, v214, v67
	v_pk_mul_f32 v[68:69], v[166:167], v[2:3]
	v_pk_mul_f32 v[70:71], v[168:169], v[0:1]
	s_waitcnt lgkmcnt(0)
	global_store_dwordx4 v[136:137], v[64:67], off offset:2304
	s_nop 1
	v_pk_mul_f32 v[64:65], v[162:163], v[6:7]
	v_pk_mul_f32 v[66:67], v[164:165], v[4:5]
	s_nop 0
	v_cvt_pk_bf16_f32 v66, v66, v67
	v_cvt_pk_bf16_f32 v65, v64, v65
	v_cvt_pk_bf16_f32 v67, v70, v71
	v_cvt_pk_bf16_f32 v68, v68, v69
	ds_bpermute_b32 v64, v214, v66
	ds_bpermute_b32 v65, v214, v65
	ds_bpermute_b32 v66, v214, v67
	ds_bpermute_b32 v67, v214, v68
	s_waitcnt lgkmcnt(0)
	global_store_dwordx4 v[72:73], v[64:67], off offset:2304
	s_waitcnt lgkmcnt(0)
	s_nop 1
	v_mov_b32_e32 v64, v152
	v_mov_b32_e32 v65, v152
	s_nop 1
	v_permlane16_swap_b32_e32 v64, v65
	v_add_f32_e32 v64, v64, v65
	v_mov_b32_e32 v65, v64
	s_nop 1
	v_permlane32_swap_b32_e32 v64, v65
	s_and_saveexec_b64 s[30:31], s[4:5]
	s_cbranch_execz .LBB0_352
; __device__ __forceinline__ float xlane(float v, int src_lane) { return __uint_as_float(__builtin_amdgcn_ds_bpermute(src_lane << 2, __float_as_uint(v))); }
;     __device__ __forceinline__ void operator()(AccT acc, const pg8::Unit& u, int wr, int wc, int fr, int fq) const {
;     ...
;                         t += ((h0[0] * h0[0] + h0[1] * h0[1]) + (h0[2] * h0[2] + h0[3] * h0[3])) + ((h1[0] * h1[0] + h1[1] * h1[1]) + (h1[2] * h1[2] + h1[3] * h1[3]));
;     ...
;         for (int g = 0; g < 8; ++g) { float t = ss[g]; t += xlane(t, lane ^ 16); t += xlane(t, lane ^ 32);
;             if (fq == 0) SSQ[(size_t)(row0 + (g >> 2) * 128 + (g & 3) * 16) * 32 + u.pn * 4 + wc] = t; }
	v_lshlrev_b64 v[66:67], 7, v[160:161]
	v_lshl_add_u64 v[66:67], s[28:29], 0, v[66:67]
	s_waitcnt lgkmcnt(0)
	v_add_f32_e32 v64, v64, v65
	global_store_dword v[66:67], v64, off
.LBB0_352:
	s_or_b64 exec, exec, s[30:31]
	v_mul_f32_e32 v64, v109, v109
	s_waitcnt lgkmcnt(0)
	v_mul_f32_e32 v65, v111, v111
	v_fmac_f32_e32 v64, v108, v108
	v_fmac_f32_e32 v65, v110, v110
	v_add_f32_e32 v64, v64, v65
	v_mul_f32_e32 v65, v105, v105
	v_mul_f32_e32 v66, v107, v107
	v_fmac_f32_e32 v65, v104, v104
	v_fmac_f32_e32 v66, v106, v106
	v_add_f32_e32 v65, v65, v66
	v_add_f32_e32 v64, v64, v65
	v_mul_f32_e32 v65, v101, v101
	v_mul_f32_e32 v66, v103, v103
	v_fmac_f32_e32 v65, v100, v100
	v_fmac_f32_e32 v66, v102, v102
	v_add_f32_e32 v65, v65, v66
	v_mul_f32_e32 v66, v97, v97
	v_mul_f32_e32 v67, v99, v99
	v_fmac_f32_e32 v66, v96, v96
	v_fmac_f32_e32 v67, v98, v98
	v_add_f32_e32 v66, v66, v67
	v_add_f32_e32 v65, v65, v66
	v_add_f32_e32 v64, v64, v65
	s_waitcnt lgkmcnt(0)
	v_mov_b32_e32 v65, v64
	s_nop 1
	v_permlane16_swap_b32_e32 v65, v64
	v_add_f32_e32 v64, v64, v65
	v_mov_b32_e32 v65, v64
	s_nop 1
	v_permlane32_swap_b32_e32 v64, v65
	s_and_saveexec_b64 s[30:31], s[4:5]
	s_cbranch_execz .LBB0_354
	v_or_b32_e32 v66, 16, v160
	v_ashrrev_i32_e32 v67, 31, v66
	v_lshlrev_b64 v[66:67], 7, v[66:67]
	v_lshl_add_u64 v[66:67], s[28:29], 0, v[66:67]
	s_waitcnt lgkmcnt(0)
	v_add_f32_e32 v64, v64, v65
	global_store_dword v[66:67], v64, off
.LBB0_354:
	s_or_b64 exec, exec, s[30:31]
	v_mul_f32_e32 v64, v93, v93
	s_waitcnt lgkmcnt(0)
	v_mul_f32_e32 v65, v95, v95
	v_fmac_f32_e32 v64, v92, v92
	v_fmac_f32_e32 v65, v94, v94
	v_add_f32_e32 v64, v64, v65
	v_mul_f32_e32 v65, v89, v89
	v_mul_f32_e32 v66, v91, v91
	v_fmac_f32_e32 v65, v88, v88
	v_fmac_f32_e32 v66, v90, v90
	v_add_f32_e32 v65, v65, v66
	v_add_f32_e32 v64, v64, v65
	v_mul_f32_e32 v65, v115, v115
	v_mul_f32_e32 v66, v113, v113
	v_fmac_f32_e32 v65, v114, v114
	v_fmac_f32_e32 v66, v112, v112
	v_add_f32_e32 v65, v65, v66
	v_mul_f32_e32 v66, v119, v119
	v_mul_f32_e32 v67, v117, v117
	v_fmac_f32_e32 v66, v118, v118
	v_fmac_f32_e32 v67, v116, v116
	v_add_f32_e32 v66, v66, v67
	v_add_f32_e32 v65, v65, v66
	v_add_f32_e32 v64, v64, v65
	s_waitcnt lgkmcnt(0)
	v_mov_b32_e32 v65, v64
	s_nop 1
	v_permlane16_swap_b32_e32 v65, v64
	v_add_f32_e32 v64, v64, v65
	v_mov_b32_e32 v65, v64
	s_nop 1
	v_permlane32_swap_b32_e32 v64, v65
	s_and_saveexec_b64 s[30:31], s[4:5]
	s_cbranch_execz .LBB0_356
	v_or_b32_e32 v66, 32, v160
	v_ashrrev_i32_e32 v67, 31, v66
	v_lshlrev_b64 v[66:67], 7, v[66:67]
	v_lshl_add_u64 v[66:67], s[28:29], 0, v[66:67]
	s_waitcnt lgkmcnt(0)
	v_add_f32_e32 v64, v64, v65
	global_store_dword v[66:67], v64, off
.LBB0_356:
	s_or_b64 exec, exec, s[30:31]
	v_mul_f32_e32 v64, v123, v123
	s_waitcnt lgkmcnt(0)
	v_mul_f32_e32 v65, v121, v121
	v_fmac_f32_e32 v64, v122, v122
	v_fmac_f32_e32 v65, v120, v120
	v_add_f32_e32 v64, v64, v65
	v_mul_f32_e32 v65, v127, v127
	v_mul_f32_e32 v66, v125, v125
	v_fmac_f32_e32 v65, v126, v126
	v_fmac_f32_e32 v66, v124, v124
	v_add_f32_e32 v65, v65, v66
	v_add_f32_e32 v64, v64, v65
	v_mul_f32_e32 v65, v131, v131
	v_mul_f32_e32 v66, v129, v129
	v_fmac_f32_e32 v65, v130, v130
	v_fmac_f32_e32 v66, v128, v128
	v_add_f32_e32 v65, v65, v66
	v_mul_f32_e32 v66, v135, v135
	v_mul_f32_e32 v67, v133, v133
	v_fmac_f32_e32 v66, v134, v134
	v_fmac_f32_e32 v67, v132, v132
	v_add_f32_e32 v66, v66, v67
	v_add_f32_e32 v65, v65, v66
	v_add_f32_e32 v64, v64, v65
	s_waitcnt lgkmcnt(0)
	v_mov_b32_e32 v65, v64
	s_nop 1
	v_permlane16_swap_b32_e32 v65, v64
	v_add_f32_e32 v64, v64, v65
	v_mov_b32_e32 v65, v64
	s_nop 1
	v_permlane32_swap_b32_e32 v64, v65
	s_and_saveexec_b64 s[30:31], s[4:5]
	s_cbranch_execz .LBB0_358
	v_or_b32_e32 v66, 48, v160
	v_ashrrev_i32_e32 v67, 31, v66
	v_lshlrev_b64 v[66:67], 7, v[66:67]
	v_lshl_add_u64 v[66:67], s[28:29], 0, v[66:67]
	s_waitcnt lgkmcnt(0)
	v_add_f32_e32 v64, v64, v65
	global_store_dword v[66:67], v64, off
; __device__ __forceinline__ float xlane(float v, int src_lane) { return __uint_as_float(__builtin_amdgcn_ds_bpermute(src_lane << 2, __float_as_uint(v))); }
;     __device__ __forceinline__ void operator()(AccT acc, const pg8::Unit& u, int wr, int wc, int fr, int fq) const {
;     ...
;                         t += ((h0[0] * h0[0] + h0[1] * h0[1]) + (h0[2] * h0[2] + h0[3] * h0[3])) + ((h1[0] * h1[0] + h1[1] * h1[1]) + (h1[2] * h1[2] + h1[3] * h1[3]));
;     ...
;         for (int g = 0; g < 8; ++g) { float t = ss[g]; t += xlane(t, lane ^ 16); t += xlane(t, lane ^ 32);
;             if (fq == 0) SSQ[(size_t)(row0 + (g >> 2) * 128 + (g & 3) * 16) * 32 + u.pn * 4 + wc] = t; }
.LBB0_358:
	s_or_b64 exec, exec, s[30:31]
	v_mul_f32_e32 v61, v61, v61
	v_mul_f32_e32 v57, v57, v57
	v_mul_f32_e32 v53, v53, v53
	v_mul_f32_e32 v49, v49, v49
	v_fmac_f32_e32 v61, v60, v60
	v_mul_f32_e32 v60, v63, v63
	v_fmac_f32_e32 v57, v56, v56
	v_mul_f32_e32 v56, v59, v59
	v_fmac_f32_e32 v53, v52, v52
	v_mul_f32_e32 v52, v55, v55
	v_fmac_f32_e32 v49, v48, v48
	v_mul_f32_e32 v48, v51, v51
	v_fmac_f32_e32 v60, v62, v62
	v_fmac_f32_e32 v56, v58, v58
	v_fmac_f32_e32 v52, v54, v54
	v_fmac_f32_e32 v48, v50, v50
	v_add_f32_e32 v60, v61, v60
	v_add_f32_e32 v56, v57, v56
	v_add_f32_e32 v52, v53, v52
	v_add_f32_e32 v48, v49, v48
	v_add_f32_e32 v56, v60, v56
	v_add_f32_e32 v48, v52, v48
	v_add_f32_e32 v48, v56, v48
	s_waitcnt lgkmcnt(0)
	v_mov_b32_e32 v49, v48
	s_nop 1
	v_permlane16_swap_b32_e32 v49, v48
	v_add_f32_e32 v48, v48, v49
	v_mov_b32_e32 v49, v48
	s_nop 1
	v_permlane32_swap_b32_e32 v48, v49
	s_and_saveexec_b64 s[30:31], s[4:5]
	s_cbranch_execz .LBB0_360
	v_lshlrev_b64 v[50:51], 7, v[160:161]
	v_lshl_add_u64 v[50:51], s[28:29], 0, v[50:51]
	s_waitcnt lgkmcnt(0)
	v_add_f32_e32 v52, v48, v49
	v_add_co_u32_e32 v48, vcc, 0x4000, v50
	s_nop 1
	v_addc_co_u32_e32 v49, vcc, 0, v51, vcc
	global_store_dword v[48:49], v52, off
.LBB0_360:
	s_or_b64 exec, exec, s[30:31]
	v_mul_f32_e32 v45, v45, v45
	v_mul_f32_e32 v41, v41, v41
	v_mul_f32_e32 v37, v37, v37
	v_mul_f32_e32 v33, v33, v33
	v_fmac_f32_e32 v45, v44, v44
	v_mul_f32_e32 v44, v47, v47
	v_fmac_f32_e32 v41, v40, v40
	v_mul_f32_e32 v40, v43, v43
	v_fmac_f32_e32 v37, v36, v36
	v_mul_f32_e32 v36, v39, v39
	v_fmac_f32_e32 v33, v32, v32
	v_mul_f32_e32 v32, v35, v35
	v_fmac_f32_e32 v44, v46, v46
	v_fmac_f32_e32 v40, v42, v42
	v_fmac_f32_e32 v36, v38, v38
	v_fmac_f32_e32 v32, v34, v34
	v_add_f32_e32 v44, v45, v44
	v_add_f32_e32 v40, v41, v40
	v_add_f32_e32 v36, v37, v36
	v_add_f32_e32 v32, v33, v32
	v_add_f32_e32 v40, v44, v40
	v_add_f32_e32 v32, v36, v32
	v_add_f32_e32 v32, v40, v32
	s_waitcnt lgkmcnt(0)
	v_mov_b32_e32 v33, v32
	s_nop 1
	v_permlane16_swap_b32_e32 v33, v32
	v_add_f32_e32 v32, v32, v33
	v_mov_b32_e32 v33, v32
	s_nop 1
	v_permlane32_swap_b32_e32 v32, v33
	s_and_saveexec_b64 s[30:31], s[4:5]
	s_cbranch_execz .LBB0_362
	v_lshlrev_b64 v[34:35], 7, v[160:161]
	v_lshl_add_u64 v[34:35], s[28:29], 0, v[34:35]
	s_waitcnt lgkmcnt(0)
	v_add_f32_e32 v36, v32, v33
	v_add_co_u32_e32 v32, vcc, 0x4000, v34
	s_nop 1
	v_addc_co_u32_e32 v33, vcc, 0, v35, vcc
	global_store_dword v[32:33], v36, off offset:2048
.LBB0_362:
	s_or_b64 exec, exec, s[30:31]
	v_mul_f32_e32 v29, v29, v29
	v_mul_f32_e32 v25, v25, v25
	v_mul_f32_e32 v21, v21, v21
	v_mul_f32_e32 v17, v17, v17
	v_fmac_f32_e32 v29, v28, v28
	v_mul_f32_e32 v28, v31, v31
	v_fmac_f32_e32 v25, v24, v24
	v_mul_f32_e32 v24, v27, v27
	v_fmac_f32_e32 v21, v20, v20
	v_mul_f32_e32 v20, v23, v23
	v_fmac_f32_e32 v17, v16, v16
	v_mul_f32_e32 v16, v19, v19
	v_fmac_f32_e32 v28, v30, v30
	v_fmac_f32_e32 v24, v26, v26
	v_fmac_f32_e32 v20, v22, v22
	v_fmac_f32_e32 v16, v18, v18
	v_add_f32_e32 v28, v29, v28
	v_add_f32_e32 v24, v25, v24
	v_add_f32_e32 v20, v21, v20
	v_add_f32_e32 v16, v17, v16
	v_add_f32_e32 v24, v28, v24
	v_add_f32_e32 v16, v20, v16
	v_add_f32_e32 v16, v24, v16
	s_waitcnt lgkmcnt(0)
	v_mov_b32_e32 v17, v16
	s_nop 1
	v_permlane16_swap_b32_e32 v17, v16
	v_add_f32_e32 v16, v16, v17
	v_mov_b32_e32 v17, v16
	s_nop 1
	v_permlane32_swap_b32_e32 v16, v17
	s_and_saveexec_b64 s[30:31], s[4:5]
	s_cbranch_execz .LBB0_364
	v_lshlrev_b64 v[18:19], 7, v[160:161]
	v_lshl_add_u64 v[18:19], s[28:29], 0, v[18:19]
	s_waitcnt lgkmcnt(0)
	v_add_f32_e32 v20, v16, v17
	v_add_co_u32_e32 v16, vcc, 0x5000, v18
	s_nop 1
	v_addc_co_u32_e32 v17, vcc, 0, v19, vcc
	global_store_dword v[16:17], v20, off
.LBB0_364:
	s_or_b64 exec, exec, s[30:31]
	v_mul_f32_e32 v13, v13, v13
	v_mul_f32_e32 v9, v9, v9
	v_mul_f32_e32 v5, v5, v5
	v_mul_f32_e32 v1, v1, v1
	v_fmac_f32_e32 v13, v12, v12
	v_mul_f32_e32 v12, v15, v15
	v_fmac_f32_e32 v9, v8, v8
	v_mul_f32_e32 v8, v11, v11
	v_fmac_f32_e32 v5, v4, v4
	v_mul_f32_e32 v4, v7, v7
	v_fmac_f32_e32 v1, v0, v0
	v_mul_f32_e32 v0, v3, v3
	v_fmac_f32_e32 v12, v14, v14
	v_fmac_f32_e32 v8, v10, v10
	v_fmac_f32_e32 v4, v6, v6
	v_fmac_f32_e32 v0, v2, v2
	v_add_f32_e32 v12, v13, v12
	v_add_f32_e32 v8, v9, v8
	v_add_f32_e32 v4, v5, v4
	v_add_f32_e32 v0, v1, v0
	v_add_f32_e32 v8, v12, v8
	v_add_f32_e32 v0, v4, v0
	v_add_f32_e32 v0, v8, v0
	s_waitcnt lgkmcnt(0)
	v_mov_b32_e32 v1, v0
	s_nop 1
	v_permlane16_swap_b32_e32 v1, v0
	v_add_f32_e32 v0, v0, v1
	v_mov_b32_e32 v1, v0
	s_nop 1
	v_permlane32_swap_b32_e32 v0, v1
	s_and_saveexec_b64 s[30:31], s[4:5]
	s_cbranch_execz .LBB0_366
	v_lshlrev_b64 v[2:3], 7, v[160:161]
	v_lshl_add_u64 v[2:3], s[28:29], 0, v[2:3]
	s_waitcnt lgkmcnt(0)
	v_add_f32_e32 v4, v0, v1
	v_add_co_u32_e32 v0, vcc, 0x5000, v2
	s_nop 1
	v_addc_co_u32_e32 v1, vcc, 0, v3, vcc
	global_store_dword v[0:1], v4, off offset:2048

;     __device__ __forceinline__ void operator()(AccT acc, const pg8::Unit& u, int wr, int wc, int fr, int fq) const {
;         const int row0 = u.pm * 256 + wr * 64 + fr, col0 = u.pn * 256 + wc * 32 + 8 * fq, lane = fq * 16 + fr;
;         const int bidx = u.pm < 64 ? (u.pm >> 4) : 4;
;         const float* gp = gate + (size_t)bidx * MODW + col0;
;         f32x4 gv[2][2], gz[2][2];
; #pragma unroll
;         for (int bj = 0; bj < 2; ++bj)
; #pragma unroll
;             for (int n = 0; n < 2; ++n) { gv[bj][n] = *(const f32x4*)(gp + bj * 128 + n * 4) * coef;
;                 if (WZ) gz[bj][n] = *(const f32x4*)(gnext + col0 + bj * 128 + n * 4) * (*(const f32x4*)(scnext + (size_t)bidx * MODW + col0 + bj * 128 + n * 4) + 1.f); }
;         const int st4 = ((lane & 3) * 16 + (lane >> 2)) * 4, ld4 = ((lane & 15) * 4 + (lane >> 4)) * 4;
;         const size_t eo = (size_t)(u.pm * 256 + wr * 64 + (lane >> 2)) * LDP + u.pn * 256 + wc * 32 + (lane & 3) * 8;
;         hf_t* hout = H + eo; bf16_t* zout = Z + eo; float ss[8];
;         if constexpr (B32) {
;             const float* base = (const float*)(u.pm < 64 ? baseL : baseC) + (size_t)row0 * D + col0;
;             f32x4 hb[4][2][2];
; #pragma unroll
;             for (int ai = 0; ai < 2; ++ai) {
; #pragma unroll
;                 for (int m = 0; m < 4; ++m)
; #pragma unroll
;                     for (int bj = 0; bj < 2; ++bj)
; #pragma unroll
;                         for (int n = 0; n < 2; ++n) hb[m][bj][n] = *(const f32x4*)(base + (size_t)(ai * 128 + m * 16) * D + bj * 128 + n * 4);
.LBB0_403:
	s_lshr_b32 s2, s85, 4
	s_lshl_b32 s23, s85, 8
	s_mul_i32 s40, s2, 0x4800
	s_add_i32 s23, s23, s57
	s_lshl_b32 s25, s96, 8
	s_lshl_b64 s[10:11], s[40:41], 2
	v_or_b32_e32 v192, s25, v249
	s_add_u32 s30, s53, s10
	s_addc_u32 s31, s54, s11
	v_lshlrev_b64 v[128:129], 2, v[192:193]
	v_lshl_add_u64 v[150:151], s[30:31], 0, v[128:129]
	global_load_dwordx4 v[130:133], v[150:151], off offset:16
	global_load_dwordx4 v[134:137], v[150:151], off
	s_add_u32 s10, s55, s10
	v_lshl_add_u64 v[152:153], s[16:17], 0, v[128:129]
	s_addc_u32 s11, s56, s11
	v_lshl_add_u64 v[154:155], s[10:11], 0, v[128:129]
	v_or_b32_e32 v192, s25, v252
	s_movk_i32 s2, 0x840
	v_or_b32_e32 v200, s23, v248
	v_ashrrev_i32_e32 v201, 31, v200
	s_lshl_b32 s40, s96, 2
	s_waitcnt vmcnt(0)
	v_pk_mul_f32 v[214:215], v[132:133], 0.5 op_sel_hi:[1,0]
	v_pk_mul_f32 v[210:211], v[136:137], 0.5 op_sel_hi:[1,0]
	v_pk_mul_f32 v[212:213], v[134:135], 0.5 op_sel_hi:[1,0]
	global_load_dwordx4 v[134:137], v[152:153], off offset:16
	global_load_dwordx4 v[138:141], v[152:153], off
	global_load_dwordx4 v[142:145], v[154:155], off offset:16
	global_load_dwordx4 v[146:149], v[154:155], off
	v_pk_mul_f32 v[216:217], v[130:131], 0.5 op_sel_hi:[1,0]
	s_waitcnt vmcnt(1)
	v_pk_add_f32 v[130:131], v[144:145], 1.0 op_sel_hi:[1,0]
	v_pk_add_f32 v[132:133], v[142:143], 1.0 op_sel_hi:[1,0]
	v_pk_mul_f32 v[206:207], v[136:137], v[130:131]
	v_pk_mul_f32 v[208:209], v[134:135], v[132:133]
	global_load_dwordx4 v[130:133], v[150:151], off offset:528
	global_load_dwordx4 v[134:137], v[150:151], off offset:512
	s_waitcnt vmcnt(2)
	v_pk_add_f32 v[148:149], v[148:149], 1.0 op_sel_hi:[1,0]
	v_pk_add_f32 v[146:147], v[146:147], 1.0 op_sel_hi:[1,0]
	v_pk_mul_f32 v[202:203], v[140:141], v[148:149]
	v_pk_mul_f32 v[204:205], v[138:139], v[146:147]
	s_waitcnt vmcnt(1)
	v_pk_mul_f32 v[232:233], v[130:131], 0.5 op_sel_hi:[1,0]
	s_waitcnt vmcnt(0)
	v_pk_mul_f32 v[218:219], v[136:137], 0.5 op_sel_hi:[1,0]
	v_pk_mul_f32 v[220:221], v[134:135], 0.5 op_sel_hi:[1,0]
	global_load_dwordx4 v[134:137], v[152:153], off offset:528
	global_load_dwordx4 v[138:141], v[152:153], off offset:512
	global_load_dwordx4 v[142:145], v[154:155], off offset:528
	global_load_dwordx4 v[146:149], v[154:155], off offset:512
	v_pk_mul_f32 v[230:231], v[132:133], 0.5 op_sel_hi:[1,0]
	s_waitcnt vmcnt(1)
	v_pk_add_f32 v[130:131], v[144:145], 1.0 op_sel_hi:[1,0]
	s_nop 0
	v_pk_mul_f32 v[226:227], v[136:137], v[130:131]
	v_or_b32_e32 v130, s23, v251
	v_mad_i64_i32 v[130:131], s[10:11], v130, s2, v[192:193]
	v_lshlrev_b64 v[130:131], 1, v[130:131]
	v_lshl_add_u64 v[236:237], s[12:13], 0, v[130:131]
	v_lshl_add_u64 v[234:235], s[14:15], 0, v[130:131]
	v_lshlrev_b64 v[130:131], 13, v[200:201]
	v_lshl_add_u64 v[130:131], s[8:9], 0, v[130:131]
	v_lshl_add_u64 v[238:239], v[130:131], 0, v[128:129]
	global_load_dwordx4 v[184:187], v[238:239], off offset:16
	global_load_dwordx4 v[188:191], v[238:239], off
	global_load_dwordx4 v[176:179], v[238:239], off offset:528
	global_load_dwordx4 v[180:183], v[238:239], off offset:512
	s_mov_b32 s2, 0x20000
	v_add_co_u32_e32 v130, vcc, s2, v238
	v_lshl_add_u64 v[128:129], v[238:239], 0, s[74:75]
	s_nop 0
	v_addc_co_u32_e32 v131, vcc, 0, v239, vcc
	global_load_dwordx4 v[172:175], v[130:131], off
	global_load_dwordx4 v[168:171], v[128:129], off offset:16
	s_mov_b64 s[10:11], 0x20200
	v_lshl_add_u64 v[128:129], v[238:239], 0, s[10:11]
	global_load_dwordx4 v[164:167], v[130:131], off offset:512
	global_load_dwordx4 v[160:163], v[128:129], off offset:16
	s_mov_b32 s2, 0x40000
	v_add_co_u32_e32 v130, vcc, s2, v238
	s_waitcnt vmcnt(8)
	v_pk_add_f32 v[148:149], v[148:149], 1.0 op_sel_hi:[1,0]
	v_pk_add_f32 v[146:147], v[146:147], 1.0 op_sel_hi:[1,0]
	s_mov_b64 s[10:11], 0x40000
	v_addc_co_u32_e32 v131, vcc, 0, v239, vcc
	v_pk_mul_f32 v[222:223], v[140:141], v[148:149]
	v_pk_mul_f32 v[224:225], v[138:139], v[146:147]
	v_lshl_add_u64 v[128:129], v[238:239], 0, s[10:11]
	global_load_dwordx4 v[148:151], v[130:131], off
	global_load_dwordx4 v[144:147], v[128:129], off offset:16
	s_mov_b64 s[10:11], 0x40200
	v_pk_add_f32 v[132:133], v[142:143], 1.0 op_sel_hi:[1,0]
	v_lshl_add_u64 v[128:129], v[238:239], 0, s[10:11]
	global_load_dwordx4 v[140:143], v[130:131], off offset:512
	global_load_dwordx4 v[136:139], v[128:129], off offset:16
	s_mov_b32 s2, 0x60000
	v_add_co_u32_e32 v130, vcc, s2, v238
	s_mov_b64 s[10:11], 0x60000
	s_nop 0
	v_addc_co_u32_e32 v131, vcc, 0, v239, vcc
	v_lshl_add_u64 v[128:129], v[238:239], 0, s[10:11]
	global_load_dwordx4 v[156:159], v[130:131], off
	global_load_dwordx4 v[152:155], v[128:129], off offset:16
	s_mov_b64 s[10:11], 0x60200
	v_lshl_add_u64 v[128:129], v[238:239], 0, s[10:11]
	v_pk_mul_f32 v[228:229], v[134:135], v[132:133]
	global_load_dwordx4 v[132:135], v[130:131], off offset:512
	s_nop 0
	global_load_dwordx4 v[128:131], v[128:129], off offset:16
	s_mov_b32 s2, 0x10000
	s_mov_b64 s[10:11], 0x100000
	s_waitcnt vmcnt(15)
	v_pk_fma_f32 v[186:187], v[122:123], v[214:215], v[186:187]
	s_waitcnt vmcnt(14)
	v_pk_fma_f32 v[126:127], v[126:127], v[210:211], v[190:191]
	v_pk_fma_f32 v[124:125], v[124:125], v[212:213], v[188:189]
	v_pk_fma_f32 v[184:185], v[120:121], v[216:217], v[184:185]
	v_cvt_pk_f16_f32 v123, v186, v187
	v_cvt_pk_f16_f32 v121, v126, v127
	v_cvt_pk_f16_f32 v122, v184, v185
	v_cvt_pk_f16_f32 v120, v124, v125
	ds_bpermute_b32 v120, v250, v120
	ds_bpermute_b32 v121, v250, v121
	ds_bpermute_b32 v122, v250, v122
	ds_bpermute_b32 v123, v250, v123
	s_waitcnt vmcnt(12)
	v_pk_fma_f32 v[118:119], v[118:119], v[218:219], v[182:183]
	v_pk_fma_f32 v[116:117], v[116:117], v[220:221], v[180:181]
	s_waitcnt vmcnt(11)
; __device__ __forceinline__ unsigned cvt_pk_bf16(float lo, float hi) { unsigned r; asm volatile("v_cvt_pk_bf16_f32 %0, %1, %2" : "=v"(r) : "v"(lo), "v"(hi)); return r; }
;     __device__ __forceinline__ void operator()(AccT acc, const pg8::Unit& u, int wr, int wc, int fr, int fq) const {
;     ...
;                 for (int m = 0; m < 4; ++m) { const size_t ro = (size_t)(ai * 128 + m * 16) * LDP; float t = 0.f;
; #pragma unroll
;                     for (int bj = 0; bj < 2; ++bj) { const f32x4 h0 = hb[m][bj][0] + gv[bj][0] * acc[ai][bj][m][0], h1 = hb[m][bj][1] + gv[bj][1] * acc[ai][bj][m][1];
;                         const h16x4 q0 = __builtin_convertvector(h0, h16x4), q1 = __builtin_convertvector(h1, h16x4);
;                         { const h16x8 hv8 = (h16x8){q0[0], q0[1], q0[2], q0[3], q1[0], q1[1], q1[2], q1[3]}; *(u32x4*)(hout + ro + bj * 128) = gather4(__builtin_bit_cast(u32x4, hv8), st4); }
;                         t += ((h0[0] * h0[0] + h0[1] * h0[1]) + (h0[2] * h0[2] + h0[3] * h0[3])) + ((h1[0] * h1[0] + h1[1] * h1[1]) + (h1[2] * h1[2] + h1[3] * h1[3]));
;                         if (WZ) { const f32x4 z0 = h0 * gz[bj][0], z1 = h1 * gz[bj][1]; u32x4 w; w.x = cvt_pk_bf16(z0[0], z0[1]); w.y = cvt_pk_bf16(z0[2], z0[3]); w.z = cvt_pk_bf16(z1[0], z1[1]); w.w = cvt_pk_bf16(z1[2], z1[3]);
;                             *(u32x4*)(zout + ro + bj * 128) = gather4(w, st4); } }
	v_pk_fma_f32 v[110:111], v[110:111], v[210:211], v[174:175]
	v_pk_fma_f32 v[108:109], v[108:109], v[212:213], v[172:173]
	s_waitcnt lgkmcnt(0)
	global_store_dwordx4 v[236:237], v[120:123], off
	s_waitcnt vmcnt(11)
	v_pk_fma_f32 v[106:107], v[106:107], v[214:215], v[170:171]
	v_pk_fma_f32 v[104:105], v[104:105], v[216:217], v[168:169]
	v_mul_f32_e32 v120, v125, v125
	v_mul_f32_e32 v121, v127, v127
	v_fmac_f32_e32 v120, v124, v124
	v_fmac_f32_e32 v121, v126, v126
	v_add_f32_e32 v120, v120, v121
	v_mul_f32_e32 v121, v185, v185
	v_mul_f32_e32 v122, v187, v187
	v_fmac_f32_e32 v121, v184, v184
	v_fmac_f32_e32 v122, v186, v186
	v_add_f32_e32 v121, v121, v122
	v_add_f32_e32 v188, v120, v121
	v_pk_mul_f32 v[120:121], v[202:203], v[126:127]
	v_pk_mul_f32 v[122:123], v[204:205], v[124:125]
	v_pk_mul_f32 v[124:125], v[206:207], v[186:187]
	v_pk_mul_f32 v[126:127], v[208:209], v[184:185]
	v_cvt_pk_bf16_f32 v122, v122, v123
	v_cvt_pk_bf16_f32 v121, v120, v121
	ds_bpermute_b32 v120, v250, v122
	v_cvt_pk_bf16_f32 v123, v126, v127
	v_cvt_pk_bf16_f32 v124, v124, v125
	ds_bpermute_b32 v121, v250, v121
	ds_bpermute_b32 v122, v250, v123
	ds_bpermute_b32 v123, v250, v124
	s_waitcnt vmcnt(8)
	v_pk_fma_f32 v[126:127], v[92:93], v[212:213], v[148:149]
	s_waitcnt vmcnt(7)
	v_pk_fma_f32 v[124:125], v[88:89], v[216:217], v[144:145]
	v_cvt_pk_f16_f32 v88, v126, v127
	ds_bpermute_b32 v88, v250, v88
	s_waitcnt lgkmcnt(1)
	global_store_dwordx4 v[234:235], v[120:123], off
	s_waitcnt vmcnt(7)
	v_pk_fma_f32 v[142:143], v[86:87], v[218:219], v[142:143]
	v_pk_fma_f32 v[140:141], v[84:85], v[220:221], v[140:141]
	v_pk_fma_f32 v[120:121], v[114:115], v[230:231], v[178:179]
	v_pk_fma_f32 v[122:123], v[112:113], v[232:233], v[176:177]
	v_cvt_pk_f16_f32 v115, v120, v121
	v_cvt_pk_f16_f32 v113, v118, v119
	v_cvt_pk_f16_f32 v114, v122, v123
	v_cvt_pk_f16_f32 v112, v116, v117
	ds_bpermute_b32 v112, v250, v112
	ds_bpermute_b32 v113, v250, v113
	ds_bpermute_b32 v114, v250, v114
	ds_bpermute_b32 v115, v250, v115
	s_waitcnt vmcnt(6)
	v_pk_fma_f32 v[138:139], v[82:83], v[230:231], v[138:139]
	v_pk_fma_f32 v[136:137], v[80:81], v[232:233], v[136:137]
	v_cvt_pk_f16_f32 v83, v138, v139
	v_cvt_pk_f16_f32 v81, v142, v143
	s_waitcnt lgkmcnt(0)
	global_store_dwordx4 v[236:237], v[112:115], off offset:256
	v_cvt_pk_f16_f32 v82, v136, v137
	v_cvt_pk_f16_f32 v80, v140, v141
	v_mul_f32_e32 v112, v117, v117
	v_mul_f32_e32 v113, v119, v119
	v_fmac_f32_e32 v112, v116, v116
	v_fmac_f32_e32 v113, v118, v118
	v_add_f32_e32 v112, v112, v113
	v_mul_f32_e32 v113, v123, v123
	v_mul_f32_e32 v114, v121, v121
	v_fmac_f32_e32 v113, v122, v122
	v_fmac_f32_e32 v114, v120, v120
	v_add_f32_e32 v113, v113, v114
	v_add_f32_e32 v112, v112, v113
	v_add_f32_e32 v176, v188, v112
	v_pk_mul_f32 v[112:113], v[222:223], v[118:119]
	v_pk_mul_f32 v[114:115], v[224:225], v[116:117]
	v_pk_mul_f32 v[116:117], v[226:227], v[120:121]
	v_pk_mul_f32 v[118:119], v[228:229], v[122:123]
	v_cvt_pk_bf16_f32 v114, v114, v115
	v_cvt_pk_bf16_f32 v113, v112, v113
	ds_bpermute_b32 v112, v250, v114
	v_cvt_pk_bf16_f32 v115, v118, v119
	v_cvt_pk_bf16_f32 v116, v116, v117
	ds_bpermute_b32 v113, v250, v113
	ds_bpermute_b32 v114, v250, v115
	ds_bpermute_b32 v115, v250, v116
	v_add_co_u32_e32 v120, vcc, s2, v236
	v_pk_mul_f32 v[116:117], v[206:207], v[106:107]
	s_nop 0
	v_addc_co_u32_e32 v121, vcc, 0, v237, vcc
	s_waitcnt lgkmcnt(0)
	global_store_dwordx4 v[234:235], v[112:115], off offset:256
	v_pk_mul_f32 v[118:119], v[208:209], v[104:105]
	v_add_co_u32_e32 v122, vcc, s2, v234
	v_cvt_pk_f16_f32 v115, v106, v107
	v_cvt_pk_f16_f32 v113, v110, v111
	v_cvt_pk_f16_f32 v114, v104, v105
	v_cvt_pk_f16_f32 v112, v108, v109
	ds_bpermute_b32 v112, v250, v112
	ds_bpermute_b32 v113, v250, v113
	ds_bpermute_b32 v114, v250, v114
	ds_bpermute_b32 v115, v250, v115
	v_addc_co_u32_e32 v123, vcc, 0, v235, vcc
	s_mov_b32 s2, 0x21000
	v_add_co_u32_e32 v92, vcc, s2, v236
	s_waitcnt lgkmcnt(0)
	global_store_dwordx4 v[120:121], v[112:115], off offset:2048
	v_addc_co_u32_e32 v93, vcc, 0, v237, vcc
	s_nop 0
	v_pk_mul_f32 v[112:113], v[202:203], v[110:111]
	v_pk_mul_f32 v[114:115], v[204:205], v[108:109]
	ds_bpermute_b32 v80, v250, v80
	v_cvt_pk_bf16_f32 v114, v114, v115
	v_cvt_pk_bf16_f32 v113, v112, v113
	v_cvt_pk_bf16_f32 v115, v118, v119
	v_cvt_pk_bf16_f32 v116, v116, v117
	ds_bpermute_b32 v112, v250, v114
	ds_bpermute_b32 v113, v250, v113
	ds_bpermute_b32 v114, v250, v115
	ds_bpermute_b32 v115, v250, v116
	v_pk_fma_f32 v[118:119], v[100:101], v[220:221], v[164:165]
	v_pk_fma_f32 v[116:117], v[96:97], v[232:233], v[160:161]
	v_cvt_pk_f16_f32 v96, v118, v119
	ds_bpermute_b32 v96, v250, v96
	s_waitcnt lgkmcnt(1)
	global_store_dwordx4 v[122:123], v[112:115], off offset:2048
	ds_bpermute_b32 v81, v250, v81
	ds_bpermute_b32 v82, v250, v82
	v_pk_fma_f32 v[114:115], v[102:103], v[218:219], v[166:167]
	v_pk_fma_f32 v[112:113], v[98:99], v[230:231], v[162:163]
	v_cvt_pk_f16_f32 v97, v114, v115
	v_cvt_pk_f16_f32 v99, v112, v113
	v_cvt_pk_f16_f32 v98, v116, v117
	ds_bpermute_b32 v97, v250, v97
	ds_bpermute_b32 v98, v250, v98
	ds_bpermute_b32 v99, v250, v99
	v_pk_mul_f32 v[100:101], v[226:227], v[112:113]
	v_pk_mul_f32 v[102:103], v[228:229], v[116:117]
	ds_bpermute_b32 v83, v250, v83
	s_waitcnt vmcnt(8)
	v_pk_fma_f32 v[144:145], v[74:75], v[214:215], v[154:155]
	s_waitcnt lgkmcnt(1)
; __device__ __forceinline__ unsigned cvt_pk_bf16(float lo, float hi) { unsigned r; asm volatile("v_cvt_pk_bf16_f32 %0, %1, %2" : "=v"(r) : "v"(lo), "v"(hi)); return r; }
;     __device__ __forceinline__ void operator()(AccT acc, const pg8::Unit& u, int wr, int wc, int fr, int fq) const {
;     ...
;                 for (int m = 0; m < 4; ++m) { const size_t ro = (size_t)(ai * 128 + m * 16) * LDP; float t = 0.f;
; #pragma unroll
;                     for (int bj = 0; bj < 2; ++bj) { const f32x4 h0 = hb[m][bj][0] + gv[bj][0] * acc[ai][bj][m][0], h1 = hb[m][bj][1] + gv[bj][1] * acc[ai][bj][m][1];
;                         const h16x4 q0 = __builtin_convertvector(h0, h16x4), q1 = __builtin_convertvector(h1, h16x4);
;                         { const h16x8 hv8 = (h16x8){q0[0], q0[1], q0[2], q0[3], q1[0], q1[1], q1[2], q1[3]}; *(u32x4*)(hout + ro + bj * 128) = gather4(__builtin_bit_cast(u32x4, hv8), st4); }
;                         t += ((h0[0] * h0[0] + h0[1] * h0[1]) + (h0[2] * h0[2] + h0[3] * h0[3])) + ((h1[0] * h1[0] + h1[1] * h1[1]) + (h1[2] * h1[2] + h1[3] * h1[3]));
;                         if (WZ) { const f32x4 z0 = h0 * gz[bj][0], z1 = h1 * gz[bj][1]; u32x4 w; w.x = cvt_pk_bf16(z0[0], z0[1]); w.y = cvt_pk_bf16(z0[2], z0[3]); w.z = cvt_pk_bf16(z1[0], z1[1]); w.w = cvt_pk_bf16(z1[2], z1[3]);
;                             *(u32x4*)(zout + ro + bj * 128) = gather4(w, st4); } }
	global_store_dwordx4 v[120:121], v[96:99], off offset:2304
	v_pk_fma_f32 v[120:121], v[90:91], v[214:215], v[146:147]
	v_cvt_pk_f16_f32 v90, v124, v125
	v_pk_mul_f32 v[96:97], v[222:223], v[114:115]
	v_pk_mul_f32 v[98:99], v[224:225], v[118:119]
	v_cvt_pk_f16_f32 v91, v120, v121
	v_cvt_pk_bf16_f32 v98, v98, v99
	v_cvt_pk_bf16_f32 v97, v96, v97
	v_cvt_pk_bf16_f32 v99, v102, v103
	v_cvt_pk_bf16_f32 v100, v100, v101
	ds_bpermute_b32 v96, v250, v98
	ds_bpermute_b32 v97, v250, v97
	ds_bpermute_b32 v98, v250, v99
	ds_bpermute_b32 v99, v250, v100
	ds_bpermute_b32 v90, v250, v90
	ds_bpermute_b32 v91, v250, v91
	v_pk_fma_f32 v[146:147], v[78:79], v[210:211], v[158:159]
	v_pk_fma_f32 v[148:149], v[72:73], v[216:217], v[152:153]
	s_waitcnt lgkmcnt(2)
	global_store_dwordx4 v[122:123], v[96:99], off offset:2304
	v_pk_fma_f32 v[122:123], v[94:95], v[210:211], v[150:151]
	v_pk_mul_f32 v[94:95], v[206:207], v[120:121]
	v_cvt_pk_f16_f32 v89, v122, v123
	ds_bpermute_b32 v89, v250, v89
	v_pk_mul_f32 v[96:97], v[208:209], v[124:125]
	v_pk_fma_f32 v[150:151], v[76:77], v[212:213], v[156:157]
	v_cvt_pk_f16_f32 v75, v144, v145
	v_cvt_pk_f16_f32 v73, v146, v147
	s_waitcnt lgkmcnt(0)
	global_store_dwordx4 v[92:93], v[88:91], off
	v_cvt_pk_f16_f32 v74, v148, v149
	v_cvt_pk_f16_f32 v72, v150, v151
	v_pk_mul_f32 v[88:89], v[202:203], v[122:123]
	v_pk_mul_f32 v[90:91], v[204:205], v[126:127]
	v_pk_mul_f32 v[84:85], v[226:227], v[138:139]
	v_cvt_pk_bf16_f32 v90, v90, v91
	v_cvt_pk_bf16_f32 v89, v88, v89
	v_cvt_pk_bf16_f32 v91, v96, v97
	v_cvt_pk_bf16_f32 v94, v94, v95
	ds_bpermute_b32 v88, v250, v90
	ds_bpermute_b32 v89, v250, v89
	ds_bpermute_b32 v90, v250, v91
	ds_bpermute_b32 v91, v250, v94
	v_add_co_u32_e32 v94, vcc, s2, v234
	global_store_dwordx4 v[92:93], v[80:83], off offset:256
	s_nop 0
	v_addc_co_u32_e32 v95, vcc, 0, v235, vcc
	v_pk_mul_f32 v[80:81], v[222:223], v[142:143]
	v_pk_mul_f32 v[82:83], v[224:225], v[140:141]
	s_waitcnt lgkmcnt(0)
	global_store_dwordx4 v[94:95], v[88:91], off
	v_pk_mul_f32 v[86:87], v[228:229], v[136:137]
	v_cvt_pk_bf16_f32 v82, v82, v83
	v_cvt_pk_bf16_f32 v81, v80, v81
	ds_bpermute_b32 v72, v250, v72
	v_cvt_pk_bf16_f32 v83, v86, v87
	ds_bpermute_b32 v73, v250, v73
	ds_bpermute_b32 v74, v250, v74
	ds_bpermute_b32 v75, v250, v75
	v_cvt_pk_bf16_f32 v84, v84, v85
	ds_bpermute_b32 v80, v250, v82
	ds_bpermute_b32 v81, v250, v81
	ds_bpermute_b32 v82, v250, v83
	ds_bpermute_b32 v83, v250, v84
	s_mov_b32 s2, 0x31000
	v_add_co_u32_e32 v76, vcc, s2, v236
	s_waitcnt vmcnt(12)
	v_pk_fma_f32 v[134:135], v[70:71], v[218:219], v[134:135]
	v_addc_co_u32_e32 v77, vcc, 0, v237, vcc
	v_pk_fma_f32 v[132:133], v[68:69], v[220:221], v[132:133]
	s_waitcnt vmcnt(11)
	v_pk_fma_f32 v[130:131], v[66:67], v[230:231], v[130:131]
	v_pk_fma_f32 v[128:129], v[64:65], v[232:233], v[128:129]
	s_waitcnt lgkmcnt(4)
	global_store_dwordx4 v[76:77], v[72:75], off offset:2048
	v_cvt_pk_f16_f32 v67, v130, v131
	v_cvt_pk_f16_f32 v65, v134, v135
	v_pk_mul_f32 v[72:73], v[202:203], v[146:147]
	v_pk_mul_f32 v[74:75], v[204:205], v[150:151]
	v_cvt_pk_f16_f32 v66, v128, v129
	v_cvt_pk_f16_f32 v64, v132, v133
	s_waitcnt lgkmcnt(0)
	global_store_dwordx4 v[94:95], v[80:83], off offset:256
	v_pk_mul_f32 v[78:79], v[206:207], v[144:145]
	v_cvt_pk_bf16_f32 v74, v74, v75
	v_cvt_pk_bf16_f32 v73, v72, v73
	ds_bpermute_b32 v64, v250, v64
	v_pk_mul_f32 v[80:81], v[208:209], v[148:149]
	ds_bpermute_b32 v65, v250, v65
	v_cvt_pk_bf16_f32 v75, v80, v81
	ds_bpermute_b32 v66, v250, v66
	ds_bpermute_b32 v67, v250, v67
	v_cvt_pk_bf16_f32 v78, v78, v79
	ds_bpermute_b32 v72, v250, v74
	ds_bpermute_b32 v73, v250, v73
	ds_bpermute_b32 v74, v250, v75
	ds_bpermute_b32 v75, v250, v78
	v_add_co_u32_e32 v78, vcc, s2, v234
	s_waitcnt lgkmcnt(4)
	global_store_dwordx4 v[76:77], v[64:67], off offset:2304
	v_addc_co_u32_e32 v79, vcc, 0, v235, vcc
	s_nop 0
	v_pk_mul_f32 v[64:65], v[222:223], v[134:135]
	v_pk_mul_f32 v[66:67], v[224:225], v[132:133]
	s_waitcnt lgkmcnt(0)
	global_store_dwordx4 v[78:79], v[72:75], off offset:2048
	v_pk_mul_f32 v[68:69], v[226:227], v[130:131]
	v_pk_mul_f32 v[70:71], v[228:229], v[128:129]
	v_cvt_pk_bf16_f32 v66, v66, v67
	v_cvt_pk_bf16_f32 v65, v64, v65
	ds_bpermute_b32 v64, v250, v66
	v_cvt_pk_bf16_f32 v67, v70, v71
	v_cvt_pk_bf16_f32 v68, v68, v69
	ds_bpermute_b32 v65, v250, v65
	ds_bpermute_b32 v66, v250, v67
	ds_bpermute_b32 v67, v250, v68
	s_mov_b32 s2, 0x100000
	s_waitcnt lgkmcnt(0)
	global_store_dwordx4 v[78:79], v[64:67], off offset:2304
	s_nop 1
	v_add_co_u32_e32 v66, vcc, s2, v238
	v_lshl_add_u64 v[64:65], v[238:239], 0, s[10:11]
	s_nop 0
	v_addc_co_u32_e32 v67, vcc, 0, v239, vcc
	global_load_dwordx4 v[152:155], v[66:67], off
	global_load_dwordx4 v[156:159], v[64:65], off offset:16
	s_mov_b64 s[10:11], 0x100200
	v_lshl_add_u64 v[64:65], v[238:239], 0, s[10:11]
	global_load_dwordx4 v[160:163], v[66:67], off offset:512
	global_load_dwordx4 v[164:167], v[64:65], off offset:16
	s_mov_b32 s2, 0x120000
	v_add_co_u32_e32 v66, vcc, s2, v238
	s_mov_b64 s[10:11], 0x120000
	s_nop 0
	v_addc_co_u32_e32 v67, vcc, 0, v239, vcc
	v_lshl_add_u64 v[64:65], v[238:239], 0, s[10:11]
	global_load_dwordx4 v[168:171], v[66:67], off
	global_load_dwordx4 v[172:175], v[64:65], off offset:16
	s_mov_b64 s[10:11], 0x120200
	v_lshl_add_u64 v[64:65], v[238:239], 0, s[10:11]
	global_load_dwordx4 v[100:103], v[66:67], off offset:512
	global_load_dwordx4 v[96:99], v[64:65], off offset:16
	s_mov_b32 s2, 0x140000
	v_add_co_u32_e32 v66, vcc, s2, v238
	s_mov_b64 s[10:11], 0x140000
	s_nop 0
	v_addc_co_u32_e32 v67, vcc, 0, v239, vcc
	v_lshl_add_u64 v[64:65], v[238:239], 0, s[10:11]
	global_load_dwordx4 v[92:95], v[66:67], off
	global_load_dwordx4 v[88:91], v[64:65], off offset:16
	s_mov_b64 s[10:11], 0x140200
	v_lshl_add_u64 v[64:65], v[238:239], 0, s[10:11]
	global_load_dwordx4 v[84:87], v[66:67], off offset:512
	global_load_dwordx4 v[80:83], v[64:65], off offset:16
	s_mov_b32 s2, 0x160000
	v_add_co_u32_e32 v66, vcc, s2, v238
	s_mov_b64 s[10:11], 0x160000
	s_nop 0
	v_addc_co_u32_e32 v67, vcc, 0, v239, vcc
	v_lshl_add_u64 v[64:65], v[238:239], 0, s[10:11]
	global_load_dwordx4 v[76:79], v[66:67], off
	global_load_dwordx4 v[72:75], v[64:65], off offset:16
	s_mov_b64 s[10:11], 0x160200
	v_lshl_add_u64 v[64:65], v[238:239], 0, s[10:11]
	global_load_dwordx4 v[68:71], v[66:67], off offset:512
	s_nop 0
	global_load_dwordx4 v[64:67], v[64:65], off offset:16
	s_mov_b32 s2, 0x84000
	s_lshl_b64 s[10:11], s[40:41], 2
	s_add_u32 s30, s87, s10
	s_addc_u32 s31, s88, s11
	s_waitcnt vmcnt(15)
; __device__ __forceinline__ unsigned cvt_pk_bf16(float lo, float hi) { unsigned r; asm volatile("v_cvt_pk_bf16_f32 %0, %1, %2" : "=v"(r) : "v"(lo), "v"(hi)); return r; }
;     __device__ __forceinline__ void operator()(AccT acc, const pg8::Unit& u, int wr, int wc, int fr, int fq) const {
;     ...
;                 for (int m = 0; m < 4; ++m) { const size_t ro = (size_t)(ai * 128 + m * 16) * LDP; float t = 0.f;
; #pragma unroll
;                     for (int bj = 0; bj < 2; ++bj) { const f32x4 h0 = hb[m][bj][0] + gv[bj][0] * acc[ai][bj][m][0], h1 = hb[m][bj][1] + gv[bj][1] * acc[ai][bj][m][1];
;                         const h16x4 q0 = __builtin_convertvector(h0, h16x4), q1 = __builtin_convertvector(h1, h16x4);
;                         { const h16x8 hv8 = (h16x8){q0[0], q0[1], q0[2], q0[3], q1[0], q1[1], q1[2], q1[3]}; *(u32x4*)(hout + ro + bj * 128) = gather4(__builtin_bit_cast(u32x4, hv8), st4); }
;                         t += ((h0[0] * h0[0] + h0[1] * h0[1]) + (h0[2] * h0[2] + h0[3] * h0[3])) + ((h1[0] * h1[0] + h1[1] * h1[1]) + (h1[2] * h1[2] + h1[3] * h1[3]));
;                         if (WZ) { const f32x4 z0 = h0 * gz[bj][0], z1 = h1 * gz[bj][1]; u32x4 w; w.x = cvt_pk_bf16(z0[0], z0[1]); w.y = cvt_pk_bf16(z0[2], z0[3]); w.z = cvt_pk_bf16(z1[0], z1[1]); w.w = cvt_pk_bf16(z1[2], z1[3]);
;                             *(u32x4*)(zout + ro + bj * 128) = gather4(w, st4); } }
	v_pk_fma_f32 v[62:63], v[62:63], v[210:211], v[154:155]
	v_pk_fma_f32 v[60:61], v[60:61], v[212:213], v[152:153]
	s_waitcnt vmcnt(14)
	v_pk_fma_f32 v[58:59], v[58:59], v[214:215], v[158:159]
	v_pk_fma_f32 v[56:57], v[56:57], v[216:217], v[156:157]
	v_cvt_pk_f16_f32 v155, v58, v59
	v_cvt_pk_f16_f32 v153, v62, v63
	v_cvt_pk_f16_f32 v154, v56, v57
	v_cvt_pk_f16_f32 v152, v60, v61
	ds_bpermute_b32 v152, v250, v152
	ds_bpermute_b32 v153, v250, v153
	ds_bpermute_b32 v154, v250, v154
	ds_bpermute_b32 v155, v250, v155
	v_add_co_u32_e32 v156, vcc, s2, v236
	v_pk_mul_f32 v[158:159], v[206:207], v[58:59]
	s_nop 0
	v_addc_co_u32_e32 v157, vcc, 0, v237, vcc
	s_waitcnt lgkmcnt(0)
	global_store_dwordx4 v[156:157], v[152:155], off
	v_pk_mul_f32 v[178:179], v[208:209], v[56:57]
	s_waitcnt vmcnt(14)
	v_pk_fma_f32 v[54:55], v[54:55], v[218:219], v[162:163]
	v_pk_mul_f32 v[152:153], v[202:203], v[62:63]
	v_pk_mul_f32 v[154:155], v[204:205], v[60:61]
	v_pk_fma_f32 v[52:53], v[52:53], v[220:221], v[160:161]
	v_cvt_pk_bf16_f32 v154, v154, v155
	v_cvt_pk_bf16_f32 v153, v152, v153
	v_cvt_pk_bf16_f32 v155, v178, v179
	v_cvt_pk_bf16_f32 v158, v158, v159
	ds_bpermute_b32 v152, v250, v154
	ds_bpermute_b32 v153, v250, v153
	ds_bpermute_b32 v154, v250, v155
	ds_bpermute_b32 v155, v250, v158
	v_add_co_u32_e32 v158, vcc, s2, v234
	s_waitcnt vmcnt(13)
	v_pk_fma_f32 v[50:51], v[50:51], v[230:231], v[166:167]
	v_addc_co_u32_e32 v159, vcc, 0, v235, vcc
	v_pk_fma_f32 v[48:49], v[48:49], v[232:233], v[164:165]
	s_waitcnt lgkmcnt(0)
	global_store_dwordx4 v[158:159], v[152:155], off
	v_pk_mul_f32 v[160:161], v[228:229], v[48:49]
	s_waitcnt vmcnt(13)
	v_pk_fma_f32 v[46:47], v[46:47], v[210:211], v[170:171]
	v_cvt_pk_f16_f32 v155, v50, v51
	v_cvt_pk_f16_f32 v153, v54, v55
	v_cvt_pk_f16_f32 v154, v48, v49
	v_cvt_pk_f16_f32 v152, v52, v53
	ds_bpermute_b32 v152, v250, v152
	ds_bpermute_b32 v153, v250, v153
	ds_bpermute_b32 v154, v250, v154
	ds_bpermute_b32 v155, v250, v155
	v_pk_fma_f32 v[44:45], v[44:45], v[212:213], v[168:169]
	s_waitcnt vmcnt(12)
	v_pk_fma_f32 v[42:43], v[42:43], v[214:215], v[174:175]
	v_pk_fma_f32 v[40:41], v[40:41], v[216:217], v[172:173]
	s_mov_b32 s2, 0x94000
	s_waitcnt lgkmcnt(0)
	global_store_dwordx4 v[156:157], v[152:155], off offset:256
	v_pk_mul_f32 v[156:157], v[226:227], v[50:51]
	s_waitcnt vmcnt(12)
	v_pk_fma_f32 v[38:39], v[38:39], v[218:219], v[102:103]
	v_pk_mul_f32 v[152:153], v[222:223], v[54:55]
	v_pk_mul_f32 v[154:155], v[224:225], v[52:53]
	v_pk_fma_f32 v[36:37], v[36:37], v[220:221], v[100:101]
	v_cvt_pk_bf16_f32 v154, v154, v155
	v_cvt_pk_bf16_f32 v153, v152, v153
	v_cvt_pk_bf16_f32 v155, v160, v161
	v_cvt_pk_bf16_f32 v156, v156, v157
	ds_bpermute_b32 v152, v250, v154
	ds_bpermute_b32 v153, v250, v153
	ds_bpermute_b32 v154, v250, v155
	ds_bpermute_b32 v155, v250, v156
	v_add_co_u32_e32 v156, vcc, s2, v236
	s_waitcnt vmcnt(11)
	v_pk_fma_f32 v[34:35], v[34:35], v[230:231], v[98:99]
	v_addc_co_u32_e32 v157, vcc, 0, v237, vcc
	s_waitcnt lgkmcnt(0)
	global_store_dwordx4 v[158:159], v[152:155], off offset:256
	v_pk_fma_f32 v[32:33], v[32:33], v[232:233], v[96:97]
	v_cvt_pk_f16_f32 v99, v34, v35
	v_cvt_pk_f16_f32 v155, v42, v43
	v_cvt_pk_f16_f32 v153, v46, v47
	v_cvt_pk_f16_f32 v154, v40, v41
	v_cvt_pk_f16_f32 v152, v44, v45
	ds_bpermute_b32 v152, v250, v152
	ds_bpermute_b32 v153, v250, v153
	ds_bpermute_b32 v154, v250, v154
	ds_bpermute_b32 v155, v250, v155
	v_cvt_pk_f16_f32 v97, v38, v39
	v_cvt_pk_f16_f32 v98, v32, v33
	v_cvt_pk_f16_f32 v96, v36, v37
	v_pk_mul_f32 v[158:159], v[206:207], v[42:43]
	s_waitcnt lgkmcnt(0)
	global_store_dwordx4 v[156:157], v[152:155], off offset:2048
	v_pk_mul_f32 v[160:161], v[208:209], v[40:41]
	ds_bpermute_b32 v96, v250, v96
	v_pk_mul_f32 v[152:153], v[202:203], v[46:47]
	v_pk_mul_f32 v[154:155], v[204:205], v[44:45]
	ds_bpermute_b32 v97, v250, v97
	v_cvt_pk_bf16_f32 v154, v154, v155
	v_cvt_pk_bf16_f32 v153, v152, v153
	v_cvt_pk_bf16_f32 v155, v160, v161
	ds_bpermute_b32 v98, v250, v98
	ds_bpermute_b32 v99, v250, v99
	v_cvt_pk_bf16_f32 v158, v158, v159
	ds_bpermute_b32 v152, v250, v154
	ds_bpermute_b32 v153, v250, v153
	ds_bpermute_b32 v154, v250, v155
	ds_bpermute_b32 v155, v250, v158
	v_add_co_u32_e32 v158, vcc, s2, v234
	s_waitcnt vmcnt(12)
	v_pk_fma_f32 v[30:31], v[30:31], v[210:211], v[94:95]
	v_pk_fma_f32 v[28:29], v[28:29], v[212:213], v[92:93]
	s_waitcnt vmcnt(11)
	v_pk_fma_f32 v[26:27], v[26:27], v[214:215], v[90:91]
	v_pk_fma_f32 v[24:25], v[24:25], v[216:217], v[88:89]
	v_addc_co_u32_e32 v159, vcc, 0, v235, vcc
	s_waitcnt lgkmcnt(4)
	global_store_dwordx4 v[156:157], v[96:99], off offset:2304
	v_cvt_pk_f16_f32 v91, v26, v27
	v_cvt_pk_f16_f32 v89, v30, v31
	v_pk_mul_f32 v[96:97], v[222:223], v[38:39]
	v_pk_mul_f32 v[98:99], v[224:225], v[36:37]
	v_cvt_pk_f16_f32 v90, v24, v25
	v_cvt_pk_f16_f32 v88, v28, v29
	s_waitcnt lgkmcnt(0)
	global_store_dwordx4 v[158:159], v[152:155], off offset:2048
	v_pk_mul_f32 v[100:101], v[226:227], v[34:35]
	v_pk_mul_f32 v[102:103], v[228:229], v[32:33]
	v_cvt_pk_bf16_f32 v98, v98, v99
	v_cvt_pk_bf16_f32 v97, v96, v97
	ds_bpermute_b32 v88, v250, v88
	v_cvt_pk_bf16_f32 v99, v102, v103
	ds_bpermute_b32 v89, v250, v89
	ds_bpermute_b32 v90, v250, v90
	ds_bpermute_b32 v91, v250, v91
	v_cvt_pk_bf16_f32 v100, v100, v101
	ds_bpermute_b32 v96, v250, v98
	ds_bpermute_b32 v97, v250, v97
	ds_bpermute_b32 v98, v250, v99
	ds_bpermute_b32 v99, v250, v100
	s_mov_b32 s2, 0xa5000
	v_add_co_u32_e32 v92, vcc, s2, v236
	s_waitcnt vmcnt(12)
	v_pk_fma_f32 v[22:23], v[22:23], v[218:219], v[86:87]
	v_addc_co_u32_e32 v93, vcc, 0, v237, vcc
	v_pk_fma_f32 v[20:21], v[20:21], v[220:221], v[84:85]
	s_waitcnt vmcnt(11)
; __device__ __forceinline__ unsigned cvt_pk_bf16(float lo, float hi) { unsigned r; asm volatile("v_cvt_pk_bf16_f32 %0, %1, %2" : "=v"(r) : "v"(lo), "v"(hi)); return r; }
; __device__ __forceinline__ float xlane(float v, int src_lane) { return __uint_as_float(__builtin_amdgcn_ds_bpermute(src_lane << 2, __float_as_uint(v))); }
;     __device__ __forceinline__ void operator()(AccT acc, const pg8::Unit& u, int wr, int wc, int fr, int fq) const {
;     ...
;                 for (int m = 0; m < 4; ++m) { const size_t ro = (size_t)(ai * 128 + m * 16) * LDP; float t = 0.f;
; #pragma unroll
;                     for (int bj = 0; bj < 2; ++bj) { const f32x4 h0 = hb[m][bj][0] + gv[bj][0] * acc[ai][bj][m][0], h1 = hb[m][bj][1] + gv[bj][1] * acc[ai][bj][m][1];
;                         const h16x4 q0 = __builtin_convertvector(h0, h16x4), q1 = __builtin_convertvector(h1, h16x4);
;                         { const h16x8 hv8 = (h16x8){q0[0], q0[1], q0[2], q0[3], q1[0], q1[1], q1[2], q1[3]}; *(u32x4*)(hout + ro + bj * 128) = gather4(__builtin_bit_cast(u32x4, hv8), st4); }
;                         t += ((h0[0] * h0[0] + h0[1] * h0[1]) + (h0[2] * h0[2] + h0[3] * h0[3])) + ((h1[0] * h1[0] + h1[1] * h1[1]) + (h1[2] * h1[2] + h1[3] * h1[3]));
;                         if (WZ) { const f32x4 z0 = h0 * gz[bj][0], z1 = h1 * gz[bj][1]; u32x4 w; w.x = cvt_pk_bf16(z0[0], z0[1]); w.y = cvt_pk_bf16(z0[2], z0[3]); w.z = cvt_pk_bf16(z1[0], z1[1]); w.w = cvt_pk_bf16(z1[2], z1[3]);
;                             *(u32x4*)(zout + ro + bj * 128) = gather4(w, st4); } }
;     ...
;         for (int g = 0; g < 8; ++g) { float t = ss[g]; t += xlane(t, lane ^ 16); t += xlane(t, lane ^ 32);
;             if (fq == 0) SSQ[(size_t)(row0 + (g >> 2) * 128 + (g & 3) * 16) * 32 + u.pn * 4 + wc] = t; }
	v_pk_fma_f32 v[18:19], v[18:19], v[230:231], v[82:83]
	v_pk_fma_f32 v[16:17], v[16:17], v[232:233], v[80:81]
	s_waitcnt lgkmcnt(4)
	global_store_dwordx4 v[92:93], v[88:91], off
	v_cvt_pk_f16_f32 v83, v18, v19
	v_cvt_pk_f16_f32 v81, v22, v23
	v_pk_mul_f32 v[88:89], v[202:203], v[30:31]
	v_pk_mul_f32 v[90:91], v[204:205], v[28:29]
	v_cvt_pk_f16_f32 v82, v16, v17
	v_cvt_pk_f16_f32 v80, v20, v21
	s_waitcnt lgkmcnt(0)
	global_store_dwordx4 v[158:159], v[96:99], off offset:2304
	v_pk_mul_f32 v[94:95], v[206:207], v[26:27]
	v_cvt_pk_bf16_f32 v90, v90, v91
	v_cvt_pk_bf16_f32 v89, v88, v89
	ds_bpermute_b32 v80, v250, v80
	v_pk_mul_f32 v[96:97], v[208:209], v[24:25]
	ds_bpermute_b32 v81, v250, v81
	v_cvt_pk_bf16_f32 v91, v96, v97
	ds_bpermute_b32 v82, v250, v82
	ds_bpermute_b32 v83, v250, v83
	v_cvt_pk_bf16_f32 v94, v94, v95
	ds_bpermute_b32 v88, v250, v90
	ds_bpermute_b32 v89, v250, v89
	ds_bpermute_b32 v90, v250, v91
	ds_bpermute_b32 v91, v250, v94
	v_add_co_u32_e32 v94, vcc, s2, v234
	s_waitcnt vmcnt(12)
	v_pk_fma_f32 v[14:15], v[14:15], v[210:211], v[78:79]
	v_pk_fma_f32 v[12:13], v[12:13], v[212:213], v[76:77]
	s_waitcnt vmcnt(11)
	v_pk_fma_f32 v[10:11], v[10:11], v[214:215], v[74:75]
	v_pk_fma_f32 v[8:9], v[8:9], v[216:217], v[72:73]
	v_addc_co_u32_e32 v95, vcc, 0, v235, vcc
	s_waitcnt lgkmcnt(4)
	global_store_dwordx4 v[92:93], v[80:83], off offset:256
	v_cvt_pk_f16_f32 v75, v10, v11
	v_cvt_pk_f16_f32 v73, v14, v15
	v_pk_mul_f32 v[80:81], v[222:223], v[22:23]
	v_pk_mul_f32 v[82:83], v[224:225], v[20:21]
	v_cvt_pk_f16_f32 v74, v8, v9
	v_cvt_pk_f16_f32 v72, v12, v13
	s_waitcnt lgkmcnt(0)
	global_store_dwordx4 v[94:95], v[88:91], off
	v_pk_mul_f32 v[84:85], v[226:227], v[18:19]
	v_pk_mul_f32 v[86:87], v[228:229], v[16:17]
	v_cvt_pk_bf16_f32 v82, v82, v83
	v_cvt_pk_bf16_f32 v81, v80, v81
	ds_bpermute_b32 v72, v250, v72
	v_cvt_pk_bf16_f32 v83, v86, v87
	ds_bpermute_b32 v73, v250, v73
	ds_bpermute_b32 v74, v250, v74
	ds_bpermute_b32 v75, v250, v75
	v_cvt_pk_bf16_f32 v84, v84, v85
	ds_bpermute_b32 v80, v250, v82
	ds_bpermute_b32 v81, v250, v81
	ds_bpermute_b32 v82, v250, v83
	ds_bpermute_b32 v83, v250, v84
	s_mov_b32 s2, 0xb5000
	v_add_co_u32_e32 v76, vcc, s2, v236
	s_waitcnt vmcnt(12)
	v_pk_fma_f32 v[6:7], v[6:7], v[218:219], v[70:71]
	v_addc_co_u32_e32 v77, vcc, 0, v237, vcc
	v_pk_fma_f32 v[4:5], v[4:5], v[220:221], v[68:69]
	s_waitcnt vmcnt(11)
	v_pk_fma_f32 v[2:3], v[2:3], v[230:231], v[66:67]
	v_pk_fma_f32 v[0:1], v[0:1], v[232:233], v[64:65]
	s_waitcnt lgkmcnt(4)
	global_store_dwordx4 v[76:77], v[72:75], off offset:2048
	v_cvt_pk_f16_f32 v67, v2, v3
	v_cvt_pk_f16_f32 v65, v6, v7
	v_pk_mul_f32 v[72:73], v[202:203], v[14:15]
	v_pk_mul_f32 v[74:75], v[204:205], v[12:13]
	v_cvt_pk_f16_f32 v66, v0, v1
	v_cvt_pk_f16_f32 v64, v4, v5
	s_waitcnt lgkmcnt(0)
	global_store_dwordx4 v[94:95], v[80:83], off offset:256
	v_pk_mul_f32 v[78:79], v[206:207], v[10:11]
	v_cvt_pk_bf16_f32 v74, v74, v75
	v_cvt_pk_bf16_f32 v73, v72, v73
	ds_bpermute_b32 v64, v250, v64
	v_pk_mul_f32 v[80:81], v[208:209], v[8:9]
	ds_bpermute_b32 v65, v250, v65
	v_cvt_pk_bf16_f32 v75, v80, v81
	ds_bpermute_b32 v66, v250, v66
	ds_bpermute_b32 v67, v250, v67
	v_cvt_pk_bf16_f32 v78, v78, v79
	ds_bpermute_b32 v72, v250, v74
	ds_bpermute_b32 v73, v250, v73
	ds_bpermute_b32 v74, v250, v75
	ds_bpermute_b32 v75, v250, v78
	v_add_co_u32_e32 v78, vcc, s2, v234
	s_waitcnt lgkmcnt(4)
	global_store_dwordx4 v[76:77], v[64:67], off offset:2304
	v_addc_co_u32_e32 v79, vcc, 0, v235, vcc
	s_nop 0
	v_pk_mul_f32 v[64:65], v[222:223], v[6:7]
	v_pk_mul_f32 v[66:67], v[224:225], v[4:5]
	s_waitcnt lgkmcnt(0)
	global_store_dwordx4 v[78:79], v[72:75], off offset:2048
	v_pk_mul_f32 v[68:69], v[226:227], v[2:3]
	v_pk_mul_f32 v[70:71], v[228:229], v[0:1]
	v_cvt_pk_bf16_f32 v66, v66, v67
	v_cvt_pk_bf16_f32 v65, v64, v65
	ds_bpermute_b32 v64, v250, v66
	v_cvt_pk_bf16_f32 v67, v70, v71
	v_cvt_pk_bf16_f32 v68, v68, v69
	ds_bpermute_b32 v65, v250, v65
	ds_bpermute_b32 v66, v250, v67
	ds_bpermute_b32 v67, v250, v68
	s_waitcnt lgkmcnt(0)
	global_store_dwordx4 v[78:79], v[64:67], off offset:2304
	s_waitcnt lgkmcnt(0)
	s_nop 1
	v_mov_b32_e32 v66, v176
	v_mov_b32_e32 v67, v176
	s_nop 1
	v_permlane16_swap_b32_e32 v66, v67
	v_add_f32_e32 v66, v66, v67
	v_mov_b32_e32 v67, v66
	s_nop 1
	v_permlane32_swap_b32_e32 v66, v67
	v_lshlrev_b64 v[64:65], 7, v[200:201]
	v_lshl_add_u64 v[64:65], s[30:31], 0, v[64:65]
	s_and_saveexec_b64 s[34:35], s[4:5]
	s_cbranch_execz .LBB0_405
	s_waitcnt lgkmcnt(0)
	v_add_f32_e32 v66, v66, v67
	global_store_dword v[64:65], v66, off
.LBB0_405:
	s_or_b64 exec, exec, s[34:35]
	v_mul_f32_e32 v66, v109, v109
	s_waitcnt lgkmcnt(0)
	v_mul_f32_e32 v67, v111, v111
	v_fmac_f32_e32 v66, v108, v108
	v_fmac_f32_e32 v67, v110, v110
	v_add_f32_e32 v66, v66, v67
	v_mul_f32_e32 v67, v105, v105
	v_mul_f32_e32 v68, v107, v107
	v_fmac_f32_e32 v67, v104, v104
	v_fmac_f32_e32 v68, v106, v106
	v_add_f32_e32 v67, v67, v68
	v_add_f32_e32 v66, v66, v67
	v_mul_f32_e32 v67, v119, v119
	v_mul_f32_e32 v68, v115, v115
	v_fmac_f32_e32 v67, v118, v118
	v_fmac_f32_e32 v68, v114, v114
	v_add_f32_e32 v67, v67, v68
	v_mul_f32_e32 v68, v117, v117
	v_mul_f32_e32 v69, v113, v113
	v_fmac_f32_e32 v68, v116, v116
	v_fmac_f32_e32 v69, v112, v112
	v_add_f32_e32 v68, v68, v69
	v_add_f32_e32 v67, v67, v68
	v_add_f32_e32 v66, v66, v67
	s_waitcnt lgkmcnt(0)
	v_mov_b32_e32 v67, v66
	s_nop 1
	v_permlane16_swap_b32_e32 v67, v66
	v_add_f32_e32 v66, v66, v67
	v_mov_b32_e32 v67, v66
	s_nop 1
	v_permlane32_swap_b32_e32 v66, v67
	s_and_saveexec_b64 s[34:35], s[4:5]
	s_cbranch_execz .LBB0_407
	v_or_b32_e32 v68, 16, v200
	v_ashrrev_i32_e32 v69, 31, v68
	v_lshlrev_b64 v[68:69], 7, v[68:69]
	v_lshl_add_u64 v[68:69], s[30:31], 0, v[68:69]
	s_waitcnt lgkmcnt(0)
	v_add_f32_e32 v66, v66, v67
	global_store_dword v[68:69], v66, off
; __device__ __forceinline__ float xlane(float v, int src_lane) { return __uint_as_float(__builtin_amdgcn_ds_bpermute(src_lane << 2, __float_as_uint(v))); }
;     __device__ __forceinline__ void operator()(AccT acc, const pg8::Unit& u, int wr, int wc, int fr, int fq) const {
;     ...
;                         t += ((h0[0] * h0[0] + h0[1] * h0[1]) + (h0[2] * h0[2] + h0[3] * h0[3])) + ((h1[0] * h1[0] + h1[1] * h1[1]) + (h1[2] * h1[2] + h1[3] * h1[3]));
;     ...
;         for (int g = 0; g < 8; ++g) { float t = ss[g]; t += xlane(t, lane ^ 16); t += xlane(t, lane ^ 32);
;             if (fq == 0) SSQ[(size_t)(row0 + (g >> 2) * 128 + (g & 3) * 16) * 32 + u.pn * 4 + wc] = t; }
.LBB0_407:
	s_or_b64 exec, exec, s[34:35]
	v_mul_f32_e32 v66, v127, v127
	s_waitcnt lgkmcnt(0)
	v_mul_f32_e32 v67, v123, v123
	v_fmac_f32_e32 v66, v126, v126
	v_fmac_f32_e32 v67, v122, v122
	v_add_f32_e32 v66, v66, v67
	v_mul_f32_e32 v67, v125, v125
	v_mul_f32_e32 v68, v121, v121
	v_fmac_f32_e32 v67, v124, v124
	v_fmac_f32_e32 v68, v120, v120
	v_add_f32_e32 v67, v67, v68
	v_add_f32_e32 v66, v66, v67
	v_mul_f32_e32 v67, v141, v141
	v_mul_f32_e32 v68, v143, v143
	v_fmac_f32_e32 v67, v140, v140
	v_fmac_f32_e32 v68, v142, v142
	v_add_f32_e32 v67, v67, v68
	v_mul_f32_e32 v68, v137, v137
	v_mul_f32_e32 v69, v139, v139
	v_fmac_f32_e32 v68, v136, v136
	v_fmac_f32_e32 v69, v138, v138
	v_add_f32_e32 v68, v68, v69
	v_add_f32_e32 v67, v67, v68
	v_add_f32_e32 v66, v66, v67
	s_waitcnt lgkmcnt(0)
	v_mov_b32_e32 v67, v66
	s_nop 1
	v_permlane16_swap_b32_e32 v67, v66
	v_add_f32_e32 v66, v66, v67
	v_mov_b32_e32 v67, v66
	s_nop 1
	v_permlane32_swap_b32_e32 v66, v67
	s_and_saveexec_b64 s[34:35], s[4:5]
	s_cbranch_execz .LBB0_409
	v_or_b32_e32 v68, 32, v200
	v_ashrrev_i32_e32 v69, 31, v68
	v_lshlrev_b64 v[68:69], 7, v[68:69]
	v_lshl_add_u64 v[68:69], s[30:31], 0, v[68:69]
	s_waitcnt lgkmcnt(0)
	v_add_f32_e32 v66, v66, v67
	global_store_dword v[68:69], v66, off
.LBB0_409:
	s_or_b64 exec, exec, s[34:35]
	v_mul_f32_e32 v66, v151, v151
	s_waitcnt lgkmcnt(0)
	v_mul_f32_e32 v67, v147, v147
	v_fmac_f32_e32 v66, v150, v150
	v_fmac_f32_e32 v67, v146, v146
	v_add_f32_e32 v66, v66, v67
	v_mul_f32_e32 v67, v149, v149
	v_mul_f32_e32 v68, v145, v145
	v_fmac_f32_e32 v67, v148, v148
	v_fmac_f32_e32 v68, v144, v144
	v_add_f32_e32 v67, v67, v68
	v_add_f32_e32 v66, v66, v67
	v_mul_f32_e32 v67, v133, v133
	v_mul_f32_e32 v68, v135, v135
	v_fmac_f32_e32 v67, v132, v132
	v_fmac_f32_e32 v68, v134, v134
	v_add_f32_e32 v67, v67, v68
	v_mul_f32_e32 v68, v129, v129
	v_mul_f32_e32 v69, v131, v131
	v_fmac_f32_e32 v68, v128, v128
	v_fmac_f32_e32 v69, v130, v130
	v_add_f32_e32 v68, v68, v69
	v_add_f32_e32 v67, v67, v68
	v_add_f32_e32 v66, v66, v67
	s_waitcnt lgkmcnt(0)
	v_mov_b32_e32 v67, v66
	s_nop 1
	v_permlane16_swap_b32_e32 v67, v66
	v_add_f32_e32 v66, v66, v67
	v_mov_b32_e32 v67, v66
	s_nop 1
	v_permlane32_swap_b32_e32 v66, v67
	s_and_saveexec_b64 s[34:35], s[4:5]
	s_cbranch_execz .LBB0_411
	v_or_b32_e32 v68, 48, v200
	v_ashrrev_i32_e32 v69, 31, v68
	v_lshlrev_b64 v[68:69], 7, v[68:69]
	v_lshl_add_u64 v[68:69], s[30:31], 0, v[68:69]
	s_waitcnt lgkmcnt(0)
	v_add_f32_e32 v66, v66, v67
	global_store_dword v[68:69], v66, off
.LBB0_411:
	s_or_b64 exec, exec, s[34:35]
	v_mul_f32_e32 v61, v61, v61
	v_mul_f32_e32 v57, v57, v57
	v_mul_f32_e32 v53, v53, v53
	v_mul_f32_e32 v49, v49, v49
	v_fmac_f32_e32 v61, v60, v60
	v_mul_f32_e32 v60, v63, v63
	v_fmac_f32_e32 v57, v56, v56
	v_mul_f32_e32 v56, v59, v59
	v_fmac_f32_e32 v53, v52, v52
	v_mul_f32_e32 v52, v55, v55
	v_fmac_f32_e32 v49, v48, v48
	v_mul_f32_e32 v48, v51, v51
	v_fmac_f32_e32 v60, v62, v62
	v_fmac_f32_e32 v56, v58, v58
	v_fmac_f32_e32 v52, v54, v54
	v_fmac_f32_e32 v48, v50, v50
	v_add_f32_e32 v60, v61, v60
	v_add_f32_e32 v56, v57, v56
	v_add_f32_e32 v52, v53, v52
	v_add_f32_e32 v48, v49, v48
	v_add_f32_e32 v56, v60, v56
	v_add_f32_e32 v48, v52, v48
	v_add_f32_e32 v48, v56, v48
	s_waitcnt lgkmcnt(0)
	v_mov_b32_e32 v49, v48
	s_nop 1
	v_permlane16_swap_b32_e32 v49, v48
	v_add_f32_e32 v48, v48, v49
	v_mov_b32_e32 v49, v48
	s_nop 1
	v_permlane32_swap_b32_e32 v48, v49
	s_and_saveexec_b64 s[30:31], s[4:5]
	s_cbranch_execz .LBB0_413
	s_waitcnt lgkmcnt(0)
	v_add_f32_e32 v50, v48, v49
	v_add_co_u32_e32 v48, vcc, 0x4000, v64
	s_nop 1
	v_addc_co_u32_e32 v49, vcc, 0, v65, vcc
	global_store_dword v[48:49], v50, off
; __device__ __forceinline__ float xlane(float v, int src_lane) { return __uint_as_float(__builtin_amdgcn_ds_bpermute(src_lane << 2, __float_as_uint(v))); }
;     __device__ __forceinline__ void operator()(AccT acc, const pg8::Unit& u, int wr, int wc, int fr, int fq) const {
;     ...
;                         t += ((h0[0] * h0[0] + h0[1] * h0[1]) + (h0[2] * h0[2] + h0[3] * h0[3])) + ((h1[0] * h1[0] + h1[1] * h1[1]) + (h1[2] * h1[2] + h1[3] * h1[3]));
;     ...
;         for (int g = 0; g < 8; ++g) { float t = ss[g]; t += xlane(t, lane ^ 16); t += xlane(t, lane ^ 32);
;             if (fq == 0) SSQ[(size_t)(row0 + (g >> 2) * 128 + (g & 3) * 16) * 32 + u.pn * 4 + wc] = t; }
.LBB0_413:
	s_or_b64 exec, exec, s[30:31]
	v_mul_f32_e32 v45, v45, v45
	v_mul_f32_e32 v41, v41, v41
	v_mul_f32_e32 v37, v37, v37
	v_mul_f32_e32 v33, v33, v33
	v_fmac_f32_e32 v45, v44, v44
	v_mul_f32_e32 v44, v47, v47
	v_fmac_f32_e32 v41, v40, v40
	v_mul_f32_e32 v40, v43, v43
	v_fmac_f32_e32 v37, v36, v36
	v_mul_f32_e32 v36, v39, v39
	v_fmac_f32_e32 v33, v32, v32
	v_mul_f32_e32 v32, v35, v35
	v_fmac_f32_e32 v44, v46, v46
	v_fmac_f32_e32 v40, v42, v42
	v_fmac_f32_e32 v36, v38, v38
	v_fmac_f32_e32 v32, v34, v34
	v_add_f32_e32 v44, v45, v44
	v_add_f32_e32 v40, v41, v40
	v_add_f32_e32 v36, v37, v36
	v_add_f32_e32 v32, v33, v32
	v_add_f32_e32 v40, v44, v40
	v_add_f32_e32 v32, v36, v32
	v_add_f32_e32 v32, v40, v32
	s_waitcnt lgkmcnt(0)
	v_mov_b32_e32 v33, v32
	s_nop 1
	v_permlane16_swap_b32_e32 v33, v32
	v_add_f32_e32 v32, v32, v33
	v_mov_b32_e32 v33, v32
	s_nop 1
	v_permlane32_swap_b32_e32 v32, v33
	s_and_saveexec_b64 s[30:31], s[4:5]
	s_cbranch_execz .LBB0_415
	s_waitcnt lgkmcnt(0)
	v_add_f32_e32 v34, v32, v33
	v_add_co_u32_e32 v32, vcc, 0x4000, v64
	s_nop 1
	v_addc_co_u32_e32 v33, vcc, 0, v65, vcc
	global_store_dword v[32:33], v34, off offset:2048
.LBB0_415:
	s_or_b64 exec, exec, s[30:31]
	v_mul_f32_e32 v29, v29, v29
	v_mul_f32_e32 v25, v25, v25
	v_mul_f32_e32 v21, v21, v21
	v_mul_f32_e32 v17, v17, v17
	v_fmac_f32_e32 v29, v28, v28
	v_mul_f32_e32 v28, v31, v31
	v_fmac_f32_e32 v25, v24, v24
	v_mul_f32_e32 v24, v27, v27
	v_fmac_f32_e32 v21, v20, v20
	v_mul_f32_e32 v20, v23, v23
	v_fmac_f32_e32 v17, v16, v16
	v_mul_f32_e32 v16, v19, v19
	v_fmac_f32_e32 v28, v30, v30
	v_fmac_f32_e32 v24, v26, v26
	v_fmac_f32_e32 v20, v22, v22
	v_fmac_f32_e32 v16, v18, v18
	v_add_f32_e32 v28, v29, v28
	v_add_f32_e32 v24, v25, v24
	v_add_f32_e32 v20, v21, v20
	v_add_f32_e32 v16, v17, v16
	v_add_f32_e32 v24, v28, v24
	v_add_f32_e32 v16, v20, v16
	v_add_f32_e32 v16, v24, v16
	s_waitcnt lgkmcnt(0)
	v_mov_b32_e32 v17, v16
	s_nop 1
	v_permlane16_swap_b32_e32 v17, v16
	v_add_f32_e32 v16, v16, v17
	v_mov_b32_e32 v17, v16
	s_nop 1
	v_permlane32_swap_b32_e32 v16, v17
	s_and_saveexec_b64 s[30:31], s[4:5]
	s_cbranch_execz .LBB0_417
	s_waitcnt lgkmcnt(0)
	v_add_f32_e32 v18, v16, v17
	v_add_co_u32_e32 v16, vcc, 0x5000, v64
	s_nop 1
	v_addc_co_u32_e32 v17, vcc, 0, v65, vcc
	global_store_dword v[16:17], v18, off
.LBB0_417:
	s_or_b64 exec, exec, s[30:31]
	v_mul_f32_e32 v13, v13, v13
	v_mul_f32_e32 v9, v9, v9
	v_mul_f32_e32 v5, v5, v5
	v_mul_f32_e32 v1, v1, v1
	v_fmac_f32_e32 v13, v12, v12
	v_mul_f32_e32 v12, v15, v15
	v_fmac_f32_e32 v9, v8, v8
	v_mul_f32_e32 v8, v11, v11
	v_fmac_f32_e32 v5, v4, v4
	v_mul_f32_e32 v4, v7, v7
	v_fmac_f32_e32 v1, v0, v0
	v_mul_f32_e32 v0, v3, v3
	v_fmac_f32_e32 v12, v14, v14
	v_fmac_f32_e32 v8, v10, v10
	v_fmac_f32_e32 v4, v6, v6
	v_fmac_f32_e32 v0, v2, v2
	v_add_f32_e32 v12, v13, v12
	v_add_f32_e32 v8, v9, v8
	v_add_f32_e32 v4, v5, v4
	v_add_f32_e32 v0, v1, v0
	v_add_f32_e32 v8, v12, v8
	v_add_f32_e32 v0, v4, v0
	v_add_f32_e32 v0, v8, v0
	s_waitcnt lgkmcnt(0)
	v_mov_b32_e32 v1, v0
	s_nop 1
	v_permlane16_swap_b32_e32 v1, v0
	v_add_f32_e32 v0, v0, v1
	v_mov_b32_e32 v1, v0
	s_nop 1
	v_permlane32_swap_b32_e32 v0, v1
	s_and_saveexec_b64 s[30:31], s[4:5]
	s_cbranch_execz .LBB0_419
	s_waitcnt lgkmcnt(0)
	v_add_f32_e32 v2, v0, v1
	v_add_co_u32_e32 v0, vcc, 0x5000, v64
	s_nop 1
	v_addc_co_u32_e32 v1, vcc, 0, v65, vcc
	global_store_dword v[0:1], v2, off offset:2048

;     __device__ __forceinline__ void operator()(AccT acc, const pg8::Unit& u, int wr, int wc, int fr, int fq) const {
;         const int row0 = u.pm * 256 + wr * 64 + fr, col0 = u.pn * 256 + wc * 32 + 8 * fq, lane = fq * 16 + fr;
;         const int bidx = u.pm < 64 ? (u.pm >> 4) : 4;
;         const float* gp = gate + (size_t)bidx * MODW + col0;
;         f32x4 gv[2][2], gz[2][2];
; #pragma unroll
;         for (int bj = 0; bj < 2; ++bj)
; #pragma unroll
;             for (int n = 0; n < 2; ++n) { gv[bj][n] = *(const f32x4*)(gp + bj * 128 + n * 4) * coef;
;                 if (WZ) gz[bj][n] = *(const f32x4*)(gnext + col0 + bj * 128 + n * 4) * (*(const f32x4*)(scnext + (size_t)bidx * MODW + col0 + bj * 128 + n * 4) + 1.f); }
;         const int st4 = ((lane & 3) * 16 + (lane >> 2)) * 4, ld4 = ((lane & 15) * 4 + (lane >> 4)) * 4;
;         const size_t eo = (size_t)(u.pm * 256 + wr * 64 + (lane >> 2)) * LDP + u.pn * 256 + wc * 32 + (lane & 3) * 8;
;         hf_t* hout = H + eo; bf16_t* zout = Z + eo; float ss[8];
;         if constexpr (B32) {
;             const float* base = (const float*)(u.pm < 64 ? baseL : baseC) + (size_t)row0 * D + col0;
;             f32x4 hb[4][2][2];
; #pragma unroll
;             for (int ai = 0; ai < 2; ++ai) {
; #pragma unroll
;                 for (int m = 0; m < 4; ++m)
; #pragma unroll
;                     for (int bj = 0; bj < 2; ++bj)
; #pragma unroll
;                         for (int n = 0; n < 2; ++n) hb[m][bj][n] = *(const f32x4*)(base + (size_t)(ai * 128 + m * 16) * D + bj * 128 + n * 4);
;                 asm volatile("" ::: "memory");
; #pragma unroll
;                 for (int m = 0; m < 4; ++m) { const size_t ro = (size_t)(ai * 128 + m * 16) * LDP; float t = 0.f;
; #pragma unroll
;                     for (int bj = 0; bj < 2; ++bj) { const f32x4 h0 = hb[m][bj][0] + gv[bj][0] * acc[ai][bj][m][0], h1 = hb[m][bj][1] + gv[bj][1] * acc[ai][bj][m][1];
;                         const h16x4 q0 = __builtin_convertvector(h0, h16x4), q1 = __builtin_convertvector(h1, h16x4);
;                         { const h16x8 hv8 = (h16x8){q0[0], q0[1], q0[2], q0[3], q1[0], q1[1], q1[2], q1[3]}; *(u32x4*)(hout + ro + bj * 128) = gather4(__builtin_bit_cast(u32x4, hv8), st4); }
.LBB0_1038:
	s_lshr_b32 s12, s77, 4
	s_lshl_b32 s11, s77, 8
	s_mul_i32 s40, s12, 0x4800
	s_add_i32 s11, s11, s83
	s_lshl_b32 s25, s65, 8
	s_lshl_b64 s[12:13], s[40:41], 2
	s_add_u32 s30, s55, s12
	v_or_b32_e32 v192, s25, v213
	s_addc_u32 s31, s57, s13
	v_lshlrev_b64 v[108:109], 2, v[192:193]
	s_add_u32 s12, s60, s12
	v_lshl_add_u64 v[152:153], s[30:31], 0, v[108:109]
	s_addc_u32 s13, s72, s13
	v_lshl_add_u64 v[154:155], s[18:19], 0, v[108:109]
	v_lshl_add_u64 v[156:157], s[12:13], 0, v[108:109]
	global_load_dwordx4 v[120:123], v[152:153], off offset:16
	global_load_dwordx4 v[124:127], v[152:153], off
	global_load_dwordx4 v[108:111], v[154:155], off offset:16
	global_load_dwordx4 v[116:119], v[154:155], off
	global_load_dwordx4 v[144:147], v[156:157], off offset:16
	global_load_dwordx4 v[148:151], v[156:157], off
	v_or_b32_e32 v176, s11, v212
	v_or_b32_e32 v192, s25, v217
	s_mov_b32 s25, 0xb5000
	s_lshl_b32 s40, s65, 2
	s_waitcnt vmcnt(0)
	v_pk_add_f32 v[150:151], v[150:151], 1.0 op_sel_hi:[1,0]
	v_pk_add_f32 v[148:149], v[148:149], 1.0 op_sel_hi:[1,0]
	v_pk_mul_f32 v[186:187], v[118:119], v[150:151]
	v_pk_mul_f32 v[188:189], v[116:117], v[148:149]
	v_pk_add_f32 v[116:117], v[146:147], 1.0 op_sel_hi:[1,0]
	v_pk_add_f32 v[118:119], v[144:145], 1.0 op_sel_hi:[1,0]
	v_pk_mul_f32 v[190:191], v[110:111], v[116:117]
	v_pk_mul_f32 v[196:197], v[108:109], v[118:119]
	global_load_dwordx4 v[108:111], v[152:153], off offset:528
	global_load_dwordx4 v[116:119], v[152:153], off offset:512
	global_load_dwordx4 v[144:147], v[154:155], off offset:528
	global_load_dwordx4 v[148:151], v[154:155], off offset:512
	s_nop 0
	global_load_dwordx4 v[152:155], v[156:157], off offset:528
	s_nop 0
	global_load_dwordx4 v[156:159], v[156:157], off offset:512
	s_waitcnt vmcnt(0)
	v_pk_add_f32 v[158:159], v[158:159], 1.0 op_sel_hi:[1,0]
	s_nop 0
	v_pk_mul_f32 v[178:179], v[150:151], v[158:159]
	v_pk_add_f32 v[150:151], v[152:153], 1.0 op_sel_hi:[1,0]
	v_pk_add_f32 v[156:157], v[156:157], 1.0 op_sel_hi:[1,0]
	v_pk_mul_f32 v[184:185], v[144:145], v[150:151]
	v_or_b32_e32 v144, s11, v215
	s_movk_i32 s11, 0x840
	v_mad_i64_i32 v[144:145], s[12:13], v144, s11, v[192:193]
	v_lshlrev_b64 v[144:145], 1, v[144:145]
	v_lshl_add_u64 v[200:201], s[14:15], 0, v[144:145]
	global_load_dwordx4 v[222:225], v[200:201], off
	global_load_dwordx4 v[168:171], v[200:201], off offset:256
	s_mov_b32 s11, 0x10000
	v_add_co_u32_e32 v206, vcc, s11, v200
	s_mov_b32 s12, 0x21000
	s_nop 0
	v_addc_co_u32_e32 v207, vcc, 0, v201, vcc
	global_load_dwordx4 v[164:167], v[206:207], off offset:2048
	global_load_dwordx4 v[160:163], v[206:207], off offset:2304
	v_add_co_u32_e32 v204, vcc, s12, v200
	s_mov_b32 s13, 0x31000
	s_nop 0
	v_addc_co_u32_e32 v205, vcc, 0, v201, vcc
	v_add_co_u32_e32 v202, vcc, s13, v200
	v_pk_mul_f32 v[180:181], v[148:149], v[156:157]
	v_pk_add_f32 v[148:149], v[154:155], 1.0 op_sel_hi:[1,0]
	v_addc_co_u32_e32 v203, vcc, 0, v201, vcc
	v_pk_mul_f32 v[182:183], v[146:147], v[148:149]
	v_lshl_add_u64 v[198:199], s[16:17], 0, v[144:145]
	global_load_dwordx4 v[156:159], v[204:205], off
	global_load_dwordx4 v[152:155], v[204:205], off offset:256
	global_load_dwordx4 v[148:151], v[202:203], off offset:2048
	global_load_dwordx4 v[144:147], v[202:203], off offset:2304
	s_waitcnt vmcnt(7)
	ds_bpermute_b32 v175, v216, v222
	ds_bpermute_b32 v177, v216, v223
	ds_bpermute_b32 v192, v216, v224
	ds_bpermute_b32 v224, v216, v225
	s_waitcnt lgkmcnt(3)
	v_cvt_f32_f16_e32 v194, v175
	v_cvt_f32_f16_sdwa v195, v175 dst_sel:DWORD dst_unused:UNUSED_PAD src0_sel:WORD_1
	s_waitcnt lgkmcnt(2)
	v_cvt_f32_f16_e32 v222, v177
	v_cvt_f32_f16_sdwa v223, v177 dst_sel:DWORD dst_unused:UNUSED_PAD src0_sel:WORD_1
	v_ashrrev_i32_e32 v177, 31, v176
	v_pk_fma_f32 v[140:141], v[140:141], v[124:125], v[194:195]
	s_waitcnt lgkmcnt(1)
	v_cvt_f32_f16_e32 v194, v192
	v_pk_fma_f32 v[142:143], v[142:143], v[126:127], v[222:223]
	v_cvt_f32_f16_sdwa v195, v192 dst_sel:DWORD dst_unused:UNUSED_PAD src0_sel:WORD_1
	s_waitcnt lgkmcnt(0)
	v_cvt_f32_f16_e32 v222, v224
	v_cvt_f32_f16_sdwa v223, v224 dst_sel:DWORD dst_unused:UNUSED_PAD src0_sel:WORD_1
	v_pk_fma_f32 v[194:195], v[136:137], v[120:121], v[194:195]
	v_cvt_pk_f16_f32 v137, v142, v143
	v_pk_fma_f32 v[222:223], v[138:139], v[122:123], v[222:223]
	v_cvt_pk_f16_f32 v138, v194, v195
	v_cvt_pk_f16_f32 v139, v222, v223
	v_cvt_pk_f16_f32 v136, v140, v141
	ds_bpermute_b32 v136, v214, v136
	ds_bpermute_b32 v137, v214, v137
	ds_bpermute_b32 v138, v214, v138
	ds_bpermute_b32 v139, v214, v139
	s_waitcnt lgkmcnt(0)
	global_store_dwordx4 v[200:201], v[136:139], off
	s_nop 1
	v_mul_f32_e32 v136, v141, v141
	v_mul_f32_e32 v137, v143, v143
	v_fmac_f32_e32 v136, v140, v140
	v_fmac_f32_e32 v137, v142, v142
	v_add_f32_e32 v136, v136, v137
	v_mul_f32_e32 v137, v195, v195
	v_mul_f32_e32 v138, v223, v223
	v_fmac_f32_e32 v137, v194, v194
	v_fmac_f32_e32 v138, v222, v222
	v_add_f32_e32 v137, v137, v138
	v_add_f32_e32 v175, v136, v137
	v_pk_mul_f32 v[136:137], v[186:187], v[142:143]
	v_pk_mul_f32 v[138:139], v[188:189], v[140:141]
	v_pk_mul_f32 v[140:141], v[190:191], v[222:223]
	v_pk_mul_f32 v[142:143], v[196:197], v[194:195]
	v_cvt_pk_bf16_f32 v138, v138, v139
	v_cvt_pk_bf16_f32 v137, v136, v137
	ds_bpermute_b32 v136, v214, v138
	v_cvt_pk_bf16_f32 v139, v142, v143
	v_cvt_pk_bf16_f32 v140, v140, v141
	ds_bpermute_b32 v137, v214, v137
	ds_bpermute_b32 v138, v214, v139
	ds_bpermute_b32 v139, v214, v140
	s_waitcnt vmcnt(7)
	ds_bpermute_b32 v140, v216, v170
	ds_bpermute_b32 v141, v216, v171
	s_waitcnt lgkmcnt(2)
	global_store_dwordx4 v[198:199], v[136:139], off
	ds_bpermute_b32 v137, v216, v168
	ds_bpermute_b32 v139, v216, v169
	s_waitcnt lgkmcnt(1)
; __device__ __forceinline__ unsigned cvt_pk_bf16(float lo, float hi) { unsigned r; asm volatile("v_cvt_pk_bf16_f32 %0, %1, %2" : "=v"(r) : "v"(lo), "v"(hi)); return r; }
;     __device__ __forceinline__ void operator()(AccT acc, const pg8::Unit& u, int wr, int wc, int fr, int fq) const {
;     ...
;                 for (int m = 0; m < 4; ++m) { const size_t ro = (size_t)(ai * 128 + m * 16) * LDP; float t = 0.f;
; #pragma unroll
;                     for (int bj = 0; bj < 2; ++bj) { const h16x8 b8 = __builtin_bit_cast(h16x8, gather4(__builtin_bit_cast(u32x4, hb[m][bj]), ld4));
;                         const f32x4 h0 = (f32x4){(float)b8[0], (float)b8[1], (float)b8[2], (float)b8[3]} + gv[bj][0] * acc[ai][bj][m][0], h1 = (f32x4){(float)b8[4], (float)b8[5], (float)b8[6], (float)b8[7]} + gv[bj][1] * acc[ai][bj][m][1];
;                         const h16x4 q0 = __builtin_convertvector(h0, h16x4), q1 = __builtin_convertvector(h1, h16x4);
;                         { const h16x8 hv8 = (h16x8){q0[0], q0[1], q0[2], q0[3], q1[0], q1[1], q1[2], q1[3]}; *(u32x4*)(hout + ro + bj * 128) = gather4(__builtin_bit_cast(u32x4, hv8), st4); }
;                         t += ((h0[0] * h0[0] + h0[1] * h0[1]) + (h0[2] * h0[2] + h0[3] * h0[3])) + ((h1[0] * h1[0] + h1[1] * h1[1]) + (h1[2] * h1[2] + h1[3] * h1[3]));
;                         if (WZ) { const f32x4 z0 = h0 * gz[bj][0], z1 = h1 * gz[bj][1]; u32x4 w; w.x = cvt_pk_bf16(z0[0], z0[1]); w.y = cvt_pk_bf16(z0[2], z0[3]); w.z = cvt_pk_bf16(z1[0], z1[1]); w.w = cvt_pk_bf16(z1[2], z1[3]);
;                             *(u32x4*)(zout + ro + bj * 128) = gather4(w, st4); } }
;                     ss[ai * 4 + m] = t; }
	v_cvt_f32_f16_e32 v136, v137
	v_cvt_f32_f16_sdwa v137, v137 dst_sel:DWORD dst_unused:UNUSED_PAD src0_sel:WORD_1
	s_waitcnt lgkmcnt(0)
	v_cvt_f32_f16_e32 v138, v139
	v_cvt_f32_f16_sdwa v139, v139 dst_sel:DWORD dst_unused:UNUSED_PAD src0_sel:WORD_1
	v_pk_fma_f32 v[132:133], v[132:133], v[116:117], v[136:137]
	v_cvt_f32_f16_e32 v136, v140
	v_pk_fma_f32 v[134:135], v[134:135], v[118:119], v[138:139]
	v_cvt_f32_f16_sdwa v137, v140 dst_sel:DWORD dst_unused:UNUSED_PAD src0_sel:WORD_1
	v_cvt_f32_f16_e32 v138, v141
	v_cvt_f32_f16_sdwa v139, v141 dst_sel:DWORD dst_unused:UNUSED_PAD src0_sel:WORD_1
	v_pk_fma_f32 v[136:137], v[128:129], v[108:109], v[136:137]
	v_cvt_pk_f16_f32 v129, v134, v135
	v_pk_fma_f32 v[138:139], v[130:131], v[110:111], v[138:139]
	v_cvt_pk_f16_f32 v130, v136, v137
	v_cvt_pk_f16_f32 v131, v138, v139
	v_cvt_pk_f16_f32 v128, v132, v133
	ds_bpermute_b32 v128, v214, v128
	ds_bpermute_b32 v129, v214, v129
	ds_bpermute_b32 v130, v214, v130
	ds_bpermute_b32 v131, v214, v131
	s_waitcnt lgkmcnt(0)
	global_store_dwordx4 v[200:201], v[128:131], off offset:256
	s_nop 1
	v_mul_f32_e32 v128, v133, v133
	v_mul_f32_e32 v129, v135, v135
	v_fmac_f32_e32 v128, v132, v132
	v_fmac_f32_e32 v129, v134, v134
	v_add_f32_e32 v128, v128, v129
	v_mul_f32_e32 v129, v137, v137
	v_mul_f32_e32 v130, v139, v139
	v_fmac_f32_e32 v129, v136, v136
	v_fmac_f32_e32 v130, v138, v138
	v_add_f32_e32 v129, v129, v130
	v_add_f32_e32 v128, v128, v129
	v_add_f32_e32 v168, v175, v128
	v_pk_mul_f32 v[128:129], v[178:179], v[134:135]
	v_pk_mul_f32 v[130:131], v[180:181], v[132:133]
	v_pk_mul_f32 v[132:133], v[182:183], v[138:139]
	v_pk_mul_f32 v[134:135], v[184:185], v[136:137]
	v_cvt_pk_bf16_f32 v130, v130, v131
	v_cvt_pk_bf16_f32 v129, v128, v129
	ds_bpermute_b32 v128, v214, v130
	v_cvt_pk_bf16_f32 v131, v134, v135
	v_cvt_pk_bf16_f32 v132, v132, v133
	ds_bpermute_b32 v129, v214, v129
	ds_bpermute_b32 v130, v214, v131
	ds_bpermute_b32 v131, v214, v132
	s_waitcnt vmcnt(8)
	ds_bpermute_b32 v132, v216, v166
	ds_bpermute_b32 v133, v216, v167
	s_waitcnt lgkmcnt(2)
	global_store_dwordx4 v[198:199], v[128:131], off offset:256
	ds_bpermute_b32 v129, v216, v164
	ds_bpermute_b32 v131, v216, v165
	s_waitcnt lgkmcnt(1)
	v_cvt_f32_f16_e32 v128, v129
	v_cvt_f32_f16_sdwa v129, v129 dst_sel:DWORD dst_unused:UNUSED_PAD src0_sel:WORD_1
	s_waitcnt lgkmcnt(0)
	v_cvt_f32_f16_e32 v130, v131
	v_cvt_f32_f16_sdwa v131, v131 dst_sel:DWORD dst_unused:UNUSED_PAD src0_sel:WORD_1
	v_pk_fma_f32 v[112:113], v[112:113], v[124:125], v[128:129]
	v_cvt_f32_f16_e32 v128, v132
	v_pk_fma_f32 v[114:115], v[114:115], v[126:127], v[130:131]
	v_cvt_f32_f16_sdwa v129, v132 dst_sel:DWORD dst_unused:UNUSED_PAD src0_sel:WORD_1
	v_cvt_f32_f16_e32 v130, v133
	v_cvt_f32_f16_sdwa v131, v133 dst_sel:DWORD dst_unused:UNUSED_PAD src0_sel:WORD_1
	v_pk_fma_f32 v[104:105], v[104:105], v[120:121], v[128:129]
	v_cvt_pk_f16_f32 v129, v114, v115
	v_pk_fma_f32 v[106:107], v[106:107], v[122:123], v[130:131]
	v_cvt_pk_f16_f32 v130, v104, v105
	v_cvt_pk_f16_f32 v131, v106, v107
	v_cvt_pk_f16_f32 v128, v112, v113
	ds_bpermute_b32 v128, v214, v128
	ds_bpermute_b32 v129, v214, v129
	ds_bpermute_b32 v130, v214, v130
	ds_bpermute_b32 v131, v214, v131
	v_pk_mul_f32 v[132:133], v[190:191], v[106:107]
	v_pk_mul_f32 v[134:135], v[196:197], v[104:105]
	s_waitcnt lgkmcnt(0)
	global_store_dwordx4 v[206:207], v[128:131], off offset:2048
	s_nop 1
	v_pk_mul_f32 v[128:129], v[186:187], v[114:115]
	v_pk_mul_f32 v[130:131], v[188:189], v[112:113]
	s_nop 0
	v_cvt_pk_bf16_f32 v130, v130, v131
	v_cvt_pk_bf16_f32 v129, v128, v129
	v_cvt_pk_bf16_f32 v131, v134, v135
	v_cvt_pk_bf16_f32 v132, v132, v133
	ds_bpermute_b32 v128, v214, v130
	ds_bpermute_b32 v129, v214, v129
	ds_bpermute_b32 v130, v214, v131
	ds_bpermute_b32 v131, v214, v132
	v_add_co_u32_e32 v132, vcc, s11, v198
	s_waitcnt vmcnt(9)
	ds_bpermute_b32 v134, v216, v162
	v_addc_co_u32_e32 v133, vcc, 0, v199, vcc
	s_waitcnt lgkmcnt(1)
	global_store_dwordx4 v[132:133], v[128:131], off offset:2048
	ds_bpermute_b32 v129, v216, v160
	ds_bpermute_b32 v131, v216, v161
	ds_bpermute_b32 v135, v216, v163
	s_mov_b32 s11, 0x84000
	s_waitcnt lgkmcnt(2)
	v_cvt_f32_f16_e32 v128, v129
	v_cvt_f32_f16_sdwa v129, v129 dst_sel:DWORD dst_unused:UNUSED_PAD src0_sel:WORD_1
	s_waitcnt lgkmcnt(1)
	v_cvt_f32_f16_e32 v130, v131
	v_cvt_f32_f16_sdwa v131, v131 dst_sel:DWORD dst_unused:UNUSED_PAD src0_sel:WORD_1
	v_pk_fma_f32 v[100:101], v[100:101], v[116:117], v[128:129]
	v_cvt_f32_f16_e32 v128, v134
	v_pk_fma_f32 v[102:103], v[102:103], v[118:119], v[130:131]
	v_cvt_f32_f16_sdwa v129, v134 dst_sel:DWORD dst_unused:UNUSED_PAD src0_sel:WORD_1
	s_waitcnt lgkmcnt(0)
	v_cvt_f32_f16_e32 v130, v135
	v_cvt_f32_f16_sdwa v131, v135 dst_sel:DWORD dst_unused:UNUSED_PAD src0_sel:WORD_1
	v_pk_fma_f32 v[96:97], v[96:97], v[108:109], v[128:129]
	v_cvt_pk_f16_f32 v129, v102, v103
	v_pk_fma_f32 v[98:99], v[98:99], v[110:111], v[130:131]
	v_cvt_pk_f16_f32 v130, v96, v97
	v_cvt_pk_f16_f32 v131, v98, v99
	v_cvt_pk_f16_f32 v128, v100, v101
	ds_bpermute_b32 v128, v214, v128
	ds_bpermute_b32 v129, v214, v129
	ds_bpermute_b32 v130, v214, v130
	ds_bpermute_b32 v131, v214, v131
	v_pk_mul_f32 v[134:135], v[182:183], v[98:99]
	v_pk_mul_f32 v[136:137], v[184:185], v[96:97]
	s_waitcnt lgkmcnt(0)
	global_store_dwordx4 v[206:207], v[128:131], off offset:2304
	s_nop 1
	v_pk_mul_f32 v[128:129], v[178:179], v[102:103]
	v_pk_mul_f32 v[130:131], v[180:181], v[100:101]
	s_nop 0
	v_cvt_pk_bf16_f32 v130, v130, v131
	v_cvt_pk_bf16_f32 v129, v128, v129
	v_cvt_pk_bf16_f32 v131, v136, v137
	v_cvt_pk_bf16_f32 v134, v134, v135
	ds_bpermute_b32 v128, v214, v130
	ds_bpermute_b32 v129, v214, v129
	ds_bpermute_b32 v130, v214, v131
	ds_bpermute_b32 v131, v214, v134
	v_add_co_u32_e32 v136, vcc, s12, v198
	s_mov_b32 s12, 0x94000
	s_nop 0
	v_addc_co_u32_e32 v137, vcc, 0, v199, vcc
	s_waitcnt lgkmcnt(0)
; __device__ __forceinline__ unsigned cvt_pk_bf16(float lo, float hi) { unsigned r; asm volatile("v_cvt_pk_bf16_f32 %0, %1, %2" : "=v"(r) : "v"(lo), "v"(hi)); return r; }
;     __device__ __forceinline__ void operator()(AccT acc, const pg8::Unit& u, int wr, int wc, int fr, int fq) const {
;     ...
;                 for (int m = 0; m < 4; ++m) { const size_t ro = (size_t)(ai * 128 + m * 16) * LDP; float t = 0.f;
; #pragma unroll
;                     for (int bj = 0; bj < 2; ++bj) { const h16x8 b8 = __builtin_bit_cast(h16x8, gather4(__builtin_bit_cast(u32x4, hb[m][bj]), ld4));
;                         const f32x4 h0 = (f32x4){(float)b8[0], (float)b8[1], (float)b8[2], (float)b8[3]} + gv[bj][0] * acc[ai][bj][m][0], h1 = (f32x4){(float)b8[4], (float)b8[5], (float)b8[6], (float)b8[7]} + gv[bj][1] * acc[ai][bj][m][1];
;                         const h16x4 q0 = __builtin_convertvector(h0, h16x4), q1 = __builtin_convertvector(h1, h16x4);
;                         { const h16x8 hv8 = (h16x8){q0[0], q0[1], q0[2], q0[3], q1[0], q1[1], q1[2], q1[3]}; *(u32x4*)(hout + ro + bj * 128) = gather4(__builtin_bit_cast(u32x4, hv8), st4); }
;                         t += ((h0[0] * h0[0] + h0[1] * h0[1]) + (h0[2] * h0[2] + h0[3] * h0[3])) + ((h1[0] * h1[0] + h1[1] * h1[1]) + (h1[2] * h1[2] + h1[3] * h1[3]));
;                         if (WZ) { const f32x4 z0 = h0 * gz[bj][0], z1 = h1 * gz[bj][1]; u32x4 w; w.x = cvt_pk_bf16(z0[0], z0[1]); w.y = cvt_pk_bf16(z0[2], z0[3]); w.z = cvt_pk_bf16(z1[0], z1[1]); w.w = cvt_pk_bf16(z1[2], z1[3]);
;                             *(u32x4*)(zout + ro + bj * 128) = gather4(w, st4); } }
;                     ss[ai * 4 + m] = t; }
	global_store_dwordx4 v[132:133], v[128:131], off offset:2304
	s_waitcnt vmcnt(11)
	ds_bpermute_b32 v129, v216, v156
	ds_bpermute_b32 v131, v216, v157
	ds_bpermute_b32 v132, v216, v158
	ds_bpermute_b32 v133, v216, v159
	s_waitcnt lgkmcnt(3)
	v_cvt_f32_f16_e32 v128, v129
	v_cvt_f32_f16_sdwa v129, v129 dst_sel:DWORD dst_unused:UNUSED_PAD src0_sel:WORD_1
	s_waitcnt lgkmcnt(2)
	v_cvt_f32_f16_e32 v130, v131
	v_cvt_f32_f16_sdwa v131, v131 dst_sel:DWORD dst_unused:UNUSED_PAD src0_sel:WORD_1
	v_pk_fma_f32 v[92:93], v[92:93], v[124:125], v[128:129]
	s_waitcnt lgkmcnt(1)
	v_cvt_f32_f16_e32 v128, v132
	v_pk_fma_f32 v[94:95], v[94:95], v[126:127], v[130:131]
	v_cvt_f32_f16_sdwa v129, v132 dst_sel:DWORD dst_unused:UNUSED_PAD src0_sel:WORD_1
	s_waitcnt lgkmcnt(0)
	v_cvt_f32_f16_e32 v130, v133
	v_cvt_f32_f16_sdwa v131, v133 dst_sel:DWORD dst_unused:UNUSED_PAD src0_sel:WORD_1
	v_pk_fma_f32 v[88:89], v[88:89], v[120:121], v[128:129]
	v_cvt_pk_f16_f32 v129, v94, v95
	v_pk_fma_f32 v[90:91], v[90:91], v[122:123], v[130:131]
	v_cvt_pk_f16_f32 v130, v88, v89
	v_cvt_pk_f16_f32 v131, v90, v91
	v_cvt_pk_f16_f32 v128, v92, v93
	ds_bpermute_b32 v128, v214, v128
	ds_bpermute_b32 v129, v214, v129
	ds_bpermute_b32 v130, v214, v130
	ds_bpermute_b32 v131, v214, v131
	v_pk_mul_f32 v[132:133], v[190:191], v[90:91]
	v_pk_mul_f32 v[134:135], v[196:197], v[88:89]
	s_waitcnt lgkmcnt(0)
	global_store_dwordx4 v[204:205], v[128:131], off
	s_nop 1
	v_pk_mul_f32 v[128:129], v[186:187], v[94:95]
	v_pk_mul_f32 v[130:131], v[188:189], v[92:93]
	s_nop 0
	v_cvt_pk_bf16_f32 v130, v130, v131
	v_cvt_pk_bf16_f32 v129, v128, v129
	v_cvt_pk_bf16_f32 v131, v134, v135
	v_cvt_pk_bf16_f32 v132, v132, v133
	ds_bpermute_b32 v128, v214, v130
	ds_bpermute_b32 v129, v214, v129
	ds_bpermute_b32 v130, v214, v131
	ds_bpermute_b32 v131, v214, v132
	s_waitcnt vmcnt(11)
	ds_bpermute_b32 v132, v216, v154
	ds_bpermute_b32 v133, v216, v155
	s_waitcnt lgkmcnt(2)
	global_store_dwordx4 v[136:137], v[128:131], off
	ds_bpermute_b32 v128, v216, v152
	ds_bpermute_b32 v129, v216, v153
	s_waitcnt lgkmcnt(1)
	v_cvt_f32_f16_e32 v130, v128
	v_cvt_f32_f16_sdwa v131, v128 dst_sel:DWORD dst_unused:UNUSED_PAD src0_sel:WORD_1
	s_waitcnt lgkmcnt(0)
	v_cvt_f32_f16_e32 v128, v129
	v_cvt_f32_f16_sdwa v129, v129 dst_sel:DWORD dst_unused:UNUSED_PAD src0_sel:WORD_1
	v_pk_fma_f32 v[130:131], v[84:85], v[116:117], v[130:131]
	v_cvt_f32_f16_e32 v84, v132
	v_pk_fma_f32 v[128:129], v[86:87], v[118:119], v[128:129]
	v_cvt_f32_f16_sdwa v85, v132 dst_sel:DWORD dst_unused:UNUSED_PAD src0_sel:WORD_1
	v_cvt_f32_f16_e32 v86, v133
	v_cvt_f32_f16_sdwa v87, v133 dst_sel:DWORD dst_unused:UNUSED_PAD src0_sel:WORD_1
	v_pk_fma_f32 v[134:135], v[80:81], v[108:109], v[84:85]
	v_cvt_pk_f16_f32 v81, v128, v129
	v_pk_fma_f32 v[132:133], v[82:83], v[110:111], v[86:87]
	v_cvt_pk_f16_f32 v82, v134, v135
	v_cvt_pk_f16_f32 v83, v132, v133
	v_cvt_pk_f16_f32 v80, v130, v131
	ds_bpermute_b32 v80, v214, v80
	ds_bpermute_b32 v81, v214, v81
	ds_bpermute_b32 v82, v214, v82
	ds_bpermute_b32 v83, v214, v83
	v_pk_mul_f32 v[84:85], v[182:183], v[132:133]
	v_pk_mul_f32 v[86:87], v[184:185], v[134:135]
	s_waitcnt lgkmcnt(0)
	global_store_dwordx4 v[204:205], v[80:83], off offset:256
	s_nop 1
	v_pk_mul_f32 v[80:81], v[178:179], v[128:129]
	v_pk_mul_f32 v[82:83], v[180:181], v[130:131]
	s_nop 0
	v_cvt_pk_bf16_f32 v82, v82, v83
	v_cvt_pk_bf16_f32 v81, v80, v81
	v_cvt_pk_bf16_f32 v83, v86, v87
	v_cvt_pk_bf16_f32 v84, v84, v85
	ds_bpermute_b32 v80, v214, v82
	ds_bpermute_b32 v81, v214, v81
	ds_bpermute_b32 v82, v214, v83
	ds_bpermute_b32 v83, v214, v84
	s_waitcnt vmcnt(12)
	ds_bpermute_b32 v84, v216, v150
	ds_bpermute_b32 v85, v216, v151
	s_waitcnt lgkmcnt(2)
	global_store_dwordx4 v[136:137], v[80:83], off offset:256
	ds_bpermute_b32 v81, v216, v148
	ds_bpermute_b32 v83, v216, v149
	s_waitcnt lgkmcnt(1)
	v_cvt_f32_f16_e32 v80, v81
	v_cvt_f32_f16_sdwa v81, v81 dst_sel:DWORD dst_unused:UNUSED_PAD src0_sel:WORD_1
	s_waitcnt lgkmcnt(0)
	v_cvt_f32_f16_e32 v82, v83
	v_cvt_f32_f16_sdwa v83, v83 dst_sel:DWORD dst_unused:UNUSED_PAD src0_sel:WORD_1
	v_pk_fma_f32 v[138:139], v[76:77], v[124:125], v[80:81]
	v_cvt_f32_f16_e32 v76, v84
	v_pk_fma_f32 v[136:137], v[78:79], v[126:127], v[82:83]
	v_cvt_f32_f16_sdwa v77, v84 dst_sel:DWORD dst_unused:UNUSED_PAD src0_sel:WORD_1
	v_cvt_f32_f16_e32 v78, v85
	v_cvt_f32_f16_sdwa v79, v85 dst_sel:DWORD dst_unused:UNUSED_PAD src0_sel:WORD_1
	v_pk_fma_f32 v[142:143], v[72:73], v[120:121], v[76:77]
	v_cvt_pk_f16_f32 v73, v136, v137
	v_pk_fma_f32 v[140:141], v[74:75], v[122:123], v[78:79]
	v_cvt_pk_f16_f32 v74, v142, v143
	v_cvt_pk_f16_f32 v75, v140, v141
	v_cvt_pk_f16_f32 v72, v138, v139
	ds_bpermute_b32 v72, v214, v72
	ds_bpermute_b32 v73, v214, v73
	ds_bpermute_b32 v74, v214, v74
	ds_bpermute_b32 v75, v214, v75
	v_pk_mul_f32 v[76:77], v[190:191], v[140:141]
	v_pk_mul_f32 v[78:79], v[196:197], v[142:143]
	s_waitcnt lgkmcnt(0)
	global_store_dwordx4 v[202:203], v[72:75], off offset:2048
	s_nop 1
	v_pk_mul_f32 v[72:73], v[186:187], v[136:137]
	v_pk_mul_f32 v[74:75], v[188:189], v[138:139]
	s_nop 0
	v_cvt_pk_bf16_f32 v74, v74, v75
	v_cvt_pk_bf16_f32 v73, v72, v73
	v_cvt_pk_bf16_f32 v75, v78, v79
	v_cvt_pk_bf16_f32 v76, v76, v77
	ds_bpermute_b32 v72, v214, v74
	ds_bpermute_b32 v73, v214, v73
	ds_bpermute_b32 v74, v214, v75
	ds_bpermute_b32 v75, v214, v76
	v_add_co_u32_e32 v76, vcc, s13, v198
	s_waitcnt vmcnt(13)
	ds_bpermute_b32 v78, v216, v146
	v_addc_co_u32_e32 v77, vcc, 0, v199, vcc
	s_waitcnt lgkmcnt(1)
	global_store_dwordx4 v[76:77], v[72:75], off offset:2048
	ds_bpermute_b32 v73, v216, v144
	ds_bpermute_b32 v75, v216, v145
	ds_bpermute_b32 v79, v216, v147
	v_add_co_u32_e32 v158, vcc, s11, v200
	s_waitcnt lgkmcnt(2)
; __device__ __forceinline__ unsigned cvt_pk_bf16(float lo, float hi) { unsigned r; asm volatile("v_cvt_pk_bf16_f32 %0, %1, %2" : "=v"(r) : "v"(lo), "v"(hi)); return r; }
;     __device__ __forceinline__ void operator()(AccT acc, const pg8::Unit& u, int wr, int wc, int fr, int fq) const {
;     ...
;                     for (int bj = 0; bj < 2; ++bj) hb[m][bj] = *(const h16x8*)(base + (size_t)(ai * 128 + m * 16) * LDP + bj * 128);
;                 asm volatile("" ::: "memory");
; #pragma unroll
;                 for (int m = 0; m < 4; ++m) { const size_t ro = (size_t)(ai * 128 + m * 16) * LDP; float t = 0.f;
; #pragma unroll
;                     for (int bj = 0; bj < 2; ++bj) { const h16x8 b8 = __builtin_bit_cast(h16x8, gather4(__builtin_bit_cast(u32x4, hb[m][bj]), ld4));
;                         const f32x4 h0 = (f32x4){(float)b8[0], (float)b8[1], (float)b8[2], (float)b8[3]} + gv[bj][0] * acc[ai][bj][m][0], h1 = (f32x4){(float)b8[4], (float)b8[5], (float)b8[6], (float)b8[7]} + gv[bj][1] * acc[ai][bj][m][1];
;                         const h16x4 q0 = __builtin_convertvector(h0, h16x4), q1 = __builtin_convertvector(h1, h16x4);
;                         { const h16x8 hv8 = (h16x8){q0[0], q0[1], q0[2], q0[3], q1[0], q1[1], q1[2], q1[3]}; *(u32x4*)(hout + ro + bj * 128) = gather4(__builtin_bit_cast(u32x4, hv8), st4); }
;                         t += ((h0[0] * h0[0] + h0[1] * h0[1]) + (h0[2] * h0[2] + h0[3] * h0[3])) + ((h1[0] * h1[0] + h1[1] * h1[1]) + (h1[2] * h1[2] + h1[3] * h1[3]));
;                         if (WZ) { const f32x4 z0 = h0 * gz[bj][0], z1 = h1 * gz[bj][1]; u32x4 w; w.x = cvt_pk_bf16(z0[0], z0[1]); w.y = cvt_pk_bf16(z0[2], z0[3]); w.z = cvt_pk_bf16(z1[0], z1[1]); w.w = cvt_pk_bf16(z1[2], z1[3]);
;                             *(u32x4*)(zout + ro + bj * 128) = gather4(w, st4); } }
;                     ss[ai * 4 + m] = t; }
	v_cvt_f32_f16_e32 v72, v73
	v_cvt_f32_f16_sdwa v73, v73 dst_sel:DWORD dst_unused:UNUSED_PAD src0_sel:WORD_1
	s_waitcnt lgkmcnt(1)
	v_cvt_f32_f16_e32 v74, v75
	v_cvt_f32_f16_sdwa v75, v75 dst_sel:DWORD dst_unused:UNUSED_PAD src0_sel:WORD_1
	v_addc_co_u32_e32 v159, vcc, 0, v201, vcc
	v_pk_fma_f32 v[146:147], v[68:69], v[116:117], v[72:73]
	v_pk_fma_f32 v[144:145], v[70:71], v[118:119], v[74:75]
	v_cvt_f32_f16_e32 v68, v78
	v_cvt_f32_f16_sdwa v69, v78 dst_sel:DWORD dst_unused:UNUSED_PAD src0_sel:WORD_1
	s_waitcnt lgkmcnt(0)
	v_cvt_f32_f16_e32 v70, v79
	v_cvt_f32_f16_sdwa v71, v79 dst_sel:DWORD dst_unused:UNUSED_PAD src0_sel:WORD_1
	v_add_co_u32_e32 v156, vcc, s12, v200
	v_pk_fma_f32 v[150:151], v[64:65], v[108:109], v[68:69]
	v_pk_fma_f32 v[148:149], v[66:67], v[110:111], v[70:71]
	v_cvt_pk_f16_f32 v66, v150, v151
	v_cvt_pk_f16_f32 v67, v148, v149
	v_cvt_pk_f16_f32 v65, v144, v145
	v_cvt_pk_f16_f32 v64, v146, v147
	ds_bpermute_b32 v64, v214, v64
	ds_bpermute_b32 v65, v214, v65
	ds_bpermute_b32 v66, v214, v66
	ds_bpermute_b32 v67, v214, v67
	v_pk_mul_f32 v[68:69], v[182:183], v[148:149]
	v_pk_mul_f32 v[70:71], v[184:185], v[150:151]
	v_addc_co_u32_e32 v157, vcc, 0, v201, vcc
	s_waitcnt lgkmcnt(0)
	global_store_dwordx4 v[202:203], v[64:67], off offset:2304
	s_mov_b32 s13, 0xa5000
	v_add_co_u32_e32 v154, vcc, s13, v200
	v_pk_mul_f32 v[64:65], v[178:179], v[144:145]
	v_pk_mul_f32 v[66:67], v[180:181], v[146:147]
	v_addc_co_u32_e32 v155, vcc, 0, v201, vcc
	v_cvt_pk_bf16_f32 v66, v66, v67
	v_cvt_pk_bf16_f32 v65, v64, v65
	v_cvt_pk_bf16_f32 v67, v70, v71
	v_cvt_pk_bf16_f32 v68, v68, v69
	ds_bpermute_b32 v64, v214, v66
	ds_bpermute_b32 v65, v214, v65
	ds_bpermute_b32 v66, v214, v67
	ds_bpermute_b32 v67, v214, v68
	v_add_co_u32_e32 v152, vcc, s25, v200
	s_waitcnt lgkmcnt(0)
	global_store_dwordx4 v[76:77], v[64:67], off offset:2304
	global_load_dwordx4 v[160:163], v[158:159], off
	global_load_dwordx4 v[164:167], v[158:159], off offset:256
	global_load_dwordx4 v[84:87], v[156:157], off offset:2048
	global_load_dwordx4 v[80:83], v[156:157], off offset:2304
	v_addc_co_u32_e32 v153, vcc, 0, v201, vcc
	global_load_dwordx4 v[76:79], v[154:155], off
	global_load_dwordx4 v[72:75], v[154:155], off offset:256
	global_load_dwordx4 v[68:71], v[152:153], off offset:2048
	global_load_dwordx4 v[64:67], v[152:153], off offset:2304
	s_waitcnt vmcnt(7)
	ds_bpermute_b32 v169, v216, v160
	ds_bpermute_b32 v170, v216, v161
	ds_bpermute_b32 v171, v216, v162
	ds_bpermute_b32 v175, v216, v163
	s_waitcnt lgkmcnt(3)
	v_cvt_f32_f16_e32 v160, v169
	v_cvt_f32_f16_sdwa v161, v169 dst_sel:DWORD dst_unused:UNUSED_PAD src0_sel:WORD_1
	s_waitcnt lgkmcnt(2)
	v_cvt_f32_f16_e32 v162, v170
	v_cvt_f32_f16_sdwa v163, v170 dst_sel:DWORD dst_unused:UNUSED_PAD src0_sel:WORD_1
	v_pk_fma_f32 v[60:61], v[60:61], v[124:125], v[160:161]
	s_waitcnt lgkmcnt(1)
	v_cvt_f32_f16_e32 v160, v171
	v_pk_fma_f32 v[62:63], v[62:63], v[126:127], v[162:163]
	v_cvt_f32_f16_sdwa v161, v171 dst_sel:DWORD dst_unused:UNUSED_PAD src0_sel:WORD_1
	s_waitcnt lgkmcnt(0)
	v_cvt_f32_f16_e32 v162, v175
	v_cvt_f32_f16_sdwa v163, v175 dst_sel:DWORD dst_unused:UNUSED_PAD src0_sel:WORD_1
	v_pk_fma_f32 v[56:57], v[56:57], v[120:121], v[160:161]
	v_cvt_pk_f16_f32 v161, v62, v63
	v_pk_fma_f32 v[58:59], v[58:59], v[122:123], v[162:163]
	v_cvt_pk_f16_f32 v162, v56, v57
	v_cvt_pk_f16_f32 v163, v58, v59
	v_cvt_pk_f16_f32 v160, v60, v61
	ds_bpermute_b32 v160, v214, v160
	ds_bpermute_b32 v161, v214, v161
	ds_bpermute_b32 v162, v214, v162
	ds_bpermute_b32 v163, v214, v163
	v_pk_mul_f32 v[194:195], v[196:197], v[56:57]
	v_pk_mul_f32 v[170:171], v[190:191], v[58:59]
	s_waitcnt lgkmcnt(0)
	global_store_dwordx4 v[158:159], v[160:163], off
	s_nop 1
	v_pk_mul_f32 v[160:161], v[186:187], v[62:63]
	v_pk_mul_f32 v[162:163], v[188:189], v[60:61]
	s_nop 0
	v_cvt_pk_bf16_f32 v162, v162, v163
	v_cvt_pk_bf16_f32 v161, v160, v161
	v_cvt_pk_bf16_f32 v163, v194, v195
	v_cvt_pk_bf16_f32 v169, v170, v171
	ds_bpermute_b32 v160, v214, v162
	ds_bpermute_b32 v161, v214, v161
	ds_bpermute_b32 v162, v214, v163
	ds_bpermute_b32 v163, v214, v169
	v_add_co_u32_e32 v170, vcc, s11, v198
	s_nop 1
	v_addc_co_u32_e32 v171, vcc, 0, v199, vcc
	s_waitcnt lgkmcnt(0)
	global_store_dwordx4 v[170:171], v[160:163], off
	s_waitcnt vmcnt(8)
	ds_bpermute_b32 v161, v216, v164
	ds_bpermute_b32 v163, v216, v165
	ds_bpermute_b32 v164, v216, v166
	ds_bpermute_b32 v165, v216, v167
	s_waitcnt lgkmcnt(3)
	v_cvt_f32_f16_e32 v160, v161
	v_cvt_f32_f16_sdwa v161, v161 dst_sel:DWORD dst_unused:UNUSED_PAD src0_sel:WORD_1
	s_waitcnt lgkmcnt(2)
	v_cvt_f32_f16_e32 v162, v163
	v_cvt_f32_f16_sdwa v163, v163 dst_sel:DWORD dst_unused:UNUSED_PAD src0_sel:WORD_1
	v_pk_fma_f32 v[52:53], v[52:53], v[116:117], v[160:161]
	s_waitcnt lgkmcnt(1)
	v_cvt_f32_f16_e32 v160, v164
	v_pk_fma_f32 v[54:55], v[54:55], v[118:119], v[162:163]
	v_cvt_f32_f16_sdwa v161, v164 dst_sel:DWORD dst_unused:UNUSED_PAD src0_sel:WORD_1
	s_waitcnt lgkmcnt(0)
	v_cvt_f32_f16_e32 v162, v165
	v_cvt_f32_f16_sdwa v163, v165 dst_sel:DWORD dst_unused:UNUSED_PAD src0_sel:WORD_1
	v_pk_fma_f32 v[48:49], v[48:49], v[108:109], v[160:161]
	v_cvt_pk_f16_f32 v161, v54, v55
	v_pk_fma_f32 v[50:51], v[50:51], v[110:111], v[162:163]
	v_cvt_pk_f16_f32 v162, v48, v49
	v_cvt_pk_f16_f32 v163, v50, v51
	v_cvt_pk_f16_f32 v160, v52, v53
	ds_bpermute_b32 v160, v214, v160
	ds_bpermute_b32 v161, v214, v161
	ds_bpermute_b32 v162, v214, v162
	ds_bpermute_b32 v163, v214, v163
	v_pk_mul_f32 v[164:165], v[184:185], v[48:49]
	s_waitcnt lgkmcnt(0)
; __device__ __forceinline__ unsigned cvt_pk_bf16(float lo, float hi) { unsigned r; asm volatile("v_cvt_pk_bf16_f32 %0, %1, %2" : "=v"(r) : "v"(lo), "v"(hi)); return r; }
;     __device__ __forceinline__ void operator()(AccT acc, const pg8::Unit& u, int wr, int wc, int fr, int fq) const {
;     ...
;                 for (int m = 0; m < 4; ++m) { const size_t ro = (size_t)(ai * 128 + m * 16) * LDP; float t = 0.f;
; #pragma unroll
;                     for (int bj = 0; bj < 2; ++bj) { const h16x8 b8 = __builtin_bit_cast(h16x8, gather4(__builtin_bit_cast(u32x4, hb[m][bj]), ld4));
;                         const f32x4 h0 = (f32x4){(float)b8[0], (float)b8[1], (float)b8[2], (float)b8[3]} + gv[bj][0] * acc[ai][bj][m][0], h1 = (f32x4){(float)b8[4], (float)b8[5], (float)b8[6], (float)b8[7]} + gv[bj][1] * acc[ai][bj][m][1];
;                         const h16x4 q0 = __builtin_convertvector(h0, h16x4), q1 = __builtin_convertvector(h1, h16x4);
;                         { const h16x8 hv8 = (h16x8){q0[0], q0[1], q0[2], q0[3], q1[0], q1[1], q1[2], q1[3]}; *(u32x4*)(hout + ro + bj * 128) = gather4(__builtin_bit_cast(u32x4, hv8), st4); }
;                         t += ((h0[0] * h0[0] + h0[1] * h0[1]) + (h0[2] * h0[2] + h0[3] * h0[3])) + ((h1[0] * h1[0] + h1[1] * h1[1]) + (h1[2] * h1[2] + h1[3] * h1[3]));
;                         if (WZ) { const f32x4 z0 = h0 * gz[bj][0], z1 = h1 * gz[bj][1]; u32x4 w; w.x = cvt_pk_bf16(z0[0], z0[1]); w.y = cvt_pk_bf16(z0[2], z0[3]); w.z = cvt_pk_bf16(z1[0], z1[1]); w.w = cvt_pk_bf16(z1[2], z1[3]);
;                             *(u32x4*)(zout + ro + bj * 128) = gather4(w, st4); } }
;                     ss[ai * 4 + m] = t; }
	global_store_dwordx4 v[158:159], v[160:163], off offset:256
	v_pk_mul_f32 v[158:159], v[178:179], v[54:55]
	s_nop 0
	v_pk_mul_f32 v[160:161], v[180:181], v[52:53]
	v_pk_mul_f32 v[162:163], v[182:183], v[50:51]
	v_cvt_pk_bf16_f32 v160, v160, v161
	v_cvt_pk_bf16_f32 v159, v158, v159
	v_cvt_pk_bf16_f32 v161, v164, v165
	ds_bpermute_b32 v158, v214, v160
	v_cvt_pk_bf16_f32 v162, v162, v163
	ds_bpermute_b32 v159, v214, v159
	ds_bpermute_b32 v160, v214, v161
	ds_bpermute_b32 v161, v214, v162
	s_waitcnt lgkmcnt(0)
	global_store_dwordx4 v[170:171], v[158:161], off offset:256
	s_waitcnt vmcnt(9)
	ds_bpermute_b32 v158, v216, v84
	ds_bpermute_b32 v159, v216, v85
	ds_bpermute_b32 v160, v216, v86
	ds_bpermute_b32 v161, v216, v87
	s_waitcnt lgkmcnt(3)
	v_cvt_f32_f16_e32 v84, v158
	v_cvt_f32_f16_sdwa v85, v158 dst_sel:DWORD dst_unused:UNUSED_PAD src0_sel:WORD_1
	s_waitcnt lgkmcnt(2)
	v_cvt_f32_f16_e32 v86, v159
	v_cvt_f32_f16_sdwa v87, v159 dst_sel:DWORD dst_unused:UNUSED_PAD src0_sel:WORD_1
	v_pk_fma_f32 v[44:45], v[44:45], v[124:125], v[84:85]
	s_waitcnt lgkmcnt(1)
	v_cvt_f32_f16_e32 v84, v160
	v_pk_fma_f32 v[46:47], v[46:47], v[126:127], v[86:87]
	v_cvt_f32_f16_sdwa v85, v160 dst_sel:DWORD dst_unused:UNUSED_PAD src0_sel:WORD_1
	s_waitcnt lgkmcnt(0)
	v_cvt_f32_f16_e32 v86, v161
	v_cvt_f32_f16_sdwa v87, v161 dst_sel:DWORD dst_unused:UNUSED_PAD src0_sel:WORD_1
	v_pk_fma_f32 v[40:41], v[40:41], v[120:121], v[84:85]
	v_cvt_pk_f16_f32 v85, v46, v47
	v_pk_fma_f32 v[42:43], v[42:43], v[122:123], v[86:87]
	v_cvt_pk_f16_f32 v86, v40, v41
	v_cvt_pk_f16_f32 v87, v42, v43
	v_cvt_pk_f16_f32 v84, v44, v45
	ds_bpermute_b32 v84, v214, v84
	ds_bpermute_b32 v85, v214, v85
	ds_bpermute_b32 v86, v214, v86
	ds_bpermute_b32 v87, v214, v87
	v_pk_mul_f32 v[158:159], v[190:191], v[42:43]
	v_pk_mul_f32 v[160:161], v[196:197], v[40:41]
	s_waitcnt lgkmcnt(0)
	global_store_dwordx4 v[156:157], v[84:87], off offset:2048
	s_nop 1
	v_pk_mul_f32 v[84:85], v[186:187], v[46:47]
	v_pk_mul_f32 v[86:87], v[188:189], v[44:45]
	s_nop 0
	v_cvt_pk_bf16_f32 v86, v86, v87
	v_cvt_pk_bf16_f32 v85, v84, v85
	v_cvt_pk_bf16_f32 v87, v160, v161
	v_cvt_pk_bf16_f32 v158, v158, v159
	ds_bpermute_b32 v84, v214, v86
	ds_bpermute_b32 v85, v214, v85
	ds_bpermute_b32 v86, v214, v87
	ds_bpermute_b32 v87, v214, v158
	v_add_co_u32_e32 v158, vcc, s12, v198
	s_nop 1
	v_addc_co_u32_e32 v159, vcc, 0, v199, vcc
	s_waitcnt lgkmcnt(0)
	global_store_dwordx4 v[158:159], v[84:87], off offset:2048
	s_waitcnt vmcnt(10)
	ds_bpermute_b32 v84, v216, v80
	ds_bpermute_b32 v85, v216, v81
	ds_bpermute_b32 v86, v216, v82
	ds_bpermute_b32 v87, v216, v83
	s_waitcnt lgkmcnt(3)
	v_cvt_f32_f16_e32 v80, v84
	v_cvt_f32_f16_sdwa v81, v84 dst_sel:DWORD dst_unused:UNUSED_PAD src0_sel:WORD_1
	s_waitcnt lgkmcnt(2)
	v_cvt_f32_f16_e32 v82, v85
	v_cvt_f32_f16_sdwa v83, v85 dst_sel:DWORD dst_unused:UNUSED_PAD src0_sel:WORD_1
	v_pk_fma_f32 v[36:37], v[36:37], v[116:117], v[80:81]
	s_waitcnt lgkmcnt(1)
	v_cvt_f32_f16_e32 v80, v86
	v_pk_fma_f32 v[38:39], v[38:39], v[118:119], v[82:83]
	v_cvt_f32_f16_sdwa v81, v86 dst_sel:DWORD dst_unused:UNUSED_PAD src0_sel:WORD_1
	s_waitcnt lgkmcnt(0)
	v_cvt_f32_f16_e32 v82, v87
	v_cvt_f32_f16_sdwa v83, v87 dst_sel:DWORD dst_unused:UNUSED_PAD src0_sel:WORD_1
	v_pk_fma_f32 v[32:33], v[32:33], v[108:109], v[80:81]
	v_cvt_pk_f16_f32 v81, v38, v39
	v_pk_fma_f32 v[34:35], v[34:35], v[110:111], v[82:83]
	v_cvt_pk_f16_f32 v82, v32, v33
	v_cvt_pk_f16_f32 v83, v34, v35
	v_cvt_pk_f16_f32 v80, v36, v37
	ds_bpermute_b32 v80, v214, v80
	ds_bpermute_b32 v81, v214, v81
	ds_bpermute_b32 v82, v214, v82
	ds_bpermute_b32 v83, v214, v83
	v_pk_mul_f32 v[84:85], v[182:183], v[34:35]
	v_pk_mul_f32 v[86:87], v[184:185], v[32:33]
	s_waitcnt lgkmcnt(0)
	global_store_dwordx4 v[156:157], v[80:83], off offset:2304
	s_nop 1
	v_pk_mul_f32 v[80:81], v[178:179], v[38:39]
	v_pk_mul_f32 v[82:83], v[180:181], v[36:37]
	s_nop 0
	v_cvt_pk_bf16_f32 v82, v82, v83
	v_cvt_pk_bf16_f32 v81, v80, v81
	v_cvt_pk_bf16_f32 v83, v86, v87
	v_cvt_pk_bf16_f32 v84, v84, v85
	ds_bpermute_b32 v80, v214, v82
	ds_bpermute_b32 v81, v214, v81
	ds_bpermute_b32 v82, v214, v83
	ds_bpermute_b32 v83, v214, v84
	s_waitcnt lgkmcnt(0)
	global_store_dwordx4 v[158:159], v[80:83], off offset:2304
	s_waitcnt vmcnt(11)
	ds_bpermute_b32 v80, v216, v76
	ds_bpermute_b32 v81, v216, v77
	ds_bpermute_b32 v82, v216, v78
	ds_bpermute_b32 v83, v216, v79
	s_waitcnt lgkmcnt(3)
	v_cvt_f32_f16_e32 v76, v80
	v_cvt_f32_f16_sdwa v77, v80 dst_sel:DWORD dst_unused:UNUSED_PAD src0_sel:WORD_1
	s_waitcnt lgkmcnt(2)
	v_cvt_f32_f16_e32 v78, v81
	v_cvt_f32_f16_sdwa v79, v81 dst_sel:DWORD dst_unused:UNUSED_PAD src0_sel:WORD_1
	v_pk_fma_f32 v[28:29], v[28:29], v[124:125], v[76:77]
	s_waitcnt lgkmcnt(1)
	v_cvt_f32_f16_e32 v76, v82
	v_pk_fma_f32 v[30:31], v[30:31], v[126:127], v[78:79]
	v_cvt_f32_f16_sdwa v77, v82 dst_sel:DWORD dst_unused:UNUSED_PAD src0_sel:WORD_1
	s_waitcnt lgkmcnt(0)
	v_cvt_f32_f16_e32 v78, v83
	v_cvt_f32_f16_sdwa v79, v83 dst_sel:DWORD dst_unused:UNUSED_PAD src0_sel:WORD_1
	v_pk_fma_f32 v[24:25], v[24:25], v[120:121], v[76:77]
	v_cvt_pk_f16_f32 v77, v30, v31
	v_pk_fma_f32 v[26:27], v[26:27], v[122:123], v[78:79]
	v_cvt_pk_f16_f32 v78, v24, v25
	v_cvt_pk_f16_f32 v79, v26, v27
	v_cvt_pk_f16_f32 v76, v28, v29
	ds_bpermute_b32 v76, v214, v76
	ds_bpermute_b32 v77, v214, v77
	ds_bpermute_b32 v78, v214, v78
	ds_bpermute_b32 v79, v214, v79
	v_pk_mul_f32 v[80:81], v[190:191], v[26:27]
	v_pk_mul_f32 v[82:83], v[196:197], v[24:25]
	s_waitcnt lgkmcnt(0)
; __device__ __forceinline__ unsigned cvt_pk_bf16(float lo, float hi) { unsigned r; asm volatile("v_cvt_pk_bf16_f32 %0, %1, %2" : "=v"(r) : "v"(lo), "v"(hi)); return r; }
; __device__ __forceinline__ float xlane(float v, int src_lane) { return __uint_as_float(__builtin_amdgcn_ds_bpermute(src_lane << 2, __float_as_uint(v))); }
;     __device__ __forceinline__ void operator()(AccT acc, const pg8::Unit& u, int wr, int wc, int fr, int fq) const {
;     ...
;                 for (int m = 0; m < 4; ++m) { const size_t ro = (size_t)(ai * 128 + m * 16) * LDP; float t = 0.f;
; #pragma unroll
;                     for (int bj = 0; bj < 2; ++bj) { const h16x8 b8 = __builtin_bit_cast(h16x8, gather4(__builtin_bit_cast(u32x4, hb[m][bj]), ld4));
;                         const f32x4 h0 = (f32x4){(float)b8[0], (float)b8[1], (float)b8[2], (float)b8[3]} + gv[bj][0] * acc[ai][bj][m][0], h1 = (f32x4){(float)b8[4], (float)b8[5], (float)b8[6], (float)b8[7]} + gv[bj][1] * acc[ai][bj][m][1];
;                         const h16x4 q0 = __builtin_convertvector(h0, h16x4), q1 = __builtin_convertvector(h1, h16x4);
;                         { const h16x8 hv8 = (h16x8){q0[0], q0[1], q0[2], q0[3], q1[0], q1[1], q1[2], q1[3]}; *(u32x4*)(hout + ro + bj * 128) = gather4(__builtin_bit_cast(u32x4, hv8), st4); }
;                         t += ((h0[0] * h0[0] + h0[1] * h0[1]) + (h0[2] * h0[2] + h0[3] * h0[3])) + ((h1[0] * h1[0] + h1[1] * h1[1]) + (h1[2] * h1[2] + h1[3] * h1[3]));
;                         if (WZ) { const f32x4 z0 = h0 * gz[bj][0], z1 = h1 * gz[bj][1]; u32x4 w; w.x = cvt_pk_bf16(z0[0], z0[1]); w.y = cvt_pk_bf16(z0[2], z0[3]); w.z = cvt_pk_bf16(z1[0], z1[1]); w.w = cvt_pk_bf16(z1[2], z1[3]);
;                             *(u32x4*)(zout + ro + bj * 128) = gather4(w, st4); } }
;                     ss[ai * 4 + m] = t; }
;     ...
;         for (int g = 0; g < 8; ++g) { float t = ss[g]; t += xlane(t, lane ^ 16); t += xlane(t, lane ^ 32);
;             if (fq == 0) SSQ[(size_t)(row0 + (g >> 2) * 128 + (g & 3) * 16) * 32 + u.pn * 4 + wc] = t; }
	global_store_dwordx4 v[154:155], v[76:79], off
	s_nop 1
	v_pk_mul_f32 v[76:77], v[186:187], v[30:31]
	v_pk_mul_f32 v[78:79], v[188:189], v[28:29]
	s_nop 0
	v_cvt_pk_bf16_f32 v78, v78, v79
	v_cvt_pk_bf16_f32 v77, v76, v77
	v_cvt_pk_bf16_f32 v79, v82, v83
	v_cvt_pk_bf16_f32 v80, v80, v81
	ds_bpermute_b32 v76, v214, v78
	ds_bpermute_b32 v77, v214, v77
	ds_bpermute_b32 v78, v214, v79
	ds_bpermute_b32 v79, v214, v80
	v_add_co_u32_e32 v80, vcc, s13, v198
	s_lshl_b64 s[12:13], s[40:41], 2
	s_nop 0
	v_addc_co_u32_e32 v81, vcc, 0, v199, vcc
	s_waitcnt lgkmcnt(0)
	global_store_dwordx4 v[80:81], v[76:79], off
	s_waitcnt vmcnt(12)
	ds_bpermute_b32 v76, v216, v72
	ds_bpermute_b32 v77, v216, v73
	ds_bpermute_b32 v78, v216, v74
	ds_bpermute_b32 v79, v216, v75
	s_add_u32 s30, s94, s12
	s_waitcnt lgkmcnt(3)
	v_cvt_f32_f16_e32 v72, v76
	v_cvt_f32_f16_sdwa v73, v76 dst_sel:DWORD dst_unused:UNUSED_PAD src0_sel:WORD_1
	s_waitcnt lgkmcnt(2)
	v_cvt_f32_f16_e32 v74, v77
	v_cvt_f32_f16_sdwa v75, v77 dst_sel:DWORD dst_unused:UNUSED_PAD src0_sel:WORD_1
	s_addc_u32 s31, s97, s13
	v_pk_fma_f32 v[20:21], v[20:21], v[116:117], v[72:73]
	s_waitcnt lgkmcnt(1)
	v_cvt_f32_f16_e32 v72, v78
	v_pk_fma_f32 v[22:23], v[22:23], v[118:119], v[74:75]
	v_cvt_f32_f16_sdwa v73, v78 dst_sel:DWORD dst_unused:UNUSED_PAD src0_sel:WORD_1
	s_waitcnt lgkmcnt(0)
	v_cvt_f32_f16_e32 v74, v79
	v_cvt_f32_f16_sdwa v75, v79 dst_sel:DWORD dst_unused:UNUSED_PAD src0_sel:WORD_1
	v_pk_fma_f32 v[16:17], v[16:17], v[108:109], v[72:73]
	v_cvt_pk_f16_f32 v73, v22, v23
	v_pk_fma_f32 v[18:19], v[18:19], v[110:111], v[74:75]
	v_cvt_pk_f16_f32 v74, v16, v17
	v_cvt_pk_f16_f32 v75, v18, v19
	v_cvt_pk_f16_f32 v72, v20, v21
	ds_bpermute_b32 v72, v214, v72
	ds_bpermute_b32 v73, v214, v73
	ds_bpermute_b32 v74, v214, v74
	ds_bpermute_b32 v75, v214, v75
	v_pk_mul_f32 v[76:77], v[182:183], v[18:19]
	v_pk_mul_f32 v[78:79], v[184:185], v[16:17]
	s_waitcnt lgkmcnt(0)
	global_store_dwordx4 v[154:155], v[72:75], off offset:256
	s_nop 1
	v_pk_mul_f32 v[72:73], v[178:179], v[22:23]
	v_pk_mul_f32 v[74:75], v[180:181], v[20:21]
	s_nop 0
	v_cvt_pk_bf16_f32 v74, v74, v75
	v_cvt_pk_bf16_f32 v73, v72, v73
	v_cvt_pk_bf16_f32 v75, v78, v79
	v_cvt_pk_bf16_f32 v76, v76, v77
	ds_bpermute_b32 v72, v214, v74
	ds_bpermute_b32 v73, v214, v73
	ds_bpermute_b32 v74, v214, v75
	ds_bpermute_b32 v75, v214, v76
	s_waitcnt lgkmcnt(0)
	global_store_dwordx4 v[80:81], v[72:75], off offset:256
	s_waitcnt vmcnt(13)
	ds_bpermute_b32 v72, v216, v68
	ds_bpermute_b32 v73, v216, v69
	ds_bpermute_b32 v74, v216, v70
	ds_bpermute_b32 v75, v216, v71
	s_waitcnt lgkmcnt(3)
	v_cvt_f32_f16_e32 v68, v72
	v_cvt_f32_f16_sdwa v69, v72 dst_sel:DWORD dst_unused:UNUSED_PAD src0_sel:WORD_1
	s_waitcnt lgkmcnt(2)
	v_cvt_f32_f16_e32 v70, v73
	v_cvt_f32_f16_sdwa v71, v73 dst_sel:DWORD dst_unused:UNUSED_PAD src0_sel:WORD_1
	v_pk_fma_f32 v[12:13], v[12:13], v[124:125], v[68:69]
	s_waitcnt lgkmcnt(1)
	v_cvt_f32_f16_e32 v68, v74
	v_pk_fma_f32 v[14:15], v[14:15], v[126:127], v[70:71]
	v_cvt_f32_f16_sdwa v69, v74 dst_sel:DWORD dst_unused:UNUSED_PAD src0_sel:WORD_1
	s_waitcnt lgkmcnt(0)
	v_cvt_f32_f16_e32 v70, v75
	v_cvt_f32_f16_sdwa v71, v75 dst_sel:DWORD dst_unused:UNUSED_PAD src0_sel:WORD_1
	v_pk_fma_f32 v[8:9], v[8:9], v[120:121], v[68:69]
	v_cvt_pk_f16_f32 v69, v14, v15
	v_pk_fma_f32 v[10:11], v[10:11], v[122:123], v[70:71]
	v_cvt_pk_f16_f32 v70, v8, v9
	v_cvt_pk_f16_f32 v71, v10, v11
	v_cvt_pk_f16_f32 v68, v12, v13
	ds_bpermute_b32 v68, v214, v68
	ds_bpermute_b32 v69, v214, v69
	ds_bpermute_b32 v70, v214, v70
	ds_bpermute_b32 v71, v214, v71
	v_pk_mul_f32 v[72:73], v[190:191], v[10:11]
	v_pk_mul_f32 v[74:75], v[196:197], v[8:9]
	s_waitcnt lgkmcnt(0)
	global_store_dwordx4 v[152:153], v[68:71], off offset:2048
	s_nop 1
	v_pk_mul_f32 v[68:69], v[186:187], v[14:15]
	v_pk_mul_f32 v[70:71], v[188:189], v[12:13]
	s_nop 0
	v_cvt_pk_bf16_f32 v70, v70, v71
	v_cvt_pk_bf16_f32 v69, v68, v69
	v_cvt_pk_bf16_f32 v71, v74, v75
	v_cvt_pk_bf16_f32 v72, v72, v73
	ds_bpermute_b32 v68, v214, v70
	ds_bpermute_b32 v69, v214, v69
	ds_bpermute_b32 v70, v214, v71
	ds_bpermute_b32 v71, v214, v72
	v_add_co_u32_e32 v72, vcc, s25, v198
	s_nop 1
	v_addc_co_u32_e32 v73, vcc, 0, v199, vcc
	s_waitcnt lgkmcnt(0)
	global_store_dwordx4 v[72:73], v[68:71], off offset:2048
	s_waitcnt vmcnt(14)
	ds_bpermute_b32 v68, v216, v64
	ds_bpermute_b32 v69, v216, v65
	ds_bpermute_b32 v70, v216, v66
	ds_bpermute_b32 v71, v216, v67
	s_waitcnt lgkmcnt(3)
	v_cvt_f32_f16_e32 v64, v68
	v_cvt_f32_f16_sdwa v65, v68 dst_sel:DWORD dst_unused:UNUSED_PAD src0_sel:WORD_1
	s_waitcnt lgkmcnt(2)
	v_cvt_f32_f16_e32 v66, v69
	v_cvt_f32_f16_sdwa v67, v69 dst_sel:DWORD dst_unused:UNUSED_PAD src0_sel:WORD_1
	v_pk_fma_f32 v[4:5], v[4:5], v[116:117], v[64:65]
	s_waitcnt lgkmcnt(1)
	v_cvt_f32_f16_e32 v64, v70
	v_pk_fma_f32 v[6:7], v[6:7], v[118:119], v[66:67]
	v_cvt_f32_f16_sdwa v65, v70 dst_sel:DWORD dst_unused:UNUSED_PAD src0_sel:WORD_1
	s_waitcnt lgkmcnt(0)
	v_cvt_f32_f16_e32 v66, v71
	v_cvt_f32_f16_sdwa v67, v71 dst_sel:DWORD dst_unused:UNUSED_PAD src0_sel:WORD_1
	v_pk_fma_f32 v[0:1], v[0:1], v[108:109], v[64:65]
	v_cvt_pk_f16_f32 v65, v6, v7
	v_pk_fma_f32 v[2:3], v[2:3], v[110:111], v[66:67]
	v_cvt_pk_f16_f32 v66, v0, v1
	v_cvt_pk_f16_f32 v67, v2, v3
	v_cvt_pk_f16_f32 v64, v4, v5
	ds_bpermute_b32 v64, v214, v64
	ds_bpermute_b32 v65, v214, v65
	ds_bpermute_b32 v66, v214, v66
	ds_bpermute_b32 v67, v214, v67
	v_pk_mul_f32 v[68:69], v[182:183], v[2:3]
	v_pk_mul_f32 v[70:71], v[184:185], v[0:1]
	s_waitcnt lgkmcnt(0)
	global_store_dwordx4 v[152:153], v[64:67], off offset:2304
	s_nop 1
	v_pk_mul_f32 v[64:65], v[178:179], v[6:7]
	v_pk_mul_f32 v[66:67], v[180:181], v[4:5]
	s_nop 0
	v_cvt_pk_bf16_f32 v66, v66, v67
	v_cvt_pk_bf16_f32 v65, v64, v65
	v_cvt_pk_bf16_f32 v67, v70, v71
	v_cvt_pk_bf16_f32 v68, v68, v69
	ds_bpermute_b32 v64, v214, v66
	ds_bpermute_b32 v65, v214, v65
	ds_bpermute_b32 v66, v214, v67
	ds_bpermute_b32 v67, v214, v68
	s_waitcnt lgkmcnt(0)
	global_store_dwordx4 v[72:73], v[64:67], off offset:2304
	s_waitcnt lgkmcnt(0)
	s_nop 1
	v_mov_b32_e32 v64, v168
	v_mov_b32_e32 v65, v168
	s_nop 1
	v_permlane16_swap_b32_e32 v64, v65
	v_add_f32_e32 v64, v64, v65
	v_mov_b32_e32 v65, v64
	s_nop 1
	v_permlane32_swap_b32_e32 v64, v65
	s_and_saveexec_b64 s[34:35], s[6:7]
	s_cbranch_execz .LBB0_1040
	v_lshlrev_b64 v[66:67], 7, v[176:177]
	v_lshl_add_u64 v[66:67], s[30:31], 0, v[66:67]
	s_waitcnt lgkmcnt(0)
	v_add_f32_e32 v64, v64, v65
	global_store_dword v[66:67], v64, off
; __device__ __forceinline__ float xlane(float v, int src_lane) { return __uint_as_float(__builtin_amdgcn_ds_bpermute(src_lane << 2, __float_as_uint(v))); }
;     __device__ __forceinline__ void operator()(AccT acc, const pg8::Unit& u, int wr, int wc, int fr, int fq) const {
;     ...
;                         t += ((h0[0] * h0[0] + h0[1] * h0[1]) + (h0[2] * h0[2] + h0[3] * h0[3])) + ((h1[0] * h1[0] + h1[1] * h1[1]) + (h1[2] * h1[2] + h1[3] * h1[3]));
;     ...
;         for (int g = 0; g < 8; ++g) { float t = ss[g]; t += xlane(t, lane ^ 16); t += xlane(t, lane ^ 32);
;             if (fq == 0) SSQ[(size_t)(row0 + (g >> 2) * 128 + (g & 3) * 16) * 32 + u.pn * 4 + wc] = t; }
.LBB0_1040:
	s_or_b64 exec, exec, s[34:35]
	v_mul_f32_e32 v64, v113, v113
	s_waitcnt lgkmcnt(0)
	v_mul_f32_e32 v65, v115, v115
	v_fmac_f32_e32 v64, v112, v112
	v_fmac_f32_e32 v65, v114, v114
	v_add_f32_e32 v64, v64, v65
	v_mul_f32_e32 v65, v105, v105
	v_mul_f32_e32 v66, v107, v107
	v_fmac_f32_e32 v65, v104, v104
	v_fmac_f32_e32 v66, v106, v106
	v_add_f32_e32 v65, v65, v66
	v_add_f32_e32 v64, v64, v65
	v_mul_f32_e32 v65, v101, v101
	v_mul_f32_e32 v66, v103, v103
	v_fmac_f32_e32 v65, v100, v100
	v_fmac_f32_e32 v66, v102, v102
	v_add_f32_e32 v65, v65, v66
	v_mul_f32_e32 v66, v97, v97
	v_mul_f32_e32 v67, v99, v99
	v_fmac_f32_e32 v66, v96, v96
	v_fmac_f32_e32 v67, v98, v98
	v_add_f32_e32 v66, v66, v67
	v_add_f32_e32 v65, v65, v66
	v_add_f32_e32 v64, v64, v65
	s_waitcnt lgkmcnt(0)
	v_mov_b32_e32 v65, v64
	s_nop 1
	v_permlane16_swap_b32_e32 v65, v64
	v_add_f32_e32 v64, v64, v65
	v_mov_b32_e32 v65, v64
	s_nop 1
	v_permlane32_swap_b32_e32 v64, v65
	s_and_saveexec_b64 s[34:35], s[6:7]
	s_cbranch_execz .LBB0_1042
	v_or_b32_e32 v66, 16, v176
	v_ashrrev_i32_e32 v67, 31, v66
	v_lshlrev_b64 v[66:67], 7, v[66:67]
	v_lshl_add_u64 v[66:67], s[30:31], 0, v[66:67]
	s_waitcnt lgkmcnt(0)
	v_add_f32_e32 v64, v64, v65
	global_store_dword v[66:67], v64, off
.LBB0_1042:
	s_or_b64 exec, exec, s[34:35]
	v_mul_f32_e32 v64, v93, v93
	s_waitcnt lgkmcnt(0)
	v_mul_f32_e32 v65, v95, v95
	v_fmac_f32_e32 v64, v92, v92
	v_fmac_f32_e32 v65, v94, v94
	v_add_f32_e32 v64, v64, v65
	v_mul_f32_e32 v65, v89, v89
	v_mul_f32_e32 v66, v91, v91
	v_fmac_f32_e32 v65, v88, v88
	v_fmac_f32_e32 v66, v90, v90
	v_add_f32_e32 v65, v65, v66
	v_add_f32_e32 v64, v64, v65
	v_mul_f32_e32 v65, v131, v131
	v_mul_f32_e32 v66, v129, v129
	v_fmac_f32_e32 v65, v130, v130
	v_fmac_f32_e32 v66, v128, v128
	v_add_f32_e32 v65, v65, v66
	v_mul_f32_e32 v66, v135, v135
	v_mul_f32_e32 v67, v133, v133
	v_fmac_f32_e32 v66, v134, v134
	v_fmac_f32_e32 v67, v132, v132
	v_add_f32_e32 v66, v66, v67
	v_add_f32_e32 v65, v65, v66
	v_add_f32_e32 v64, v64, v65
	s_waitcnt lgkmcnt(0)
	v_mov_b32_e32 v65, v64
	s_nop 1
	v_permlane16_swap_b32_e32 v65, v64
	v_add_f32_e32 v64, v64, v65
	v_mov_b32_e32 v65, v64
	s_nop 1
	v_permlane32_swap_b32_e32 v64, v65
	s_and_saveexec_b64 s[34:35], s[6:7]
	s_cbranch_execz .LBB0_1044
	v_or_b32_e32 v66, 32, v176
	v_ashrrev_i32_e32 v67, 31, v66
	v_lshlrev_b64 v[66:67], 7, v[66:67]
	v_lshl_add_u64 v[66:67], s[30:31], 0, v[66:67]
	s_waitcnt lgkmcnt(0)
	v_add_f32_e32 v64, v64, v65
	global_store_dword v[66:67], v64, off
.LBB0_1044:
	s_or_b64 exec, exec, s[34:35]
	v_mul_f32_e32 v64, v139, v139
	s_waitcnt lgkmcnt(0)
	v_mul_f32_e32 v65, v137, v137
	v_fmac_f32_e32 v64, v138, v138
	v_fmac_f32_e32 v65, v136, v136
	v_add_f32_e32 v64, v64, v65
	v_mul_f32_e32 v65, v143, v143
	v_mul_f32_e32 v66, v141, v141
	v_fmac_f32_e32 v65, v142, v142
	v_fmac_f32_e32 v66, v140, v140
	v_add_f32_e32 v65, v65, v66
	v_add_f32_e32 v64, v64, v65
	v_mul_f32_e32 v65, v147, v147
	v_mul_f32_e32 v66, v145, v145
	v_fmac_f32_e32 v65, v146, v146
	v_fmac_f32_e32 v66, v144, v144
	v_add_f32_e32 v65, v65, v66
	v_mul_f32_e32 v66, v151, v151
	v_mul_f32_e32 v67, v149, v149
	v_fmac_f32_e32 v66, v150, v150
	v_fmac_f32_e32 v67, v148, v148
	v_add_f32_e32 v66, v66, v67
	v_add_f32_e32 v65, v65, v66
	v_add_f32_e32 v64, v64, v65
	s_waitcnt lgkmcnt(0)
	v_mov_b32_e32 v65, v64
	s_nop 1
	v_permlane16_swap_b32_e32 v65, v64
	v_add_f32_e32 v64, v64, v65
	v_mov_b32_e32 v65, v64
	s_nop 1
	v_permlane32_swap_b32_e32 v64, v65
	s_and_saveexec_b64 s[34:35], s[6:7]
	s_cbranch_execz .LBB0_1046
	v_or_b32_e32 v66, 48, v176
	v_ashrrev_i32_e32 v67, 31, v66
	v_lshlrev_b64 v[66:67], 7, v[66:67]
	v_lshl_add_u64 v[66:67], s[30:31], 0, v[66:67]
	s_waitcnt lgkmcnt(0)
	v_add_f32_e32 v64, v64, v65
	global_store_dword v[66:67], v64, off
; __device__ __forceinline__ float xlane(float v, int src_lane) { return __uint_as_float(__builtin_amdgcn_ds_bpermute(src_lane << 2, __float_as_uint(v))); }
;     __device__ __forceinline__ void operator()(AccT acc, const pg8::Unit& u, int wr, int wc, int fr, int fq) const {
;     ...
;                         t += ((h0[0] * h0[0] + h0[1] * h0[1]) + (h0[2] * h0[2] + h0[3] * h0[3])) + ((h1[0] * h1[0] + h1[1] * h1[1]) + (h1[2] * h1[2] + h1[3] * h1[3]));
;     ...
;         for (int g = 0; g < 8; ++g) { float t = ss[g]; t += xlane(t, lane ^ 16); t += xlane(t, lane ^ 32);
;             if (fq == 0) SSQ[(size_t)(row0 + (g >> 2) * 128 + (g & 3) * 16) * 32 + u.pn * 4 + wc] = t; }
.LBB0_1046:
	s_or_b64 exec, exec, s[34:35]
	v_mul_f32_e32 v61, v61, v61
	v_mul_f32_e32 v57, v57, v57
	v_mul_f32_e32 v53, v53, v53
	v_mul_f32_e32 v49, v49, v49
	v_fmac_f32_e32 v61, v60, v60
	v_mul_f32_e32 v60, v63, v63
	v_fmac_f32_e32 v57, v56, v56
	v_mul_f32_e32 v56, v59, v59
	v_fmac_f32_e32 v53, v52, v52
	v_mul_f32_e32 v52, v55, v55
	v_fmac_f32_e32 v49, v48, v48
	v_mul_f32_e32 v48, v51, v51
	v_fmac_f32_e32 v60, v62, v62
	v_fmac_f32_e32 v56, v58, v58
	v_fmac_f32_e32 v52, v54, v54
	v_fmac_f32_e32 v48, v50, v50
	v_add_f32_e32 v60, v61, v60
	v_add_f32_e32 v56, v57, v56
	v_add_f32_e32 v52, v53, v52
	v_add_f32_e32 v48, v49, v48
	v_add_f32_e32 v56, v60, v56
	v_add_f32_e32 v48, v52, v48
	v_add_f32_e32 v48, v56, v48
	s_waitcnt lgkmcnt(0)
	v_mov_b32_e32 v49, v48
	s_nop 1
	v_permlane16_swap_b32_e32 v49, v48
	v_add_f32_e32 v48, v48, v49
	v_mov_b32_e32 v49, v48
	s_nop 1
	v_permlane32_swap_b32_e32 v48, v49
	s_and_saveexec_b64 s[34:35], s[6:7]
	s_cbranch_execz .LBB0_1048
	v_lshlrev_b64 v[50:51], 7, v[176:177]
	v_lshl_add_u64 v[50:51], s[30:31], 0, v[50:51]
	s_waitcnt lgkmcnt(0)
	v_add_f32_e32 v52, v48, v49
	v_add_co_u32_e32 v48, vcc, 0x4000, v50
	s_nop 1
	v_addc_co_u32_e32 v49, vcc, 0, v51, vcc
	global_store_dword v[48:49], v52, off
.LBB0_1048:
	s_or_b64 exec, exec, s[34:35]
	v_mul_f32_e32 v45, v45, v45
	v_mul_f32_e32 v41, v41, v41
	v_mul_f32_e32 v37, v37, v37
	v_mul_f32_e32 v33, v33, v33
	v_fmac_f32_e32 v45, v44, v44
	v_mul_f32_e32 v44, v47, v47
	v_fmac_f32_e32 v41, v40, v40
	v_mul_f32_e32 v40, v43, v43
	v_fmac_f32_e32 v37, v36, v36
	v_mul_f32_e32 v36, v39, v39
	v_fmac_f32_e32 v33, v32, v32
	v_mul_f32_e32 v32, v35, v35
	v_fmac_f32_e32 v44, v46, v46
	v_fmac_f32_e32 v40, v42, v42
	v_fmac_f32_e32 v36, v38, v38
	v_fmac_f32_e32 v32, v34, v34
	v_add_f32_e32 v44, v45, v44
	v_add_f32_e32 v40, v41, v40
	v_add_f32_e32 v36, v37, v36
	v_add_f32_e32 v32, v33, v32
	v_add_f32_e32 v40, v44, v40
	v_add_f32_e32 v32, v36, v32
	v_add_f32_e32 v32, v40, v32
	s_waitcnt lgkmcnt(0)
	v_mov_b32_e32 v33, v32
	s_nop 1
	v_permlane16_swap_b32_e32 v33, v32
	v_add_f32_e32 v32, v32, v33
	v_mov_b32_e32 v33, v32
	s_nop 1
	v_permlane32_swap_b32_e32 v32, v33
	s_and_saveexec_b64 s[34:35], s[6:7]
	s_cbranch_execz .LBB0_1050
	v_lshlrev_b64 v[34:35], 7, v[176:177]
	v_lshl_add_u64 v[34:35], s[30:31], 0, v[34:35]
	s_waitcnt lgkmcnt(0)
	v_add_f32_e32 v36, v32, v33
	v_add_co_u32_e32 v32, vcc, 0x4000, v34
	s_nop 1
	v_addc_co_u32_e32 v33, vcc, 0, v35, vcc
	global_store_dword v[32:33], v36, off offset:2048
.LBB0_1050:
	s_or_b64 exec, exec, s[34:35]
	v_mul_f32_e32 v29, v29, v29
	v_mul_f32_e32 v25, v25, v25
	v_mul_f32_e32 v21, v21, v21
	v_mul_f32_e32 v17, v17, v17
	v_fmac_f32_e32 v29, v28, v28
	v_mul_f32_e32 v28, v31, v31
	v_fmac_f32_e32 v25, v24, v24
	v_mul_f32_e32 v24, v27, v27
	v_fmac_f32_e32 v21, v20, v20
	v_mul_f32_e32 v20, v23, v23
	v_fmac_f32_e32 v17, v16, v16
	v_mul_f32_e32 v16, v19, v19
	v_fmac_f32_e32 v28, v30, v30
	v_fmac_f32_e32 v24, v26, v26
	v_fmac_f32_e32 v20, v22, v22
	v_fmac_f32_e32 v16, v18, v18
	v_add_f32_e32 v28, v29, v28
	v_add_f32_e32 v24, v25, v24
	v_add_f32_e32 v20, v21, v20
	v_add_f32_e32 v16, v17, v16
	v_add_f32_e32 v24, v28, v24
	v_add_f32_e32 v16, v20, v16
	v_add_f32_e32 v16, v24, v16
	s_waitcnt lgkmcnt(0)
	v_mov_b32_e32 v17, v16
	s_nop 1
	v_permlane16_swap_b32_e32 v17, v16
	v_add_f32_e32 v16, v16, v17
	v_mov_b32_e32 v17, v16
	s_nop 1
	v_permlane32_swap_b32_e32 v16, v17
	s_and_saveexec_b64 s[34:35], s[6:7]
	s_cbranch_execz .LBB0_1052
	v_lshlrev_b64 v[18:19], 7, v[176:177]
	v_lshl_add_u64 v[18:19], s[30:31], 0, v[18:19]
	s_waitcnt lgkmcnt(0)
	v_add_f32_e32 v20, v16, v17
	v_add_co_u32_e32 v16, vcc, 0x5000, v18
	s_nop 1
	v_addc_co_u32_e32 v17, vcc, 0, v19, vcc
	global_store_dword v[16:17], v20, off
.LBB0_1052:
	s_or_b64 exec, exec, s[34:35]
	v_mul_f32_e32 v13, v13, v13
	v_mul_f32_e32 v9, v9, v9
	v_mul_f32_e32 v5, v5, v5
	v_mul_f32_e32 v1, v1, v1
	v_fmac_f32_e32 v13, v12, v12
	v_mul_f32_e32 v12, v15, v15
	v_fmac_f32_e32 v9, v8, v8
	v_mul_f32_e32 v8, v11, v11
	v_fmac_f32_e32 v5, v4, v4
	v_mul_f32_e32 v4, v7, v7
	v_fmac_f32_e32 v1, v0, v0
	v_mul_f32_e32 v0, v3, v3
	v_fmac_f32_e32 v12, v14, v14
	v_fmac_f32_e32 v8, v10, v10
	v_fmac_f32_e32 v4, v6, v6
	v_fmac_f32_e32 v0, v2, v2
	v_add_f32_e32 v12, v13, v12
	v_add_f32_e32 v8, v9, v8
	v_add_f32_e32 v4, v5, v4
	v_add_f32_e32 v0, v1, v0
	v_add_f32_e32 v8, v12, v8
	v_add_f32_e32 v0, v4, v0
	v_add_f32_e32 v0, v8, v0
	s_waitcnt lgkmcnt(0)
	v_mov_b32_e32 v1, v0
	s_nop 1
	v_permlane16_swap_b32_e32 v1, v0
	v_add_f32_e32 v0, v0, v1
	v_mov_b32_e32 v1, v0
	s_nop 1
	v_permlane32_swap_b32_e32 v0, v1
	s_and_saveexec_b64 s[34:35], s[6:7]
	s_cbranch_execz .LBB0_1054
	v_lshlrev_b64 v[2:3], 7, v[176:177]
	v_lshl_add_u64 v[2:3], s[30:31], 0, v[2:3]
	s_waitcnt lgkmcnt(0)
	v_add_f32_e32 v4, v0, v1
	v_add_co_u32_e32 v0, vcc, 0x5000, v2
	s_nop 1
	v_addc_co_u32_e32 v1, vcc, 0, v3, vcc
	global_store_dword v[0:1], v4, off offset:2048

;     __device__ __forceinline__ void operator()(AccT acc, const pg8::Unit& u, int wr, int wc, int fr, int fq) const {
;         const int row0 = u.pm * 256 + wr * 64 + fr, col0 = u.pn * 256 + wc * 32 + 8 * fq, lane = fq * 16 + fr;
;         const int bidx = u.pm < 64 ? (u.pm >> 4) : 4;
;         const float* gp = gate + (size_t)bidx * MODW + col0;
;         f32x4 gv[2][2], gz[2][2];
; #pragma unroll
;         for (int bj = 0; bj < 2; ++bj)
; #pragma unroll
;             for (int n = 0; n < 2; ++n) { gv[bj][n] = *(const f32x4*)(gp + bj * 128 + n * 4) * coef;
;                 if (WZ) gz[bj][n] = *(const f32x4*)(gnext + col0 + bj * 128 + n * 4) * (*(const f32x4*)(scnext + (size_t)bidx * MODW + col0 + bj * 128 + n * 4) + 1.f); }
;         const int st4 = ((lane & 3) * 16 + (lane >> 2)) * 4, ld4 = ((lane & 15) * 4 + (lane >> 4)) * 4;
;         const size_t eo = (size_t)(u.pm * 256 + wr * 64 + (lane >> 2)) * LDP + u.pn * 256 + wc * 32 + (lane & 3) * 8;
;         hf_t* hout = H + eo; bf16_t* zout = Z + eo; float ss[8];
;         if constexpr (B32) {
;             const float* base = (const float*)(u.pm < 64 ? baseL : baseC) + (size_t)row0 * D + col0;
;             f32x4 hb[4][2][2];
; #pragma unroll
;             for (int ai = 0; ai < 2; ++ai) {
; #pragma unroll
;                 for (int m = 0; m < 4; ++m)
; #pragma unroll
;                     for (int bj = 0; bj < 2; ++bj)
; #pragma unroll
;                         for (int n = 0; n < 2; ++n) hb[m][bj][n] = *(const f32x4*)(base + (size_t)(ai * 128 + m * 16) * D + bj * 128 + n * 4);
;                 asm volatile("" ::: "memory");
; #pragma unroll
;                 for (int m = 0; m < 4; ++m) { const size_t ro = (size_t)(ai * 128 + m * 16) * LDP; float t = 0.f;
; #pragma unroll
;                     for (int bj = 0; bj < 2; ++bj) { const f32x4 h0 = hb[m][bj][0] + gv[bj][0] * acc[ai][bj][m][0], h1 = hb[m][bj][1] + gv[bj][1] * acc[ai][bj][m][1];
;                         const h16x4 q0 = __builtin_convertvector(h0, h16x4), q1 = __builtin_convertvector(h1, h16x4);
;                         { const h16x8 hv8 = (h16x8){q0[0], q0[1], q0[2], q0[3], q1[0], q1[1], q1[2], q1[3]}; *(u32x4*)(hout + ro + bj * 128) = gather4(__builtin_bit_cast(u32x4, hv8), st4); }
.LBB0_1247:
	s_lshl_b32 s2, s40, 8
	s_add_i32 s2, s2, s43
	s_lshl_b32 s22, s60, 8
	s_lshr_b32 s20, s40, 4
	s_cmp_lt_u32 s40, 64
	s_mulk_i32 s20, 0x4800
	s_cselect_b32 s40, s20, 0x12000
	s_lshl_b64 s[20:21], s[40:41], 2
	s_add_u32 s20, s37, s20
	v_or_b32_e32 v192, s22, v187
	s_addc_u32 s21, s42, s21
	v_lshl_add_u64 v[136:137], v[192:193], 2, s[20:21]
	global_load_dwordx4 v[128:131], v[136:137], off offset:16
	global_load_dwordx4 v[132:135], v[136:137], off
	v_or_b32_e32 v156, s2, v186
	s_lshl_b32 s40, s60, 2
	s_waitcnt vmcnt(0)
	v_pk_mul_f32 v[168:169], v[130:131], 0.5 op_sel_hi:[1,0]
	v_pk_mul_f32 v[170:171], v[134:135], 0.5 op_sel_hi:[1,0]
	v_pk_mul_f32 v[172:173], v[132:133], 0.5 op_sel_hi:[1,0]
	v_pk_mul_f32 v[166:167], v[128:129], 0.5 op_sel_hi:[1,0]
	global_load_dwordx4 v[128:131], v[136:137], off offset:528
	global_load_dwordx4 v[132:135], v[136:137], off offset:512
	s_waitcnt vmcnt(1)
	v_pk_mul_f32 v[160:161], v[130:131], 0.5 op_sel_hi:[1,0]
	v_pk_mul_f32 v[158:159], v[128:129], 0.5 op_sel_hi:[1,0]
	v_or_b32_e32 v130, s2, v188
	v_or_b32_e32 v131, s22, v191
	v_mov_b64_e32 v[128:129], s[10:11]
	v_mad_i64_i32 v[128:129], s[20:21], v130, s66, v[128:129]
	v_lshlrev_b32_e32 v192, 1, v131
	v_lshl_add_u64 v[174:175], v[128:129], 0, v[192:193]
	global_load_dwordx4 v[198:201], v[174:175], off
	global_load_dwordx4 v[152:155], v[174:175], off offset:256
	s_mov_b32 s2, 0x10000
	v_add_co_u32_e32 v180, vcc, s2, v174
	s_mov_b32 s2, 0x21000
	s_nop 0
	v_addc_co_u32_e32 v181, vcc, 0, v175, vcc
	global_load_dwordx4 v[148:151], v[180:181], off offset:2048
	global_load_dwordx4 v[144:147], v[180:181], off offset:2304
	v_add_co_u32_e32 v178, vcc, s2, v174
	s_mov_b32 s2, 0x31000
	s_nop 0
	v_addc_co_u32_e32 v179, vcc, 0, v175, vcc
	global_load_dwordx4 v[140:143], v[178:179], off
	global_load_dwordx4 v[136:139], v[178:179], off offset:256
	v_add_co_u32_e32 v176, vcc, s2, v174
	s_waitcnt vmcnt(6)
	v_pk_mul_f32 v[162:163], v[134:135], 0.5 op_sel_hi:[1,0]
	v_addc_co_u32_e32 v177, vcc, 0, v175, vcc
	v_pk_mul_f32 v[164:165], v[132:133], 0.5 op_sel_hi:[1,0]
	global_load_dwordx4 v[132:135], v[176:177], off offset:2048
	global_load_dwordx4 v[128:131], v[176:177], off offset:2304
	s_mov_b32 s2, 0x84000
	s_lshl_b64 s[20:21], s[40:41], 2
	s_add_u32 s20, s54, s20
	s_addc_u32 s21, s55, s21
	s_waitcnt vmcnt(7)
	ds_bpermute_b32 v157, v190, v198
	ds_bpermute_b32 v192, v190, v199
	ds_bpermute_b32 v202, v190, v200
	ds_bpermute_b32 v203, v190, v201
	s_waitcnt lgkmcnt(3)
	v_cvt_f32_f16_e32 v198, v157
	v_cvt_f32_f16_sdwa v199, v157 dst_sel:DWORD dst_unused:UNUSED_PAD src0_sel:WORD_1
	s_waitcnt lgkmcnt(2)
	v_cvt_f32_f16_e32 v200, v192
	v_cvt_f32_f16_sdwa v201, v192 dst_sel:DWORD dst_unused:UNUSED_PAD src0_sel:WORD_1
	v_pk_fma_f32 v[124:125], v[124:125], v[172:173], v[198:199]
	s_waitcnt lgkmcnt(1)
	v_cvt_f32_f16_e32 v198, v202
	v_pk_fma_f32 v[126:127], v[126:127], v[170:171], v[200:201]
	v_cvt_f32_f16_sdwa v199, v202 dst_sel:DWORD dst_unused:UNUSED_PAD src0_sel:WORD_1
	s_waitcnt lgkmcnt(0)
	v_cvt_f32_f16_e32 v200, v203
	v_cvt_f32_f16_sdwa v201, v203 dst_sel:DWORD dst_unused:UNUSED_PAD src0_sel:WORD_1
	v_pk_fma_f32 v[198:199], v[120:121], v[166:167], v[198:199]
	v_cvt_pk_f16_f32 v121, v126, v127
	v_pk_fma_f32 v[200:201], v[122:123], v[168:169], v[200:201]
	v_cvt_pk_f16_f32 v122, v198, v199
	v_cvt_pk_f16_f32 v123, v200, v201
	v_cvt_pk_f16_f32 v120, v124, v125
	ds_bpermute_b32 v120, v189, v120
	ds_bpermute_b32 v121, v189, v121
	ds_bpermute_b32 v122, v189, v122
	ds_bpermute_b32 v123, v189, v123
	s_waitcnt lgkmcnt(0)
	global_store_dwordx4 v[174:175], v[120:123], off
	s_nop 1
	v_mul_f32_e32 v120, v125, v125
	v_mul_f32_e32 v121, v127, v127
	v_fmac_f32_e32 v120, v124, v124
	v_fmac_f32_e32 v121, v126, v126
	v_add_f32_e32 v120, v120, v121
	v_mul_f32_e32 v121, v199, v199
	v_mul_f32_e32 v122, v201, v201
	v_fmac_f32_e32 v121, v198, v198
	v_fmac_f32_e32 v122, v200, v200
	v_add_f32_e32 v121, v121, v122
	v_add_f32_e32 v124, v120, v121
	s_waitcnt vmcnt(7)
	ds_bpermute_b32 v121, v190, v152
	ds_bpermute_b32 v123, v190, v153
	ds_bpermute_b32 v125, v190, v154
	ds_bpermute_b32 v126, v190, v155
	s_waitcnt lgkmcnt(3)
	v_cvt_f32_f16_e32 v120, v121
	v_cvt_f32_f16_sdwa v121, v121 dst_sel:DWORD dst_unused:UNUSED_PAD src0_sel:WORD_1
	s_waitcnt lgkmcnt(2)
	v_cvt_f32_f16_e32 v122, v123
	v_cvt_f32_f16_sdwa v123, v123 dst_sel:DWORD dst_unused:UNUSED_PAD src0_sel:WORD_1
	v_pk_fma_f32 v[116:117], v[116:117], v[164:165], v[120:121]
	s_waitcnt lgkmcnt(1)
	v_cvt_f32_f16_e32 v120, v125
	v_pk_fma_f32 v[118:119], v[118:119], v[162:163], v[122:123]
	v_cvt_f32_f16_sdwa v121, v125 dst_sel:DWORD dst_unused:UNUSED_PAD src0_sel:WORD_1
	s_waitcnt lgkmcnt(0)
	v_cvt_f32_f16_e32 v122, v126
	v_cvt_f32_f16_sdwa v123, v126 dst_sel:DWORD dst_unused:UNUSED_PAD src0_sel:WORD_1
	v_pk_fma_f32 v[120:121], v[112:113], v[158:159], v[120:121]
	v_cvt_pk_f16_f32 v113, v118, v119
	v_pk_fma_f32 v[122:123], v[114:115], v[160:161], v[122:123]
	v_cvt_pk_f16_f32 v114, v120, v121
	v_cvt_pk_f16_f32 v115, v122, v123
	v_cvt_pk_f16_f32 v112, v116, v117
	ds_bpermute_b32 v112, v189, v112
	ds_bpermute_b32 v113, v189, v113
	ds_bpermute_b32 v114, v189, v114
	ds_bpermute_b32 v115, v189, v115
	s_waitcnt lgkmcnt(0)
	global_store_dwordx4 v[174:175], v[112:115], off offset:256
	s_nop 1
	v_mul_f32_e32 v112, v117, v117
	v_mul_f32_e32 v113, v119, v119
	v_fmac_f32_e32 v112, v116, v116
	v_fmac_f32_e32 v113, v118, v118
	v_add_f32_e32 v112, v112, v113
	v_mul_f32_e32 v113, v121, v121
	v_mul_f32_e32 v114, v123, v123
	v_fmac_f32_e32 v113, v120, v120
	v_fmac_f32_e32 v114, v122, v122
	v_add_f32_e32 v113, v113, v114
	v_add_f32_e32 v112, v112, v113
	s_waitcnt vmcnt(7)
;     __device__ __forceinline__ void operator()(AccT acc, const pg8::Unit& u, int wr, int wc, int fr, int fq) const {
;     ...
;                 for (int m = 0; m < 4; ++m) { const size_t ro = (size_t)(ai * 128 + m * 16) * LDP; float t = 0.f;
; #pragma unroll
;                     for (int bj = 0; bj < 2; ++bj) { const h16x8 b8 = __builtin_bit_cast(h16x8, gather4(__builtin_bit_cast(u32x4, hb[m][bj]), ld4));
;                         const f32x4 h0 = (f32x4){(float)b8[0], (float)b8[1], (float)b8[2], (float)b8[3]} + gv[bj][0] * acc[ai][bj][m][0], h1 = (f32x4){(float)b8[4], (float)b8[5], (float)b8[6], (float)b8[7]} + gv[bj][1] * acc[ai][bj][m][1];
;                         const h16x4 q0 = __builtin_convertvector(h0, h16x4), q1 = __builtin_convertvector(h1, h16x4);
;                         { const h16x8 hv8 = (h16x8){q0[0], q0[1], q0[2], q0[3], q1[0], q1[1], q1[2], q1[3]}; *(u32x4*)(hout + ro + bj * 128) = gather4(__builtin_bit_cast(u32x4, hv8), st4); }
;                         t += ((h0[0] * h0[0] + h0[1] * h0[1]) + (h0[2] * h0[2] + h0[3] * h0[3])) + ((h1[0] * h1[0] + h1[1] * h1[1]) + (h1[2] * h1[2] + h1[3] * h1[3]));
	ds_bpermute_b32 v113, v190, v148
	ds_bpermute_b32 v115, v190, v149
	ds_bpermute_b32 v116, v190, v150
	ds_bpermute_b32 v117, v190, v151
	v_add_f32_e32 v152, v124, v112
	s_waitcnt lgkmcnt(3)
	v_cvt_f32_f16_e32 v112, v113
	v_cvt_f32_f16_sdwa v113, v113 dst_sel:DWORD dst_unused:UNUSED_PAD src0_sel:WORD_1
	s_waitcnt lgkmcnt(2)
	v_cvt_f32_f16_e32 v114, v115
	v_cvt_f32_f16_sdwa v115, v115 dst_sel:DWORD dst_unused:UNUSED_PAD src0_sel:WORD_1
	v_pk_fma_f32 v[108:109], v[108:109], v[172:173], v[112:113]
	s_waitcnt lgkmcnt(1)
	v_cvt_f32_f16_e32 v112, v116
	v_pk_fma_f32 v[110:111], v[110:111], v[170:171], v[114:115]
	v_cvt_f32_f16_sdwa v113, v116 dst_sel:DWORD dst_unused:UNUSED_PAD src0_sel:WORD_1
	s_waitcnt lgkmcnt(0)
	v_cvt_f32_f16_e32 v114, v117
	v_cvt_f32_f16_sdwa v115, v117 dst_sel:DWORD dst_unused:UNUSED_PAD src0_sel:WORD_1
	s_waitcnt vmcnt(6)
	ds_bpermute_b32 v116, v190, v146
	v_pk_fma_f32 v[104:105], v[104:105], v[166:167], v[112:113]
	v_cvt_pk_f16_f32 v113, v110, v111
	v_pk_fma_f32 v[106:107], v[106:107], v[168:169], v[114:115]
	v_cvt_pk_f16_f32 v114, v104, v105
	v_cvt_pk_f16_f32 v115, v106, v107
	v_cvt_pk_f16_f32 v112, v108, v109
	ds_bpermute_b32 v112, v189, v112
	ds_bpermute_b32 v113, v189, v113
	ds_bpermute_b32 v114, v189, v114
	ds_bpermute_b32 v115, v189, v115
	ds_bpermute_b32 v117, v190, v147
	s_waitcnt lgkmcnt(1)
	global_store_dwordx4 v[180:181], v[112:115], off offset:2048
	ds_bpermute_b32 v113, v190, v144
	ds_bpermute_b32 v115, v190, v145
	s_waitcnt lgkmcnt(1)
	v_cvt_f32_f16_e32 v112, v113
	v_cvt_f32_f16_sdwa v113, v113 dst_sel:DWORD dst_unused:UNUSED_PAD src0_sel:WORD_1
	s_waitcnt lgkmcnt(0)
	v_cvt_f32_f16_e32 v114, v115
	v_cvt_f32_f16_sdwa v115, v115 dst_sel:DWORD dst_unused:UNUSED_PAD src0_sel:WORD_1
	v_pk_fma_f32 v[100:101], v[100:101], v[164:165], v[112:113]
	v_cvt_f32_f16_e32 v112, v116
	v_pk_fma_f32 v[102:103], v[102:103], v[162:163], v[114:115]
	v_cvt_f32_f16_sdwa v113, v116 dst_sel:DWORD dst_unused:UNUSED_PAD src0_sel:WORD_1
	v_cvt_f32_f16_e32 v114, v117
	v_cvt_f32_f16_sdwa v115, v117 dst_sel:DWORD dst_unused:UNUSED_PAD src0_sel:WORD_1
	s_waitcnt vmcnt(6)
	ds_bpermute_b32 v116, v190, v142
	v_pk_fma_f32 v[96:97], v[96:97], v[158:159], v[112:113]
	v_cvt_pk_f16_f32 v113, v102, v103
	v_pk_fma_f32 v[98:99], v[98:99], v[160:161], v[114:115]
	v_cvt_pk_f16_f32 v114, v96, v97
	v_cvt_pk_f16_f32 v115, v98, v99
	v_cvt_pk_f16_f32 v112, v100, v101
	ds_bpermute_b32 v112, v189, v112
	ds_bpermute_b32 v113, v189, v113
	ds_bpermute_b32 v114, v189, v114
	ds_bpermute_b32 v115, v189, v115
	ds_bpermute_b32 v117, v190, v143
	v_add_co_u32_e32 v142, vcc, s2, v174
	s_mov_b32 s2, 0x94000
	s_waitcnt lgkmcnt(1)
	global_store_dwordx4 v[180:181], v[112:115], off offset:2304
	ds_bpermute_b32 v113, v190, v140
	ds_bpermute_b32 v115, v190, v141
	v_addc_co_u32_e32 v143, vcc, 0, v175, vcc
	v_add_co_u32_e32 v140, vcc, s2, v174
	s_waitcnt lgkmcnt(1)
	v_cvt_f32_f16_e32 v112, v113
	v_cvt_f32_f16_sdwa v113, v113 dst_sel:DWORD dst_unused:UNUSED_PAD src0_sel:WORD_1
	s_waitcnt lgkmcnt(0)
	v_cvt_f32_f16_e32 v114, v115
	v_cvt_f32_f16_sdwa v115, v115 dst_sel:DWORD dst_unused:UNUSED_PAD src0_sel:WORD_1
	v_addc_co_u32_e32 v141, vcc, 0, v175, vcc
	v_pk_fma_f32 v[92:93], v[92:93], v[172:173], v[112:113]
	v_pk_fma_f32 v[94:95], v[94:95], v[170:171], v[114:115]
	v_cvt_f32_f16_e32 v112, v116
	v_cvt_f32_f16_sdwa v113, v116 dst_sel:DWORD dst_unused:UNUSED_PAD src0_sel:WORD_1
	v_cvt_f32_f16_e32 v114, v117
	v_cvt_f32_f16_sdwa v115, v117 dst_sel:DWORD dst_unused:UNUSED_PAD src0_sel:WORD_1
	s_waitcnt vmcnt(6)
	ds_bpermute_b32 v116, v190, v138
	v_pk_fma_f32 v[88:89], v[88:89], v[166:167], v[112:113]
	v_cvt_pk_f16_f32 v113, v94, v95
	v_pk_fma_f32 v[90:91], v[90:91], v[168:169], v[114:115]
	v_cvt_pk_f16_f32 v114, v88, v89
	v_cvt_pk_f16_f32 v115, v90, v91
	v_cvt_pk_f16_f32 v112, v92, v93
	ds_bpermute_b32 v112, v189, v112
	ds_bpermute_b32 v113, v189, v113
	ds_bpermute_b32 v114, v189, v114
	ds_bpermute_b32 v115, v189, v115
	ds_bpermute_b32 v117, v190, v139
	s_mov_b32 s2, 0xa5000
	v_add_co_u32_e32 v138, vcc, s2, v174
	s_waitcnt lgkmcnt(1)
	global_store_dwordx4 v[178:179], v[112:115], off
	ds_bpermute_b32 v112, v190, v136
	ds_bpermute_b32 v113, v190, v137
	v_addc_co_u32_e32 v139, vcc, 0, v175, vcc
	s_mov_b32 s2, 0xb5000
	s_waitcnt lgkmcnt(1)
	v_cvt_f32_f16_e32 v114, v112
	v_cvt_f32_f16_sdwa v115, v112 dst_sel:DWORD dst_unused:UNUSED_PAD src0_sel:WORD_1
	s_waitcnt lgkmcnt(0)
	v_cvt_f32_f16_e32 v112, v113
	v_cvt_f32_f16_sdwa v113, v113 dst_sel:DWORD dst_unused:UNUSED_PAD src0_sel:WORD_1
	v_add_co_u32_e32 v136, vcc, s2, v174
	v_pk_fma_f32 v[114:115], v[84:85], v[164:165], v[114:115]
	v_pk_fma_f32 v[112:113], v[86:87], v[162:163], v[112:113]
	v_cvt_f32_f16_e32 v84, v116
	v_cvt_f32_f16_sdwa v85, v116 dst_sel:DWORD dst_unused:UNUSED_PAD src0_sel:WORD_1
	v_cvt_f32_f16_e32 v86, v117
	v_cvt_f32_f16_sdwa v87, v117 dst_sel:DWORD dst_unused:UNUSED_PAD src0_sel:WORD_1
	v_addc_co_u32_e32 v137, vcc, 0, v175, vcc
	v_pk_fma_f32 v[118:119], v[80:81], v[158:159], v[84:85]
	v_pk_fma_f32 v[116:117], v[82:83], v[160:161], v[86:87]
	v_cvt_pk_f16_f32 v82, v118, v119
	v_cvt_pk_f16_f32 v83, v116, v117
	v_cvt_pk_f16_f32 v81, v112, v113
	v_cvt_pk_f16_f32 v80, v114, v115
	ds_bpermute_b32 v80, v189, v80
	ds_bpermute_b32 v81, v189, v81
	ds_bpermute_b32 v82, v189, v82
	ds_bpermute_b32 v83, v189, v83
	s_waitcnt vmcnt(6)
	ds_bpermute_b32 v84, v190, v134
	ds_bpermute_b32 v85, v190, v135
	s_waitcnt lgkmcnt(2)
	global_store_dwordx4 v[178:179], v[80:83], off offset:256
	ds_bpermute_b32 v81, v190, v132
	ds_bpermute_b32 v83, v190, v133
	s_waitcnt lgkmcnt(1)
	v_cvt_f32_f16_e32 v80, v81
	v_cvt_f32_f16_sdwa v81, v81 dst_sel:DWORD dst_unused:UNUSED_PAD src0_sel:WORD_1
	s_waitcnt lgkmcnt(0)
; __device__ __forceinline__ unsigned cvt_pk_bf16(float lo, float hi) { unsigned r; asm volatile("v_cvt_pk_bf16_f32 %0, %1, %2" : "=v"(r) : "v"(lo), "v"(hi)); return r; }
;     __device__ __forceinline__ void operator()(AccT acc, const pg8::Unit& u, int wr, int wc, int fr, int fq) const {
;     ...
;                 for (int m = 0; m < 4; ++m) { const size_t ro = (size_t)(ai * 128 + m * 16) * LDP; float t = 0.f;
; #pragma unroll
;                     for (int bj = 0; bj < 2; ++bj) { const h16x8 b8 = __builtin_bit_cast(h16x8, gather4(__builtin_bit_cast(u32x4, hb[m][bj]), ld4));
;                         const f32x4 h0 = (f32x4){(float)b8[0], (float)b8[1], (float)b8[2], (float)b8[3]} + gv[bj][0] * acc[ai][bj][m][0], h1 = (f32x4){(float)b8[4], (float)b8[5], (float)b8[6], (float)b8[7]} + gv[bj][1] * acc[ai][bj][m][1];
;                         const h16x4 q0 = __builtin_convertvector(h0, h16x4), q1 = __builtin_convertvector(h1, h16x4);
;                         { const h16x8 hv8 = (h16x8){q0[0], q0[1], q0[2], q0[3], q1[0], q1[1], q1[2], q1[3]}; *(u32x4*)(hout + ro + bj * 128) = gather4(__builtin_bit_cast(u32x4, hv8), st4); }
;                         t += ((h0[0] * h0[0] + h0[1] * h0[1]) + (h0[2] * h0[2] + h0[3] * h0[3])) + ((h1[0] * h1[0] + h1[1] * h1[1]) + (h1[2] * h1[2] + h1[3] * h1[3]));
;                         if (WZ) { const f32x4 z0 = h0 * gz[bj][0], z1 = h1 * gz[bj][1]; u32x4 w; w.x = cvt_pk_bf16(z0[0], z0[1]); w.y = cvt_pk_bf16(z0[2], z0[3]); w.z = cvt_pk_bf16(z1[0], z1[1]); w.w = cvt_pk_bf16(z1[2], z1[3]);
;                             *(u32x4*)(zout + ro + bj * 128) = gather4(w, st4); } }
	v_cvt_f32_f16_e32 v82, v83
	v_cvt_f32_f16_sdwa v83, v83 dst_sel:DWORD dst_unused:UNUSED_PAD src0_sel:WORD_1
	v_pk_fma_f32 v[122:123], v[76:77], v[172:173], v[80:81]
	v_cvt_f32_f16_e32 v76, v84
	v_pk_fma_f32 v[120:121], v[78:79], v[170:171], v[82:83]
	v_cvt_f32_f16_sdwa v77, v84 dst_sel:DWORD dst_unused:UNUSED_PAD src0_sel:WORD_1
	v_cvt_f32_f16_e32 v78, v85
	v_cvt_f32_f16_sdwa v79, v85 dst_sel:DWORD dst_unused:UNUSED_PAD src0_sel:WORD_1
	v_pk_fma_f32 v[126:127], v[72:73], v[166:167], v[76:77]
	v_cvt_pk_f16_f32 v73, v120, v121
	v_pk_fma_f32 v[124:125], v[74:75], v[168:169], v[78:79]
	v_cvt_pk_f16_f32 v74, v126, v127
	v_cvt_pk_f16_f32 v75, v124, v125
	v_cvt_pk_f16_f32 v72, v122, v123
	ds_bpermute_b32 v72, v189, v72
	ds_bpermute_b32 v73, v189, v73
	ds_bpermute_b32 v74, v189, v74
	ds_bpermute_b32 v75, v189, v75
	s_waitcnt vmcnt(6)
	ds_bpermute_b32 v76, v190, v130
	ds_bpermute_b32 v77, v190, v131
	s_waitcnt lgkmcnt(2)
	global_store_dwordx4 v[176:177], v[72:75], off offset:2048
	ds_bpermute_b32 v73, v190, v128
	ds_bpermute_b32 v75, v190, v129
	s_waitcnt lgkmcnt(1)
	v_cvt_f32_f16_e32 v72, v73
	v_cvt_f32_f16_sdwa v73, v73 dst_sel:DWORD dst_unused:UNUSED_PAD src0_sel:WORD_1
	s_waitcnt lgkmcnt(0)
	v_cvt_f32_f16_e32 v74, v75
	v_cvt_f32_f16_sdwa v75, v75 dst_sel:DWORD dst_unused:UNUSED_PAD src0_sel:WORD_1
	v_pk_fma_f32 v[130:131], v[68:69], v[164:165], v[72:73]
	v_cvt_f32_f16_e32 v68, v76
	v_pk_fma_f32 v[128:129], v[70:71], v[162:163], v[74:75]
	v_cvt_f32_f16_sdwa v69, v76 dst_sel:DWORD dst_unused:UNUSED_PAD src0_sel:WORD_1
	v_cvt_f32_f16_e32 v70, v77
	v_cvt_f32_f16_sdwa v71, v77 dst_sel:DWORD dst_unused:UNUSED_PAD src0_sel:WORD_1
	v_pk_fma_f32 v[134:135], v[64:65], v[158:159], v[68:69]
	v_cvt_pk_f16_f32 v65, v128, v129
	v_pk_fma_f32 v[132:133], v[66:67], v[160:161], v[70:71]
	v_cvt_pk_f16_f32 v66, v134, v135
	v_cvt_pk_f16_f32 v67, v132, v133
	v_cvt_pk_f16_f32 v64, v130, v131
	ds_bpermute_b32 v64, v189, v64
	ds_bpermute_b32 v65, v189, v65
	ds_bpermute_b32 v66, v189, v66
	ds_bpermute_b32 v67, v189, v67
	s_waitcnt lgkmcnt(0)
	global_store_dwordx4 v[176:177], v[64:67], off offset:2304
	global_load_dwordx4 v[144:147], v[142:143], off
	global_load_dwordx4 v[148:151], v[142:143], off offset:256
	global_load_dwordx4 v[84:87], v[140:141], off offset:2048
	global_load_dwordx4 v[80:83], v[140:141], off offset:2304
	global_load_dwordx4 v[76:79], v[138:139], off
	global_load_dwordx4 v[72:75], v[138:139], off offset:256
	global_load_dwordx4 v[68:71], v[136:137], off offset:2048
	global_load_dwordx4 v[64:67], v[136:137], off offset:2304
	s_waitcnt vmcnt(7)
	ds_bpermute_b32 v153, v190, v144
	ds_bpermute_b32 v154, v190, v145
	ds_bpermute_b32 v155, v190, v146
	ds_bpermute_b32 v157, v190, v147
	s_waitcnt lgkmcnt(3)
	v_cvt_f32_f16_e32 v144, v153
	v_cvt_f32_f16_sdwa v145, v153 dst_sel:DWORD dst_unused:UNUSED_PAD src0_sel:WORD_1
	s_waitcnt lgkmcnt(2)
	v_cvt_f32_f16_e32 v146, v154
	v_cvt_f32_f16_sdwa v147, v154 dst_sel:DWORD dst_unused:UNUSED_PAD src0_sel:WORD_1
	v_pk_fma_f32 v[60:61], v[60:61], v[172:173], v[144:145]
	s_waitcnt lgkmcnt(1)
	v_cvt_f32_f16_e32 v144, v155
	v_pk_fma_f32 v[62:63], v[62:63], v[170:171], v[146:147]
	v_cvt_f32_f16_sdwa v145, v155 dst_sel:DWORD dst_unused:UNUSED_PAD src0_sel:WORD_1
	s_waitcnt lgkmcnt(0)
	v_cvt_f32_f16_e32 v146, v157
	v_cvt_f32_f16_sdwa v147, v157 dst_sel:DWORD dst_unused:UNUSED_PAD src0_sel:WORD_1
	v_ashrrev_i32_e32 v157, 31, v156
	v_pk_fma_f32 v[56:57], v[56:57], v[166:167], v[144:145]
	v_cvt_pk_f16_f32 v145, v62, v63
	v_pk_fma_f32 v[58:59], v[58:59], v[168:169], v[146:147]
	v_cvt_pk_f16_f32 v146, v56, v57
	v_cvt_pk_f16_f32 v147, v58, v59
	v_cvt_pk_f16_f32 v144, v60, v61
	ds_bpermute_b32 v144, v189, v144
	ds_bpermute_b32 v145, v189, v145
	ds_bpermute_b32 v146, v189, v146
	ds_bpermute_b32 v147, v189, v147
	s_waitcnt lgkmcnt(0)
	global_store_dwordx4 v[142:143], v[144:147], off
	s_waitcnt vmcnt(7)
	ds_bpermute_b32 v145, v190, v148
	ds_bpermute_b32 v147, v190, v149
	ds_bpermute_b32 v148, v190, v150
	ds_bpermute_b32 v149, v190, v151
	s_waitcnt lgkmcnt(3)
	v_cvt_f32_f16_e32 v144, v145
	v_cvt_f32_f16_sdwa v145, v145 dst_sel:DWORD dst_unused:UNUSED_PAD src0_sel:WORD_1
	s_waitcnt lgkmcnt(2)
	v_cvt_f32_f16_e32 v146, v147
	v_cvt_f32_f16_sdwa v147, v147 dst_sel:DWORD dst_unused:UNUSED_PAD src0_sel:WORD_1
	v_pk_fma_f32 v[52:53], v[52:53], v[164:165], v[144:145]
	s_waitcnt lgkmcnt(1)
	v_cvt_f32_f16_e32 v144, v148
	v_pk_fma_f32 v[54:55], v[54:55], v[162:163], v[146:147]
	v_cvt_f32_f16_sdwa v145, v148 dst_sel:DWORD dst_unused:UNUSED_PAD src0_sel:WORD_1
	s_waitcnt lgkmcnt(0)
	v_cvt_f32_f16_e32 v146, v149
	v_cvt_f32_f16_sdwa v147, v149 dst_sel:DWORD dst_unused:UNUSED_PAD src0_sel:WORD_1
	v_pk_fma_f32 v[48:49], v[48:49], v[158:159], v[144:145]
	v_cvt_pk_f16_f32 v145, v54, v55
	v_pk_fma_f32 v[50:51], v[50:51], v[160:161], v[146:147]
	v_cvt_pk_f16_f32 v146, v48, v49
	v_cvt_pk_f16_f32 v147, v50, v51
	v_cvt_pk_f16_f32 v144, v52, v53
	ds_bpermute_b32 v144, v189, v144
	ds_bpermute_b32 v145, v189, v145
	ds_bpermute_b32 v146, v189, v146
	ds_bpermute_b32 v147, v189, v147
	s_waitcnt lgkmcnt(0)
	global_store_dwordx4 v[142:143], v[144:147], off offset:256
	s_waitcnt vmcnt(7)
	ds_bpermute_b32 v142, v190, v84
	ds_bpermute_b32 v143, v190, v85
	ds_bpermute_b32 v144, v190, v86
	ds_bpermute_b32 v145, v190, v87
	s_waitcnt lgkmcnt(3)
	v_cvt_f32_f16_e32 v84, v142
	v_cvt_f32_f16_sdwa v85, v142 dst_sel:DWORD dst_unused:UNUSED_PAD src0_sel:WORD_1
	s_waitcnt lgkmcnt(2)
	v_cvt_f32_f16_e32 v86, v143
	v_cvt_f32_f16_sdwa v87, v143 dst_sel:DWORD dst_unused:UNUSED_PAD src0_sel:WORD_1
	v_pk_fma_f32 v[44:45], v[44:45], v[172:173], v[84:85]
	s_waitcnt lgkmcnt(1)
; __device__ __forceinline__ unsigned cvt_pk_bf16(float lo, float hi) { unsigned r; asm volatile("v_cvt_pk_bf16_f32 %0, %1, %2" : "=v"(r) : "v"(lo), "v"(hi)); return r; }
;     __device__ __forceinline__ void operator()(AccT acc, const pg8::Unit& u, int wr, int wc, int fr, int fq) const {
;     ...
;                 for (int m = 0; m < 4; ++m) { const size_t ro = (size_t)(ai * 128 + m * 16) * LDP; float t = 0.f;
; #pragma unroll
;                     for (int bj = 0; bj < 2; ++bj) { const h16x8 b8 = __builtin_bit_cast(h16x8, gather4(__builtin_bit_cast(u32x4, hb[m][bj]), ld4));
;                         const f32x4 h0 = (f32x4){(float)b8[0], (float)b8[1], (float)b8[2], (float)b8[3]} + gv[bj][0] * acc[ai][bj][m][0], h1 = (f32x4){(float)b8[4], (float)b8[5], (float)b8[6], (float)b8[7]} + gv[bj][1] * acc[ai][bj][m][1];
;                         const h16x4 q0 = __builtin_convertvector(h0, h16x4), q1 = __builtin_convertvector(h1, h16x4);
;                         { const h16x8 hv8 = (h16x8){q0[0], q0[1], q0[2], q0[3], q1[0], q1[1], q1[2], q1[3]}; *(u32x4*)(hout + ro + bj * 128) = gather4(__builtin_bit_cast(u32x4, hv8), st4); }
;                         t += ((h0[0] * h0[0] + h0[1] * h0[1]) + (h0[2] * h0[2] + h0[3] * h0[3])) + ((h1[0] * h1[0] + h1[1] * h1[1]) + (h1[2] * h1[2] + h1[3] * h1[3]));
;                         if (WZ) { const f32x4 z0 = h0 * gz[bj][0], z1 = h1 * gz[bj][1]; u32x4 w; w.x = cvt_pk_bf16(z0[0], z0[1]); w.y = cvt_pk_bf16(z0[2], z0[3]); w.z = cvt_pk_bf16(z1[0], z1[1]); w.w = cvt_pk_bf16(z1[2], z1[3]);
;                             *(u32x4*)(zout + ro + bj * 128) = gather4(w, st4); } }
	v_cvt_f32_f16_e32 v84, v144
	v_pk_fma_f32 v[46:47], v[46:47], v[170:171], v[86:87]
	v_cvt_f32_f16_sdwa v85, v144 dst_sel:DWORD dst_unused:UNUSED_PAD src0_sel:WORD_1
	s_waitcnt lgkmcnt(0)
	v_cvt_f32_f16_e32 v86, v145
	v_cvt_f32_f16_sdwa v87, v145 dst_sel:DWORD dst_unused:UNUSED_PAD src0_sel:WORD_1
	v_pk_fma_f32 v[40:41], v[40:41], v[166:167], v[84:85]
	v_cvt_pk_f16_f32 v85, v46, v47
	v_pk_fma_f32 v[42:43], v[42:43], v[168:169], v[86:87]
	v_cvt_pk_f16_f32 v86, v40, v41
	v_cvt_pk_f16_f32 v87, v42, v43
	v_cvt_pk_f16_f32 v84, v44, v45
	ds_bpermute_b32 v84, v189, v84
	ds_bpermute_b32 v85, v189, v85
	ds_bpermute_b32 v86, v189, v86
	ds_bpermute_b32 v87, v189, v87
	s_waitcnt lgkmcnt(0)
	global_store_dwordx4 v[140:141], v[84:87], off offset:2048
	s_waitcnt vmcnt(7)
	ds_bpermute_b32 v84, v190, v80
	ds_bpermute_b32 v85, v190, v81
	ds_bpermute_b32 v86, v190, v82
	ds_bpermute_b32 v87, v190, v83
	s_waitcnt lgkmcnt(3)
	v_cvt_f32_f16_e32 v80, v84
	v_cvt_f32_f16_sdwa v81, v84 dst_sel:DWORD dst_unused:UNUSED_PAD src0_sel:WORD_1
	s_waitcnt lgkmcnt(2)
	v_cvt_f32_f16_e32 v82, v85
	v_cvt_f32_f16_sdwa v83, v85 dst_sel:DWORD dst_unused:UNUSED_PAD src0_sel:WORD_1
	v_pk_fma_f32 v[36:37], v[36:37], v[164:165], v[80:81]
	s_waitcnt lgkmcnt(1)
	v_cvt_f32_f16_e32 v80, v86
	v_pk_fma_f32 v[38:39], v[38:39], v[162:163], v[82:83]
	v_cvt_f32_f16_sdwa v81, v86 dst_sel:DWORD dst_unused:UNUSED_PAD src0_sel:WORD_1
	s_waitcnt lgkmcnt(0)
	v_cvt_f32_f16_e32 v82, v87
	v_cvt_f32_f16_sdwa v83, v87 dst_sel:DWORD dst_unused:UNUSED_PAD src0_sel:WORD_1
	v_pk_fma_f32 v[32:33], v[32:33], v[158:159], v[80:81]
	v_cvt_pk_f16_f32 v81, v38, v39
	v_pk_fma_f32 v[34:35], v[34:35], v[160:161], v[82:83]
	v_cvt_pk_f16_f32 v82, v32, v33
	v_cvt_pk_f16_f32 v83, v34, v35
	v_cvt_pk_f16_f32 v80, v36, v37
	ds_bpermute_b32 v80, v189, v80
	ds_bpermute_b32 v81, v189, v81
	ds_bpermute_b32 v82, v189, v82
	ds_bpermute_b32 v83, v189, v83
	s_waitcnt lgkmcnt(0)
	global_store_dwordx4 v[140:141], v[80:83], off offset:2304
	s_waitcnt vmcnt(7)
	ds_bpermute_b32 v80, v190, v76
	ds_bpermute_b32 v81, v190, v77
	ds_bpermute_b32 v82, v190, v78
	ds_bpermute_b32 v83, v190, v79
	s_waitcnt lgkmcnt(3)
	v_cvt_f32_f16_e32 v76, v80
	v_cvt_f32_f16_sdwa v77, v80 dst_sel:DWORD dst_unused:UNUSED_PAD src0_sel:WORD_1
	s_waitcnt lgkmcnt(2)
	v_cvt_f32_f16_e32 v78, v81
	v_cvt_f32_f16_sdwa v79, v81 dst_sel:DWORD dst_unused:UNUSED_PAD src0_sel:WORD_1
	v_pk_fma_f32 v[28:29], v[28:29], v[172:173], v[76:77]
	s_waitcnt lgkmcnt(1)
	v_cvt_f32_f16_e32 v76, v82
	v_pk_fma_f32 v[30:31], v[30:31], v[170:171], v[78:79]
	v_cvt_f32_f16_sdwa v77, v82 dst_sel:DWORD dst_unused:UNUSED_PAD src0_sel:WORD_1
	s_waitcnt lgkmcnt(0)
	v_cvt_f32_f16_e32 v78, v83
	v_cvt_f32_f16_sdwa v79, v83 dst_sel:DWORD dst_unused:UNUSED_PAD src0_sel:WORD_1
	v_pk_fma_f32 v[24:25], v[24:25], v[166:167], v[76:77]
	v_cvt_pk_f16_f32 v77, v30, v31
	v_pk_fma_f32 v[26:27], v[26:27], v[168:169], v[78:79]
	v_cvt_pk_f16_f32 v78, v24, v25
	v_cvt_pk_f16_f32 v79, v26, v27
	v_cvt_pk_f16_f32 v76, v28, v29
	ds_bpermute_b32 v76, v189, v76
	ds_bpermute_b32 v77, v189, v77
	ds_bpermute_b32 v78, v189, v78
	ds_bpermute_b32 v79, v189, v79
	s_waitcnt lgkmcnt(0)
	global_store_dwordx4 v[138:139], v[76:79], off
	s_waitcnt vmcnt(7)
	ds_bpermute_b32 v76, v190, v72
	ds_bpermute_b32 v77, v190, v73
	ds_bpermute_b32 v78, v190, v74
	ds_bpermute_b32 v79, v190, v75
	s_waitcnt lgkmcnt(3)
	v_cvt_f32_f16_e32 v72, v76
	v_cvt_f32_f16_sdwa v73, v76 dst_sel:DWORD dst_unused:UNUSED_PAD src0_sel:WORD_1
	s_waitcnt lgkmcnt(2)
	v_cvt_f32_f16_e32 v74, v77
	v_cvt_f32_f16_sdwa v75, v77 dst_sel:DWORD dst_unused:UNUSED_PAD src0_sel:WORD_1
	v_pk_fma_f32 v[20:21], v[20:21], v[164:165], v[72:73]
	s_waitcnt lgkmcnt(1)
	v_cvt_f32_f16_e32 v72, v78
	v_pk_fma_f32 v[22:23], v[22:23], v[162:163], v[74:75]
	v_cvt_f32_f16_sdwa v73, v78 dst_sel:DWORD dst_unused:UNUSED_PAD src0_sel:WORD_1
	s_waitcnt lgkmcnt(0)
	v_cvt_f32_f16_e32 v74, v79
	v_cvt_f32_f16_sdwa v75, v79 dst_sel:DWORD dst_unused:UNUSED_PAD src0_sel:WORD_1
	v_pk_fma_f32 v[16:17], v[16:17], v[158:159], v[72:73]
	v_cvt_pk_f16_f32 v73, v22, v23
	v_pk_fma_f32 v[18:19], v[18:19], v[160:161], v[74:75]
	v_cvt_pk_f16_f32 v74, v16, v17
	v_cvt_pk_f16_f32 v75, v18, v19
	v_cvt_pk_f16_f32 v72, v20, v21
	ds_bpermute_b32 v72, v189, v72
	ds_bpermute_b32 v73, v189, v73
	ds_bpermute_b32 v74, v189, v74
	ds_bpermute_b32 v75, v189, v75
	s_waitcnt lgkmcnt(0)
	global_store_dwordx4 v[138:139], v[72:75], off offset:256
	s_waitcnt vmcnt(7)
	ds_bpermute_b32 v72, v190, v68
	ds_bpermute_b32 v73, v190, v69
	ds_bpermute_b32 v74, v190, v70
	ds_bpermute_b32 v75, v190, v71
	s_waitcnt lgkmcnt(3)
	v_cvt_f32_f16_e32 v68, v72
	v_cvt_f32_f16_sdwa v69, v72 dst_sel:DWORD dst_unused:UNUSED_PAD src0_sel:WORD_1
	s_waitcnt lgkmcnt(2)
	v_cvt_f32_f16_e32 v70, v73
	v_cvt_f32_f16_sdwa v71, v73 dst_sel:DWORD dst_unused:UNUSED_PAD src0_sel:WORD_1
	v_pk_fma_f32 v[12:13], v[12:13], v[172:173], v[68:69]
	s_waitcnt lgkmcnt(1)
	v_cvt_f32_f16_e32 v68, v74
	v_pk_fma_f32 v[14:15], v[14:15], v[170:171], v[70:71]
	v_cvt_f32_f16_sdwa v69, v74 dst_sel:DWORD dst_unused:UNUSED_PAD src0_sel:WORD_1
	s_waitcnt lgkmcnt(0)
	v_cvt_f32_f16_e32 v70, v75
	v_cvt_f32_f16_sdwa v71, v75 dst_sel:DWORD dst_unused:UNUSED_PAD src0_sel:WORD_1
	v_pk_fma_f32 v[8:9], v[8:9], v[166:167], v[68:69]
	v_cvt_pk_f16_f32 v69, v14, v15
	v_pk_fma_f32 v[10:11], v[10:11], v[168:169], v[70:71]
	v_cvt_pk_f16_f32 v70, v8, v9
	v_cvt_pk_f16_f32 v71, v10, v11
	v_cvt_pk_f16_f32 v68, v12, v13
	ds_bpermute_b32 v68, v189, v68
	ds_bpermute_b32 v69, v189, v69
	ds_bpermute_b32 v70, v189, v70
	ds_bpermute_b32 v71, v189, v71
	s_waitcnt lgkmcnt(0)
	global_store_dwordx4 v[136:137], v[68:71], off offset:2048
	s_waitcnt vmcnt(7)
; __device__ __forceinline__ unsigned cvt_pk_bf16(float lo, float hi) { unsigned r; asm volatile("v_cvt_pk_bf16_f32 %0, %1, %2" : "=v"(r) : "v"(lo), "v"(hi)); return r; }
; __device__ __forceinline__ float xlane(float v, int src_lane) { return __uint_as_float(__builtin_amdgcn_ds_bpermute(src_lane << 2, __float_as_uint(v))); }
;     __device__ __forceinline__ void operator()(AccT acc, const pg8::Unit& u, int wr, int wc, int fr, int fq) const {
;     ...
;                 for (int m = 0; m < 4; ++m) { const size_t ro = (size_t)(ai * 128 + m * 16) * LDP; float t = 0.f;
; #pragma unroll
;                     for (int bj = 0; bj < 2; ++bj) { const h16x8 b8 = __builtin_bit_cast(h16x8, gather4(__builtin_bit_cast(u32x4, hb[m][bj]), ld4));
;                         const f32x4 h0 = (f32x4){(float)b8[0], (float)b8[1], (float)b8[2], (float)b8[3]} + gv[bj][0] * acc[ai][bj][m][0], h1 = (f32x4){(float)b8[4], (float)b8[5], (float)b8[6], (float)b8[7]} + gv[bj][1] * acc[ai][bj][m][1];
;                         const h16x4 q0 = __builtin_convertvector(h0, h16x4), q1 = __builtin_convertvector(h1, h16x4);
;                         { const h16x8 hv8 = (h16x8){q0[0], q0[1], q0[2], q0[3], q1[0], q1[1], q1[2], q1[3]}; *(u32x4*)(hout + ro + bj * 128) = gather4(__builtin_bit_cast(u32x4, hv8), st4); }
;                         t += ((h0[0] * h0[0] + h0[1] * h0[1]) + (h0[2] * h0[2] + h0[3] * h0[3])) + ((h1[0] * h1[0] + h1[1] * h1[1]) + (h1[2] * h1[2] + h1[3] * h1[3]));
;                         if (WZ) { const f32x4 z0 = h0 * gz[bj][0], z1 = h1 * gz[bj][1]; u32x4 w; w.x = cvt_pk_bf16(z0[0], z0[1]); w.y = cvt_pk_bf16(z0[2], z0[3]); w.z = cvt_pk_bf16(z1[0], z1[1]); w.w = cvt_pk_bf16(z1[2], z1[3]);
;                             *(u32x4*)(zout + ro + bj * 128) = gather4(w, st4); } }
;                     ss[ai * 4 + m] = t; }
;                 asm volatile("" ::: "memory");
;             }
;         }
; #pragma unroll
;         for (int g = 0; g < 8; ++g) { float t = ss[g]; t += xlane(t, lane ^ 16); t += xlane(t, lane ^ 32);
;             if (fq == 0) SSQ[(size_t)(row0 + (g >> 2) * 128 + (g & 3) * 16) * 32 + u.pn * 4 + wc] = t; }
	ds_bpermute_b32 v68, v190, v64
	ds_bpermute_b32 v69, v190, v65
	ds_bpermute_b32 v70, v190, v66
	ds_bpermute_b32 v71, v190, v67
	s_waitcnt lgkmcnt(3)
	v_cvt_f32_f16_e32 v64, v68
	v_cvt_f32_f16_sdwa v65, v68 dst_sel:DWORD dst_unused:UNUSED_PAD src0_sel:WORD_1
	s_waitcnt lgkmcnt(2)
	v_cvt_f32_f16_e32 v66, v69
	v_cvt_f32_f16_sdwa v67, v69 dst_sel:DWORD dst_unused:UNUSED_PAD src0_sel:WORD_1
	v_pk_fma_f32 v[4:5], v[4:5], v[164:165], v[64:65]
	s_waitcnt lgkmcnt(1)
	v_cvt_f32_f16_e32 v64, v70
	v_pk_fma_f32 v[6:7], v[6:7], v[162:163], v[66:67]
	v_cvt_f32_f16_sdwa v65, v70 dst_sel:DWORD dst_unused:UNUSED_PAD src0_sel:WORD_1
	s_waitcnt lgkmcnt(0)
	v_cvt_f32_f16_e32 v66, v71
	v_cvt_f32_f16_sdwa v67, v71 dst_sel:DWORD dst_unused:UNUSED_PAD src0_sel:WORD_1
	v_pk_fma_f32 v[0:1], v[0:1], v[158:159], v[64:65]
	v_cvt_pk_f16_f32 v65, v6, v7
	v_pk_fma_f32 v[2:3], v[2:3], v[160:161], v[66:67]
	v_cvt_pk_f16_f32 v66, v0, v1
	v_cvt_pk_f16_f32 v67, v2, v3
	v_cvt_pk_f16_f32 v64, v4, v5
	ds_bpermute_b32 v64, v189, v64
	ds_bpermute_b32 v65, v189, v65
	ds_bpermute_b32 v66, v189, v66
	ds_bpermute_b32 v67, v189, v67
	s_waitcnt lgkmcnt(0)
	global_store_dwordx4 v[136:137], v[64:67], off offset:2304
	s_waitcnt lgkmcnt(0)
	s_nop 1
	v_mov_b32_e32 v64, v152
	v_mov_b32_e32 v65, v152
	s_nop 1
	v_permlane16_swap_b32_e32 v64, v65
	v_add_f32_e32 v64, v64, v65
	v_mov_b32_e32 v65, v64
	s_nop 1
	v_permlane32_swap_b32_e32 v64, v65
	s_and_saveexec_b64 s[22:23], s[6:7]
	s_cbranch_execz .LBB0_1249
	s_waitcnt lgkmcnt(0)
	v_add_f32_e32 v66, v64, v65
	v_lshlrev_b64 v[64:65], 7, v[156:157]
	v_lshl_add_u64 v[64:65], s[20:21], 0, v[64:65]
	global_store_dword v[64:65], v66, off
.LBB0_1249:
	s_or_b64 exec, exec, s[22:23]
	v_mul_f32_e32 v64, v109, v109
	s_waitcnt lgkmcnt(0)
	v_mul_f32_e32 v65, v111, v111
	v_fmac_f32_e32 v64, v108, v108
	v_fmac_f32_e32 v65, v110, v110
	v_add_f32_e32 v64, v64, v65
	v_mul_f32_e32 v65, v105, v105
	v_mul_f32_e32 v66, v107, v107
	v_fmac_f32_e32 v65, v104, v104
	v_fmac_f32_e32 v66, v106, v106
	v_add_f32_e32 v65, v65, v66
	v_add_f32_e32 v64, v64, v65
	v_mul_f32_e32 v65, v101, v101
	v_mul_f32_e32 v66, v103, v103
	v_fmac_f32_e32 v65, v100, v100
	v_fmac_f32_e32 v66, v102, v102
	v_add_f32_e32 v65, v65, v66
	v_mul_f32_e32 v66, v97, v97
	v_mul_f32_e32 v67, v99, v99
	v_fmac_f32_e32 v66, v96, v96
	v_fmac_f32_e32 v67, v98, v98
	v_add_f32_e32 v66, v66, v67
	v_add_f32_e32 v65, v65, v66
	v_add_f32_e32 v64, v64, v65
	s_waitcnt lgkmcnt(0)
	v_mov_b32_e32 v65, v64
	s_nop 1
	v_permlane16_swap_b32_e32 v65, v64
	v_add_f32_e32 v64, v64, v65
	v_mov_b32_e32 v65, v64
	s_nop 1
	v_permlane32_swap_b32_e32 v64, v65
	s_and_saveexec_b64 s[22:23], s[6:7]
	s_cbranch_execz .LBB0_1251
	s_waitcnt lgkmcnt(0)
	v_add_f32_e32 v66, v64, v65
	v_or_b32_e32 v64, 16, v156
	v_ashrrev_i32_e32 v65, 31, v64
	v_lshlrev_b64 v[64:65], 7, v[64:65]
	v_lshl_add_u64 v[64:65], s[20:21], 0, v[64:65]
	global_store_dword v[64:65], v66, off
.LBB0_1251:
	s_or_b64 exec, exec, s[22:23]
	v_mul_f32_e32 v64, v93, v93
	s_waitcnt lgkmcnt(0)
	v_mul_f32_e32 v65, v95, v95
	v_fmac_f32_e32 v64, v92, v92
	v_fmac_f32_e32 v65, v94, v94
	v_add_f32_e32 v64, v64, v65
	v_mul_f32_e32 v65, v89, v89
	v_mul_f32_e32 v66, v91, v91
	v_fmac_f32_e32 v65, v88, v88
	v_fmac_f32_e32 v66, v90, v90
	v_add_f32_e32 v65, v65, v66
	v_add_f32_e32 v64, v64, v65
	v_mul_f32_e32 v65, v115, v115
	v_mul_f32_e32 v66, v113, v113
	v_fmac_f32_e32 v65, v114, v114
	v_fmac_f32_e32 v66, v112, v112
	v_add_f32_e32 v65, v65, v66
	v_mul_f32_e32 v66, v119, v119
	v_mul_f32_e32 v67, v117, v117
	v_fmac_f32_e32 v66, v118, v118
	v_fmac_f32_e32 v67, v116, v116
	v_add_f32_e32 v66, v66, v67
	v_add_f32_e32 v65, v65, v66
	v_add_f32_e32 v64, v64, v65
	s_waitcnt lgkmcnt(0)
	v_mov_b32_e32 v65, v64
	s_nop 1
	v_permlane16_swap_b32_e32 v65, v64
	v_add_f32_e32 v64, v64, v65
	v_mov_b32_e32 v65, v64
	s_nop 1
	v_permlane32_swap_b32_e32 v64, v65
	s_and_saveexec_b64 s[22:23], s[6:7]
	s_cbranch_execz .LBB0_1253
	s_waitcnt lgkmcnt(0)
	v_add_f32_e32 v66, v64, v65
	v_or_b32_e32 v64, 32, v156
	v_ashrrev_i32_e32 v65, 31, v64
	v_lshlrev_b64 v[64:65], 7, v[64:65]
	v_lshl_add_u64 v[64:65], s[20:21], 0, v[64:65]
	global_store_dword v[64:65], v66, off
.LBB0_1253:
	s_or_b64 exec, exec, s[22:23]
	v_mul_f32_e32 v64, v123, v123
	s_waitcnt lgkmcnt(0)
	v_mul_f32_e32 v65, v121, v121
	v_fmac_f32_e32 v64, v122, v122
	v_fmac_f32_e32 v65, v120, v120
	v_add_f32_e32 v64, v64, v65
	v_mul_f32_e32 v65, v127, v127
	v_mul_f32_e32 v66, v125, v125
	v_fmac_f32_e32 v65, v126, v126
	v_fmac_f32_e32 v66, v124, v124
	v_add_f32_e32 v65, v65, v66
	v_add_f32_e32 v64, v64, v65
	v_mul_f32_e32 v65, v131, v131
	v_mul_f32_e32 v66, v129, v129
	v_fmac_f32_e32 v65, v130, v130
	v_fmac_f32_e32 v66, v128, v128
	v_add_f32_e32 v65, v65, v66
	v_mul_f32_e32 v66, v135, v135
	v_mul_f32_e32 v67, v133, v133
	v_fmac_f32_e32 v66, v134, v134
	v_fmac_f32_e32 v67, v132, v132
	v_add_f32_e32 v66, v66, v67
	v_add_f32_e32 v65, v65, v66
	v_add_f32_e32 v64, v64, v65
	s_waitcnt lgkmcnt(0)
	v_mov_b32_e32 v65, v64
	s_nop 1
	v_permlane16_swap_b32_e32 v65, v64
	v_add_f32_e32 v64, v64, v65
	v_mov_b32_e32 v65, v64
	s_nop 1
	v_permlane32_swap_b32_e32 v64, v65
	s_and_saveexec_b64 s[22:23], s[6:7]
	s_cbranch_execz .LBB0_1255
	s_waitcnt lgkmcnt(0)
	v_add_f32_e32 v66, v64, v65
	v_or_b32_e32 v64, 48, v156
	v_ashrrev_i32_e32 v65, 31, v64
	v_lshlrev_b64 v[64:65], 7, v[64:65]
	v_lshl_add_u64 v[64:65], s[20:21], 0, v[64:65]
	global_store_dword v[64:65], v66, off
; __device__ __forceinline__ unsigned cvt_pk_bf16(float lo, float hi) { unsigned r; asm volatile("v_cvt_pk_bf16_f32 %0, %1, %2" : "=v"(r) : "v"(lo), "v"(hi)); return r; }
; __device__ __forceinline__ float xlane(float v, int src_lane) { return __uint_as_float(__builtin_amdgcn_ds_bpermute(src_lane << 2, __float_as_uint(v))); }
;     __device__ __forceinline__ void operator()(AccT acc, const pg8::Unit& u, int wr, int wc, int fr, int fq) const {
;     ...
;                         t += ((h0[0] * h0[0] + h0[1] * h0[1]) + (h0[2] * h0[2] + h0[3] * h0[3])) + ((h1[0] * h1[0] + h1[1] * h1[1]) + (h1[2] * h1[2] + h1[3] * h1[3]));
;                         if (WZ) { const f32x4 z0 = h0 * gz[bj][0], z1 = h1 * gz[bj][1]; u32x4 w; w.x = cvt_pk_bf16(z0[0], z0[1]); w.y = cvt_pk_bf16(z0[2], z0[3]); w.z = cvt_pk_bf16(z1[0], z1[1]); w.w = cvt_pk_bf16(z1[2], z1[3]);
;                             *(u32x4*)(zout + ro + bj * 128) = gather4(w, st4); } }
;                     ss[ai * 4 + m] = t; }
;                 asm volatile("" ::: "memory");
;             }
;         }
; #pragma unroll
;         for (int g = 0; g < 8; ++g) { float t = ss[g]; t += xlane(t, lane ^ 16); t += xlane(t, lane ^ 32);
;             if (fq == 0) SSQ[(size_t)(row0 + (g >> 2) * 128 + (g & 3) * 16) * 32 + u.pn * 4 + wc] = t; }
.LBB0_1255:
	s_or_b64 exec, exec, s[22:23]
	v_mul_f32_e32 v61, v61, v61
	v_mul_f32_e32 v57, v57, v57
	v_mul_f32_e32 v53, v53, v53
	v_mul_f32_e32 v49, v49, v49
	v_fmac_f32_e32 v61, v60, v60
	v_mul_f32_e32 v60, v63, v63
	v_fmac_f32_e32 v57, v56, v56
	v_mul_f32_e32 v56, v59, v59
	v_fmac_f32_e32 v53, v52, v52
	v_mul_f32_e32 v52, v55, v55
	v_fmac_f32_e32 v49, v48, v48
	v_mul_f32_e32 v48, v51, v51
	v_fmac_f32_e32 v60, v62, v62
	v_fmac_f32_e32 v56, v58, v58
	v_fmac_f32_e32 v52, v54, v54
	v_fmac_f32_e32 v48, v50, v50
	v_add_f32_e32 v60, v61, v60
	v_add_f32_e32 v56, v57, v56
	v_add_f32_e32 v52, v53, v52
	v_add_f32_e32 v48, v49, v48
	v_add_f32_e32 v56, v60, v56
	v_add_f32_e32 v48, v52, v48
	v_add_f32_e32 v48, v56, v48
	s_waitcnt lgkmcnt(0)
	v_mov_b32_e32 v49, v48
	s_nop 1
	v_permlane16_swap_b32_e32 v49, v48
	v_add_f32_e32 v48, v48, v49
	v_mov_b32_e32 v49, v48
	s_nop 1
	v_permlane32_swap_b32_e32 v48, v49
	s_and_saveexec_b64 s[22:23], s[6:7]
	s_cbranch_execz .LBB0_1257
	s_waitcnt lgkmcnt(0)
	v_add_f32_e32 v50, v48, v49
	v_lshlrev_b64 v[48:49], 7, v[156:157]
	v_lshl_add_u64 v[48:49], s[20:21], 0, v[48:49]
	v_add_co_u32_e32 v48, vcc, 0x4000, v48
	s_nop 1
	v_addc_co_u32_e32 v49, vcc, 0, v49, vcc
	global_store_dword v[48:49], v50, off
.LBB0_1257:
	s_or_b64 exec, exec, s[22:23]
	v_mul_f32_e32 v45, v45, v45
	v_mul_f32_e32 v41, v41, v41
	v_mul_f32_e32 v37, v37, v37
	v_mul_f32_e32 v33, v33, v33
	v_fmac_f32_e32 v45, v44, v44
	v_mul_f32_e32 v44, v47, v47
	v_fmac_f32_e32 v41, v40, v40
	v_mul_f32_e32 v40, v43, v43
	v_fmac_f32_e32 v37, v36, v36
	v_mul_f32_e32 v36, v39, v39
	v_fmac_f32_e32 v33, v32, v32
	v_mul_f32_e32 v32, v35, v35
	v_fmac_f32_e32 v44, v46, v46
	v_fmac_f32_e32 v40, v42, v42
	v_fmac_f32_e32 v36, v38, v38
	v_fmac_f32_e32 v32, v34, v34
	v_add_f32_e32 v44, v45, v44
	v_add_f32_e32 v40, v41, v40
	v_add_f32_e32 v36, v37, v36
	v_add_f32_e32 v32, v33, v32
	v_add_f32_e32 v40, v44, v40
	v_add_f32_e32 v32, v36, v32
	v_add_f32_e32 v32, v40, v32
	s_waitcnt lgkmcnt(0)
	v_mov_b32_e32 v33, v32
	s_nop 1
	v_permlane16_swap_b32_e32 v33, v32
	v_add_f32_e32 v32, v32, v33
	v_mov_b32_e32 v33, v32
	s_nop 1
	v_permlane32_swap_b32_e32 v32, v33
	s_and_saveexec_b64 s[22:23], s[6:7]
	s_cbranch_execz .LBB0_1259
	s_waitcnt lgkmcnt(0)
	v_add_f32_e32 v34, v32, v33
	v_lshlrev_b64 v[32:33], 7, v[156:157]
	v_lshl_add_u64 v[32:33], s[20:21], 0, v[32:33]
	v_add_co_u32_e32 v32, vcc, 0x4000, v32
	s_nop 1
	v_addc_co_u32_e32 v33, vcc, 0, v33, vcc
	global_store_dword v[32:33], v34, off offset:2048
.LBB0_1259:
	s_or_b64 exec, exec, s[22:23]
	v_mul_f32_e32 v29, v29, v29
	v_mul_f32_e32 v25, v25, v25
	v_mul_f32_e32 v21, v21, v21
	v_mul_f32_e32 v17, v17, v17
	v_fmac_f32_e32 v29, v28, v28
	v_mul_f32_e32 v28, v31, v31
	v_fmac_f32_e32 v25, v24, v24
	v_mul_f32_e32 v24, v27, v27
	v_fmac_f32_e32 v21, v20, v20
	v_mul_f32_e32 v20, v23, v23
	v_fmac_f32_e32 v17, v16, v16
	v_mul_f32_e32 v16, v19, v19
	v_fmac_f32_e32 v28, v30, v30
	v_fmac_f32_e32 v24, v26, v26
	v_fmac_f32_e32 v20, v22, v22
	v_fmac_f32_e32 v16, v18, v18
	v_add_f32_e32 v28, v29, v28
	v_add_f32_e32 v24, v25, v24
	v_add_f32_e32 v20, v21, v20
	v_add_f32_e32 v16, v17, v16
	v_add_f32_e32 v24, v28, v24
	v_add_f32_e32 v16, v20, v16
	v_add_f32_e32 v16, v24, v16
	s_waitcnt lgkmcnt(0)
	v_mov_b32_e32 v17, v16
	s_nop 1
	v_permlane16_swap_b32_e32 v17, v16
	v_add_f32_e32 v16, v16, v17
	v_mov_b32_e32 v17, v16
	s_nop 1
	v_permlane32_swap_b32_e32 v16, v17
	s_and_saveexec_b64 s[22:23], s[6:7]
	s_cbranch_execz .LBB0_1261
	s_waitcnt lgkmcnt(0)
	v_add_f32_e32 v18, v16, v17
	v_lshlrev_b64 v[16:17], 7, v[156:157]
	v_lshl_add_u64 v[16:17], s[20:21], 0, v[16:17]
	v_add_co_u32_e32 v16, vcc, 0x5000, v16
	s_nop 1
	v_addc_co_u32_e32 v17, vcc, 0, v17, vcc
	global_store_dword v[16:17], v18, off
.LBB0_1261:
	s_or_b64 exec, exec, s[22:23]
	v_mul_f32_e32 v13, v13, v13
	v_mul_f32_e32 v9, v9, v9
	v_mul_f32_e32 v5, v5, v5
	v_mul_f32_e32 v1, v1, v1
	v_fmac_f32_e32 v13, v12, v12
	v_mul_f32_e32 v12, v15, v15
	v_fmac_f32_e32 v9, v8, v8
	v_mul_f32_e32 v8, v11, v11
	v_fmac_f32_e32 v5, v4, v4
	v_mul_f32_e32 v4, v7, v7
	v_fmac_f32_e32 v1, v0, v0
	v_mul_f32_e32 v0, v3, v3
	v_fmac_f32_e32 v12, v14, v14
	v_fmac_f32_e32 v8, v10, v10
	v_fmac_f32_e32 v4, v6, v6
	v_fmac_f32_e32 v0, v2, v2
	v_add_f32_e32 v12, v13, v12
	v_add_f32_e32 v8, v9, v8
	v_add_f32_e32 v4, v5, v4
	v_add_f32_e32 v0, v1, v0
	v_add_f32_e32 v8, v12, v8
	v_add_f32_e32 v0, v4, v0
	v_add_f32_e32 v0, v8, v0
	s_waitcnt lgkmcnt(0)
	v_mov_b32_e32 v1, v0
	s_nop 1
	v_permlane16_swap_b32_e32 v1, v0
	v_add_f32_e32 v0, v0, v1
	v_mov_b32_e32 v1, v0
	s_nop 1
	v_permlane32_swap_b32_e32 v0, v1
	s_and_saveexec_b64 s[22:23], s[6:7]
	s_cbranch_execz .LBB0_1263
	s_waitcnt lgkmcnt(0)
	v_add_f32_e32 v2, v0, v1
	v_lshlrev_b64 v[0:1], 7, v[156:157]
	v_lshl_add_u64 v[0:1], s[20:21], 0, v[0:1]
	v_add_co_u32_e32 v0, vcc, 0x5000, v0
	s_nop 1
	v_addc_co_u32_e32 v1, vcc, 0, v1, vcc
	global_store_dword v[0:1], v2, off offset:2048

;     __device__ __forceinline__ void operator()(AccT acc, const pg8::Unit& u, int wr, int wc, int fr, int fq) const {
;         const int row0 = u.pm * 256 + wr * 64 + fr, col0 = u.pn * 256 + wc * 32 + 8 * fq, lane = fq * 16 + fr;
;         const int bidx = u.pm < 64 ? (u.pm >> 4) : 4;
;         const float* gp = gate + (size_t)bidx * MODW + col0;
;         f32x4 gv[2][2], gz[2][2];
; #pragma unroll
;         for (int bj = 0; bj < 2; ++bj)
; #pragma unroll
;             for (int n = 0; n < 2; ++n) { gv[bj][n] = *(const f32x4*)(gp + bj * 128 + n * 4) * coef;
;                 if (WZ) gz[bj][n] = *(const f32x4*)(gnext + col0 + bj * 128 + n * 4) * (*(const f32x4*)(scnext + (size_t)bidx * MODW + col0 + bj * 128 + n * 4) + 1.f); }
;         const int st4 = ((lane & 3) * 16 + (lane >> 2)) * 4, ld4 = ((lane & 15) * 4 + (lane >> 4)) * 4;
;         const size_t eo = (size_t)(u.pm * 256 + wr * 64 + (lane >> 2)) * LDP + u.pn * 256 + wc * 32 + (lane & 3) * 8;
;         hf_t* hout = H + eo; bf16_t* zout = Z + eo; float ss[8];
;         if constexpr (B32) {
;             const float* base = (const float*)(u.pm < 64 ? baseL : baseC) + (size_t)row0 * D + col0;
;             f32x4 hb[4][2][2];
; #pragma unroll
;             for (int ai = 0; ai < 2; ++ai) {
; #pragma unroll
;                 for (int m = 0; m < 4; ++m)
; #pragma unroll
;                     for (int bj = 0; bj < 2; ++bj)
; #pragma unroll
;                         for (int n = 0; n < 2; ++n) hb[m][bj][n] = *(const f32x4*)(base + (size_t)(ai * 128 + m * 16) * D + bj * 128 + n * 4);
;                 asm volatile("" ::: "memory");
; #pragma unroll
;                 for (int m = 0; m < 4; ++m) { const size_t ro = (size_t)(ai * 128 + m * 16) * LDP; float t = 0.f;
; #pragma unroll
;                     for (int bj = 0; bj < 2; ++bj) { const f32x4 h0 = hb[m][bj][0] + gv[bj][0] * acc[ai][bj][m][0], h1 = hb[m][bj][1] + gv[bj][1] * acc[ai][bj][m][1];
;                         const h16x4 q0 = __builtin_convertvector(h0, h16x4), q1 = __builtin_convertvector(h1, h16x4);
;                         { const h16x8 hv8 = (h16x8){q0[0], q0[1], q0[2], q0[3], q1[0], q1[1], q1[2], q1[3]}; *(u32x4*)(hout + ro + bj * 128) = gather4(__builtin_bit_cast(u32x4, hv8), st4); }
.LBB0_1343:
	s_lshr_b32 s2, s33, 4
	s_lshl_b32 s23, s33, 8
	s_mul_i32 s40, s2, 0x4800
	s_add_i32 s23, s23, s84
	s_lshl_b32 s25, s96, 8
	s_lshl_b64 s[10:11], s[40:41], 2
	s_add_u32 s30, s54, s10
	v_or_b32_e32 v192, s25, v213
	s_addc_u32 s31, s55, s11
	v_lshlrev_b64 v[128:129], 2, v[192:193]
	s_add_u32 s10, s57, s10
	v_lshl_add_u64 v[148:149], s[30:31], 0, v[128:129]
	s_addc_u32 s11, s72, s11
	v_lshl_add_u64 v[150:151], s[16:17], 0, v[128:129]
	v_lshl_add_u64 v[152:153], s[10:11], 0, v[128:129]
	global_load_dwordx4 v[128:131], v[148:149], off offset:16
	global_load_dwordx4 v[132:135], v[148:149], off
	v_or_b32_e32 v192, s25, v217
	s_movk_i32 s2, 0x840
	v_or_b32_e32 v160, s23, v212
	s_lshl_b32 s40, s96, 2
	s_waitcnt vmcnt(0)
	v_pk_mul_f32 v[186:187], v[130:131], 0.5 op_sel_hi:[1,0]
	v_pk_mul_f32 v[190:191], v[134:135], 0.5 op_sel_hi:[1,0]
	v_pk_mul_f32 v[196:197], v[132:133], 0.5 op_sel_hi:[1,0]
	global_load_dwordx4 v[132:135], v[150:151], off offset:16
	global_load_dwordx4 v[136:139], v[150:151], off
	global_load_dwordx4 v[140:143], v[152:153], off offset:16
	global_load_dwordx4 v[144:147], v[152:153], off
	v_pk_mul_f32 v[188:189], v[128:129], 0.5 op_sel_hi:[1,0]
	s_waitcnt vmcnt(1)
	v_pk_add_f32 v[128:129], v[142:143], 1.0 op_sel_hi:[1,0]
	v_pk_add_f32 v[130:131], v[140:141], 1.0 op_sel_hi:[1,0]
	v_pk_mul_f32 v[178:179], v[134:135], v[128:129]
	v_pk_mul_f32 v[180:181], v[132:133], v[130:131]
	global_load_dwordx4 v[128:131], v[148:149], off offset:528
	global_load_dwordx4 v[132:135], v[148:149], off offset:512
	s_waitcnt vmcnt(2)
	v_pk_add_f32 v[146:147], v[146:147], 1.0 op_sel_hi:[1,0]
	v_pk_add_f32 v[144:145], v[144:145], 1.0 op_sel_hi:[1,0]
	v_pk_mul_f32 v[174:175], v[138:139], v[146:147]
	v_pk_mul_f32 v[176:177], v[136:137], v[144:145]
	s_waitcnt vmcnt(1)
	v_pk_mul_f32 v[172:173], v[128:129], 0.5 op_sel_hi:[1,0]
	s_waitcnt vmcnt(0)
	v_pk_mul_f32 v[182:183], v[134:135], 0.5 op_sel_hi:[1,0]
	v_pk_mul_f32 v[184:185], v[132:133], 0.5 op_sel_hi:[1,0]
	global_load_dwordx4 v[132:135], v[150:151], off offset:528
	global_load_dwordx4 v[136:139], v[150:151], off offset:512
	global_load_dwordx4 v[140:143], v[152:153], off offset:528
	global_load_dwordx4 v[144:147], v[152:153], off offset:512
	v_pk_mul_f32 v[170:171], v[130:131], 0.5 op_sel_hi:[1,0]
	s_waitcnt vmcnt(1)
	v_pk_add_f32 v[128:129], v[142:143], 1.0 op_sel_hi:[1,0]
	s_nop 0
	v_pk_mul_f32 v[166:167], v[134:135], v[128:129]
	v_or_b32_e32 v128, s23, v215
	v_mad_i64_i32 v[128:129], s[10:11], v128, s2, v[192:193]
	v_lshlrev_b64 v[128:129], 1, v[128:129]
	v_lshl_add_u64 v[200:201], s[12:13], 0, v[128:129]
	global_load_dwordx4 v[222:225], v[200:201], off
	global_load_dwordx4 v[152:155], v[200:201], off offset:256
	s_mov_b32 s2, 0x10000
	v_add_co_u32_e32 v206, vcc, s2, v200
	s_waitcnt vmcnt(2)
	v_pk_add_f32 v[146:147], v[146:147], 1.0 op_sel_hi:[1,0]
	v_pk_add_f32 v[144:145], v[144:145], 1.0 op_sel_hi:[1,0]
	v_addc_co_u32_e32 v207, vcc, 0, v201, vcc
	v_pk_mul_f32 v[162:163], v[138:139], v[146:147]
	v_pk_mul_f32 v[164:165], v[136:137], v[144:145]
	global_load_dwordx4 v[148:151], v[206:207], off offset:2048
	global_load_dwordx4 v[144:147], v[206:207], off offset:2304
	s_mov_b32 s10, 0x21000
	v_add_co_u32_e32 v204, vcc, s10, v200
	s_mov_b32 s11, 0x31000
	s_nop 0
	v_addc_co_u32_e32 v205, vcc, 0, v201, vcc
	v_add_co_u32_e32 v202, vcc, s11, v200
	v_pk_add_f32 v[130:131], v[140:141], 1.0 op_sel_hi:[1,0]
	s_nop 0
	v_addc_co_u32_e32 v203, vcc, 0, v201, vcc
	v_pk_mul_f32 v[168:169], v[132:133], v[130:131]
	v_lshl_add_u64 v[198:199], s[14:15], 0, v[128:129]
	global_load_dwordx4 v[140:143], v[204:205], off
	global_load_dwordx4 v[136:139], v[204:205], off offset:256
	global_load_dwordx4 v[132:135], v[202:203], off offset:2048
	global_load_dwordx4 v[128:131], v[202:203], off offset:2304
	s_mov_b32 s23, 0xb5000
	s_waitcnt vmcnt(7)
	ds_bpermute_b32 v159, v216, v222
	ds_bpermute_b32 v161, v216, v223
	ds_bpermute_b32 v192, v216, v224
	ds_bpermute_b32 v224, v216, v225
	s_waitcnt lgkmcnt(3)
	v_cvt_f32_f16_e32 v194, v159
	v_cvt_f32_f16_sdwa v195, v159 dst_sel:DWORD dst_unused:UNUSED_PAD src0_sel:WORD_1
	s_waitcnt lgkmcnt(2)
	v_cvt_f32_f16_e32 v222, v161
	v_cvt_f32_f16_sdwa v223, v161 dst_sel:DWORD dst_unused:UNUSED_PAD src0_sel:WORD_1
	v_ashrrev_i32_e32 v161, 31, v160
	v_pk_fma_f32 v[124:125], v[124:125], v[196:197], v[194:195]
	s_waitcnt lgkmcnt(1)
	v_cvt_f32_f16_e32 v194, v192
	v_pk_fma_f32 v[126:127], v[126:127], v[190:191], v[222:223]
	v_cvt_f32_f16_sdwa v195, v192 dst_sel:DWORD dst_unused:UNUSED_PAD src0_sel:WORD_1
	s_waitcnt lgkmcnt(0)
	v_cvt_f32_f16_e32 v222, v224
	v_cvt_f32_f16_sdwa v223, v224 dst_sel:DWORD dst_unused:UNUSED_PAD src0_sel:WORD_1
	v_pk_fma_f32 v[194:195], v[120:121], v[188:189], v[194:195]
	v_cvt_pk_f16_f32 v121, v126, v127
	v_pk_fma_f32 v[222:223], v[122:123], v[186:187], v[222:223]
	v_cvt_pk_f16_f32 v122, v194, v195
	v_cvt_pk_f16_f32 v123, v222, v223
	v_cvt_pk_f16_f32 v120, v124, v125
	ds_bpermute_b32 v120, v214, v120
	ds_bpermute_b32 v121, v214, v121
	ds_bpermute_b32 v122, v214, v122
	ds_bpermute_b32 v123, v214, v123
	s_waitcnt lgkmcnt(0)
	global_store_dwordx4 v[200:201], v[120:123], off
	s_nop 1
	v_mul_f32_e32 v120, v125, v125
	v_mul_f32_e32 v121, v127, v127
	v_fmac_f32_e32 v120, v124, v124
	v_fmac_f32_e32 v121, v126, v126
	v_add_f32_e32 v120, v120, v121
	v_mul_f32_e32 v121, v195, v195
	v_mul_f32_e32 v122, v223, v223
	v_fmac_f32_e32 v121, v194, v194
	v_fmac_f32_e32 v122, v222, v222
	v_add_f32_e32 v121, v121, v122
	v_add_f32_e32 v159, v120, v121
	v_pk_mul_f32 v[120:121], v[174:175], v[126:127]
	v_pk_mul_f32 v[122:123], v[176:177], v[124:125]
	v_pk_mul_f32 v[124:125], v[178:179], v[222:223]
	v_pk_mul_f32 v[126:127], v[180:181], v[194:195]
	v_cvt_pk_bf16_f32 v122, v122, v123
	v_cvt_pk_bf16_f32 v121, v120, v121
	ds_bpermute_b32 v120, v214, v122
	v_cvt_pk_bf16_f32 v123, v126, v127
	v_cvt_pk_bf16_f32 v124, v124, v125
	ds_bpermute_b32 v121, v214, v121
	ds_bpermute_b32 v122, v214, v123
	ds_bpermute_b32 v123, v214, v124
	s_waitcnt vmcnt(7)
; __device__ __forceinline__ unsigned cvt_pk_bf16(float lo, float hi) { unsigned r; asm volatile("v_cvt_pk_bf16_f32 %0, %1, %2" : "=v"(r) : "v"(lo), "v"(hi)); return r; }
;     __device__ __forceinline__ void operator()(AccT acc, const pg8::Unit& u, int wr, int wc, int fr, int fq) const {
;     ...
;                 for (int m = 0; m < 4; ++m) { const size_t ro = (size_t)(ai * 128 + m * 16) * LDP; float t = 0.f;
; #pragma unroll
;                     for (int bj = 0; bj < 2; ++bj) { const h16x8 b8 = __builtin_bit_cast(h16x8, gather4(__builtin_bit_cast(u32x4, hb[m][bj]), ld4));
;                         const f32x4 h0 = (f32x4){(float)b8[0], (float)b8[1], (float)b8[2], (float)b8[3]} + gv[bj][0] * acc[ai][bj][m][0], h1 = (f32x4){(float)b8[4], (float)b8[5], (float)b8[6], (float)b8[7]} + gv[bj][1] * acc[ai][bj][m][1];
;                         const h16x4 q0 = __builtin_convertvector(h0, h16x4), q1 = __builtin_convertvector(h1, h16x4);
;                         { const h16x8 hv8 = (h16x8){q0[0], q0[1], q0[2], q0[3], q1[0], q1[1], q1[2], q1[3]}; *(u32x4*)(hout + ro + bj * 128) = gather4(__builtin_bit_cast(u32x4, hv8), st4); }
;                         t += ((h0[0] * h0[0] + h0[1] * h0[1]) + (h0[2] * h0[2] + h0[3] * h0[3])) + ((h1[0] * h1[0] + h1[1] * h1[1]) + (h1[2] * h1[2] + h1[3] * h1[3]));
;                         if (WZ) { const f32x4 z0 = h0 * gz[bj][0], z1 = h1 * gz[bj][1]; u32x4 w; w.x = cvt_pk_bf16(z0[0], z0[1]); w.y = cvt_pk_bf16(z0[2], z0[3]); w.z = cvt_pk_bf16(z1[0], z1[1]); w.w = cvt_pk_bf16(z1[2], z1[3]);
;                             *(u32x4*)(zout + ro + bj * 128) = gather4(w, st4); } }
	ds_bpermute_b32 v124, v216, v154
	ds_bpermute_b32 v125, v216, v155
	s_waitcnt lgkmcnt(2)
	global_store_dwordx4 v[198:199], v[120:123], off
	ds_bpermute_b32 v121, v216, v152
	ds_bpermute_b32 v123, v216, v153
	s_waitcnt lgkmcnt(1)
	v_cvt_f32_f16_e32 v120, v121
	v_cvt_f32_f16_sdwa v121, v121 dst_sel:DWORD dst_unused:UNUSED_PAD src0_sel:WORD_1
	s_waitcnt lgkmcnt(0)
	v_cvt_f32_f16_e32 v122, v123
	v_cvt_f32_f16_sdwa v123, v123 dst_sel:DWORD dst_unused:UNUSED_PAD src0_sel:WORD_1
	v_pk_fma_f32 v[116:117], v[116:117], v[184:185], v[120:121]
	v_cvt_f32_f16_e32 v120, v124
	v_pk_fma_f32 v[118:119], v[118:119], v[182:183], v[122:123]
	v_cvt_f32_f16_sdwa v121, v124 dst_sel:DWORD dst_unused:UNUSED_PAD src0_sel:WORD_1
	v_cvt_f32_f16_e32 v122, v125
	v_cvt_f32_f16_sdwa v123, v125 dst_sel:DWORD dst_unused:UNUSED_PAD src0_sel:WORD_1
	v_pk_fma_f32 v[120:121], v[112:113], v[172:173], v[120:121]
	v_cvt_pk_f16_f32 v113, v118, v119
	v_pk_fma_f32 v[122:123], v[114:115], v[170:171], v[122:123]
	v_cvt_pk_f16_f32 v114, v120, v121
	v_cvt_pk_f16_f32 v115, v122, v123
	v_cvt_pk_f16_f32 v112, v116, v117
	ds_bpermute_b32 v112, v214, v112
	ds_bpermute_b32 v113, v214, v113
	ds_bpermute_b32 v114, v214, v114
	ds_bpermute_b32 v115, v214, v115
	s_waitcnt lgkmcnt(0)
	global_store_dwordx4 v[200:201], v[112:115], off offset:256
	s_nop 1
	v_mul_f32_e32 v112, v117, v117
	v_mul_f32_e32 v113, v119, v119
	v_fmac_f32_e32 v112, v116, v116
	v_fmac_f32_e32 v113, v118, v118
	v_add_f32_e32 v112, v112, v113
	v_mul_f32_e32 v113, v121, v121
	v_mul_f32_e32 v114, v123, v123
	v_fmac_f32_e32 v113, v120, v120
	v_fmac_f32_e32 v114, v122, v122
	v_add_f32_e32 v113, v113, v114
	v_add_f32_e32 v112, v112, v113
	v_add_f32_e32 v152, v159, v112
	v_pk_mul_f32 v[112:113], v[162:163], v[118:119]
	v_pk_mul_f32 v[114:115], v[164:165], v[116:117]
	v_pk_mul_f32 v[116:117], v[166:167], v[122:123]
	v_pk_mul_f32 v[118:119], v[168:169], v[120:121]
	v_cvt_pk_bf16_f32 v114, v114, v115
	v_cvt_pk_bf16_f32 v113, v112, v113
	ds_bpermute_b32 v112, v214, v114
	v_cvt_pk_bf16_f32 v115, v118, v119
	v_cvt_pk_bf16_f32 v116, v116, v117
	ds_bpermute_b32 v113, v214, v113
	ds_bpermute_b32 v114, v214, v115
	ds_bpermute_b32 v115, v214, v116
	s_waitcnt vmcnt(8)
	ds_bpermute_b32 v116, v216, v150
	ds_bpermute_b32 v117, v216, v151
	s_waitcnt lgkmcnt(2)
	global_store_dwordx4 v[198:199], v[112:115], off offset:256
	ds_bpermute_b32 v113, v216, v148
	ds_bpermute_b32 v115, v216, v149
	s_waitcnt lgkmcnt(1)
	v_cvt_f32_f16_e32 v112, v113
	v_cvt_f32_f16_sdwa v113, v113 dst_sel:DWORD dst_unused:UNUSED_PAD src0_sel:WORD_1
	s_waitcnt lgkmcnt(0)
	v_cvt_f32_f16_e32 v114, v115
	v_cvt_f32_f16_sdwa v115, v115 dst_sel:DWORD dst_unused:UNUSED_PAD src0_sel:WORD_1
	v_pk_fma_f32 v[108:109], v[108:109], v[196:197], v[112:113]
	v_cvt_f32_f16_e32 v112, v116
	v_pk_fma_f32 v[110:111], v[110:111], v[190:191], v[114:115]
	v_cvt_f32_f16_sdwa v113, v116 dst_sel:DWORD dst_unused:UNUSED_PAD src0_sel:WORD_1
	v_cvt_f32_f16_e32 v114, v117
	v_cvt_f32_f16_sdwa v115, v117 dst_sel:DWORD dst_unused:UNUSED_PAD src0_sel:WORD_1
	v_pk_fma_f32 v[104:105], v[104:105], v[188:189], v[112:113]
	v_cvt_pk_f16_f32 v113, v110, v111
	v_pk_fma_f32 v[106:107], v[106:107], v[186:187], v[114:115]
	v_cvt_pk_f16_f32 v114, v104, v105
	v_cvt_pk_f16_f32 v115, v106, v107
	v_cvt_pk_f16_f32 v112, v108, v109
	ds_bpermute_b32 v112, v214, v112
	ds_bpermute_b32 v113, v214, v113
	ds_bpermute_b32 v114, v214, v114
	ds_bpermute_b32 v115, v214, v115
	v_pk_mul_f32 v[116:117], v[178:179], v[106:107]
	v_pk_mul_f32 v[118:119], v[180:181], v[104:105]
	s_waitcnt lgkmcnt(0)
	global_store_dwordx4 v[206:207], v[112:115], off offset:2048
	s_nop 1
	v_pk_mul_f32 v[112:113], v[174:175], v[110:111]
	v_pk_mul_f32 v[114:115], v[176:177], v[108:109]
	s_nop 0
	v_cvt_pk_bf16_f32 v114, v114, v115
	v_cvt_pk_bf16_f32 v113, v112, v113
	v_cvt_pk_bf16_f32 v115, v118, v119
	v_cvt_pk_bf16_f32 v116, v116, v117
	ds_bpermute_b32 v112, v214, v114
	ds_bpermute_b32 v113, v214, v113
	ds_bpermute_b32 v114, v214, v115
	ds_bpermute_b32 v115, v214, v116
	v_add_co_u32_e32 v116, vcc, s2, v198
	s_waitcnt vmcnt(9)
	ds_bpermute_b32 v118, v216, v146
	v_addc_co_u32_e32 v117, vcc, 0, v199, vcc
	s_waitcnt lgkmcnt(1)
	global_store_dwordx4 v[116:117], v[112:115], off offset:2048
	ds_bpermute_b32 v113, v216, v144
	ds_bpermute_b32 v115, v216, v145
	ds_bpermute_b32 v119, v216, v147
	s_mov_b32 s2, 0x84000
	s_waitcnt lgkmcnt(2)
	v_cvt_f32_f16_e32 v112, v113
	v_cvt_f32_f16_sdwa v113, v113 dst_sel:DWORD dst_unused:UNUSED_PAD src0_sel:WORD_1
	s_waitcnt lgkmcnt(1)
	v_cvt_f32_f16_e32 v114, v115
	v_cvt_f32_f16_sdwa v115, v115 dst_sel:DWORD dst_unused:UNUSED_PAD src0_sel:WORD_1
	v_pk_fma_f32 v[100:101], v[100:101], v[184:185], v[112:113]
	v_cvt_f32_f16_e32 v112, v118
	v_pk_fma_f32 v[102:103], v[102:103], v[182:183], v[114:115]
	v_cvt_f32_f16_sdwa v113, v118 dst_sel:DWORD dst_unused:UNUSED_PAD src0_sel:WORD_1
	s_waitcnt lgkmcnt(0)
	v_cvt_f32_f16_e32 v114, v119
	v_cvt_f32_f16_sdwa v115, v119 dst_sel:DWORD dst_unused:UNUSED_PAD src0_sel:WORD_1
	v_pk_fma_f32 v[96:97], v[96:97], v[172:173], v[112:113]
	v_cvt_pk_f16_f32 v113, v102, v103
	v_pk_fma_f32 v[98:99], v[98:99], v[170:171], v[114:115]
	v_cvt_pk_f16_f32 v114, v96, v97
	v_cvt_pk_f16_f32 v115, v98, v99
	v_cvt_pk_f16_f32 v112, v100, v101
	ds_bpermute_b32 v112, v214, v112
	ds_bpermute_b32 v113, v214, v113
	ds_bpermute_b32 v114, v214, v114
	ds_bpermute_b32 v115, v214, v115
	v_pk_mul_f32 v[118:119], v[166:167], v[98:99]
	v_pk_mul_f32 v[120:121], v[168:169], v[96:97]
	s_waitcnt lgkmcnt(0)
; __device__ __forceinline__ unsigned cvt_pk_bf16(float lo, float hi) { unsigned r; asm volatile("v_cvt_pk_bf16_f32 %0, %1, %2" : "=v"(r) : "v"(lo), "v"(hi)); return r; }
;     __device__ __forceinline__ void operator()(AccT acc, const pg8::Unit& u, int wr, int wc, int fr, int fq) const {
;     ...
;                 for (int m = 0; m < 4; ++m) { const size_t ro = (size_t)(ai * 128 + m * 16) * LDP; float t = 0.f;
; #pragma unroll
;                     for (int bj = 0; bj < 2; ++bj) { const h16x8 b8 = __builtin_bit_cast(h16x8, gather4(__builtin_bit_cast(u32x4, hb[m][bj]), ld4));
;                         const f32x4 h0 = (f32x4){(float)b8[0], (float)b8[1], (float)b8[2], (float)b8[3]} + gv[bj][0] * acc[ai][bj][m][0], h1 = (f32x4){(float)b8[4], (float)b8[5], (float)b8[6], (float)b8[7]} + gv[bj][1] * acc[ai][bj][m][1];
;                         const h16x4 q0 = __builtin_convertvector(h0, h16x4), q1 = __builtin_convertvector(h1, h16x4);
;                         { const h16x8 hv8 = (h16x8){q0[0], q0[1], q0[2], q0[3], q1[0], q1[1], q1[2], q1[3]}; *(u32x4*)(hout + ro + bj * 128) = gather4(__builtin_bit_cast(u32x4, hv8), st4); }
;                         t += ((h0[0] * h0[0] + h0[1] * h0[1]) + (h0[2] * h0[2] + h0[3] * h0[3])) + ((h1[0] * h1[0] + h1[1] * h1[1]) + (h1[2] * h1[2] + h1[3] * h1[3]));
;                         if (WZ) { const f32x4 z0 = h0 * gz[bj][0], z1 = h1 * gz[bj][1]; u32x4 w; w.x = cvt_pk_bf16(z0[0], z0[1]); w.y = cvt_pk_bf16(z0[2], z0[3]); w.z = cvt_pk_bf16(z1[0], z1[1]); w.w = cvt_pk_bf16(z1[2], z1[3]);
;                             *(u32x4*)(zout + ro + bj * 128) = gather4(w, st4); } }
	global_store_dwordx4 v[206:207], v[112:115], off offset:2304
	s_nop 1
	v_pk_mul_f32 v[112:113], v[162:163], v[102:103]
	v_pk_mul_f32 v[114:115], v[164:165], v[100:101]
	s_nop 0
	v_cvt_pk_bf16_f32 v114, v114, v115
	v_cvt_pk_bf16_f32 v113, v112, v113
	v_cvt_pk_bf16_f32 v115, v120, v121
	v_cvt_pk_bf16_f32 v118, v118, v119
	ds_bpermute_b32 v112, v214, v114
	ds_bpermute_b32 v113, v214, v113
	ds_bpermute_b32 v114, v214, v115
	ds_bpermute_b32 v115, v214, v118
	v_add_co_u32_e32 v120, vcc, s10, v198
	s_mov_b32 s10, 0x94000
	s_nop 0
	v_addc_co_u32_e32 v121, vcc, 0, v199, vcc
	s_waitcnt lgkmcnt(0)
	global_store_dwordx4 v[116:117], v[112:115], off offset:2304
	s_waitcnt vmcnt(11)
	ds_bpermute_b32 v113, v216, v140
	ds_bpermute_b32 v115, v216, v141
	ds_bpermute_b32 v116, v216, v142
	ds_bpermute_b32 v117, v216, v143
	s_waitcnt lgkmcnt(3)
	v_cvt_f32_f16_e32 v112, v113
	v_cvt_f32_f16_sdwa v113, v113 dst_sel:DWORD dst_unused:UNUSED_PAD src0_sel:WORD_1
	s_waitcnt lgkmcnt(2)
	v_cvt_f32_f16_e32 v114, v115
	v_cvt_f32_f16_sdwa v115, v115 dst_sel:DWORD dst_unused:UNUSED_PAD src0_sel:WORD_1
	v_pk_fma_f32 v[92:93], v[92:93], v[196:197], v[112:113]
	s_waitcnt lgkmcnt(1)
	v_cvt_f32_f16_e32 v112, v116
	v_pk_fma_f32 v[94:95], v[94:95], v[190:191], v[114:115]
	v_cvt_f32_f16_sdwa v113, v116 dst_sel:DWORD dst_unused:UNUSED_PAD src0_sel:WORD_1
	s_waitcnt lgkmcnt(0)
	v_cvt_f32_f16_e32 v114, v117
	v_cvt_f32_f16_sdwa v115, v117 dst_sel:DWORD dst_unused:UNUSED_PAD src0_sel:WORD_1
	v_pk_fma_f32 v[88:89], v[88:89], v[188:189], v[112:113]
	v_cvt_pk_f16_f32 v113, v94, v95
	v_pk_fma_f32 v[90:91], v[90:91], v[186:187], v[114:115]
	v_cvt_pk_f16_f32 v114, v88, v89
	v_cvt_pk_f16_f32 v115, v90, v91
	v_cvt_pk_f16_f32 v112, v92, v93
	ds_bpermute_b32 v112, v214, v112
	ds_bpermute_b32 v113, v214, v113
	ds_bpermute_b32 v114, v214, v114
	ds_bpermute_b32 v115, v214, v115
	v_pk_mul_f32 v[116:117], v[178:179], v[90:91]
	v_pk_mul_f32 v[118:119], v[180:181], v[88:89]
	s_waitcnt lgkmcnt(0)
	global_store_dwordx4 v[204:205], v[112:115], off
	s_nop 1
	v_pk_mul_f32 v[112:113], v[174:175], v[94:95]
	v_pk_mul_f32 v[114:115], v[176:177], v[92:93]
	s_nop 0
	v_cvt_pk_bf16_f32 v114, v114, v115
	v_cvt_pk_bf16_f32 v113, v112, v113
	v_cvt_pk_bf16_f32 v115, v118, v119
	v_cvt_pk_bf16_f32 v116, v116, v117
	ds_bpermute_b32 v112, v214, v114
	ds_bpermute_b32 v113, v214, v113
	ds_bpermute_b32 v114, v214, v115
	ds_bpermute_b32 v115, v214, v116
	s_waitcnt vmcnt(11)
	ds_bpermute_b32 v116, v216, v138
	ds_bpermute_b32 v117, v216, v139
	s_waitcnt lgkmcnt(2)
	global_store_dwordx4 v[120:121], v[112:115], off
	ds_bpermute_b32 v112, v216, v136
	ds_bpermute_b32 v113, v216, v137
	s_waitcnt lgkmcnt(1)
	v_cvt_f32_f16_e32 v114, v112
	v_cvt_f32_f16_sdwa v115, v112 dst_sel:DWORD dst_unused:UNUSED_PAD src0_sel:WORD_1
	s_waitcnt lgkmcnt(0)
	v_cvt_f32_f16_e32 v112, v113
	v_cvt_f32_f16_sdwa v113, v113 dst_sel:DWORD dst_unused:UNUSED_PAD src0_sel:WORD_1
	v_pk_fma_f32 v[114:115], v[84:85], v[184:185], v[114:115]
	v_cvt_f32_f16_e32 v84, v116
	v_pk_fma_f32 v[112:113], v[86:87], v[182:183], v[112:113]
	v_cvt_f32_f16_sdwa v85, v116 dst_sel:DWORD dst_unused:UNUSED_PAD src0_sel:WORD_1
	v_cvt_f32_f16_e32 v86, v117
	v_cvt_f32_f16_sdwa v87, v117 dst_sel:DWORD dst_unused:UNUSED_PAD src0_sel:WORD_1
	v_pk_fma_f32 v[118:119], v[80:81], v[172:173], v[84:85]
	v_cvt_pk_f16_f32 v81, v112, v113
	v_pk_fma_f32 v[116:117], v[82:83], v[170:171], v[86:87]
	v_cvt_pk_f16_f32 v82, v118, v119
	v_cvt_pk_f16_f32 v83, v116, v117
	v_cvt_pk_f16_f32 v80, v114, v115
	ds_bpermute_b32 v80, v214, v80
	ds_bpermute_b32 v81, v214, v81
	ds_bpermute_b32 v82, v214, v82
	ds_bpermute_b32 v83, v214, v83
	v_pk_mul_f32 v[84:85], v[166:167], v[116:117]
	v_pk_mul_f32 v[86:87], v[168:169], v[118:119]
	s_waitcnt lgkmcnt(0)
	global_store_dwordx4 v[204:205], v[80:83], off offset:256
	s_nop 1
	v_pk_mul_f32 v[80:81], v[162:163], v[112:113]
	v_pk_mul_f32 v[82:83], v[164:165], v[114:115]
	s_nop 0
	v_cvt_pk_bf16_f32 v82, v82, v83
	v_cvt_pk_bf16_f32 v81, v80, v81
	v_cvt_pk_bf16_f32 v83, v86, v87
	v_cvt_pk_bf16_f32 v84, v84, v85
	ds_bpermute_b32 v80, v214, v82
	ds_bpermute_b32 v81, v214, v81
	ds_bpermute_b32 v82, v214, v83
	ds_bpermute_b32 v83, v214, v84
	s_waitcnt vmcnt(12)
	ds_bpermute_b32 v84, v216, v134
	ds_bpermute_b32 v85, v216, v135
	s_waitcnt lgkmcnt(2)
	global_store_dwordx4 v[120:121], v[80:83], off offset:256
	ds_bpermute_b32 v81, v216, v132
	ds_bpermute_b32 v83, v216, v133
	s_waitcnt lgkmcnt(1)
	v_cvt_f32_f16_e32 v80, v81
	v_cvt_f32_f16_sdwa v81, v81 dst_sel:DWORD dst_unused:UNUSED_PAD src0_sel:WORD_1
	s_waitcnt lgkmcnt(0)
	v_cvt_f32_f16_e32 v82, v83
	v_cvt_f32_f16_sdwa v83, v83 dst_sel:DWORD dst_unused:UNUSED_PAD src0_sel:WORD_1
	v_pk_fma_f32 v[122:123], v[76:77], v[196:197], v[80:81]
	v_cvt_f32_f16_e32 v76, v84
	v_pk_fma_f32 v[120:121], v[78:79], v[190:191], v[82:83]
	v_cvt_f32_f16_sdwa v77, v84 dst_sel:DWORD dst_unused:UNUSED_PAD src0_sel:WORD_1
	v_cvt_f32_f16_e32 v78, v85
	v_cvt_f32_f16_sdwa v79, v85 dst_sel:DWORD dst_unused:UNUSED_PAD src0_sel:WORD_1
	v_pk_fma_f32 v[126:127], v[72:73], v[188:189], v[76:77]
	v_cvt_pk_f16_f32 v73, v120, v121
	v_pk_fma_f32 v[124:125], v[74:75], v[186:187], v[78:79]
	v_cvt_pk_f16_f32 v74, v126, v127
	v_cvt_pk_f16_f32 v75, v124, v125
	v_cvt_pk_f16_f32 v72, v122, v123
	ds_bpermute_b32 v72, v214, v72
	ds_bpermute_b32 v73, v214, v73
	ds_bpermute_b32 v74, v214, v74
	ds_bpermute_b32 v75, v214, v75
	v_pk_mul_f32 v[76:77], v[178:179], v[124:125]
	v_pk_mul_f32 v[78:79], v[180:181], v[126:127]
	s_waitcnt lgkmcnt(0)
; __device__ __forceinline__ unsigned cvt_pk_bf16(float lo, float hi) { unsigned r; asm volatile("v_cvt_pk_bf16_f32 %0, %1, %2" : "=v"(r) : "v"(lo), "v"(hi)); return r; }
;     __device__ __forceinline__ void operator()(AccT acc, const pg8::Unit& u, int wr, int wc, int fr, int fq) const {
;     ...
;             const hf_t* base = (const hf_t*)(u.pm < 64 ? baseL : baseC) + eo;
;             h16x8 hb[4][2];
; #pragma unroll
;             for (int ai = 0; ai < 2; ++ai) {
; #pragma unroll
;                 for (int m = 0; m < 4; ++m)
; #pragma unroll
;                     for (int bj = 0; bj < 2; ++bj) hb[m][bj] = *(const h16x8*)(base + (size_t)(ai * 128 + m * 16) * LDP + bj * 128);
;                 asm volatile("" ::: "memory");
; #pragma unroll
;                 for (int m = 0; m < 4; ++m) { const size_t ro = (size_t)(ai * 128 + m * 16) * LDP; float t = 0.f;
; #pragma unroll
;                     for (int bj = 0; bj < 2; ++bj) { const h16x8 b8 = __builtin_bit_cast(h16x8, gather4(__builtin_bit_cast(u32x4, hb[m][bj]), ld4));
;                         const f32x4 h0 = (f32x4){(float)b8[0], (float)b8[1], (float)b8[2], (float)b8[3]} + gv[bj][0] * acc[ai][bj][m][0], h1 = (f32x4){(float)b8[4], (float)b8[5], (float)b8[6], (float)b8[7]} + gv[bj][1] * acc[ai][bj][m][1];
;                         const h16x4 q0 = __builtin_convertvector(h0, h16x4), q1 = __builtin_convertvector(h1, h16x4);
;                         { const h16x8 hv8 = (h16x8){q0[0], q0[1], q0[2], q0[3], q1[0], q1[1], q1[2], q1[3]}; *(u32x4*)(hout + ro + bj * 128) = gather4(__builtin_bit_cast(u32x4, hv8), st4); }
;                         t += ((h0[0] * h0[0] + h0[1] * h0[1]) + (h0[2] * h0[2] + h0[3] * h0[3])) + ((h1[0] * h1[0] + h1[1] * h1[1]) + (h1[2] * h1[2] + h1[3] * h1[3]));
;                         if (WZ) { const f32x4 z0 = h0 * gz[bj][0], z1 = h1 * gz[bj][1]; u32x4 w; w.x = cvt_pk_bf16(z0[0], z0[1]); w.y = cvt_pk_bf16(z0[2], z0[3]); w.z = cvt_pk_bf16(z1[0], z1[1]); w.w = cvt_pk_bf16(z1[2], z1[3]);
;                             *(u32x4*)(zout + ro + bj * 128) = gather4(w, st4); } }
	global_store_dwordx4 v[202:203], v[72:75], off offset:2048
	s_nop 1
	v_pk_mul_f32 v[72:73], v[174:175], v[120:121]
	v_pk_mul_f32 v[74:75], v[176:177], v[122:123]
	s_nop 0
	v_cvt_pk_bf16_f32 v74, v74, v75
	v_cvt_pk_bf16_f32 v73, v72, v73
	v_cvt_pk_bf16_f32 v75, v78, v79
	v_cvt_pk_bf16_f32 v76, v76, v77
	ds_bpermute_b32 v72, v214, v74
	ds_bpermute_b32 v73, v214, v73
	ds_bpermute_b32 v74, v214, v75
	ds_bpermute_b32 v75, v214, v76
	v_add_co_u32_e32 v76, vcc, s11, v198
	s_waitcnt vmcnt(13)
	ds_bpermute_b32 v78, v216, v130
	v_addc_co_u32_e32 v77, vcc, 0, v199, vcc
	s_waitcnt lgkmcnt(1)
	global_store_dwordx4 v[76:77], v[72:75], off offset:2048
	ds_bpermute_b32 v73, v216, v128
	ds_bpermute_b32 v75, v216, v129
	ds_bpermute_b32 v79, v216, v131
	v_add_co_u32_e32 v142, vcc, s2, v200
	s_waitcnt lgkmcnt(2)
	v_cvt_f32_f16_e32 v72, v73
	v_cvt_f32_f16_sdwa v73, v73 dst_sel:DWORD dst_unused:UNUSED_PAD src0_sel:WORD_1
	s_waitcnt lgkmcnt(1)
	v_cvt_f32_f16_e32 v74, v75
	v_cvt_f32_f16_sdwa v75, v75 dst_sel:DWORD dst_unused:UNUSED_PAD src0_sel:WORD_1
	v_addc_co_u32_e32 v143, vcc, 0, v201, vcc
	v_pk_fma_f32 v[130:131], v[68:69], v[184:185], v[72:73]
	v_pk_fma_f32 v[128:129], v[70:71], v[182:183], v[74:75]
	v_cvt_f32_f16_e32 v68, v78
	v_cvt_f32_f16_sdwa v69, v78 dst_sel:DWORD dst_unused:UNUSED_PAD src0_sel:WORD_1
	s_waitcnt lgkmcnt(0)
	v_cvt_f32_f16_e32 v70, v79
	v_cvt_f32_f16_sdwa v71, v79 dst_sel:DWORD dst_unused:UNUSED_PAD src0_sel:WORD_1
	v_add_co_u32_e32 v140, vcc, s10, v200
	v_pk_fma_f32 v[134:135], v[64:65], v[172:173], v[68:69]
	v_pk_fma_f32 v[132:133], v[66:67], v[170:171], v[70:71]
	v_cvt_pk_f16_f32 v66, v134, v135
	v_cvt_pk_f16_f32 v67, v132, v133
	v_cvt_pk_f16_f32 v65, v128, v129
	v_cvt_pk_f16_f32 v64, v130, v131
	ds_bpermute_b32 v64, v214, v64
	ds_bpermute_b32 v65, v214, v65
	ds_bpermute_b32 v66, v214, v66
	ds_bpermute_b32 v67, v214, v67
	v_pk_mul_f32 v[68:69], v[166:167], v[132:133]
	v_pk_mul_f32 v[70:71], v[168:169], v[134:135]
	v_addc_co_u32_e32 v141, vcc, 0, v201, vcc
	s_waitcnt lgkmcnt(0)
	global_store_dwordx4 v[202:203], v[64:67], off offset:2304
	s_mov_b32 s11, 0xa5000
	v_add_co_u32_e32 v138, vcc, s11, v200
	v_pk_mul_f32 v[64:65], v[162:163], v[128:129]
	v_pk_mul_f32 v[66:67], v[164:165], v[130:131]
	v_addc_co_u32_e32 v139, vcc, 0, v201, vcc
	v_cvt_pk_bf16_f32 v66, v66, v67
	v_cvt_pk_bf16_f32 v65, v64, v65
	v_cvt_pk_bf16_f32 v67, v70, v71
	v_cvt_pk_bf16_f32 v68, v68, v69
	ds_bpermute_b32 v64, v214, v66
	ds_bpermute_b32 v65, v214, v65
	ds_bpermute_b32 v66, v214, v67
	ds_bpermute_b32 v67, v214, v68
	v_add_co_u32_e32 v136, vcc, s23, v200
	s_waitcnt lgkmcnt(0)
	global_store_dwordx4 v[76:77], v[64:67], off offset:2304
	global_load_dwordx4 v[144:147], v[142:143], off
	global_load_dwordx4 v[148:151], v[142:143], off offset:256
	global_load_dwordx4 v[84:87], v[140:141], off offset:2048
	global_load_dwordx4 v[80:83], v[140:141], off offset:2304
	v_addc_co_u32_e32 v137, vcc, 0, v201, vcc
	global_load_dwordx4 v[76:79], v[138:139], off
	global_load_dwordx4 v[72:75], v[138:139], off offset:256
	global_load_dwordx4 v[68:71], v[136:137], off offset:2048
	global_load_dwordx4 v[64:67], v[136:137], off offset:2304
	s_waitcnt vmcnt(7)
	ds_bpermute_b32 v153, v216, v144
	ds_bpermute_b32 v154, v216, v145
	ds_bpermute_b32 v155, v216, v146
	ds_bpermute_b32 v159, v216, v147
	s_waitcnt lgkmcnt(3)
	v_cvt_f32_f16_e32 v144, v153
	v_cvt_f32_f16_sdwa v145, v153 dst_sel:DWORD dst_unused:UNUSED_PAD src0_sel:WORD_1
	s_waitcnt lgkmcnt(2)
	v_cvt_f32_f16_e32 v146, v154
	v_cvt_f32_f16_sdwa v147, v154 dst_sel:DWORD dst_unused:UNUSED_PAD src0_sel:WORD_1
	v_pk_fma_f32 v[60:61], v[60:61], v[196:197], v[144:145]
	s_waitcnt lgkmcnt(1)
	v_cvt_f32_f16_e32 v144, v155
	v_pk_fma_f32 v[62:63], v[62:63], v[190:191], v[146:147]
	v_cvt_f32_f16_sdwa v145, v155 dst_sel:DWORD dst_unused:UNUSED_PAD src0_sel:WORD_1
	s_waitcnt lgkmcnt(0)
	v_cvt_f32_f16_e32 v146, v159
	v_cvt_f32_f16_sdwa v147, v159 dst_sel:DWORD dst_unused:UNUSED_PAD src0_sel:WORD_1
	v_pk_fma_f32 v[56:57], v[56:57], v[188:189], v[144:145]
	v_cvt_pk_f16_f32 v145, v62, v63
	v_pk_fma_f32 v[58:59], v[58:59], v[186:187], v[146:147]
	v_cvt_pk_f16_f32 v146, v56, v57
	v_cvt_pk_f16_f32 v147, v58, v59
	v_cvt_pk_f16_f32 v144, v60, v61
	ds_bpermute_b32 v144, v214, v144
	ds_bpermute_b32 v145, v214, v145
	ds_bpermute_b32 v146, v214, v146
	ds_bpermute_b32 v147, v214, v147
	v_pk_mul_f32 v[194:195], v[180:181], v[56:57]
	v_pk_mul_f32 v[154:155], v[178:179], v[58:59]
	s_waitcnt lgkmcnt(0)
	global_store_dwordx4 v[142:143], v[144:147], off
	s_nop 1
	v_pk_mul_f32 v[144:145], v[174:175], v[62:63]
	v_pk_mul_f32 v[146:147], v[176:177], v[60:61]
	s_nop 0
	v_cvt_pk_bf16_f32 v146, v146, v147
	v_cvt_pk_bf16_f32 v145, v144, v145
	v_cvt_pk_bf16_f32 v147, v194, v195
	v_cvt_pk_bf16_f32 v153, v154, v155
	ds_bpermute_b32 v144, v214, v146
	ds_bpermute_b32 v145, v214, v145
	ds_bpermute_b32 v146, v214, v147
	ds_bpermute_b32 v147, v214, v153
	v_add_co_u32_e32 v154, vcc, s2, v198
	s_nop 1
	v_addc_co_u32_e32 v155, vcc, 0, v199, vcc
	s_waitcnt lgkmcnt(0)
	global_store_dwordx4 v[154:155], v[144:147], off
	s_waitcnt vmcnt(8)
	ds_bpermute_b32 v145, v216, v148
	ds_bpermute_b32 v147, v216, v149
	ds_bpermute_b32 v148, v216, v150
	ds_bpermute_b32 v149, v216, v151
	s_waitcnt lgkmcnt(3)
	v_cvt_f32_f16_e32 v144, v145
	v_cvt_f32_f16_sdwa v145, v145 dst_sel:DWORD dst_unused:UNUSED_PAD src0_sel:WORD_1
	s_waitcnt lgkmcnt(2)
	v_cvt_f32_f16_e32 v146, v147
	v_cvt_f32_f16_sdwa v147, v147 dst_sel:DWORD dst_unused:UNUSED_PAD src0_sel:WORD_1
	v_pk_fma_f32 v[52:53], v[52:53], v[184:185], v[144:145]
	s_waitcnt lgkmcnt(1)
; __device__ __forceinline__ unsigned cvt_pk_bf16(float lo, float hi) { unsigned r; asm volatile("v_cvt_pk_bf16_f32 %0, %1, %2" : "=v"(r) : "v"(lo), "v"(hi)); return r; }
;     __device__ __forceinline__ void operator()(AccT acc, const pg8::Unit& u, int wr, int wc, int fr, int fq) const {
;     ...
;                 for (int m = 0; m < 4; ++m) { const size_t ro = (size_t)(ai * 128 + m * 16) * LDP; float t = 0.f;
; #pragma unroll
;                     for (int bj = 0; bj < 2; ++bj) { const h16x8 b8 = __builtin_bit_cast(h16x8, gather4(__builtin_bit_cast(u32x4, hb[m][bj]), ld4));
;                         const f32x4 h0 = (f32x4){(float)b8[0], (float)b8[1], (float)b8[2], (float)b8[3]} + gv[bj][0] * acc[ai][bj][m][0], h1 = (f32x4){(float)b8[4], (float)b8[5], (float)b8[6], (float)b8[7]} + gv[bj][1] * acc[ai][bj][m][1];
;                         const h16x4 q0 = __builtin_convertvector(h0, h16x4), q1 = __builtin_convertvector(h1, h16x4);
;                         { const h16x8 hv8 = (h16x8){q0[0], q0[1], q0[2], q0[3], q1[0], q1[1], q1[2], q1[3]}; *(u32x4*)(hout + ro + bj * 128) = gather4(__builtin_bit_cast(u32x4, hv8), st4); }
;                         t += ((h0[0] * h0[0] + h0[1] * h0[1]) + (h0[2] * h0[2] + h0[3] * h0[3])) + ((h1[0] * h1[0] + h1[1] * h1[1]) + (h1[2] * h1[2] + h1[3] * h1[3]));
;                         if (WZ) { const f32x4 z0 = h0 * gz[bj][0], z1 = h1 * gz[bj][1]; u32x4 w; w.x = cvt_pk_bf16(z0[0], z0[1]); w.y = cvt_pk_bf16(z0[2], z0[3]); w.z = cvt_pk_bf16(z1[0], z1[1]); w.w = cvt_pk_bf16(z1[2], z1[3]);
;                             *(u32x4*)(zout + ro + bj * 128) = gather4(w, st4); } }
	v_cvt_f32_f16_e32 v144, v148
	v_pk_fma_f32 v[54:55], v[54:55], v[182:183], v[146:147]
	v_cvt_f32_f16_sdwa v145, v148 dst_sel:DWORD dst_unused:UNUSED_PAD src0_sel:WORD_1
	s_waitcnt lgkmcnt(0)
	v_cvt_f32_f16_e32 v146, v149
	v_cvt_f32_f16_sdwa v147, v149 dst_sel:DWORD dst_unused:UNUSED_PAD src0_sel:WORD_1
	v_pk_fma_f32 v[48:49], v[48:49], v[172:173], v[144:145]
	v_cvt_pk_f16_f32 v145, v54, v55
	v_pk_fma_f32 v[50:51], v[50:51], v[170:171], v[146:147]
	v_cvt_pk_f16_f32 v146, v48, v49
	v_cvt_pk_f16_f32 v147, v50, v51
	v_cvt_pk_f16_f32 v144, v52, v53
	ds_bpermute_b32 v144, v214, v144
	ds_bpermute_b32 v145, v214, v145
	ds_bpermute_b32 v146, v214, v146
	ds_bpermute_b32 v147, v214, v147
	v_pk_mul_f32 v[148:149], v[168:169], v[48:49]
	s_waitcnt lgkmcnt(0)
	global_store_dwordx4 v[142:143], v[144:147], off offset:256
	v_pk_mul_f32 v[142:143], v[162:163], v[54:55]
	s_nop 0
	v_pk_mul_f32 v[144:145], v[164:165], v[52:53]
	v_pk_mul_f32 v[146:147], v[166:167], v[50:51]
	v_cvt_pk_bf16_f32 v144, v144, v145
	v_cvt_pk_bf16_f32 v143, v142, v143
	v_cvt_pk_bf16_f32 v145, v148, v149
	ds_bpermute_b32 v142, v214, v144
	v_cvt_pk_bf16_f32 v146, v146, v147
	ds_bpermute_b32 v143, v214, v143
	ds_bpermute_b32 v144, v214, v145
	ds_bpermute_b32 v145, v214, v146
	s_waitcnt lgkmcnt(0)
	global_store_dwordx4 v[154:155], v[142:145], off offset:256
	s_waitcnt vmcnt(9)
	ds_bpermute_b32 v142, v216, v84
	ds_bpermute_b32 v143, v216, v85
	ds_bpermute_b32 v144, v216, v86
	ds_bpermute_b32 v145, v216, v87
	s_waitcnt lgkmcnt(3)
	v_cvt_f32_f16_e32 v84, v142
	v_cvt_f32_f16_sdwa v85, v142 dst_sel:DWORD dst_unused:UNUSED_PAD src0_sel:WORD_1
	s_waitcnt lgkmcnt(2)
	v_cvt_f32_f16_e32 v86, v143
	v_cvt_f32_f16_sdwa v87, v143 dst_sel:DWORD dst_unused:UNUSED_PAD src0_sel:WORD_1
	v_pk_fma_f32 v[44:45], v[44:45], v[196:197], v[84:85]
	s_waitcnt lgkmcnt(1)
	v_cvt_f32_f16_e32 v84, v144
	v_pk_fma_f32 v[46:47], v[46:47], v[190:191], v[86:87]
	v_cvt_f32_f16_sdwa v85, v144 dst_sel:DWORD dst_unused:UNUSED_PAD src0_sel:WORD_1
	s_waitcnt lgkmcnt(0)
	v_cvt_f32_f16_e32 v86, v145
	v_cvt_f32_f16_sdwa v87, v145 dst_sel:DWORD dst_unused:UNUSED_PAD src0_sel:WORD_1
	v_pk_fma_f32 v[40:41], v[40:41], v[188:189], v[84:85]
	v_cvt_pk_f16_f32 v85, v46, v47
	v_pk_fma_f32 v[42:43], v[42:43], v[186:187], v[86:87]
	v_cvt_pk_f16_f32 v86, v40, v41
	v_cvt_pk_f16_f32 v87, v42, v43
	v_cvt_pk_f16_f32 v84, v44, v45
	ds_bpermute_b32 v84, v214, v84
	ds_bpermute_b32 v85, v214, v85
	ds_bpermute_b32 v86, v214, v86
	ds_bpermute_b32 v87, v214, v87
	v_pk_mul_f32 v[142:143], v[178:179], v[42:43]
	v_pk_mul_f32 v[144:145], v[180:181], v[40:41]
	s_waitcnt lgkmcnt(0)
	global_store_dwordx4 v[140:141], v[84:87], off offset:2048
	s_nop 1
	v_pk_mul_f32 v[84:85], v[174:175], v[46:47]
	v_pk_mul_f32 v[86:87], v[176:177], v[44:45]
	s_nop 0
	v_cvt_pk_bf16_f32 v86, v86, v87
	v_cvt_pk_bf16_f32 v85, v84, v85
	v_cvt_pk_bf16_f32 v87, v144, v145
	v_cvt_pk_bf16_f32 v142, v142, v143
	ds_bpermute_b32 v84, v214, v86
	ds_bpermute_b32 v85, v214, v85
	ds_bpermute_b32 v86, v214, v87
	ds_bpermute_b32 v87, v214, v142
	v_add_co_u32_e32 v142, vcc, s10, v198
	s_nop 1
	v_addc_co_u32_e32 v143, vcc, 0, v199, vcc
	s_waitcnt lgkmcnt(0)
	global_store_dwordx4 v[142:143], v[84:87], off offset:2048
	s_waitcnt vmcnt(10)
	ds_bpermute_b32 v84, v216, v80
	ds_bpermute_b32 v85, v216, v81
	ds_bpermute_b32 v86, v216, v82
	ds_bpermute_b32 v87, v216, v83
	s_waitcnt lgkmcnt(3)
	v_cvt_f32_f16_e32 v80, v84
	v_cvt_f32_f16_sdwa v81, v84 dst_sel:DWORD dst_unused:UNUSED_PAD src0_sel:WORD_1
	s_waitcnt lgkmcnt(2)
	v_cvt_f32_f16_e32 v82, v85
	v_cvt_f32_f16_sdwa v83, v85 dst_sel:DWORD dst_unused:UNUSED_PAD src0_sel:WORD_1
	v_pk_fma_f32 v[36:37], v[36:37], v[184:185], v[80:81]
	s_waitcnt lgkmcnt(1)
	v_cvt_f32_f16_e32 v80, v86
	v_pk_fma_f32 v[38:39], v[38:39], v[182:183], v[82:83]
	v_cvt_f32_f16_sdwa v81, v86 dst_sel:DWORD dst_unused:UNUSED_PAD src0_sel:WORD_1
	s_waitcnt lgkmcnt(0)
	v_cvt_f32_f16_e32 v82, v87
	v_cvt_f32_f16_sdwa v83, v87 dst_sel:DWORD dst_unused:UNUSED_PAD src0_sel:WORD_1
	v_pk_fma_f32 v[32:33], v[32:33], v[172:173], v[80:81]
	v_cvt_pk_f16_f32 v81, v38, v39
	v_pk_fma_f32 v[34:35], v[34:35], v[170:171], v[82:83]
	v_cvt_pk_f16_f32 v82, v32, v33
	v_cvt_pk_f16_f32 v83, v34, v35
	v_cvt_pk_f16_f32 v80, v36, v37
	ds_bpermute_b32 v80, v214, v80
	ds_bpermute_b32 v81, v214, v81
	ds_bpermute_b32 v82, v214, v82
	ds_bpermute_b32 v83, v214, v83
	v_pk_mul_f32 v[84:85], v[166:167], v[34:35]
	v_pk_mul_f32 v[86:87], v[168:169], v[32:33]
	s_waitcnt lgkmcnt(0)
	global_store_dwordx4 v[140:141], v[80:83], off offset:2304
	s_nop 1
	v_pk_mul_f32 v[80:81], v[162:163], v[38:39]
	v_pk_mul_f32 v[82:83], v[164:165], v[36:37]
	s_nop 0
	v_cvt_pk_bf16_f32 v82, v82, v83
	v_cvt_pk_bf16_f32 v81, v80, v81
	v_cvt_pk_bf16_f32 v83, v86, v87
	v_cvt_pk_bf16_f32 v84, v84, v85
	ds_bpermute_b32 v80, v214, v82
	ds_bpermute_b32 v81, v214, v81
	ds_bpermute_b32 v82, v214, v83
	ds_bpermute_b32 v83, v214, v84
	s_waitcnt lgkmcnt(0)
	global_store_dwordx4 v[142:143], v[80:83], off offset:2304
	s_waitcnt vmcnt(11)
	ds_bpermute_b32 v80, v216, v76
	ds_bpermute_b32 v81, v216, v77
	ds_bpermute_b32 v82, v216, v78
	ds_bpermute_b32 v83, v216, v79
	s_waitcnt lgkmcnt(3)
	v_cvt_f32_f16_e32 v76, v80
	v_cvt_f32_f16_sdwa v77, v80 dst_sel:DWORD dst_unused:UNUSED_PAD src0_sel:WORD_1
	s_waitcnt lgkmcnt(2)
	v_cvt_f32_f16_e32 v78, v81
	v_cvt_f32_f16_sdwa v79, v81 dst_sel:DWORD dst_unused:UNUSED_PAD src0_sel:WORD_1
	v_pk_fma_f32 v[28:29], v[28:29], v[196:197], v[76:77]
	s_waitcnt lgkmcnt(1)
	v_cvt_f32_f16_e32 v76, v82
	v_pk_fma_f32 v[30:31], v[30:31], v[190:191], v[78:79]
	v_cvt_f32_f16_sdwa v77, v82 dst_sel:DWORD dst_unused:UNUSED_PAD src0_sel:WORD_1
	s_waitcnt lgkmcnt(0)
; __device__ __forceinline__ unsigned cvt_pk_bf16(float lo, float hi) { unsigned r; asm volatile("v_cvt_pk_bf16_f32 %0, %1, %2" : "=v"(r) : "v"(lo), "v"(hi)); return r; }
; __device__ __forceinline__ float xlane(float v, int src_lane) { return __uint_as_float(__builtin_amdgcn_ds_bpermute(src_lane << 2, __float_as_uint(v))); }
;     __device__ __forceinline__ void operator()(AccT acc, const pg8::Unit& u, int wr, int wc, int fr, int fq) const {
;     ...
;                 for (int m = 0; m < 4; ++m) { const size_t ro = (size_t)(ai * 128 + m * 16) * LDP; float t = 0.f;
; #pragma unroll
;                     for (int bj = 0; bj < 2; ++bj) { const h16x8 b8 = __builtin_bit_cast(h16x8, gather4(__builtin_bit_cast(u32x4, hb[m][bj]), ld4));
;                         const f32x4 h0 = (f32x4){(float)b8[0], (float)b8[1], (float)b8[2], (float)b8[3]} + gv[bj][0] * acc[ai][bj][m][0], h1 = (f32x4){(float)b8[4], (float)b8[5], (float)b8[6], (float)b8[7]} + gv[bj][1] * acc[ai][bj][m][1];
;                         const h16x4 q0 = __builtin_convertvector(h0, h16x4), q1 = __builtin_convertvector(h1, h16x4);
;                         { const h16x8 hv8 = (h16x8){q0[0], q0[1], q0[2], q0[3], q1[0], q1[1], q1[2], q1[3]}; *(u32x4*)(hout + ro + bj * 128) = gather4(__builtin_bit_cast(u32x4, hv8), st4); }
;                         t += ((h0[0] * h0[0] + h0[1] * h0[1]) + (h0[2] * h0[2] + h0[3] * h0[3])) + ((h1[0] * h1[0] + h1[1] * h1[1]) + (h1[2] * h1[2] + h1[3] * h1[3]));
;                         if (WZ) { const f32x4 z0 = h0 * gz[bj][0], z1 = h1 * gz[bj][1]; u32x4 w; w.x = cvt_pk_bf16(z0[0], z0[1]); w.y = cvt_pk_bf16(z0[2], z0[3]); w.z = cvt_pk_bf16(z1[0], z1[1]); w.w = cvt_pk_bf16(z1[2], z1[3]);
;                             *(u32x4*)(zout + ro + bj * 128) = gather4(w, st4); } }
;                     ss[ai * 4 + m] = t; }
;                 asm volatile("" ::: "memory");
;             }
;         }
; #pragma unroll
;         for (int g = 0; g < 8; ++g) { float t = ss[g]; t += xlane(t, lane ^ 16); t += xlane(t, lane ^ 32);
;             if (fq == 0) SSQ[(size_t)(row0 + (g >> 2) * 128 + (g & 3) * 16) * 32 + u.pn * 4 + wc] = t; }
	v_cvt_f32_f16_e32 v78, v83
	v_cvt_f32_f16_sdwa v79, v83 dst_sel:DWORD dst_unused:UNUSED_PAD src0_sel:WORD_1
	v_pk_fma_f32 v[24:25], v[24:25], v[188:189], v[76:77]
	v_cvt_pk_f16_f32 v77, v30, v31
	v_pk_fma_f32 v[26:27], v[26:27], v[186:187], v[78:79]
	v_cvt_pk_f16_f32 v78, v24, v25
	v_cvt_pk_f16_f32 v79, v26, v27
	v_cvt_pk_f16_f32 v76, v28, v29
	ds_bpermute_b32 v76, v214, v76
	ds_bpermute_b32 v77, v214, v77
	ds_bpermute_b32 v78, v214, v78
	ds_bpermute_b32 v79, v214, v79
	v_pk_mul_f32 v[80:81], v[178:179], v[26:27]
	v_pk_mul_f32 v[82:83], v[180:181], v[24:25]
	s_waitcnt lgkmcnt(0)
	global_store_dwordx4 v[138:139], v[76:79], off
	s_nop 1
	v_pk_mul_f32 v[76:77], v[174:175], v[30:31]
	v_pk_mul_f32 v[78:79], v[176:177], v[28:29]
	s_nop 0
	v_cvt_pk_bf16_f32 v78, v78, v79
	v_cvt_pk_bf16_f32 v77, v76, v77
	v_cvt_pk_bf16_f32 v79, v82, v83
	v_cvt_pk_bf16_f32 v80, v80, v81
	ds_bpermute_b32 v76, v214, v78
	ds_bpermute_b32 v77, v214, v77
	ds_bpermute_b32 v78, v214, v79
	ds_bpermute_b32 v79, v214, v80
	v_add_co_u32_e32 v80, vcc, s11, v198
	s_lshl_b64 s[10:11], s[40:41], 2
	s_nop 0
	v_addc_co_u32_e32 v81, vcc, 0, v199, vcc
	s_waitcnt lgkmcnt(0)
	global_store_dwordx4 v[80:81], v[76:79], off
	s_waitcnt vmcnt(12)
	ds_bpermute_b32 v76, v216, v72
	ds_bpermute_b32 v77, v216, v73
	ds_bpermute_b32 v78, v216, v74
	ds_bpermute_b32 v79, v216, v75
	s_add_u32 s30, s97, s10
	s_waitcnt lgkmcnt(3)
	v_cvt_f32_f16_e32 v72, v76
	v_cvt_f32_f16_sdwa v73, v76 dst_sel:DWORD dst_unused:UNUSED_PAD src0_sel:WORD_1
	s_waitcnt lgkmcnt(2)
	v_cvt_f32_f16_e32 v74, v77
	v_cvt_f32_f16_sdwa v75, v77 dst_sel:DWORD dst_unused:UNUSED_PAD src0_sel:WORD_1
	s_addc_u32 s31, s90, s11
	v_pk_fma_f32 v[20:21], v[20:21], v[184:185], v[72:73]
	s_waitcnt lgkmcnt(1)
	v_cvt_f32_f16_e32 v72, v78
	v_pk_fma_f32 v[22:23], v[22:23], v[182:183], v[74:75]
	v_cvt_f32_f16_sdwa v73, v78 dst_sel:DWORD dst_unused:UNUSED_PAD src0_sel:WORD_1
	s_waitcnt lgkmcnt(0)
	v_cvt_f32_f16_e32 v74, v79
	v_cvt_f32_f16_sdwa v75, v79 dst_sel:DWORD dst_unused:UNUSED_PAD src0_sel:WORD_1
	v_pk_fma_f32 v[16:17], v[16:17], v[172:173], v[72:73]
	v_cvt_pk_f16_f32 v73, v22, v23
	v_pk_fma_f32 v[18:19], v[18:19], v[170:171], v[74:75]
	v_cvt_pk_f16_f32 v74, v16, v17
	v_cvt_pk_f16_f32 v75, v18, v19
	v_cvt_pk_f16_f32 v72, v20, v21
	ds_bpermute_b32 v72, v214, v72
	ds_bpermute_b32 v73, v214, v73
	ds_bpermute_b32 v74, v214, v74
	ds_bpermute_b32 v75, v214, v75
	v_pk_mul_f32 v[76:77], v[166:167], v[18:19]
	v_pk_mul_f32 v[78:79], v[168:169], v[16:17]
	s_waitcnt lgkmcnt(0)
	global_store_dwordx4 v[138:139], v[72:75], off offset:256
	s_nop 1
	v_pk_mul_f32 v[72:73], v[162:163], v[22:23]
	v_pk_mul_f32 v[74:75], v[164:165], v[20:21]
	s_nop 0
	v_cvt_pk_bf16_f32 v74, v74, v75
	v_cvt_pk_bf16_f32 v73, v72, v73
	v_cvt_pk_bf16_f32 v75, v78, v79
	v_cvt_pk_bf16_f32 v76, v76, v77
	ds_bpermute_b32 v72, v214, v74
	ds_bpermute_b32 v73, v214, v73
	ds_bpermute_b32 v74, v214, v75
	ds_bpermute_b32 v75, v214, v76
	s_waitcnt lgkmcnt(0)
	global_store_dwordx4 v[80:81], v[72:75], off offset:256
	s_waitcnt vmcnt(13)
	ds_bpermute_b32 v72, v216, v68
	ds_bpermute_b32 v73, v216, v69
	ds_bpermute_b32 v74, v216, v70
	ds_bpermute_b32 v75, v216, v71
	s_waitcnt lgkmcnt(3)
	v_cvt_f32_f16_e32 v68, v72
	v_cvt_f32_f16_sdwa v69, v72 dst_sel:DWORD dst_unused:UNUSED_PAD src0_sel:WORD_1
	s_waitcnt lgkmcnt(2)
	v_cvt_f32_f16_e32 v70, v73
	v_cvt_f32_f16_sdwa v71, v73 dst_sel:DWORD dst_unused:UNUSED_PAD src0_sel:WORD_1
	v_pk_fma_f32 v[12:13], v[12:13], v[196:197], v[68:69]
	s_waitcnt lgkmcnt(1)
	v_cvt_f32_f16_e32 v68, v74
	v_pk_fma_f32 v[14:15], v[14:15], v[190:191], v[70:71]
	v_cvt_f32_f16_sdwa v69, v74 dst_sel:DWORD dst_unused:UNUSED_PAD src0_sel:WORD_1
	s_waitcnt lgkmcnt(0)
	v_cvt_f32_f16_e32 v70, v75
	v_cvt_f32_f16_sdwa v71, v75 dst_sel:DWORD dst_unused:UNUSED_PAD src0_sel:WORD_1
	v_pk_fma_f32 v[8:9], v[8:9], v[188:189], v[68:69]
	v_cvt_pk_f16_f32 v69, v14, v15
	v_pk_fma_f32 v[10:11], v[10:11], v[186:187], v[70:71]
	v_cvt_pk_f16_f32 v70, v8, v9
	v_cvt_pk_f16_f32 v71, v10, v11
	v_cvt_pk_f16_f32 v68, v12, v13
	ds_bpermute_b32 v68, v214, v68
	ds_bpermute_b32 v69, v214, v69
	ds_bpermute_b32 v70, v214, v70
	ds_bpermute_b32 v71, v214, v71
	v_pk_mul_f32 v[72:73], v[178:179], v[10:11]
	v_pk_mul_f32 v[74:75], v[180:181], v[8:9]
	s_waitcnt lgkmcnt(0)
	global_store_dwordx4 v[136:137], v[68:71], off offset:2048
	s_nop 1
	v_pk_mul_f32 v[68:69], v[174:175], v[14:15]
	v_pk_mul_f32 v[70:71], v[176:177], v[12:13]
	s_nop 0
	v_cvt_pk_bf16_f32 v70, v70, v71
	v_cvt_pk_bf16_f32 v69, v68, v69
	v_cvt_pk_bf16_f32 v71, v74, v75
	v_cvt_pk_bf16_f32 v72, v72, v73
	ds_bpermute_b32 v68, v214, v70
	ds_bpermute_b32 v69, v214, v69
	ds_bpermute_b32 v70, v214, v71
	ds_bpermute_b32 v71, v214, v72
	v_add_co_u32_e32 v72, vcc, s23, v198
	s_nop 1
	v_addc_co_u32_e32 v73, vcc, 0, v199, vcc
	s_waitcnt lgkmcnt(0)
	global_store_dwordx4 v[72:73], v[68:71], off offset:2048
	s_waitcnt vmcnt(14)
	ds_bpermute_b32 v68, v216, v64
	ds_bpermute_b32 v69, v216, v65
	ds_bpermute_b32 v70, v216, v66
	ds_bpermute_b32 v71, v216, v67
	s_waitcnt lgkmcnt(3)
	v_cvt_f32_f16_e32 v64, v68
	v_cvt_f32_f16_sdwa v65, v68 dst_sel:DWORD dst_unused:UNUSED_PAD src0_sel:WORD_1
	s_waitcnt lgkmcnt(2)
	v_cvt_f32_f16_e32 v66, v69
	v_cvt_f32_f16_sdwa v67, v69 dst_sel:DWORD dst_unused:UNUSED_PAD src0_sel:WORD_1
	v_pk_fma_f32 v[4:5], v[4:5], v[184:185], v[64:65]
	s_waitcnt lgkmcnt(1)
	v_cvt_f32_f16_e32 v64, v70
	v_pk_fma_f32 v[6:7], v[6:7], v[182:183], v[66:67]
	v_cvt_f32_f16_sdwa v65, v70 dst_sel:DWORD dst_unused:UNUSED_PAD src0_sel:WORD_1
	s_waitcnt lgkmcnt(0)
	v_cvt_f32_f16_e32 v66, v71
	v_cvt_f32_f16_sdwa v67, v71 dst_sel:DWORD dst_unused:UNUSED_PAD src0_sel:WORD_1
	v_pk_fma_f32 v[0:1], v[0:1], v[172:173], v[64:65]
	v_cvt_pk_f16_f32 v65, v6, v7
	v_pk_fma_f32 v[2:3], v[2:3], v[170:171], v[66:67]
	v_cvt_pk_f16_f32 v66, v0, v1
	v_cvt_pk_f16_f32 v67, v2, v3
	v_cvt_pk_f16_f32 v64, v4, v5
	ds_bpermute_b32 v64, v214, v64
	ds_bpermute_b32 v65, v214, v65
	ds_bpermute_b32 v66, v214, v66
	ds_bpermute_b32 v67, v214, v67
	v_pk_mul_f32 v[68:69], v[166:167], v[2:3]
	v_pk_mul_f32 v[70:71], v[168:169], v[0:1]
	s_waitcnt lgkmcnt(0)
	global_store_dwordx4 v[136:137], v[64:67], off offset:2304
	s_nop 1
	v_pk_mul_f32 v[64:65], v[162:163], v[6:7]
	v_pk_mul_f32 v[66:67], v[164:165], v[4:5]
	s_nop 0
	v_cvt_pk_bf16_f32 v66, v66, v67
	v_cvt_pk_bf16_f32 v65, v64, v65
	v_cvt_pk_bf16_f32 v67, v70, v71
	v_cvt_pk_bf16_f32 v68, v68, v69
	ds_bpermute_b32 v64, v214, v66
	ds_bpermute_b32 v65, v214, v65
	ds_bpermute_b32 v66, v214, v67
	ds_bpermute_b32 v67, v214, v68
	s_waitcnt lgkmcnt(0)
	global_store_dwordx4 v[72:73], v[64:67], off offset:2304
	s_waitcnt lgkmcnt(0)
	s_nop 1
	v_mov_b32_e32 v64, v152
	v_mov_b32_e32 v65, v152
	s_nop 1
	v_permlane16_swap_b32_e32 v64, v65
	v_add_f32_e32 v64, v64, v65
	v_mov_b32_e32 v65, v64
	s_nop 1
	v_permlane32_swap_b32_e32 v64, v65
	s_and_saveexec_b64 s[34:35], s[6:7]
	s_cbranch_execz .LBB0_1345
; __device__ __forceinline__ unsigned cvt_pk_bf16(float lo, float hi) { unsigned r; asm volatile("v_cvt_pk_bf16_f32 %0, %1, %2" : "=v"(r) : "v"(lo), "v"(hi)); return r; }
; __device__ __forceinline__ float xlane(float v, int src_lane) { return __uint_as_float(__builtin_amdgcn_ds_bpermute(src_lane << 2, __float_as_uint(v))); }
;     __device__ __forceinline__ void operator()(AccT acc, const pg8::Unit& u, int wr, int wc, int fr, int fq) const {
;     ...
;                         t += ((h0[0] * h0[0] + h0[1] * h0[1]) + (h0[2] * h0[2] + h0[3] * h0[3])) + ((h1[0] * h1[0] + h1[1] * h1[1]) + (h1[2] * h1[2] + h1[3] * h1[3]));
;                         if (WZ) { const f32x4 z0 = h0 * gz[bj][0], z1 = h1 * gz[bj][1]; u32x4 w; w.x = cvt_pk_bf16(z0[0], z0[1]); w.y = cvt_pk_bf16(z0[2], z0[3]); w.z = cvt_pk_bf16(z1[0], z1[1]); w.w = cvt_pk_bf16(z1[2], z1[3]);
;                             *(u32x4*)(zout + ro + bj * 128) = gather4(w, st4); } }
;                     ss[ai * 4 + m] = t; }
;                 asm volatile("" ::: "memory");
;             }
;         }
; #pragma unroll
;         for (int g = 0; g < 8; ++g) { float t = ss[g]; t += xlane(t, lane ^ 16); t += xlane(t, lane ^ 32);
;             if (fq == 0) SSQ[(size_t)(row0 + (g >> 2) * 128 + (g & 3) * 16) * 32 + u.pn * 4 + wc] = t; }
	v_lshlrev_b64 v[66:67], 7, v[160:161]
	v_lshl_add_u64 v[66:67], s[30:31], 0, v[66:67]
	s_waitcnt lgkmcnt(0)
	v_add_f32_e32 v64, v64, v65
	global_store_dword v[66:67], v64, off
.LBB0_1345:
	s_or_b64 exec, exec, s[34:35]
	v_mul_f32_e32 v64, v109, v109
	s_waitcnt lgkmcnt(0)
	v_mul_f32_e32 v65, v111, v111
	v_fmac_f32_e32 v64, v108, v108
	v_fmac_f32_e32 v65, v110, v110
	v_add_f32_e32 v64, v64, v65
	v_mul_f32_e32 v65, v105, v105
	v_mul_f32_e32 v66, v107, v107
	v_fmac_f32_e32 v65, v104, v104
	v_fmac_f32_e32 v66, v106, v106
	v_add_f32_e32 v65, v65, v66
	v_add_f32_e32 v64, v64, v65
	v_mul_f32_e32 v65, v101, v101
	v_mul_f32_e32 v66, v103, v103
	v_fmac_f32_e32 v65, v100, v100
	v_fmac_f32_e32 v66, v102, v102
	v_add_f32_e32 v65, v65, v66
	v_mul_f32_e32 v66, v97, v97
	v_mul_f32_e32 v67, v99, v99
	v_fmac_f32_e32 v66, v96, v96
	v_fmac_f32_e32 v67, v98, v98
	v_add_f32_e32 v66, v66, v67
	v_add_f32_e32 v65, v65, v66
	v_add_f32_e32 v64, v64, v65
	s_waitcnt lgkmcnt(0)
	v_mov_b32_e32 v65, v64
	s_nop 1
	v_permlane16_swap_b32_e32 v65, v64
	v_add_f32_e32 v64, v64, v65
	v_mov_b32_e32 v65, v64
	s_nop 1
	v_permlane32_swap_b32_e32 v64, v65
	s_and_saveexec_b64 s[34:35], s[6:7]
	s_cbranch_execz .LBB0_1347
	v_or_b32_e32 v66, 16, v160
	v_ashrrev_i32_e32 v67, 31, v66
	v_lshlrev_b64 v[66:67], 7, v[66:67]
	v_lshl_add_u64 v[66:67], s[30:31], 0, v[66:67]
	s_waitcnt lgkmcnt(0)
	v_add_f32_e32 v64, v64, v65
	global_store_dword v[66:67], v64, off
.LBB0_1347:
	s_or_b64 exec, exec, s[34:35]
	v_mul_f32_e32 v64, v93, v93
	s_waitcnt lgkmcnt(0)
	v_mul_f32_e32 v65, v95, v95
	v_fmac_f32_e32 v64, v92, v92
	v_fmac_f32_e32 v65, v94, v94
	v_add_f32_e32 v64, v64, v65
	v_mul_f32_e32 v65, v89, v89
	v_mul_f32_e32 v66, v91, v91
	v_fmac_f32_e32 v65, v88, v88
	v_fmac_f32_e32 v66, v90, v90
	v_add_f32_e32 v65, v65, v66
	v_add_f32_e32 v64, v64, v65
	v_mul_f32_e32 v65, v115, v115
	v_mul_f32_e32 v66, v113, v113
	v_fmac_f32_e32 v65, v114, v114
	v_fmac_f32_e32 v66, v112, v112
	v_add_f32_e32 v65, v65, v66
	v_mul_f32_e32 v66, v119, v119
	v_mul_f32_e32 v67, v117, v117
	v_fmac_f32_e32 v66, v118, v118
	v_fmac_f32_e32 v67, v116, v116
	v_add_f32_e32 v66, v66, v67
	v_add_f32_e32 v65, v65, v66
	v_add_f32_e32 v64, v64, v65
	s_waitcnt lgkmcnt(0)
	v_mov_b32_e32 v65, v64
	s_nop 1
	v_permlane16_swap_b32_e32 v65, v64
	v_add_f32_e32 v64, v64, v65
	v_mov_b32_e32 v65, v64
	s_nop 1
	v_permlane32_swap_b32_e32 v64, v65
	s_and_saveexec_b64 s[34:35], s[6:7]
	s_cbranch_execz .LBB0_1349
	v_or_b32_e32 v66, 32, v160
	v_ashrrev_i32_e32 v67, 31, v66
	v_lshlrev_b64 v[66:67], 7, v[66:67]
	v_lshl_add_u64 v[66:67], s[30:31], 0, v[66:67]
	s_waitcnt lgkmcnt(0)
	v_add_f32_e32 v64, v64, v65
	global_store_dword v[66:67], v64, off
.LBB0_1349:
	s_or_b64 exec, exec, s[34:35]
	v_mul_f32_e32 v64, v123, v123
	s_waitcnt lgkmcnt(0)
	v_mul_f32_e32 v65, v121, v121
	v_fmac_f32_e32 v64, v122, v122
	v_fmac_f32_e32 v65, v120, v120
	v_add_f32_e32 v64, v64, v65
	v_mul_f32_e32 v65, v127, v127
	v_mul_f32_e32 v66, v125, v125
	v_fmac_f32_e32 v65, v126, v126
	v_fmac_f32_e32 v66, v124, v124
	v_add_f32_e32 v65, v65, v66
	v_add_f32_e32 v64, v64, v65
	v_mul_f32_e32 v65, v131, v131
	v_mul_f32_e32 v66, v129, v129
	v_fmac_f32_e32 v65, v130, v130
	v_fmac_f32_e32 v66, v128, v128
	v_add_f32_e32 v65, v65, v66
	v_mul_f32_e32 v66, v135, v135
	v_mul_f32_e32 v67, v133, v133
	v_fmac_f32_e32 v66, v134, v134
	v_fmac_f32_e32 v67, v132, v132
	v_add_f32_e32 v66, v66, v67
	v_add_f32_e32 v65, v65, v66
	v_add_f32_e32 v64, v64, v65
	s_waitcnt lgkmcnt(0)
	v_mov_b32_e32 v65, v64
	s_nop 1
	v_permlane16_swap_b32_e32 v65, v64
	v_add_f32_e32 v64, v64, v65
	v_mov_b32_e32 v65, v64
	s_nop 1
	v_permlane32_swap_b32_e32 v64, v65
	s_and_saveexec_b64 s[34:35], s[6:7]
	s_cbranch_execz .LBB0_1351
	v_or_b32_e32 v66, 48, v160
	v_ashrrev_i32_e32 v67, 31, v66
	v_lshlrev_b64 v[66:67], 7, v[66:67]
	v_lshl_add_u64 v[66:67], s[30:31], 0, v[66:67]
	s_waitcnt lgkmcnt(0)
	v_add_f32_e32 v64, v64, v65
	global_store_dword v[66:67], v64, off
; __device__ __forceinline__ unsigned cvt_pk_bf16(float lo, float hi) { unsigned r; asm volatile("v_cvt_pk_bf16_f32 %0, %1, %2" : "=v"(r) : "v"(lo), "v"(hi)); return r; }
; __device__ __forceinline__ float xlane(float v, int src_lane) { return __uint_as_float(__builtin_amdgcn_ds_bpermute(src_lane << 2, __float_as_uint(v))); }
;     __device__ __forceinline__ void operator()(AccT acc, const pg8::Unit& u, int wr, int wc, int fr, int fq) const {
;     ...
;                         t += ((h0[0] * h0[0] + h0[1] * h0[1]) + (h0[2] * h0[2] + h0[3] * h0[3])) + ((h1[0] * h1[0] + h1[1] * h1[1]) + (h1[2] * h1[2] + h1[3] * h1[3]));
;                         if (WZ) { const f32x4 z0 = h0 * gz[bj][0], z1 = h1 * gz[bj][1]; u32x4 w; w.x = cvt_pk_bf16(z0[0], z0[1]); w.y = cvt_pk_bf16(z0[2], z0[3]); w.z = cvt_pk_bf16(z1[0], z1[1]); w.w = cvt_pk_bf16(z1[2], z1[3]);
;                             *(u32x4*)(zout + ro + bj * 128) = gather4(w, st4); } }
;                     ss[ai * 4 + m] = t; }
;                 asm volatile("" ::: "memory");
;             }
;         }
; #pragma unroll
;         for (int g = 0; g < 8; ++g) { float t = ss[g]; t += xlane(t, lane ^ 16); t += xlane(t, lane ^ 32);
;             if (fq == 0) SSQ[(size_t)(row0 + (g >> 2) * 128 + (g & 3) * 16) * 32 + u.pn * 4 + wc] = t; }
.LBB0_1351:
	s_or_b64 exec, exec, s[34:35]
	v_mul_f32_e32 v61, v61, v61
	v_mul_f32_e32 v57, v57, v57
	v_mul_f32_e32 v53, v53, v53
	v_mul_f32_e32 v49, v49, v49
	v_fmac_f32_e32 v61, v60, v60
	v_mul_f32_e32 v60, v63, v63
	v_fmac_f32_e32 v57, v56, v56
	v_mul_f32_e32 v56, v59, v59
	v_fmac_f32_e32 v53, v52, v52
	v_mul_f32_e32 v52, v55, v55
	v_fmac_f32_e32 v49, v48, v48
	v_mul_f32_e32 v48, v51, v51
	v_fmac_f32_e32 v60, v62, v62
	v_fmac_f32_e32 v56, v58, v58
	v_fmac_f32_e32 v52, v54, v54
	v_fmac_f32_e32 v48, v50, v50
	v_add_f32_e32 v60, v61, v60
	v_add_f32_e32 v56, v57, v56
	v_add_f32_e32 v52, v53, v52
	v_add_f32_e32 v48, v49, v48
	v_add_f32_e32 v56, v60, v56
	v_add_f32_e32 v48, v52, v48
	v_add_f32_e32 v48, v56, v48
	s_waitcnt lgkmcnt(0)
	v_mov_b32_e32 v49, v48
	s_nop 1
	v_permlane16_swap_b32_e32 v49, v48
	v_add_f32_e32 v48, v48, v49
	v_mov_b32_e32 v49, v48
	s_nop 1
	v_permlane32_swap_b32_e32 v48, v49
	s_and_saveexec_b64 s[34:35], s[6:7]
	s_cbranch_execz .LBB0_1353
	v_lshlrev_b64 v[50:51], 7, v[160:161]
	v_lshl_add_u64 v[50:51], s[30:31], 0, v[50:51]
	s_waitcnt lgkmcnt(0)
	v_add_f32_e32 v52, v48, v49
	v_add_co_u32_e32 v48, vcc, 0x4000, v50
	s_nop 1
	v_addc_co_u32_e32 v49, vcc, 0, v51, vcc
	global_store_dword v[48:49], v52, off
.LBB0_1353:
	s_or_b64 exec, exec, s[34:35]
	v_mul_f32_e32 v45, v45, v45
	v_mul_f32_e32 v41, v41, v41
	v_mul_f32_e32 v37, v37, v37
	v_mul_f32_e32 v33, v33, v33
	v_fmac_f32_e32 v45, v44, v44
	v_mul_f32_e32 v44, v47, v47
	v_fmac_f32_e32 v41, v40, v40
	v_mul_f32_e32 v40, v43, v43
	v_fmac_f32_e32 v37, v36, v36
	v_mul_f32_e32 v36, v39, v39
	v_fmac_f32_e32 v33, v32, v32
	v_mul_f32_e32 v32, v35, v35
	v_fmac_f32_e32 v44, v46, v46
	v_fmac_f32_e32 v40, v42, v42
	v_fmac_f32_e32 v36, v38, v38
	v_fmac_f32_e32 v32, v34, v34
	v_add_f32_e32 v44, v45, v44
	v_add_f32_e32 v40, v41, v40
	v_add_f32_e32 v36, v37, v36
	v_add_f32_e32 v32, v33, v32
	v_add_f32_e32 v40, v44, v40
	v_add_f32_e32 v32, v36, v32
	v_add_f32_e32 v32, v40, v32
	s_waitcnt lgkmcnt(0)
	v_mov_b32_e32 v33, v32
	s_nop 1
	v_permlane16_swap_b32_e32 v33, v32
	v_add_f32_e32 v32, v32, v33
	v_mov_b32_e32 v33, v32
	s_nop 1
	v_permlane32_swap_b32_e32 v32, v33
	s_and_saveexec_b64 s[34:35], s[6:7]
	s_cbranch_execz .LBB0_1355
	v_lshlrev_b64 v[34:35], 7, v[160:161]
	v_lshl_add_u64 v[34:35], s[30:31], 0, v[34:35]
	s_waitcnt lgkmcnt(0)
	v_add_f32_e32 v36, v32, v33
	v_add_co_u32_e32 v32, vcc, 0x4000, v34
	s_nop 1
	v_addc_co_u32_e32 v33, vcc, 0, v35, vcc
	global_store_dword v[32:33], v36, off offset:2048
.LBB0_1355:
	s_or_b64 exec, exec, s[34:35]
	v_mul_f32_e32 v29, v29, v29
	v_mul_f32_e32 v25, v25, v25
	v_mul_f32_e32 v21, v21, v21
	v_mul_f32_e32 v17, v17, v17
	v_fmac_f32_e32 v29, v28, v28
	v_mul_f32_e32 v28, v31, v31
	v_fmac_f32_e32 v25, v24, v24
	v_mul_f32_e32 v24, v27, v27
	v_fmac_f32_e32 v21, v20, v20
	v_mul_f32_e32 v20, v23, v23
	v_fmac_f32_e32 v17, v16, v16
	v_mul_f32_e32 v16, v19, v19
	v_fmac_f32_e32 v28, v30, v30
	v_fmac_f32_e32 v24, v26, v26
	v_fmac_f32_e32 v20, v22, v22
	v_fmac_f32_e32 v16, v18, v18
	v_add_f32_e32 v28, v29, v28
	v_add_f32_e32 v24, v25, v24
	v_add_f32_e32 v20, v21, v20
	v_add_f32_e32 v16, v17, v16
	v_add_f32_e32 v24, v28, v24
	v_add_f32_e32 v16, v20, v16
	v_add_f32_e32 v16, v24, v16
	s_waitcnt lgkmcnt(0)
	v_mov_b32_e32 v17, v16
	s_nop 1
	v_permlane16_swap_b32_e32 v17, v16
	v_add_f32_e32 v16, v16, v17
	v_mov_b32_e32 v17, v16
	s_nop 1
	v_permlane32_swap_b32_e32 v16, v17
	s_and_saveexec_b64 s[34:35], s[6:7]
	s_cbranch_execz .LBB0_1357
	v_lshlrev_b64 v[18:19], 7, v[160:161]
	v_lshl_add_u64 v[18:19], s[30:31], 0, v[18:19]
	s_waitcnt lgkmcnt(0)
	v_add_f32_e32 v20, v16, v17
	v_add_co_u32_e32 v16, vcc, 0x5000, v18
	s_nop 1
	v_addc_co_u32_e32 v17, vcc, 0, v19, vcc
	global_store_dword v[16:17], v20, off
.LBB0_1357:
	s_or_b64 exec, exec, s[34:35]
	v_mul_f32_e32 v13, v13, v13
	v_mul_f32_e32 v9, v9, v9
	v_mul_f32_e32 v5, v5, v5
	v_mul_f32_e32 v1, v1, v1
	v_fmac_f32_e32 v13, v12, v12
	v_mul_f32_e32 v12, v15, v15
	v_fmac_f32_e32 v9, v8, v8
	v_mul_f32_e32 v8, v11, v11
	v_fmac_f32_e32 v5, v4, v4
	v_mul_f32_e32 v4, v7, v7
	v_fmac_f32_e32 v1, v0, v0
	v_mul_f32_e32 v0, v3, v3
	v_fmac_f32_e32 v12, v14, v14
	v_fmac_f32_e32 v8, v10, v10
	v_fmac_f32_e32 v4, v6, v6
	v_fmac_f32_e32 v0, v2, v2
	v_add_f32_e32 v12, v13, v12
	v_add_f32_e32 v8, v9, v8
	v_add_f32_e32 v4, v5, v4
	v_add_f32_e32 v0, v1, v0
	v_add_f32_e32 v8, v12, v8
	v_add_f32_e32 v0, v4, v0
	v_add_f32_e32 v0, v8, v0
	s_waitcnt lgkmcnt(0)
	v_mov_b32_e32 v1, v0
	s_nop 1
	v_permlane16_swap_b32_e32 v1, v0
	v_add_f32_e32 v0, v0, v1
	v_mov_b32_e32 v1, v0
	s_nop 1
	v_permlane32_swap_b32_e32 v0, v1
	s_and_saveexec_b64 s[34:35], s[6:7]
	s_cbranch_execz .LBB0_1359
	v_lshlrev_b64 v[2:3], 7, v[160:161]
	v_lshl_add_u64 v[2:3], s[30:31], 0, v[2:3]
	s_waitcnt lgkmcnt(0)
	v_add_f32_e32 v4, v0, v1
	v_add_co_u32_e32 v0, vcc, 0x5000, v2
	s_nop 1
	v_addc_co_u32_e32 v1, vcc, 0, v3, vcc
	global_store_dword v[0:1], v4, off offset:2048
